# PEER u/v gathers: scalar-base addressing (s[98:99] + 32-bit per-lane offset) instead of 64-bit VALU address math; redundant lgkm wait ladders collapsed
# speedup vs baseline: 1.0232x; 1.0063x over previous
; #define MFMA(a, b, c) __builtin_amdgcn_mfma_f32_32x32x16_bf16((a), (b), (c), 0, 0, 0)
; DI unsigned f2ord(float f) { const unsigned u = __float_as_uint(f); return (u & 0x80000000u) ? ~u : (u | 0x80000000u); }
; DI void peer_topk_phase(const bf16_t* __restrict__ qpk, const bf16_t* __restrict__ subk, int* __restrict__ eidx, float* __restrict__ gout) {
;     ...
;             const bf16_t* qp = qpk + (size_t)(t0 + r) * 1024 + hh * 128 + c * 64 + h * 8;
;             const bf16_t* kp = subk + ((size_t)(hh * 2 + c) * 128 + r) * 64 + h * 8;
; #pragma unroll
;             for (int ks = 0; ks < 4; ++ks) {
;                 const bf16x8 qfr = *(const bf16x8*)(qp + ks * 16);
; #pragma unroll
;                 for (int nb = 0; nb < 4; ++nb) {
;                     const bf16x8 kf = *(const bf16x8*)(kp + nb * 32 * 64 + ks * 16);
;                     acc[nb] = MFMA(kf, qfr, acc[nb]);
;                 }
;             }
;             unsigned key[64];
; #pragma unroll
;             for (int nb = 0; nb < 4; ++nb)
; #pragma unroll
;                 for (int i = 0; i < 16; ++i) {
;                     const int n = nb * 32 + (i & 3) + 8 * (i >> 2) + 4 * h;
;                     key[nb * 16 + i] = (f2ord(acc[nb][i]) & ~127u) | (unsigned)(127 - n);
.LBB0_466:
	v_and_or_b32 v80, v154, s21, v84
	v_ashrrev_i32_e32 v81, 31, v80
	v_and_b32_e32 v156, 7, v1
	v_lshlrev_b64 v[2:3], 11, v[80:81]
	v_lshl_add_u64 v[2:3], s[40:41], 0, v[2:3]
	v_lshlrev_b32_e32 v74, 8, v156
	v_lshl_add_u64 v[2:3], v[2:3], 0, v[74:75]
	v_mov_b32_e32 v79, v75
	v_lshl_add_u64 v[66:67], v[2:3], 0, v[78:79]
	v_lshl_or_b32 v74, v156, 15, v155
	v_lshl_add_u64 v[68:69], v[76:77], 0, v[74:75]
	v_add_co_u32_e32 v72, vcc, s24, v68
	s_nop 1
	v_addc_co_u32_e32 v73, vcc, 0, v69, vcc
	v_add_co_u32_e32 v82, vcc, s25, v68
	s_nop 1
	v_addc_co_u32_e32 v83, vcc, 0, v69, vcc
	v_add_co_u32_e32 v166, vcc, s27, v68
	s_nop 1
	v_addc_co_u32_e32 v167, vcc, 0, v69, vcc
	v_add_co_u32_e32 v70, vcc, s4, v68
	s_nop 1
	v_addc_co_u32_e32 v71, vcc, 0, v69, vcc
	global_load_dwordx4 v[2:5], v[66:67], off
	global_load_dwordx4 v[6:9], v[68:69], off
	global_load_dwordx4 v[162:165], v[72:73], off
	global_load_dwordx4 v[198:201], v[82:83], off
	global_load_dwordx4 v[210:213], v[166:167], off
	global_load_dwordx4 v[158:161], v[66:67], off offset:32
	global_load_dwordx4 v[214:217], v[68:69], off offset:32
	global_load_dwordx4 v[218:221], v[72:73], off offset:32
	global_load_dwordx4 v[222:225], v[82:83], off offset:32
	global_load_dwordx4 v[226:229], v[166:167], off offset:32
	global_load_dwordx4 v[182:185], v[66:67], off offset:64
	global_load_dwordx4 v[232:235], v[68:69], off offset:64
	global_load_dwordx4 v[236:239], v[72:73], off offset:64
	global_load_dwordx4 v[240:243], v[82:83], off offset:64
	global_load_dwordx4 v[244:247], v[166:167], off offset:64
	global_load_dwordx4 v[186:189], v[66:67], off offset:96
	global_load_dwordx4 v[248:251], v[68:69], off offset:96
	s_waitcnt vmcnt(15)
	v_mfma_f32_32x32x16_bf16 v[50:65], v[6:9], v[2:5], 0
	s_waitcnt vmcnt(14)
	v_mfma_f32_32x32x16_bf16 v[34:49], v[162:165], v[2:5], 0
	s_waitcnt vmcnt(13)
	v_mfma_f32_32x32x16_bf16 v[18:33], v[198:201], v[2:5], 0
	s_waitcnt vmcnt(12)
	v_mfma_f32_32x32x16_bf16 v[2:17], v[210:213], v[2:5], 0
	global_load_dwordx4 v[162:165], v[72:73], off offset:96
	global_load_dwordx4 v[198:201], v[82:83], off offset:96
	global_load_dwordx4 v[210:213], v[166:167], off offset:96
	s_waitcnt vmcnt(13)
	v_mfma_f32_32x32x16_bf16 v[50:65], v[214:217], v[158:161], v[50:65]
	s_waitcnt vmcnt(12)
	v_mfma_f32_32x32x16_bf16 v[34:49], v[218:221], v[158:161], v[34:49]
	s_waitcnt vmcnt(11)
	v_mfma_f32_32x32x16_bf16 v[18:33], v[222:225], v[158:161], v[18:33]
	s_waitcnt vmcnt(10)
	v_mfma_f32_32x32x16_bf16 v[2:17], v[226:229], v[158:161], v[2:17]
	s_waitcnt vmcnt(8)
	v_mfma_f32_32x32x16_bf16 v[50:65], v[232:235], v[182:185], v[50:65]
	s_waitcnt vmcnt(7)
	v_mfma_f32_32x32x16_bf16 v[34:49], v[236:239], v[182:185], v[34:49]
	s_waitcnt vmcnt(6)
	v_mfma_f32_32x32x16_bf16 v[18:33], v[240:243], v[182:185], v[18:33]
	s_waitcnt vmcnt(5)
	v_mfma_f32_32x32x16_bf16 v[2:17], v[244:247], v[182:185], v[2:17]
	s_waitcnt vmcnt(3)
	v_mfma_f32_32x32x16_bf16 v[50:65], v[248:251], v[186:189], v[50:65]
	s_nop 11
	v_not_b32_e32 v72, v50
	v_or_b32_e32 v73, 0x80000000, v50
	v_cmp_gt_i32_e32 vcc, 0, v50
	s_waitcnt vmcnt(2)
	v_mfma_f32_32x32x16_bf16 v[34:49], v[162:165], v[186:189], v[34:49]
	v_cndmask_b32_e32 v50, v73, v72, vcc
	v_not_b32_e32 v72, v51
	v_or_b32_e32 v73, 0x80000000, v51
	v_cmp_gt_i32_e32 vcc, 0, v51
	v_and_or_b32 v50, v50, s42, v85
	s_nop 0
	v_cndmask_b32_e32 v51, v73, v72, vcc
	v_not_b32_e32 v72, v52
	v_or_b32_e32 v73, 0x80000000, v52
	v_cmp_gt_i32_e32 vcc, 0, v52
	v_and_or_b32 v51, v51, s42, v86
	s_waitcnt vmcnt(1)
	v_mfma_f32_32x32x16_bf16 v[18:33], v[198:201], v[186:189], v[18:33]
	v_cndmask_b32_e32 v52, v73, v72, vcc
	v_not_b32_e32 v72, v53
	v_or_b32_e32 v73, 0x80000000, v53
	v_cmp_gt_i32_e32 vcc, 0, v53
	v_and_or_b32 v52, v52, s42, v87
	s_nop 0
	v_cndmask_b32_e32 v53, v73, v72, vcc
	v_not_b32_e32 v72, v54
	v_or_b32_e32 v73, 0x80000000, v54
	v_cmp_gt_i32_e32 vcc, 0, v54
	v_and_or_b32 v53, v53, s42, v88
	s_waitcnt vmcnt(0)
	v_mfma_f32_32x32x16_bf16 v[2:17], v[210:213], v[186:189], v[2:17]
	v_cndmask_b32_e32 v54, v73, v72, vcc
	v_not_b32_e32 v72, v55
	v_or_b32_e32 v73, 0x80000000, v55
	v_cmp_gt_i32_e32 vcc, 0, v55
	v_and_or_b32 v54, v54, s42, v89
	s_nop 0
	v_cndmask_b32_e32 v55, v73, v72, vcc
	v_not_b32_e32 v72, v56
	v_or_b32_e32 v73, 0x80000000, v56
	v_cmp_gt_i32_e32 vcc, 0, v56
	v_and_or_b32 v55, v55, s42, v90
	s_nop 0
	v_cndmask_b32_e32 v56, v73, v72, vcc
	v_not_b32_e32 v72, v57
	v_or_b32_e32 v73, 0x80000000, v57
	v_cmp_gt_i32_e32 vcc, 0, v57
	v_and_or_b32 v56, v56, s42, v91
	s_nop 0
	v_cndmask_b32_e32 v57, v73, v72, vcc
	v_not_b32_e32 v72, v58
	v_or_b32_e32 v73, 0x80000000, v58
	v_cmp_gt_i32_e32 vcc, 0, v58
	v_and_or_b32 v57, v57, s42, v92
	s_nop 0
	v_cndmask_b32_e32 v58, v73, v72, vcc
	v_not_b32_e32 v72, v59
	v_or_b32_e32 v73, 0x80000000, v59
	v_cmp_gt_i32_e32 vcc, 0, v59
	v_and_or_b32 v58, v58, s42, v93
	s_nop 0
	v_cndmask_b32_e32 v59, v73, v72, vcc
	v_not_b32_e32 v72, v60
	v_or_b32_e32 v73, 0x80000000, v60
	v_cmp_gt_i32_e32 vcc, 0, v60
	v_and_or_b32 v59, v59, s42, v94
	s_nop 0
	v_cndmask_b32_e32 v60, v73, v72, vcc
	v_not_b32_e32 v72, v61
	v_or_b32_e32 v73, 0x80000000, v61
	v_cmp_gt_i32_e32 vcc, 0, v61
	v_and_or_b32 v60, v60, s42, v95
	s_nop 0
	v_cndmask_b32_e32 v61, v73, v72, vcc
	v_not_b32_e32 v72, v62
	v_or_b32_e32 v73, 0x80000000, v62
	v_cmp_gt_i32_e32 vcc, 0, v62
	v_and_or_b32 v61, v61, s42, v96
	s_nop 0
	v_cndmask_b32_e32 v62, v73, v72, vcc
	v_not_b32_e32 v72, v63
	v_or_b32_e32 v73, 0x80000000, v63
	v_cmp_gt_i32_e32 vcc, 0, v63
	v_and_or_b32 v62, v62, s42, v97
	s_nop 0
	v_cndmask_b32_e32 v63, v73, v72, vcc
	v_not_b32_e32 v72, v64
	v_or_b32_e32 v73, 0x80000000, v64
	v_cmp_gt_i32_e32 vcc, 0, v64
; DI unsigned f2ord(float f) { const unsigned u = __float_as_uint(f); return (u & 0x80000000u) ? ~u : (u | 0x80000000u); }
; DI void peer_topk_phase(const bf16_t* __restrict__ qpk, const bf16_t* __restrict__ subk, int* __restrict__ eidx, float* __restrict__ gout) {
;     ...
;             for (int nb = 0; nb < 4; ++nb)
; #pragma unroll
;                 for (int i = 0; i < 16; ++i) {
;                     const int n = nb * 32 + (i & 3) + 8 * (i >> 2) + 4 * h;
;                     key[nb * 16 + i] = (f2ord(acc[nb][i]) & ~127u) | (unsigned)(127 - n);
	v_and_or_b32 v63, v63, s42, v98
	s_nop 0
	v_cndmask_b32_e32 v64, v73, v72, vcc
	v_not_b32_e32 v72, v65
	v_or_b32_e32 v73, 0x80000000, v65
	v_cmp_gt_i32_e32 vcc, 0, v65
	v_and_or_b32 v64, v64, s42, v99
	s_nop 0
	v_cndmask_b32_e32 v65, v73, v72, vcc
	v_not_b32_e32 v72, v34
	v_or_b32_e32 v73, 0x80000000, v34
	v_cmp_gt_i32_e32 vcc, 0, v34
	v_and_or_b32 v65, v65, s42, v100
	s_nop 0
	v_cndmask_b32_e32 v34, v73, v72, vcc
	v_not_b32_e32 v72, v35
	v_or_b32_e32 v73, 0x80000000, v35
	v_cmp_gt_i32_e32 vcc, 0, v35
	v_and_or_b32 v34, v34, s42, v101
	s_nop 0
	v_cndmask_b32_e32 v35, v73, v72, vcc
	v_not_b32_e32 v72, v36
	v_or_b32_e32 v73, 0x80000000, v36
	v_cmp_gt_i32_e32 vcc, 0, v36
	v_and_or_b32 v35, v35, s42, v102
	s_nop 0
	v_cndmask_b32_e32 v36, v73, v72, vcc
	v_not_b32_e32 v72, v37
	v_or_b32_e32 v73, 0x80000000, v37
	v_cmp_gt_i32_e32 vcc, 0, v37
	v_and_or_b32 v36, v36, s42, v103
	s_nop 0
	v_cndmask_b32_e32 v37, v73, v72, vcc
	v_not_b32_e32 v72, v38
	v_or_b32_e32 v73, 0x80000000, v38
	v_cmp_gt_i32_e32 vcc, 0, v38
	v_and_or_b32 v37, v37, s42, v104
	s_nop 0
	v_cndmask_b32_e32 v38, v73, v72, vcc
	v_not_b32_e32 v72, v39
	v_or_b32_e32 v73, 0x80000000, v39
	v_cmp_gt_i32_e32 vcc, 0, v39
	v_and_or_b32 v38, v38, s42, v105
	s_nop 0
	v_cndmask_b32_e32 v39, v73, v72, vcc
	v_not_b32_e32 v72, v40
	v_or_b32_e32 v73, 0x80000000, v40
	v_cmp_gt_i32_e32 vcc, 0, v40
	v_and_or_b32 v39, v39, s42, v106
	s_nop 0
	v_cndmask_b32_e32 v40, v73, v72, vcc
	v_not_b32_e32 v72, v41
	v_or_b32_e32 v73, 0x80000000, v41
	v_cmp_gt_i32_e32 vcc, 0, v41
	v_and_or_b32 v40, v40, s42, v107
	s_nop 0
	v_cndmask_b32_e32 v41, v73, v72, vcc
	v_not_b32_e32 v72, v42
	v_or_b32_e32 v73, 0x80000000, v42
	v_cmp_gt_i32_e32 vcc, 0, v42
	v_and_or_b32 v41, v41, s42, v108
	s_nop 0
	v_cndmask_b32_e32 v42, v73, v72, vcc
	v_not_b32_e32 v72, v43
	v_or_b32_e32 v73, 0x80000000, v43
	v_cmp_gt_i32_e32 vcc, 0, v43
	v_and_or_b32 v42, v42, s42, v109
	s_nop 0
	v_cndmask_b32_e32 v43, v73, v72, vcc
	v_not_b32_e32 v72, v44
	v_or_b32_e32 v73, 0x80000000, v44
	v_cmp_gt_i32_e32 vcc, 0, v44
	v_and_or_b32 v43, v43, s42, v110
	s_nop 0
	v_cndmask_b32_e32 v44, v73, v72, vcc
	v_not_b32_e32 v72, v45
	v_or_b32_e32 v73, 0x80000000, v45
	v_cmp_gt_i32_e32 vcc, 0, v45
	v_and_or_b32 v44, v44, s42, v111
	s_nop 0
	v_cndmask_b32_e32 v45, v73, v72, vcc
	v_not_b32_e32 v72, v46
	v_or_b32_e32 v73, 0x80000000, v46
	v_cmp_gt_i32_e32 vcc, 0, v46
	v_and_or_b32 v45, v45, s42, v112
	s_nop 0
	v_cndmask_b32_e32 v46, v73, v72, vcc
	v_not_b32_e32 v72, v47
	v_or_b32_e32 v73, 0x80000000, v47
	v_cmp_gt_i32_e32 vcc, 0, v47
	v_and_or_b32 v46, v46, s42, v113
	s_nop 0
	v_cndmask_b32_e32 v47, v73, v72, vcc
	v_not_b32_e32 v72, v48
	v_or_b32_e32 v73, 0x80000000, v48
	v_cmp_gt_i32_e32 vcc, 0, v48
	v_and_or_b32 v47, v47, s42, v114
	s_nop 0
	v_cndmask_b32_e32 v48, v73, v72, vcc
	v_not_b32_e32 v72, v49
	v_or_b32_e32 v73, 0x80000000, v49
	v_cmp_gt_i32_e32 vcc, 0, v49
	v_and_or_b32 v48, v48, s42, v115
	s_nop 0
	v_cndmask_b32_e32 v49, v73, v72, vcc
	v_not_b32_e32 v72, v18
	v_or_b32_e32 v73, 0x80000000, v18
	v_cmp_gt_i32_e32 vcc, 0, v18
	v_and_or_b32 v49, v49, s42, v116
	s_nop 0
	v_cndmask_b32_e32 v18, v73, v72, vcc
	v_not_b32_e32 v72, v19
	v_or_b32_e32 v73, 0x80000000, v19
	v_cmp_gt_i32_e32 vcc, 0, v19
	v_and_or_b32 v18, v18, s42, v117
	s_nop 0
	v_cndmask_b32_e32 v19, v73, v72, vcc
	v_not_b32_e32 v72, v20
	v_or_b32_e32 v73, 0x80000000, v20
	v_cmp_gt_i32_e32 vcc, 0, v20
	v_and_or_b32 v19, v19, s42, v118
	s_nop 0
	v_cndmask_b32_e32 v20, v73, v72, vcc
	v_not_b32_e32 v72, v21
	v_or_b32_e32 v73, 0x80000000, v21
	v_cmp_gt_i32_e32 vcc, 0, v21
	v_and_or_b32 v20, v20, s42, v119
	s_nop 0
	v_cndmask_b32_e32 v21, v73, v72, vcc
	v_not_b32_e32 v72, v22
	v_or_b32_e32 v73, 0x80000000, v22
	v_cmp_gt_i32_e32 vcc, 0, v22
	v_and_or_b32 v21, v21, s42, v120
	s_nop 0
	v_cndmask_b32_e32 v22, v73, v72, vcc
	v_not_b32_e32 v72, v23
	v_or_b32_e32 v73, 0x80000000, v23
	v_cmp_gt_i32_e32 vcc, 0, v23
	v_and_or_b32 v22, v22, s42, v121
	s_nop 0
	v_cndmask_b32_e32 v23, v73, v72, vcc
	v_not_b32_e32 v72, v24
	v_or_b32_e32 v73, 0x80000000, v24
	v_cmp_gt_i32_e32 vcc, 0, v24
	v_and_or_b32 v23, v23, s42, v122
	s_nop 0
	v_cndmask_b32_e32 v24, v73, v72, vcc
	v_not_b32_e32 v72, v25
	v_or_b32_e32 v73, 0x80000000, v25
	v_cmp_gt_i32_e32 vcc, 0, v25
	v_and_or_b32 v24, v24, s42, v123
	s_nop 0
	v_cndmask_b32_e32 v25, v73, v72, vcc
	v_not_b32_e32 v72, v26
	v_or_b32_e32 v73, 0x80000000, v26
	v_cmp_gt_i32_e32 vcc, 0, v26
	v_and_or_b32 v25, v25, s42, v124
	s_nop 0
	v_cndmask_b32_e32 v26, v73, v72, vcc
	v_not_b32_e32 v72, v27
	v_or_b32_e32 v73, 0x80000000, v27
	v_cmp_gt_i32_e32 vcc, 0, v27
	v_and_or_b32 v26, v26, s42, v125
	s_nop 0
	v_cndmask_b32_e32 v27, v73, v72, vcc
	v_not_b32_e32 v72, v28
	v_or_b32_e32 v73, 0x80000000, v28
	v_cmp_gt_i32_e32 vcc, 0, v28
	v_and_or_b32 v27, v27, s42, v126
	s_nop 0
	v_cndmask_b32_e32 v28, v73, v72, vcc
	v_not_b32_e32 v72, v29
	v_or_b32_e32 v73, 0x80000000, v29
	v_cmp_gt_i32_e32 vcc, 0, v29
	v_and_or_b32 v28, v28, s42, v127
	s_nop 0
	v_cndmask_b32_e32 v29, v73, v72, vcc
	v_not_b32_e32 v72, v30
	v_or_b32_e32 v73, 0x80000000, v30
	v_cmp_gt_i32_e32 vcc, 0, v30
	v_and_or_b32 v29, v29, s42, v128
	s_nop 0
	v_cndmask_b32_e32 v30, v73, v72, vcc
	v_not_b32_e32 v72, v31
	v_or_b32_e32 v73, 0x80000000, v31
	v_cmp_gt_i32_e32 vcc, 0, v31
	v_and_or_b32 v30, v30, s42, v129
	s_nop 0
	v_cndmask_b32_e32 v31, v73, v72, vcc
	v_not_b32_e32 v72, v32
	v_or_b32_e32 v73, 0x80000000, v32
	v_cmp_gt_i32_e32 vcc, 0, v32
	v_and_or_b32 v31, v31, s42, v130
	s_nop 0
	v_cndmask_b32_e32 v32, v73, v72, vcc
	v_not_b32_e32 v72, v33
	v_or_b32_e32 v73, 0x80000000, v33
	v_cmp_gt_i32_e32 vcc, 0, v33
	v_and_or_b32 v32, v32, s42, v131
; DI unsigned f2ord(float f) { const unsigned u = __float_as_uint(f); return (u & 0x80000000u) ? ~u : (u | 0x80000000u); }
; DI void peer_topk_phase(const bf16_t* __restrict__ qpk, const bf16_t* __restrict__ subk, int* __restrict__ eidx, float* __restrict__ gout) {
;     ...
;             for (int nb = 0; nb < 4; ++nb)
; #pragma unroll
;                 for (int i = 0; i < 16; ++i) {
;                     const int n = nb * 32 + (i & 3) + 8 * (i >> 2) + 4 * h;
;                     key[nb * 16 + i] = (f2ord(acc[nb][i]) & ~127u) | (unsigned)(127 - n);
;                 }
;             unsigned g0[16], g1[16], g2[16], g3[16];
; #pragma unroll
;             for (int i = 0; i < 16; ++i) { g0[i] = key[i]; g1[i] = key[16 + i]; g2[i] = key[32 + i]; g3[i] = key[48 + i]; }
; #pragma unroll
;             for (int n = 0; n < 63; ++n) { cex(g0[SORT16[n][0]], g0[SORT16[n][1]]); cex(g1[SORT16[n][0]], g1[SORT16[n][1]]); cex(g2[SORT16[n][0]], g2[SORT16[n][1]]); cex(g3[SORT16[n][0]], g3[SORT16[n][1]]); }
	s_nop 0
	v_cndmask_b32_e32 v33, v73, v72, vcc
	v_not_b32_e32 v72, v2
	v_or_b32_e32 v73, 0x80000000, v2
	v_cmp_gt_i32_e32 vcc, 0, v2
	v_and_or_b32 v33, v33, s42, v132
	s_nop 0
	v_cndmask_b32_e32 v2, v73, v72, vcc
	v_not_b32_e32 v72, v3
	v_or_b32_e32 v73, 0x80000000, v3
	v_cmp_gt_i32_e32 vcc, 0, v3
	v_and_or_b32 v2, v2, s42, v133
	s_nop 0
	v_cndmask_b32_e32 v3, v73, v72, vcc
	v_not_b32_e32 v72, v4
	v_or_b32_e32 v73, 0x80000000, v4
	v_cmp_gt_i32_e32 vcc, 0, v4
	v_and_or_b32 v3, v3, s42, v134
	s_nop 0
	v_cndmask_b32_e32 v4, v73, v72, vcc
	v_not_b32_e32 v72, v5
	v_or_b32_e32 v73, 0x80000000, v5
	v_cmp_gt_i32_e32 vcc, 0, v5
	v_and_or_b32 v4, v4, s42, v135
	s_nop 0
	v_cndmask_b32_e32 v5, v73, v72, vcc
	v_not_b32_e32 v72, v6
	v_or_b32_e32 v73, 0x80000000, v6
	v_cmp_gt_i32_e32 vcc, 0, v6
	v_and_or_b32 v5, v5, s42, v136
	s_nop 0
	v_cndmask_b32_e32 v6, v73, v72, vcc
	v_not_b32_e32 v72, v7
	v_or_b32_e32 v73, 0x80000000, v7
	v_cmp_gt_i32_e32 vcc, 0, v7
	v_and_or_b32 v6, v6, s42, v137
	s_nop 0
	v_cndmask_b32_e32 v7, v73, v72, vcc
	v_not_b32_e32 v72, v8
	v_or_b32_e32 v73, 0x80000000, v8
	v_cmp_gt_i32_e32 vcc, 0, v8
	v_and_or_b32 v7, v7, s42, v138
	s_nop 0
	v_cndmask_b32_e32 v8, v73, v72, vcc
	v_not_b32_e32 v72, v9
	v_or_b32_e32 v73, 0x80000000, v9
	v_cmp_gt_i32_e32 vcc, 0, v9
	v_and_or_b32 v8, v8, s42, v139
	s_nop 0
	v_cndmask_b32_e32 v9, v73, v72, vcc
	v_not_b32_e32 v72, v10
	v_or_b32_e32 v73, 0x80000000, v10
	v_cmp_gt_i32_e32 vcc, 0, v10
	v_and_or_b32 v9, v9, s42, v140
	s_nop 0
	v_cndmask_b32_e32 v10, v73, v72, vcc
	v_not_b32_e32 v72, v11
	v_or_b32_e32 v73, 0x80000000, v11
	v_cmp_gt_i32_e32 vcc, 0, v11
	v_and_or_b32 v10, v10, s42, v141
	s_nop 0
	v_cndmask_b32_e32 v11, v73, v72, vcc
	v_not_b32_e32 v72, v12
	v_or_b32_e32 v73, 0x80000000, v12
	v_cmp_gt_i32_e32 vcc, 0, v12
	v_and_or_b32 v11, v11, s42, v142
	s_nop 0
	v_cndmask_b32_e32 v12, v73, v72, vcc
	v_not_b32_e32 v72, v13
	v_or_b32_e32 v73, 0x80000000, v13
	v_cmp_gt_i32_e32 vcc, 0, v13
	v_and_or_b32 v12, v12, s42, v143
	s_nop 0
	v_cndmask_b32_e32 v13, v73, v72, vcc
	v_not_b32_e32 v72, v14
	v_or_b32_e32 v73, 0x80000000, v14
	v_cmp_gt_i32_e32 vcc, 0, v14
	v_and_or_b32 v13, v13, s42, v144
	s_nop 0
	v_cndmask_b32_e32 v14, v73, v72, vcc
	v_not_b32_e32 v72, v15
	v_or_b32_e32 v73, 0x80000000, v15
	v_cmp_gt_i32_e32 vcc, 0, v15
	v_and_or_b32 v14, v14, s42, v145
	s_nop 0
	v_cndmask_b32_e32 v15, v73, v72, vcc
	v_not_b32_e32 v72, v16
	v_or_b32_e32 v73, 0x80000000, v16
	v_cmp_gt_i32_e32 vcc, 0, v16
	v_and_or_b32 v15, v15, s42, v149
	s_nop 0
	v_cndmask_b32_e32 v16, v73, v72, vcc
	v_not_b32_e32 v72, v17
	v_or_b32_e32 v73, 0x80000000, v17
	v_cmp_gt_i32_e32 vcc, 0, v17
	v_and_or_b32 v16, v16, s42, v152
	s_nop 0
	v_cndmask_b32_e32 v17, v73, v72, vcc
	v_max_u32_e32 v72, v50, v51
	v_min_u32_e32 v50, v50, v51
	v_max_u32_e32 v51, v34, v35
	v_min_u32_e32 v34, v34, v35
	v_max_u32_e32 v35, v18, v19
	v_min_u32_e32 v18, v18, v19
	v_max_u32_e32 v19, v2, v3
	v_min_u32_e32 v2, v2, v3
	v_max_u32_e32 v3, v52, v53
	v_min_u32_e32 v52, v52, v53
	v_max_u32_e32 v53, v36, v37
	v_min_u32_e32 v36, v36, v37
	v_max_u32_e32 v37, v20, v21
	v_min_u32_e32 v20, v20, v21
	v_max_u32_e32 v21, v4, v5
	v_min_u32_e32 v4, v4, v5
	v_max_u32_e32 v5, v72, v3
	v_min_u32_e32 v3, v72, v3
	v_max_u32_e32 v72, v51, v53
	v_min_u32_e32 v51, v51, v53
	v_max_u32_e32 v53, v35, v37
	v_min_u32_e32 v35, v35, v37
	v_max_u32_e32 v37, v19, v21
	v_min_u32_e32 v19, v19, v21
	v_max_u32_e32 v21, v50, v52
	v_min_u32_e32 v50, v50, v52
	v_max_u32_e32 v52, v34, v36
	v_min_u32_e32 v34, v34, v36
	v_max_u32_e32 v36, v18, v20
	v_min_u32_e32 v18, v18, v20
	v_max_u32_e32 v20, v2, v4
	v_min_u32_e32 v2, v2, v4
	v_max_u32_e32 v4, v21, v3
	v_min_u32_e32 v3, v21, v3
	v_max_u32_e32 v21, v52, v51
	v_min_u32_e32 v51, v52, v51
	v_max_u32_e32 v52, v36, v35
	v_min_u32_e32 v35, v36, v35
	v_max_u32_e32 v36, v20, v19
	v_min_u32_e32 v19, v20, v19
	v_max_u32_e32 v20, v54, v55
	v_min_u32_e32 v54, v54, v55
	v_max_u32_e32 v55, v38, v39
	v_min_u32_e32 v38, v38, v39
	v_max_u32_e32 v39, v22, v23
	v_min_u32_e32 v22, v22, v23
	v_max_u32_e32 v23, v6, v7
	v_min_u32_e32 v6, v6, v7
	v_max_u32_e32 v7, v56, v57
	v_min_u32_e32 v56, v56, v57
	v_max_u32_e32 v57, v40, v41
	v_min_u32_e32 v40, v40, v41
	v_max_u32_e32 v41, v24, v25
	v_min_u32_e32 v24, v24, v25
	v_max_u32_e32 v25, v8, v9
	v_min_u32_e32 v8, v8, v9
	v_max_u32_e32 v9, v20, v7
	v_min_u32_e32 v7, v20, v7
	v_max_u32_e32 v20, v55, v57
	v_min_u32_e32 v55, v55, v57
	v_max_u32_e32 v57, v39, v41
	v_min_u32_e32 v39, v39, v41
	v_max_u32_e32 v41, v23, v25
	v_min_u32_e32 v23, v23, v25
	v_max_u32_e32 v25, v54, v56
	v_min_u32_e32 v54, v54, v56
	v_max_u32_e32 v56, v38, v40
	v_min_u32_e32 v38, v38, v40
	v_max_u32_e32 v40, v22, v24
	v_min_u32_e32 v22, v22, v24
	v_max_u32_e32 v24, v6, v8
	v_min_u32_e32 v6, v6, v8
	v_max_u32_e32 v8, v25, v7
	v_min_u32_e32 v7, v25, v7
	v_max_u32_e32 v25, v56, v55
	v_min_u32_e32 v55, v56, v55
	v_max_u32_e32 v56, v40, v39
	v_min_u32_e32 v39, v40, v39
	v_max_u32_e32 v40, v24, v23
	v_min_u32_e32 v23, v24, v23
	v_max_u32_e32 v24, v5, v9
	v_min_u32_e32 v5, v5, v9
	v_max_u32_e32 v9, v72, v20
	v_min_u32_e32 v20, v72, v20
	v_max_u32_e32 v72, v53, v57
	v_min_u32_e32 v53, v53, v57
	v_max_u32_e32 v57, v37, v41
	v_min_u32_e32 v37, v37, v41
	v_max_u32_e32 v41, v3, v7
	v_min_u32_e32 v3, v3, v7
	v_max_u32_e32 v7, v51, v55
	v_min_u32_e32 v51, v51, v55
	v_max_u32_e32 v55, v35, v39
	v_min_u32_e32 v35, v35, v39
	v_max_u32_e32 v39, v19, v23
	v_min_u32_e32 v19, v19, v23
	v_max_u32_e32 v23, v41, v5
	v_min_u32_e32 v5, v41, v5
	v_max_u32_e32 v41, v7, v20
	v_min_u32_e32 v7, v7, v20
	v_max_u32_e32 v20, v55, v53
	v_min_u32_e32 v53, v55, v53
	v_max_u32_e32 v55, v39, v37
; DI void peer_topk_phase(const bf16_t* __restrict__ qpk, const bf16_t* __restrict__ subk, int* __restrict__ eidx, float* __restrict__ gout) {
;     ...
; #pragma unroll
;             for (int n = 0; n < 63; ++n) { cex(g0[SORT16[n][0]], g0[SORT16[n][1]]); cex(g1[SORT16[n][0]], g1[SORT16[n][1]]); cex(g2[SORT16[n][0]], g2[SORT16[n][1]]); cex(g3[SORT16[n][0]], g3[SORT16[n][1]]); }
	v_min_u32_e32 v37, v39, v37
	v_max_u32_e32 v39, v4, v8
	v_min_u32_e32 v4, v4, v8
	v_max_u32_e32 v8, v21, v25
	v_min_u32_e32 v21, v21, v25
	v_max_u32_e32 v25, v52, v56
	v_min_u32_e32 v52, v52, v56
	v_max_u32_e32 v56, v36, v40
	v_min_u32_e32 v36, v36, v40
	v_max_u32_e32 v40, v50, v54
	v_min_u32_e32 v50, v50, v54
	v_max_u32_e32 v54, v34, v38
	v_min_u32_e32 v34, v34, v38
	v_max_u32_e32 v38, v18, v22
	v_min_u32_e32 v18, v18, v22
	v_max_u32_e32 v22, v2, v6
	v_min_u32_e32 v2, v2, v6
	v_max_u32_e32 v6, v40, v4
	v_min_u32_e32 v4, v40, v4
	v_max_u32_e32 v40, v54, v21
	v_min_u32_e32 v21, v54, v21
	v_max_u32_e32 v54, v38, v52
	v_min_u32_e32 v38, v38, v52
	v_max_u32_e32 v52, v22, v36
	v_min_u32_e32 v22, v22, v36
	v_max_u32_e32 v36, v39, v23
	v_min_u32_e32 v23, v39, v23
	v_max_u32_e32 v39, v8, v41
	v_min_u32_e32 v8, v8, v41
	v_max_u32_e32 v41, v25, v20
	v_min_u32_e32 v20, v25, v20
	v_max_u32_e32 v25, v56, v55
	v_min_u32_e32 v55, v56, v55
	v_max_u32_e32 v56, v6, v5
	v_min_u32_e32 v5, v6, v5
	v_max_u32_e32 v6, v40, v7
	v_min_u32_e32 v7, v40, v7
	v_max_u32_e32 v40, v54, v53
	v_min_u32_e32 v53, v54, v53
	v_max_u32_e32 v54, v52, v37
	v_min_u32_e32 v37, v52, v37
	v_max_u32_e32 v52, v4, v3
	v_min_u32_e32 v3, v4, v3
	v_max_u32_e32 v4, v21, v51
	v_min_u32_e32 v21, v21, v51
	v_max_u32_e32 v51, v38, v35
	v_min_u32_e32 v35, v38, v35
	v_max_u32_e32 v38, v22, v19
	v_min_u32_e32 v19, v22, v19
	v_max_u32_e32 v22, v58, v59
	v_min_u32_e32 v58, v58, v59
	v_max_u32_e32 v59, v42, v43
	v_min_u32_e32 v42, v42, v43
	v_max_u32_e32 v43, v26, v27
	v_min_u32_e32 v26, v26, v27
	v_max_u32_e32 v27, v10, v11
	v_min_u32_e32 v10, v10, v11
	v_max_u32_e32 v11, v60, v61
	v_min_u32_e32 v60, v60, v61
	v_max_u32_e32 v61, v44, v45
	v_min_u32_e32 v44, v44, v45
	v_max_u32_e32 v45, v28, v29
	v_min_u32_e32 v28, v28, v29
	v_max_u32_e32 v29, v12, v13
	v_min_u32_e32 v12, v12, v13
	v_and_or_b32 v17, v17, s42, v153
	v_max_u32_e32 v13, v22, v11
	v_min_u32_e32 v11, v22, v11
	v_max_u32_e32 v22, v59, v61
	v_min_u32_e32 v59, v59, v61
	v_max_u32_e32 v61, v43, v45
	v_min_u32_e32 v43, v43, v45
	v_max_u32_e32 v45, v27, v29
	v_min_u32_e32 v27, v27, v29
	v_max_u32_e32 v29, v58, v60
	v_min_u32_e32 v58, v58, v60
	v_max_u32_e32 v60, v42, v44
	v_min_u32_e32 v42, v42, v44
	v_max_u32_e32 v44, v26, v28
	v_min_u32_e32 v26, v26, v28
	v_max_u32_e32 v28, v10, v12
	v_min_u32_e32 v10, v10, v12
	v_max_u32_e32 v12, v29, v11
	v_min_u32_e32 v11, v29, v11
	v_max_u32_e32 v29, v60, v59
	v_min_u32_e32 v59, v60, v59
	v_max_u32_e32 v60, v44, v43
	v_min_u32_e32 v43, v44, v43
	v_max_u32_e32 v44, v28, v27
	v_min_u32_e32 v27, v28, v27
	v_max_u32_e32 v28, v62, v63
	v_min_u32_e32 v62, v62, v63
	v_max_u32_e32 v63, v46, v47
	v_min_u32_e32 v46, v46, v47
	v_max_u32_e32 v47, v30, v31
	v_min_u32_e32 v30, v30, v31
	v_max_u32_e32 v31, v14, v15
	v_min_u32_e32 v14, v14, v15
	v_max_u32_e32 v15, v64, v65
	v_min_u32_e32 v64, v64, v65
	v_max_u32_e32 v65, v48, v49
	v_min_u32_e32 v48, v48, v49
	v_max_u32_e32 v49, v32, v33
	v_min_u32_e32 v32, v32, v33
	v_max_u32_e32 v33, v16, v17
	v_min_u32_e32 v16, v16, v17
	v_max_u32_e32 v17, v28, v15
	v_min_u32_e32 v15, v28, v15
	v_max_u32_e32 v28, v63, v65
	v_min_u32_e32 v63, v63, v65
	v_max_u32_e32 v65, v47, v49
	v_min_u32_e32 v47, v47, v49
	v_max_u32_e32 v49, v31, v33
	v_min_u32_e32 v31, v31, v33
	v_max_u32_e32 v33, v62, v64
	v_min_u32_e32 v62, v62, v64
	v_max_u32_e32 v64, v46, v48
	v_min_u32_e32 v46, v46, v48
	v_max_u32_e32 v48, v30, v32
	v_min_u32_e32 v30, v30, v32
	v_max_u32_e32 v32, v14, v16
	v_min_u32_e32 v14, v14, v16
	v_max_u32_e32 v16, v33, v15
	v_min_u32_e32 v15, v33, v15
	v_max_u32_e32 v33, v64, v63
	v_min_u32_e32 v63, v64, v63
	v_max_u32_e32 v64, v48, v47
	v_min_u32_e32 v47, v48, v47
	v_max_u32_e32 v48, v32, v31
	v_min_u32_e32 v31, v32, v31
	v_max_u32_e32 v32, v13, v17
	v_min_u32_e32 v13, v13, v17
	v_max_u32_e32 v17, v22, v28
	v_min_u32_e32 v22, v22, v28
	v_max_u32_e32 v28, v61, v65
	v_min_u32_e32 v61, v61, v65
	v_max_u32_e32 v65, v45, v49
	v_min_u32_e32 v45, v45, v49
	v_max_u32_e32 v49, v11, v15
	v_min_u32_e32 v11, v11, v15
	v_max_u32_e32 v15, v59, v63
	v_min_u32_e32 v59, v59, v63
	v_max_u32_e32 v63, v43, v47
	v_min_u32_e32 v43, v43, v47
	v_max_u32_e32 v47, v27, v31
	v_min_u32_e32 v27, v27, v31
	v_max_u32_e32 v31, v49, v13
	v_min_u32_e32 v13, v49, v13
	v_max_u32_e32 v49, v15, v22
	v_min_u32_e32 v15, v15, v22
	v_max_u32_e32 v22, v63, v61
	v_min_u32_e32 v61, v63, v61
	v_max_u32_e32 v63, v47, v45
	v_min_u32_e32 v45, v47, v45
	v_max_u32_e32 v47, v12, v16
	v_min_u32_e32 v12, v12, v16
	v_max_u32_e32 v16, v29, v33
	v_min_u32_e32 v29, v29, v33
	v_max_u32_e32 v33, v60, v64
	v_min_u32_e32 v60, v60, v64
	v_max_u32_e32 v64, v44, v48
	v_min_u32_e32 v44, v44, v48
	v_max_u32_e32 v48, v58, v62
	v_min_u32_e32 v58, v58, v62
	v_max_u32_e32 v62, v42, v46
	v_min_u32_e32 v42, v42, v46
	v_max_u32_e32 v46, v26, v30
	v_min_u32_e32 v26, v26, v30
	v_max_u32_e32 v30, v10, v14
	v_min_u32_e32 v10, v10, v14
	v_max_u32_e32 v14, v48, v12
	v_min_u32_e32 v12, v48, v12
	v_max_u32_e32 v48, v62, v29
	v_min_u32_e32 v29, v62, v29
	v_max_u32_e32 v62, v46, v60
	v_min_u32_e32 v46, v46, v60
	v_max_u32_e32 v60, v30, v44
	v_min_u32_e32 v30, v30, v44
	v_max_u32_e32 v44, v47, v31
	v_min_u32_e32 v31, v47, v31
	v_max_u32_e32 v47, v16, v49
	v_min_u32_e32 v16, v16, v49
	v_max_u32_e32 v49, v33, v22
	v_min_u32_e32 v22, v33, v22
	v_max_u32_e32 v33, v64, v63
	v_min_u32_e32 v63, v64, v63
	v_max_u32_e32 v64, v14, v13
	v_min_u32_e32 v13, v14, v13
	v_max_u32_e32 v14, v48, v15
	v_min_u32_e32 v15, v48, v15
	v_max_u32_e32 v48, v62, v61
	v_min_u32_e32 v61, v62, v61
	v_max_u32_e32 v62, v60, v45
	v_min_u32_e32 v45, v60, v45
	v_max_u32_e32 v60, v12, v11
; DI void merge_top16(unsigned (&A)[16], const unsigned (&B)[16]) {
; #pragma unroll
;     for (int i = 0; i < 16; ++i) A[i] = max(A[i], B[15 - i]);
; #pragma unroll
;     for (int n = 0; n < 32; ++n) cex(A[BMERGE16[n][0]], A[BMERGE16[n][1]]);
; }
; DI void peer_topk_phase(const bf16_t* __restrict__ qpk, const bf16_t* __restrict__ subk, int* __restrict__ eidx, float* __restrict__ gout) {
;     ...
;             for (int n = 0; n < 63; ++n) { cex(g0[SORT16[n][0]], g0[SORT16[n][1]]); cex(g1[SORT16[n][0]], g1[SORT16[n][1]]); cex(g2[SORT16[n][0]], g2[SORT16[n][1]]); cex(g3[SORT16[n][0]], g3[SORT16[n][1]]); }
;             merge_top16(g0, g1); merge_top16(g2, g3); merge_top16(g0, g2);
	v_min_u32_e32 v11, v12, v11
	v_max_u32_e32 v12, v29, v59
	v_min_u32_e32 v29, v29, v59
	v_max_u32_e32 v59, v46, v43
	v_min_u32_e32 v43, v46, v43
	v_max_u32_e32 v46, v30, v27
	v_min_u32_e32 v27, v30, v27
	v_min_u32_e32 v30, v24, v32
	v_min_u32_e32 v73, v9, v17
	v_min_u32_e32 v74, v72, v28
	v_min_u32_e32 v79, v57, v65
	v_max_u32_e32 v82, v5, v13
	v_min_u32_e32 v5, v5, v13
	v_max_u32_e32 v13, v7, v15
	v_min_u32_e32 v7, v7, v15
	v_max_u32_e32 v15, v53, v61
	v_min_u32_e32 v53, v53, v61
	v_max_u32_e32 v61, v37, v45
	v_min_u32_e32 v37, v37, v45
	v_max_u32_e32 v45, v82, v30
	v_min_u32_e32 v30, v82, v30
	v_max_u32_e32 v82, v13, v73
	v_min_u32_e32 v13, v13, v73
	v_max_u32_e32 v73, v15, v74
	v_min_u32_e32 v15, v15, v74
	v_max_u32_e32 v74, v61, v79
	v_min_u32_e32 v61, v61, v79
	v_max_u32_e32 v79, v23, v31
	v_min_u32_e32 v23, v23, v31
	v_max_u32_e32 v31, v8, v16
	v_min_u32_e32 v8, v8, v16
	v_max_u32_e32 v16, v20, v22
	v_min_u32_e32 v20, v20, v22
	v_max_u32_e32 v22, v55, v63
	v_min_u32_e32 v55, v55, v63
	v_max_u32_e32 v63, v3, v11
	v_min_u32_e32 v3, v3, v11
	v_max_u32_e32 v11, v21, v29
	v_min_u32_e32 v21, v21, v29
	v_max_u32_e32 v29, v35, v43
	v_min_u32_e32 v35, v35, v43
	v_max_u32_e32 v43, v19, v27
	v_min_u32_e32 v19, v19, v27
	v_max_u32_e32 v27, v63, v23
	v_min_u32_e32 v23, v63, v23
	v_max_u32_e32 v63, v11, v8
	v_min_u32_e32 v8, v11, v8
	v_max_u32_e32 v11, v29, v20
	v_min_u32_e32 v20, v29, v20
	v_max_u32_e32 v29, v43, v55
	v_min_u32_e32 v43, v43, v55
	v_max_u32_e32 v55, v79, v45
	v_min_u32_e32 v45, v79, v45
	v_max_u32_e32 v79, v31, v82
	v_min_u32_e32 v31, v31, v82
	v_max_u32_e32 v82, v16, v73
	v_min_u32_e32 v16, v16, v73
	v_max_u32_e32 v73, v22, v74
	v_min_u32_e32 v22, v22, v74
	v_max_u32_e32 v74, v27, v30
	v_min_u32_e32 v27, v27, v30
	v_max_u32_e32 v30, v63, v13
	v_min_u32_e32 v13, v63, v13
	v_max_u32_e32 v63, v11, v15
	v_min_u32_e32 v11, v11, v15
	v_max_u32_e32 v15, v29, v61
	v_min_u32_e32 v29, v29, v61
	v_max_u32_e32 v61, v23, v5
	v_min_u32_e32 v5, v23, v5
	v_max_u32_e32 v23, v8, v7
	v_min_u32_e32 v7, v8, v7
	v_max_u32_e32 v8, v20, v53
	v_min_u32_e32 v20, v20, v53
	v_max_u32_e32 v53, v43, v37
	v_min_u32_e32 v37, v43, v37
	v_max_u32_e32 v43, v36, v44
	v_min_u32_e32 v36, v36, v44
	v_max_u32_e32 v44, v39, v47
	v_min_u32_e32 v39, v39, v47
	v_max_u32_e32 v47, v41, v49
	v_min_u32_e32 v41, v41, v49
	v_max_u32_e32 v49, v25, v33
	v_min_u32_e32 v25, v25, v33
	v_max_u32_e32 v33, v52, v60
	v_min_u32_e32 v52, v52, v60
	v_max_u32_e32 v60, v4, v12
	v_min_u32_e32 v4, v4, v12
	v_max_u32_e32 v12, v51, v59
	v_min_u32_e32 v51, v51, v59
	v_max_u32_e32 v59, v38, v46
	v_min_u32_e32 v38, v38, v46
	v_max_u32_e32 v46, v33, v36
	v_min_u32_e32 v33, v33, v36
	v_max_u32_e32 v36, v60, v39
	v_min_u32_e32 v39, v60, v39
	v_max_u32_e32 v60, v12, v41
	v_min_u32_e32 v12, v12, v41
	v_max_u32_e32 v41, v59, v25
	v_min_u32_e32 v25, v59, v25
	v_max_u32_e32 v59, v56, v64
	v_min_u32_e32 v56, v56, v64
	v_max_u32_e32 v64, v6, v14
	v_min_u32_e32 v6, v6, v14
	v_max_u32_e32 v14, v40, v48
	v_min_u32_e32 v40, v40, v48
	v_max_u32_e32 v48, v54, v62
	v_min_u32_e32 v54, v54, v62
	v_max_u32_e32 v62, v50, v58
	v_min_u32_e32 v50, v50, v58
	v_max_u32_e32 v58, v34, v42
	v_min_u32_e32 v34, v34, v42
	v_max_u32_e32 v42, v18, v26
	v_min_u32_e32 v18, v18, v26
	v_max_u32_e32 v26, v2, v10
	v_min_u32_e32 v2, v2, v10
	v_max_u32_e32 v10, v62, v56
	v_min_u32_e32 v56, v62, v56
	v_max_u32_e32 v62, v58, v6
	v_min_u32_e32 v6, v58, v6
	v_max_u32_e32 v58, v42, v40
	v_min_u32_e32 v40, v42, v40
	v_max_u32_e32 v42, v26, v54
	v_min_u32_e32 v26, v26, v54
	v_max_u32_e32 v54, v59, v46
	v_min_u32_e32 v46, v59, v46
	v_max_u32_e32 v59, v64, v36
	v_min_u32_e32 v36, v64, v36
	v_max_u32_e32 v64, v14, v60
	v_min_u32_e32 v14, v14, v60
	v_max_u32_e32 v60, v48, v41
	v_min_u32_e32 v41, v48, v41
	v_max_u32_e32 v48, v10, v33
	v_min_u32_e32 v10, v10, v33
	v_max_u32_e32 v33, v62, v39
	v_min_u32_e32 v39, v62, v39
	v_max_u32_e32 v62, v58, v12
	v_min_u32_e32 v12, v58, v12
	v_max_u32_e32 v58, v42, v25
	v_min_u32_e32 v25, v42, v25
	v_max_u32_e32 v42, v56, v52
	v_min_u32_e32 v52, v56, v52
	v_max_u32_e32 v56, v6, v4
	v_min_u32_e32 v4, v6, v4
	v_max_u32_e32 v6, v40, v51
	v_min_u32_e32 v40, v40, v51
	v_max_u32_e32 v51, v26, v38
	v_min_u32_e32 v26, v26, v38
	v_min_u32_e32 v38, v43, v55
	v_min_u32_e32 v83, v44, v79
	v_min_u32_e32 v157, v47, v82
	v_min_u32_e32 v158, v49, v73
	v_min_u32_e32 v159, v54, v45
	v_min_u32_e32 v160, v59, v31
	v_min_u32_e32 v161, v64, v16
	v_min_u32_e32 v162, v60, v22
	v_min_u32_e32 v163, v46, v74
	v_min_u32_e32 v164, v36, v30
	v_min_u32_e32 v165, v14, v63
	v_min_u32_e32 v166, v41, v15
	v_min_u32_e32 v167, v48, v27
	v_min_u32_e32 v168, v33, v13
	v_min_u32_e32 v169, v62, v11
	v_min_u32_e32 v182, v58, v29
	v_min_u32_e32 v183, v10, v61
	v_min_u32_e32 v184, v39, v23
	v_min_u32_e32 v185, v12, v8
	v_min_u32_e32 v186, v25, v53
	v_min_u32_e32 v187, v42, v5
	v_min_u32_e32 v188, v56, v7
	v_min_u32_e32 v189, v6, v20
	v_min_u32_e32 v190, v51, v37
	v_min_u32_e32 v191, v52, v3
	v_min_u32_e32 v198, v4, v21
	v_min_u32_e32 v199, v40, v35
	v_min_u32_e32 v200, v26, v19
	v_max3_u32 v24, v24, v32, v34
	v_max3_u32 v32, v43, v55, v198
	v_max3_u32 v4, v38, v4, v21
	v_max3_u32 v21, v54, v45, v188
	v_max3_u32 v7, v159, v56, v7
	v_max3_u32 v34, v46, v74, v184
	v_max3_u32 v23, v163, v39, v23
	v_max3_u32 v27, v48, v27, v168
	v_max3_u32 v13, v167, v33, v13
	v_max3_u32 v10, v10, v61, v164
	v_max3_u32 v30, v183, v36, v30
	v_max3_u32 v5, v42, v5, v160
	v_max3_u32 v31, v187, v59, v31
	v_max3_u32 v3, v52, v3, v83
	v_max3_u32 v33, v191, v44, v79
	v_max3_u32 v9, v50, v9, v17
	v_max3_u32 v2, v72, v28, v2
	v_max3_u32 v28, v47, v82, v200
	v_max3_u32 v19, v157, v26, v19
; DI void merge_top16(unsigned (&A)[16], const unsigned (&B)[16]) {
; #pragma unroll
;     for (int i = 0; i < 16; ++i) A[i] = max(A[i], B[15 - i]);
; #pragma unroll
;     for (int n = 0; n < 32; ++n) cex(A[BMERGE16[n][0]], A[BMERGE16[n][1]]);
; }
; DI void peer_topk_phase(const bf16_t* __restrict__ qpk, const bf16_t* __restrict__ subk, int* __restrict__ eidx, float* __restrict__ gout) {
;     ...
;             merge_top16(g0, g1); merge_top16(g2, g3); merge_top16(g0, g2);
;             unsigned pb[16];
; #pragma unroll
;             for (int i = 0; i < 16; ++i) pb[i] = (unsigned)__shfl_xor((int)g0[i], 32);
;             merge_top16(g0, pb);
	v_max3_u32 v16, v64, v16, v190
	v_max3_u32 v26, v161, v51, v37
	v_max3_u32 v14, v14, v63, v186
	v_max3_u32 v25, v165, v25, v53
	v_max3_u32 v11, v62, v11, v182
	v_max3_u32 v29, v169, v58, v29
	v_max3_u32 v8, v12, v8, v166
	v_max3_u32 v12, v185, v41, v15
	v_max3_u32 v6, v6, v20, v162
	v_max3_u32 v15, v189, v60, v22
	v_max3_u32 v20, v40, v35, v158
	v_max3_u32 v22, v199, v49, v73
	v_max3_u32 v18, v18, v57, v65
	v_max_u32_e32 v17, v24, v13
	v_min_u32_e32 v13, v24, v13
	v_max_u32_e32 v24, v32, v10
	v_min_u32_e32 v10, v32, v10
	v_max_u32_e32 v32, v4, v30
	v_min_u32_e32 v4, v4, v30
	v_max_u32_e32 v30, v21, v5
	v_min_u32_e32 v5, v21, v5
	v_max_u32_e32 v21, v7, v31
	v_min_u32_e32 v7, v7, v31
	v_max_u32_e32 v31, v34, v3
	v_min_u32_e32 v3, v34, v3
	v_max_u32_e32 v34, v23, v33
	v_min_u32_e32 v23, v23, v33
	v_max_u32_e32 v33, v27, v9
	v_min_u32_e32 v9, v27, v9
	v_max_u32_e32 v35, v2, v29
	v_min_u32_e32 v2, v2, v29
	v_max_u32_e32 v29, v28, v8
	v_min_u32_e32 v8, v28, v8
	v_max_u32_e32 v28, v19, v12
	v_min_u32_e32 v12, v19, v12
	v_max_u32_e32 v19, v16, v6
	v_min_u32_e32 v6, v16, v6
	v_max_u32_e32 v16, v26, v15
	v_min_u32_e32 v15, v26, v15
	v_max_u32_e32 v26, v14, v20
	v_min_u32_e32 v14, v14, v20
	v_max_u32_e32 v20, v25, v22
	v_min_u32_e32 v22, v25, v22
	v_max_u32_e32 v25, v11, v18
	v_min_u32_e32 v11, v11, v18
	v_max_u32_e32 v27, v17, v21
	v_min_u32_e32 v17, v17, v21
	v_max_u32_e32 v21, v24, v31
	v_min_u32_e32 v24, v24, v31
	v_max_u32_e32 v31, v32, v34
	v_min_u32_e32 v32, v32, v34
	v_max_u32_e32 v34, v30, v33
	v_min_u32_e32 v30, v30, v33
	v_max_u32_e32 v33, v13, v7
	v_min_u32_e32 v7, v13, v7
	v_max_u32_e32 v13, v10, v3
	v_min_u32_e32 v3, v10, v3
	v_max_u32_e32 v10, v4, v23
	v_min_u32_e32 v4, v4, v23
	v_max_u32_e32 v23, v5, v9
	v_min_u32_e32 v5, v5, v9
	v_max_u32_e32 v18, v35, v16
	v_min_u32_e32 v16, v35, v16
	v_max_u32_e32 v35, v29, v26
	v_min_u32_e32 v26, v29, v26
	v_max_u32_e32 v29, v28, v20
	v_min_u32_e32 v20, v28, v20
	v_max_u32_e32 v28, v19, v25
	v_min_u32_e32 v19, v19, v25
	v_max_u32_e32 v25, v2, v15
	v_min_u32_e32 v2, v2, v15
	v_max_u32_e32 v15, v8, v14
	v_min_u32_e32 v8, v8, v14
	v_max_u32_e32 v14, v12, v22
	v_min_u32_e32 v12, v12, v22
	v_max_u32_e32 v22, v6, v11
	v_min_u32_e32 v6, v6, v11
	v_max_u32_e32 v9, v27, v31
	v_min_u32_e32 v27, v27, v31
	v_max_u32_e32 v31, v21, v34
	v_min_u32_e32 v21, v21, v34
	v_max_u32_e32 v34, v17, v32
	v_min_u32_e32 v17, v17, v32
	v_max_u32_e32 v32, v24, v30
	v_min_u32_e32 v24, v24, v30
	v_max_u32_e32 v30, v33, v10
	v_min_u32_e32 v10, v33, v10
	v_max_u32_e32 v33, v13, v23
	v_min_u32_e32 v13, v13, v23
	v_max_u32_e32 v23, v7, v4
	v_min_u32_e32 v4, v7, v4
	v_max_u32_e32 v7, v3, v5
	v_min_u32_e32 v3, v3, v5
	v_max_u32_e32 v11, v18, v29
	v_min_u32_e32 v18, v18, v29
	v_max_u32_e32 v29, v35, v28
	v_min_u32_e32 v28, v35, v28
	v_max_u32_e32 v35, v16, v20
	v_min_u32_e32 v16, v16, v20
	v_max_u32_e32 v20, v26, v19
	v_min_u32_e32 v19, v26, v19
	v_max_u32_e32 v26, v25, v14
	v_min_u32_e32 v14, v25, v14
	v_max_u32_e32 v25, v15, v22
	v_min_u32_e32 v15, v15, v22
	v_max_u32_e32 v22, v2, v12
	v_min_u32_e32 v2, v2, v12
	v_max_u32_e32 v12, v8, v6
	v_min_u32_e32 v6, v8, v6
	v_min_u32_e32 v5, v9, v31
	v_min_u32_e32 v36, v27, v21
	v_min_u32_e32 v38, v34, v32
	v_min_u32_e32 v39, v17, v24
	v_min_u32_e32 v42, v30, v33
	v_min_u32_e32 v43, v10, v13
	v_min_u32_e32 v44, v23, v7
	v_min_u32_e32 v45, v4, v3
	v_min_u32_e32 v8, v11, v29
	v_min_u32_e32 v37, v18, v28
	v_min_u32_e32 v40, v35, v20
	v_min_u32_e32 v41, v16, v19
	v_min_u32_e32 v46, v26, v25
	v_min_u32_e32 v47, v14, v15
	v_min_u32_e32 v48, v22, v12
	v_min_u32_e32 v49, v2, v6
	v_max3_u32 v9, v9, v31, v49
	v_max3_u32 v2, v5, v2, v6
	v_max3_u32 v5, v27, v21, v48
	v_max3_u32 v6, v36, v22, v12
	v_max3_u32 v12, v34, v32, v47
	v_max3_u32 v14, v38, v14, v15
	v_max3_u32 v15, v17, v24, v46
	v_max3_u32 v17, v39, v26, v25
	v_max3_u32 v21, v30, v33, v41
	v_max3_u32 v16, v42, v16, v19
	v_max3_u32 v10, v10, v13, v40
	v_max3_u32 v13, v43, v35, v20
	v_max3_u32 v7, v23, v7, v37
	v_max3_u32 v18, v44, v18, v28
	v_max3_u32 v3, v4, v3, v8
	v_max3_u32 v4, v45, v11, v29
	v_max_u32_e32 v8, v9, v21
	v_min_u32_e32 v9, v9, v21
	v_max_u32_e32 v11, v2, v16
	v_min_u32_e32 v2, v2, v16
	v_max_u32_e32 v16, v5, v10
	v_min_u32_e32 v5, v5, v10
	v_max_u32_e32 v10, v6, v13
	v_min_u32_e32 v6, v6, v13
	v_max_u32_e32 v13, v12, v7
	v_min_u32_e32 v7, v12, v7
	v_max_u32_e32 v12, v14, v18
	v_min_u32_e32 v14, v14, v18
	v_max_u32_e32 v18, v15, v3
	v_min_u32_e32 v3, v15, v3
	v_max_u32_e32 v15, v17, v4
	v_min_u32_e32 v4, v17, v4
	v_max_u32_e32 v17, v8, v13
	v_min_u32_e32 v8, v8, v13
	v_max_u32_e32 v13, v11, v12
	v_min_u32_e32 v11, v11, v12
	v_max_u32_e32 v12, v16, v18
	v_min_u32_e32 v16, v16, v18
	v_max_u32_e32 v18, v10, v15
	v_min_u32_e32 v10, v10, v15
	v_max_u32_e32 v15, v9, v7
	v_min_u32_e32 v7, v9, v7
	v_max_u32_e32 v9, v2, v14
	v_min_u32_e32 v2, v2, v14
	v_max_u32_e32 v14, v5, v3
	v_min_u32_e32 v3, v5, v3
	v_max_u32_e32 v5, v6, v4
	v_min_u32_e32 v4, v6, v4
	v_max_u32_e32 v6, v17, v12
	v_min_u32_e32 v12, v17, v12
	v_max_u32_e32 v17, v13, v18
	v_min_u32_e32 v13, v13, v18
	v_max_u32_e32 v18, v8, v16
	v_min_u32_e32 v8, v8, v16
	v_max_u32_e32 v16, v11, v10
	v_min_u32_e32 v10, v11, v10
	v_max_u32_e32 v11, v15, v14
	v_min_u32_e32 v14, v15, v14
	v_max_u32_e32 v15, v9, v5
	v_min_u32_e32 v5, v9, v5
	v_max_u32_e32 v9, v7, v3
	v_min_u32_e32 v3, v7, v3
	v_max_u32_e32 v7, v2, v4
	v_min_u32_e32 v2, v2, v4
	v_max_u32_e32 v4, v6, v17
	v_min_u32_e32 v6, v6, v17
	v_max_u32_e32 v17, v12, v13
	v_min_u32_e32 v12, v12, v13
	v_max_u32_e32 v13, v18, v16
	v_min_u32_e32 v16, v18, v16
	v_max_u32_e32 v18, v8, v10
	v_min_u32_e32 v8, v8, v10
	v_max_u32_e32 v10, v11, v15
	v_min_u32_e32 v11, v11, v15
	v_max_u32_e32 v15, v14, v5
	v_min_u32_e32 v5, v14, v5
	v_max_u32_e32 v14, v9, v7
	v_min_u32_e32 v7, v9, v7
	v_max_u32_e32 v9, v3, v2
	v_min_u32_e32 v2, v3, v2
	ds_bpermute_b32 v3, v173, v4
	ds_bpermute_b32 v19, v173, v6
	ds_bpermute_b32 v20, v173, v17
	ds_bpermute_b32 v21, v173, v12
	ds_bpermute_b32 v22, v173, v13
	ds_bpermute_b32 v23, v173, v16
	ds_bpermute_b32 v24, v173, v18
	ds_bpermute_b32 v25, v173, v8
	ds_bpermute_b32 v26, v173, v10
	ds_bpermute_b32 v27, v173, v11
	ds_bpermute_b32 v28, v173, v15
	ds_bpermute_b32 v29, v173, v5
	ds_bpermute_b32 v30, v173, v14
	ds_bpermute_b32 v31, v173, v7
	ds_bpermute_b32 v32, v173, v9
	ds_bpermute_b32 v33, v173, v2
	s_waitcnt lgkmcnt(4)
; #define MFMA(a, b, c) __builtin_amdgcn_mfma_f32_32x32x16_bf16((a), (b), (c), 0, 0, 0)
; DI void peer_topk_phase(const bf16_t* __restrict__ qpk, const bf16_t* __restrict__ subk, int* __restrict__ eidx, float* __restrict__ gout) {
;     ...
;             const bf16_t* qp = qpk + (size_t)(t0 + r) * 1024 + hh * 128 + c * 64 + h * 8;
;             const bf16_t* kp = subk + ((size_t)(hh * 2 + c) * 128 + r) * 64 + h * 8;
; #pragma unroll
;             for (int ks = 0; ks < 4; ++ks) {
;                 const bf16x8 qfr = *(const bf16x8*)(qp + ks * 16);
; #pragma unroll
;                 for (int nb = 0; nb < 4; ++nb) {
;                     const bf16x8 kf = *(const bf16x8*)(kp + nb * 32 * 64 + ks * 16);
;                     acc[nb] = MFMA(kf, qfr, acc[nb]);
;                 }
;             }
;     ...
;             for (int i = 0; i < 16; ++i) pb[i] = (unsigned)__shfl_xor((int)g0[i], 32);
;             merge_top16(g0, pb);
; #pragma unroll
;             for (int i = 0; i < 16; ++i) top[c][i] = g0[i];
	v_max_u32_e32 v13, v13, v29
	s_waitcnt lgkmcnt(3)
	v_max_u32_e32 v12, v12, v30
	s_waitcnt lgkmcnt(2)
	v_max_u32_e32 v17, v17, v31
	s_waitcnt lgkmcnt(1)
	v_max_u32_e32 v6, v6, v32
	s_waitcnt lgkmcnt(0)
	v_max_u32_e32 v4, v4, v33
	v_max_u32_e32 v16, v16, v28
	v_max_u32_e32 v18, v18, v27
	v_max_u32_e32 v8, v8, v26
	v_max_u32_e32 v10, v10, v25
	v_max_u32_e32 v11, v11, v24
	v_max_u32_e32 v15, v15, v23
	v_max_u32_e32 v5, v5, v22
	v_max_u32_e32 v14, v14, v21
	v_max_u32_e32 v7, v7, v20
	v_max_u32_e32 v9, v9, v19
	v_max_u32_e32 v2, v2, v3
	v_max_u32_e32 v3, v4, v10
	v_min_u32_e32 v4, v4, v10
	v_max_u32_e32 v10, v6, v11
	v_min_u32_e32 v6, v6, v11
	v_max_u32_e32 v11, v17, v15
	v_min_u32_e32 v15, v17, v15
	v_max_u32_e32 v17, v12, v5
	v_min_u32_e32 v5, v12, v5
	v_max_u32_e32 v12, v13, v14
	v_min_u32_e32 v13, v13, v14
	v_max_u32_e32 v14, v16, v7
	v_min_u32_e32 v7, v16, v7
	v_max_u32_e32 v16, v18, v9
	v_min_u32_e32 v9, v18, v9
	v_max_u32_e32 v18, v8, v2
	v_min_u32_e32 v2, v8, v2
	v_max_u32_e32 v8, v3, v12
	v_min_u32_e32 v3, v3, v12
	v_max_u32_e32 v12, v10, v14
	v_min_u32_e32 v10, v10, v14
	v_max_u32_e32 v14, v11, v16
	v_min_u32_e32 v11, v11, v16
	v_max_u32_e32 v16, v17, v18
	v_min_u32_e32 v17, v17, v18
	v_max_u32_e32 v18, v4, v13
	v_min_u32_e32 v4, v4, v13
	v_max_u32_e32 v13, v6, v7
	v_min_u32_e32 v6, v6, v7
	v_max_u32_e32 v7, v15, v9
	v_min_u32_e32 v9, v15, v9
	v_max_u32_e32 v15, v5, v2
	v_min_u32_e32 v2, v5, v2
	v_max_u32_e32 v5, v8, v14
	v_min_u32_e32 v8, v8, v14
	v_max_u32_e32 v14, v12, v16
	v_min_u32_e32 v12, v12, v16
	v_max_u32_e32 v16, v3, v11
	v_min_u32_e32 v3, v3, v11
	v_max_u32_e32 v11, v10, v17
	v_min_u32_e32 v10, v10, v17
	v_max_u32_e32 v17, v18, v7
	v_min_u32_e32 v7, v18, v7
	v_max_u32_e32 v18, v13, v15
	v_min_u32_e32 v13, v13, v15
	v_max_u32_e32 v15, v4, v9
	v_min_u32_e32 v4, v4, v9
	v_max_u32_e32 v9, v6, v2
	v_min_u32_e32 v2, v6, v2
	v_max_u32_e32 v168, v5, v14
	v_min_u32_e32 v182, v5, v14
	v_max_u32_e32 v164, v3, v10
	v_min_u32_e32 v163, v3, v10
	v_max_u32_e32 v79, v4, v2
	v_min_u32_e32 v74, v4, v2
	v_max_u32_e32 v162, v17, v18
	v_min_u32_e32 v161, v17, v18
	v_max_u32_e32 v169, v8, v12
	v_min_u32_e32 v167, v8, v12
	v_max_u32_e32 v166, v16, v11
	v_min_u32_e32 v165, v16, v11
	v_max_u32_e32 v160, v7, v13
	v_min_u32_e32 v159, v7, v13
	v_max_u32_e32 v158, v15, v9
	v_min_u32_e32 v157, v15, v9
	v_add_co_u32_e32 v72, vcc, s43, v68
	s_nop 1
	v_addc_co_u32_e32 v73, vcc, 0, v69, vcc
	v_add_co_u32_e32 v82, vcc, s52, v68
	s_nop 1
	v_addc_co_u32_e32 v83, vcc, 0, v69, vcc
	v_add_co_u32_e32 v198, vcc, s53, v68
	s_nop 1
	v_addc_co_u32_e32 v199, vcc, 0, v69, vcc
	global_load_dwordx4 v[50:53], v[66:67], off offset:128
	global_load_dwordx4 v[214:217], v[70:71], off
	global_load_dwordx4 v[218:221], v[82:83], off offset:-4096
	global_load_dwordx4 v[2:5], v[82:83], off
	global_load_dwordx4 v[54:57], v[198:199], off
	global_load_dwordx4 v[184:187], v[66:67], off offset:160
	global_load_dwordx4 v[222:225], v[70:71], off offset:32
	global_load_dwordx4 v[226:229], v[72:73], off offset:32
	global_load_dwordx4 v[232:235], v[82:83], off offset:32
	global_load_dwordx4 v[236:239], v[198:199], off offset:32
	global_load_dwordx4 v[188:191], v[66:67], off offset:192
	global_load_dwordx4 v[240:243], v[70:71], off offset:64
	global_load_dwordx4 v[244:247], v[72:73], off offset:64
	global_load_dwordx4 v[248:251], v[82:83], off offset:64
	global_load_dwordx4 v[210:213], v[66:67], off offset:224
	s_waitcnt vmcnt(13)
	v_mfma_f32_32x32x16_bf16 v[34:49], v[214:217], v[50:53], 0
	s_waitcnt vmcnt(12)
	v_mfma_f32_32x32x16_bf16 v[18:33], v[218:221], v[50:53], 0
	s_waitcnt vmcnt(11)
	v_mfma_f32_32x32x16_bf16 v[2:17], v[2:5], v[50:53], 0
	s_waitcnt vmcnt(10)
	v_mfma_f32_32x32x16_bf16 v[50:65], v[54:57], v[50:53], 0
	global_load_dwordx4 v[214:217], v[198:199], off offset:64
	global_load_dwordx4 v[218:221], v[70:71], off offset:96
	s_waitcnt vmcnt(10)
	v_mfma_f32_32x32x16_bf16 v[34:49], v[222:225], v[184:187], v[34:49]
	s_waitcnt vmcnt(9)
	v_mfma_f32_32x32x16_bf16 v[18:33], v[226:229], v[184:187], v[18:33]
	s_waitcnt vmcnt(8)
	v_mfma_f32_32x32x16_bf16 v[2:17], v[232:235], v[184:187], v[2:17]
	s_waitcnt vmcnt(7)
	v_mfma_f32_32x32x16_bf16 v[50:65], v[236:239], v[184:187], v[50:65]
	global_load_dwordx4 v[222:225], v[72:73], off offset:96
	global_load_dwordx4 v[226:229], v[82:83], off offset:96
	global_load_dwordx4 v[232:235], v[198:199], off offset:96
	s_waitcnt vmcnt(8)
	v_mfma_f32_32x32x16_bf16 v[34:49], v[240:243], v[188:191], v[34:49]
	s_waitcnt vmcnt(7)
	v_mfma_f32_32x32x16_bf16 v[18:33], v[244:247], v[188:191], v[18:33]
	s_waitcnt vmcnt(6)
	v_mfma_f32_32x32x16_bf16 v[2:17], v[248:251], v[188:191], v[2:17]
	s_waitcnt vmcnt(4)
	v_mfma_f32_32x32x16_bf16 v[50:65], v[214:217], v[188:191], v[50:65]
	s_waitcnt vmcnt(3)
	v_mfma_f32_32x32x16_bf16 v[34:49], v[218:221], v[210:213], v[34:49]
	s_waitcnt vmcnt(2)
	v_mfma_f32_32x32x16_bf16 v[18:33], v[222:225], v[210:213], v[18:33]
	s_waitcnt vmcnt(1)
	v_mfma_f32_32x32x16_bf16 v[2:17], v[226:229], v[210:213], v[2:17]
	s_waitcnt vmcnt(0)
; DI unsigned f2ord(float f) { const unsigned u = __float_as_uint(f); return (u & 0x80000000u) ? ~u : (u | 0x80000000u); }
; DI void peer_topk_phase(const bf16_t* __restrict__ qpk, const bf16_t* __restrict__ subk, int* __restrict__ eidx, float* __restrict__ gout) {
;     ...
;             }
;             unsigned key[64];
; #pragma unroll
;             for (int nb = 0; nb < 4; ++nb)
; #pragma unroll
;                 for (int i = 0; i < 16; ++i) {
;                     const int n = nb * 32 + (i & 3) + 8 * (i >> 2) + 4 * h;
;                     key[nb * 16 + i] = (f2ord(acc[nb][i]) & ~127u) | (unsigned)(127 - n);
	v_mfma_f32_32x32x16_bf16 v[50:65], v[232:235], v[210:213], v[50:65]
	s_nop 9
	v_not_b32_e32 v66, v34
	v_or_b32_e32 v67, 0x80000000, v34
	v_cmp_gt_i32_e32 vcc, 0, v34
	s_nop 1
	v_cndmask_b32_e32 v34, v67, v66, vcc
	v_not_b32_e32 v66, v35
	v_or_b32_e32 v67, 0x80000000, v35
	v_cmp_gt_i32_e32 vcc, 0, v35
	v_and_or_b32 v34, v34, s42, v85
	s_nop 0
	v_cndmask_b32_e32 v35, v67, v66, vcc
	v_not_b32_e32 v66, v36
	v_or_b32_e32 v67, 0x80000000, v36
	v_cmp_gt_i32_e32 vcc, 0, v36
	v_and_or_b32 v35, v35, s42, v86
	s_nop 0
	v_cndmask_b32_e32 v36, v67, v66, vcc
	v_not_b32_e32 v66, v37
	v_or_b32_e32 v67, 0x80000000, v37
	v_cmp_gt_i32_e32 vcc, 0, v37
	v_and_or_b32 v36, v36, s42, v87
	s_nop 0
	v_cndmask_b32_e32 v37, v67, v66, vcc
	v_not_b32_e32 v66, v38
	v_or_b32_e32 v67, 0x80000000, v38
	v_cmp_gt_i32_e32 vcc, 0, v38
	v_and_or_b32 v37, v37, s42, v88
	s_nop 0
	v_cndmask_b32_e32 v38, v67, v66, vcc
	v_not_b32_e32 v66, v39
	v_or_b32_e32 v67, 0x80000000, v39
	v_cmp_gt_i32_e32 vcc, 0, v39
	v_and_or_b32 v38, v38, s42, v89
	s_nop 0
	v_cndmask_b32_e32 v39, v67, v66, vcc
	v_not_b32_e32 v66, v40
	v_or_b32_e32 v67, 0x80000000, v40
	v_cmp_gt_i32_e32 vcc, 0, v40
	v_and_or_b32 v39, v39, s42, v90
	s_nop 0
	v_cndmask_b32_e32 v40, v67, v66, vcc
	v_not_b32_e32 v66, v41
	v_or_b32_e32 v67, 0x80000000, v41
	v_cmp_gt_i32_e32 vcc, 0, v41
	v_and_or_b32 v40, v40, s42, v91
	s_nop 0
	v_cndmask_b32_e32 v41, v67, v66, vcc
	v_not_b32_e32 v66, v42
	v_or_b32_e32 v67, 0x80000000, v42
	v_cmp_gt_i32_e32 vcc, 0, v42
	v_and_or_b32 v41, v41, s42, v92
	s_nop 0
	v_cndmask_b32_e32 v42, v67, v66, vcc
	v_not_b32_e32 v66, v43
	v_or_b32_e32 v67, 0x80000000, v43
	v_cmp_gt_i32_e32 vcc, 0, v43
	v_and_or_b32 v42, v42, s42, v93
	s_nop 0
	v_cndmask_b32_e32 v43, v67, v66, vcc
	v_not_b32_e32 v66, v44
	v_or_b32_e32 v67, 0x80000000, v44
	v_cmp_gt_i32_e32 vcc, 0, v44
	v_and_or_b32 v43, v43, s42, v94
	s_nop 0
	v_cndmask_b32_e32 v44, v67, v66, vcc
	v_not_b32_e32 v66, v45
	v_or_b32_e32 v67, 0x80000000, v45
	v_cmp_gt_i32_e32 vcc, 0, v45
	v_and_or_b32 v44, v44, s42, v95
	s_nop 0
	v_cndmask_b32_e32 v45, v67, v66, vcc
	v_not_b32_e32 v66, v46
	v_or_b32_e32 v67, 0x80000000, v46
	v_cmp_gt_i32_e32 vcc, 0, v46
	v_and_or_b32 v45, v45, s42, v96
	s_nop 0
	v_cndmask_b32_e32 v46, v67, v66, vcc
	v_not_b32_e32 v66, v47
	v_or_b32_e32 v67, 0x80000000, v47
	v_cmp_gt_i32_e32 vcc, 0, v47
	v_and_or_b32 v46, v46, s42, v97
	s_nop 0
	v_cndmask_b32_e32 v47, v67, v66, vcc
	v_not_b32_e32 v66, v48
	v_or_b32_e32 v67, 0x80000000, v48
	v_cmp_gt_i32_e32 vcc, 0, v48
	v_and_or_b32 v47, v47, s42, v98
	s_nop 0
	v_cndmask_b32_e32 v48, v67, v66, vcc
	v_not_b32_e32 v66, v49
	v_or_b32_e32 v67, 0x80000000, v49
	v_cmp_gt_i32_e32 vcc, 0, v49
	v_and_or_b32 v48, v48, s42, v99
	s_nop 0
	v_cndmask_b32_e32 v49, v67, v66, vcc
	v_not_b32_e32 v66, v18
	v_or_b32_e32 v67, 0x80000000, v18
	v_cmp_gt_i32_e32 vcc, 0, v18
	v_and_or_b32 v49, v49, s42, v100
	s_nop 0
	v_cndmask_b32_e32 v18, v67, v66, vcc
	v_not_b32_e32 v66, v19
	v_or_b32_e32 v67, 0x80000000, v19
	v_cmp_gt_i32_e32 vcc, 0, v19
	v_and_or_b32 v18, v18, s42, v101
	s_nop 0
	v_cndmask_b32_e32 v19, v67, v66, vcc
	v_not_b32_e32 v66, v20
	v_or_b32_e32 v67, 0x80000000, v20
	v_cmp_gt_i32_e32 vcc, 0, v20
	v_and_or_b32 v19, v19, s42, v102
	s_nop 0
	v_cndmask_b32_e32 v20, v67, v66, vcc
	v_not_b32_e32 v66, v21
	v_or_b32_e32 v67, 0x80000000, v21
	v_cmp_gt_i32_e32 vcc, 0, v21
	v_and_or_b32 v20, v20, s42, v103
	s_nop 0
	v_cndmask_b32_e32 v21, v67, v66, vcc
	v_not_b32_e32 v66, v22
	v_or_b32_e32 v67, 0x80000000, v22
	v_cmp_gt_i32_e32 vcc, 0, v22
	v_and_or_b32 v21, v21, s42, v104
	s_nop 0
	v_cndmask_b32_e32 v22, v67, v66, vcc
	v_not_b32_e32 v66, v23
	v_or_b32_e32 v67, 0x80000000, v23
	v_cmp_gt_i32_e32 vcc, 0, v23
	v_and_or_b32 v22, v22, s42, v105
	s_nop 0
	v_cndmask_b32_e32 v23, v67, v66, vcc
	v_not_b32_e32 v66, v24
	v_or_b32_e32 v67, 0x80000000, v24
	v_cmp_gt_i32_e32 vcc, 0, v24
	v_and_or_b32 v23, v23, s42, v106
	s_nop 0
	v_cndmask_b32_e32 v24, v67, v66, vcc
	v_not_b32_e32 v66, v25
	v_or_b32_e32 v67, 0x80000000, v25
	v_cmp_gt_i32_e32 vcc, 0, v25
	v_and_or_b32 v24, v24, s42, v107
	s_nop 0
	v_cndmask_b32_e32 v25, v67, v66, vcc
	v_not_b32_e32 v66, v26
	v_or_b32_e32 v67, 0x80000000, v26
	v_cmp_gt_i32_e32 vcc, 0, v26
	v_and_or_b32 v25, v25, s42, v108
	s_nop 0
	v_cndmask_b32_e32 v26, v67, v66, vcc
	v_not_b32_e32 v66, v27
	v_or_b32_e32 v67, 0x80000000, v27
	v_cmp_gt_i32_e32 vcc, 0, v27
	v_and_or_b32 v26, v26, s42, v109
	s_nop 0
	v_cndmask_b32_e32 v27, v67, v66, vcc
	v_not_b32_e32 v66, v28
	v_or_b32_e32 v67, 0x80000000, v28
	v_cmp_gt_i32_e32 vcc, 0, v28
	v_and_or_b32 v27, v27, s42, v110
	s_nop 0
	v_cndmask_b32_e32 v28, v67, v66, vcc
	v_not_b32_e32 v66, v29
	v_or_b32_e32 v67, 0x80000000, v29
	v_cmp_gt_i32_e32 vcc, 0, v29
	v_and_or_b32 v28, v28, s42, v111
	s_nop 0
	v_cndmask_b32_e32 v29, v67, v66, vcc
	v_not_b32_e32 v66, v30
	v_or_b32_e32 v67, 0x80000000, v30
	v_cmp_gt_i32_e32 vcc, 0, v30
	v_and_or_b32 v29, v29, s42, v112
	s_nop 0
	v_cndmask_b32_e32 v30, v67, v66, vcc
	v_not_b32_e32 v66, v31
	v_or_b32_e32 v67, 0x80000000, v31
	v_cmp_gt_i32_e32 vcc, 0, v31
	v_and_or_b32 v30, v30, s42, v113
	s_nop 0
	v_cndmask_b32_e32 v31, v67, v66, vcc
	v_not_b32_e32 v66, v32
	v_or_b32_e32 v67, 0x80000000, v32
	v_cmp_gt_i32_e32 vcc, 0, v32
	v_and_or_b32 v31, v31, s42, v114
	s_nop 0
	v_cndmask_b32_e32 v32, v67, v66, vcc
	v_not_b32_e32 v66, v33
	v_or_b32_e32 v67, 0x80000000, v33
	v_cmp_gt_i32_e32 vcc, 0, v33
	v_and_or_b32 v32, v32, s42, v115
	s_nop 0
	v_cndmask_b32_e32 v33, v67, v66, vcc
	v_not_b32_e32 v66, v2
	v_or_b32_e32 v67, 0x80000000, v2
	v_cmp_gt_i32_e32 vcc, 0, v2
	v_and_or_b32 v33, v33, s42, v116
	s_nop 0
	v_cndmask_b32_e32 v2, v67, v66, vcc
; DI unsigned f2ord(float f) { const unsigned u = __float_as_uint(f); return (u & 0x80000000u) ? ~u : (u | 0x80000000u); }
; DI void peer_topk_phase(const bf16_t* __restrict__ qpk, const bf16_t* __restrict__ subk, int* __restrict__ eidx, float* __restrict__ gout) {
;     ...
;             for (int nb = 0; nb < 4; ++nb)
; #pragma unroll
;                 for (int i = 0; i < 16; ++i) {
;                     const int n = nb * 32 + (i & 3) + 8 * (i >> 2) + 4 * h;
;                     key[nb * 16 + i] = (f2ord(acc[nb][i]) & ~127u) | (unsigned)(127 - n);
;                 }
;             unsigned g0[16], g1[16], g2[16], g3[16];
; #pragma unroll
;             for (int i = 0; i < 16; ++i) { g0[i] = key[i]; g1[i] = key[16 + i]; g2[i] = key[32 + i]; g3[i] = key[48 + i]; }
; #pragma unroll
;             for (int n = 0; n < 63; ++n) { cex(g0[SORT16[n][0]], g0[SORT16[n][1]]); cex(g1[SORT16[n][0]], g1[SORT16[n][1]]); cex(g2[SORT16[n][0]], g2[SORT16[n][1]]); cex(g3[SORT16[n][0]], g3[SORT16[n][1]]); }
	v_not_b32_e32 v66, v3
	v_or_b32_e32 v67, 0x80000000, v3
	v_cmp_gt_i32_e32 vcc, 0, v3
	v_and_or_b32 v2, v2, s42, v117
	s_nop 0
	v_cndmask_b32_e32 v3, v67, v66, vcc
	v_not_b32_e32 v66, v4
	v_or_b32_e32 v67, 0x80000000, v4
	v_cmp_gt_i32_e32 vcc, 0, v4
	v_and_or_b32 v3, v3, s42, v118
	s_nop 0
	v_cndmask_b32_e32 v4, v67, v66, vcc
	v_not_b32_e32 v66, v5
	v_or_b32_e32 v67, 0x80000000, v5
	v_cmp_gt_i32_e32 vcc, 0, v5
	v_and_or_b32 v4, v4, s42, v119
	s_nop 0
	v_cndmask_b32_e32 v5, v67, v66, vcc
	v_not_b32_e32 v66, v6
	v_or_b32_e32 v67, 0x80000000, v6
	v_cmp_gt_i32_e32 vcc, 0, v6
	v_and_or_b32 v5, v5, s42, v120
	s_nop 0
	v_cndmask_b32_e32 v6, v67, v66, vcc
	v_not_b32_e32 v66, v7
	v_or_b32_e32 v67, 0x80000000, v7
	v_cmp_gt_i32_e32 vcc, 0, v7
	v_and_or_b32 v6, v6, s42, v121
	s_nop 0
	v_cndmask_b32_e32 v7, v67, v66, vcc
	v_not_b32_e32 v66, v8
	v_or_b32_e32 v67, 0x80000000, v8
	v_cmp_gt_i32_e32 vcc, 0, v8
	v_and_or_b32 v7, v7, s42, v122
	s_nop 0
	v_cndmask_b32_e32 v8, v67, v66, vcc
	v_not_b32_e32 v66, v9
	v_or_b32_e32 v67, 0x80000000, v9
	v_cmp_gt_i32_e32 vcc, 0, v9
	v_and_or_b32 v8, v8, s42, v123
	s_nop 0
	v_cndmask_b32_e32 v9, v67, v66, vcc
	v_not_b32_e32 v66, v10
	v_or_b32_e32 v67, 0x80000000, v10
	v_cmp_gt_i32_e32 vcc, 0, v10
	v_and_or_b32 v9, v9, s42, v124
	s_nop 0
	v_cndmask_b32_e32 v10, v67, v66, vcc
	v_not_b32_e32 v66, v11
	v_or_b32_e32 v67, 0x80000000, v11
	v_cmp_gt_i32_e32 vcc, 0, v11
	v_and_or_b32 v10, v10, s42, v125
	s_nop 0
	v_cndmask_b32_e32 v11, v67, v66, vcc
	v_not_b32_e32 v66, v12
	v_or_b32_e32 v67, 0x80000000, v12
	v_cmp_gt_i32_e32 vcc, 0, v12
	v_and_or_b32 v11, v11, s42, v126
	s_nop 0
	v_cndmask_b32_e32 v12, v67, v66, vcc
	v_not_b32_e32 v66, v13
	v_or_b32_e32 v67, 0x80000000, v13
	v_cmp_gt_i32_e32 vcc, 0, v13
	v_and_or_b32 v12, v12, s42, v127
	s_nop 0
	v_cndmask_b32_e32 v13, v67, v66, vcc
	v_not_b32_e32 v66, v14
	v_or_b32_e32 v67, 0x80000000, v14
	v_cmp_gt_i32_e32 vcc, 0, v14
	v_and_or_b32 v13, v13, s42, v128
	s_nop 0
	v_cndmask_b32_e32 v14, v67, v66, vcc
	v_not_b32_e32 v66, v15
	v_or_b32_e32 v67, 0x80000000, v15
	v_cmp_gt_i32_e32 vcc, 0, v15
	v_and_or_b32 v14, v14, s42, v129
	s_nop 0
	v_cndmask_b32_e32 v15, v67, v66, vcc
	v_not_b32_e32 v66, v16
	v_or_b32_e32 v67, 0x80000000, v16
	v_cmp_gt_i32_e32 vcc, 0, v16
	v_and_or_b32 v15, v15, s42, v130
	s_nop 0
	v_cndmask_b32_e32 v16, v67, v66, vcc
	v_not_b32_e32 v66, v17
	v_or_b32_e32 v67, 0x80000000, v17
	v_cmp_gt_i32_e32 vcc, 0, v17
	v_and_or_b32 v16, v16, s42, v131
	s_nop 0
	v_cndmask_b32_e32 v17, v67, v66, vcc
	v_not_b32_e32 v66, v50
	v_or_b32_e32 v67, 0x80000000, v50
	v_cmp_gt_i32_e32 vcc, 0, v50
	v_and_or_b32 v17, v17, s42, v132
	s_nop 0
	v_cndmask_b32_e32 v50, v67, v66, vcc
	v_not_b32_e32 v66, v51
	v_or_b32_e32 v67, 0x80000000, v51
	v_cmp_gt_i32_e32 vcc, 0, v51
	v_and_or_b32 v50, v50, s42, v133
	s_nop 0
	v_cndmask_b32_e32 v51, v67, v66, vcc
	v_not_b32_e32 v66, v52
	v_or_b32_e32 v67, 0x80000000, v52
	v_cmp_gt_i32_e32 vcc, 0, v52
	v_and_or_b32 v51, v51, s42, v134
	s_nop 0
	v_cndmask_b32_e32 v52, v67, v66, vcc
	v_not_b32_e32 v66, v53
	v_or_b32_e32 v67, 0x80000000, v53
	v_cmp_gt_i32_e32 vcc, 0, v53
	v_and_or_b32 v52, v52, s42, v135
	s_nop 0
	v_cndmask_b32_e32 v53, v67, v66, vcc
	v_not_b32_e32 v66, v54
	v_or_b32_e32 v67, 0x80000000, v54
	v_cmp_gt_i32_e32 vcc, 0, v54
	v_and_or_b32 v53, v53, s42, v136
	s_nop 0
	v_cndmask_b32_e32 v54, v67, v66, vcc
	v_not_b32_e32 v66, v55
	v_or_b32_e32 v67, 0x80000000, v55
	v_cmp_gt_i32_e32 vcc, 0, v55
	v_and_or_b32 v54, v54, s42, v137
	s_nop 0
	v_cndmask_b32_e32 v55, v67, v66, vcc
	v_not_b32_e32 v66, v56
	v_or_b32_e32 v67, 0x80000000, v56
	v_cmp_gt_i32_e32 vcc, 0, v56
	v_and_or_b32 v55, v55, s42, v138
	s_nop 0
	v_cndmask_b32_e32 v56, v67, v66, vcc
	v_not_b32_e32 v66, v57
	v_or_b32_e32 v67, 0x80000000, v57
	v_cmp_gt_i32_e32 vcc, 0, v57
	v_and_or_b32 v56, v56, s42, v139
	s_nop 0
	v_cndmask_b32_e32 v57, v67, v66, vcc
	v_not_b32_e32 v66, v58
	v_or_b32_e32 v67, 0x80000000, v58
	v_cmp_gt_i32_e32 vcc, 0, v58
	v_and_or_b32 v57, v57, s42, v140
	s_nop 0
	v_cndmask_b32_e32 v58, v67, v66, vcc
	v_not_b32_e32 v66, v59
	v_or_b32_e32 v67, 0x80000000, v59
	v_cmp_gt_i32_e32 vcc, 0, v59
	v_and_or_b32 v58, v58, s42, v141
	s_nop 0
	v_cndmask_b32_e32 v59, v67, v66, vcc
	v_not_b32_e32 v66, v60
	v_or_b32_e32 v67, 0x80000000, v60
	v_cmp_gt_i32_e32 vcc, 0, v60
	v_and_or_b32 v59, v59, s42, v142
	s_nop 0
	v_cndmask_b32_e32 v60, v67, v66, vcc
	v_not_b32_e32 v66, v61
	v_or_b32_e32 v67, 0x80000000, v61
	v_cmp_gt_i32_e32 vcc, 0, v61
	v_and_or_b32 v60, v60, s42, v143
	s_nop 0
	v_cndmask_b32_e32 v61, v67, v66, vcc
	v_not_b32_e32 v66, v62
	v_or_b32_e32 v67, 0x80000000, v62
	v_cmp_gt_i32_e32 vcc, 0, v62
	v_and_or_b32 v61, v61, s42, v144
	s_nop 0
	v_cndmask_b32_e32 v62, v67, v66, vcc
	v_not_b32_e32 v66, v63
	v_or_b32_e32 v67, 0x80000000, v63
	v_cmp_gt_i32_e32 vcc, 0, v63
	v_and_or_b32 v62, v62, s42, v145
	s_nop 0
	v_cndmask_b32_e32 v63, v67, v66, vcc
	v_not_b32_e32 v66, v64
	v_or_b32_e32 v67, 0x80000000, v64
	v_cmp_gt_i32_e32 vcc, 0, v64
	v_and_or_b32 v63, v63, s42, v149
	s_nop 0
	v_cndmask_b32_e32 v64, v67, v66, vcc
	v_not_b32_e32 v66, v65
	v_or_b32_e32 v67, 0x80000000, v65
	v_cmp_gt_i32_e32 vcc, 0, v65
	v_and_or_b32 v64, v64, s42, v152
	s_nop 0
	v_cndmask_b32_e32 v65, v67, v66, vcc
	v_max_u32_e32 v66, v34, v35
	v_min_u32_e32 v34, v34, v35
	v_max_u32_e32 v35, v18, v19
	v_min_u32_e32 v18, v18, v19
	v_max_u32_e32 v19, v2, v3
	v_min_u32_e32 v2, v2, v3
	v_max_u32_e32 v3, v50, v51
	v_min_u32_e32 v50, v50, v51
	v_max_u32_e32 v51, v36, v37
	v_min_u32_e32 v36, v36, v37
	v_max_u32_e32 v37, v20, v21
	v_min_u32_e32 v20, v20, v21
	v_max_u32_e32 v21, v4, v5
	v_min_u32_e32 v4, v4, v5
	v_max_u32_e32 v5, v52, v53
; DI void peer_topk_phase(const bf16_t* __restrict__ qpk, const bf16_t* __restrict__ subk, int* __restrict__ eidx, float* __restrict__ gout) {
;     ...
; #pragma unroll
;             for (int n = 0; n < 63; ++n) { cex(g0[SORT16[n][0]], g0[SORT16[n][1]]); cex(g1[SORT16[n][0]], g1[SORT16[n][1]]); cex(g2[SORT16[n][0]], g2[SORT16[n][1]]); cex(g3[SORT16[n][0]], g3[SORT16[n][1]]); }
	v_min_u32_e32 v52, v52, v53
	v_max_u32_e32 v53, v66, v51
	v_min_u32_e32 v51, v66, v51
	v_max_u32_e32 v66, v35, v37
	v_min_u32_e32 v35, v35, v37
	v_max_u32_e32 v37, v19, v21
	v_min_u32_e32 v19, v19, v21
	v_max_u32_e32 v21, v3, v5
	v_min_u32_e32 v3, v3, v5
	v_max_u32_e32 v5, v34, v36
	v_min_u32_e32 v34, v34, v36
	v_max_u32_e32 v36, v18, v20
	v_min_u32_e32 v18, v18, v20
	v_max_u32_e32 v20, v2, v4
	v_min_u32_e32 v2, v2, v4
	v_max_u32_e32 v4, v50, v52
	v_min_u32_e32 v50, v50, v52
	v_max_u32_e32 v52, v5, v51
	v_min_u32_e32 v5, v5, v51
	v_max_u32_e32 v51, v36, v35
	v_min_u32_e32 v35, v36, v35
	v_max_u32_e32 v36, v20, v19
	v_min_u32_e32 v19, v20, v19
	v_max_u32_e32 v20, v4, v3
	v_min_u32_e32 v3, v4, v3
	v_max_u32_e32 v4, v38, v39
	v_min_u32_e32 v38, v38, v39
	v_max_u32_e32 v39, v22, v23
	v_min_u32_e32 v22, v22, v23
	v_max_u32_e32 v23, v6, v7
	v_min_u32_e32 v6, v6, v7
	v_max_u32_e32 v7, v54, v55
	v_min_u32_e32 v54, v54, v55
	v_max_u32_e32 v55, v40, v41
	v_min_u32_e32 v40, v40, v41
	v_max_u32_e32 v41, v24, v25
	v_min_u32_e32 v24, v24, v25
	v_max_u32_e32 v25, v8, v9
	v_min_u32_e32 v8, v8, v9
	v_max_u32_e32 v9, v56, v57
	v_min_u32_e32 v56, v56, v57
	v_max_u32_e32 v57, v4, v55
	v_min_u32_e32 v4, v4, v55
	v_max_u32_e32 v55, v39, v41
	v_min_u32_e32 v39, v39, v41
	v_max_u32_e32 v41, v23, v25
	v_min_u32_e32 v23, v23, v25
	v_max_u32_e32 v25, v7, v9
	v_min_u32_e32 v7, v7, v9
	v_max_u32_e32 v9, v38, v40
	v_min_u32_e32 v38, v38, v40
	v_max_u32_e32 v40, v22, v24
	v_min_u32_e32 v22, v22, v24
	v_max_u32_e32 v24, v6, v8
	v_min_u32_e32 v6, v6, v8
	v_max_u32_e32 v8, v54, v56
	v_min_u32_e32 v54, v54, v56
	v_max_u32_e32 v56, v9, v4
	v_min_u32_e32 v4, v9, v4
	v_max_u32_e32 v9, v40, v39
	v_min_u32_e32 v39, v40, v39
	v_max_u32_e32 v40, v24, v23
	v_min_u32_e32 v23, v24, v23
	v_max_u32_e32 v24, v8, v7
	v_min_u32_e32 v7, v8, v7
	v_max_u32_e32 v8, v53, v57
	v_min_u32_e32 v53, v53, v57
	v_max_u32_e32 v57, v66, v55
	v_min_u32_e32 v55, v66, v55
	v_max_u32_e32 v66, v37, v41
	v_min_u32_e32 v37, v37, v41
	v_max_u32_e32 v41, v21, v25
	v_min_u32_e32 v21, v21, v25
	v_max_u32_e32 v25, v5, v4
	v_min_u32_e32 v4, v5, v4
	v_max_u32_e32 v5, v35, v39
	v_min_u32_e32 v35, v35, v39
	v_max_u32_e32 v39, v19, v23
	v_min_u32_e32 v19, v19, v23
	v_max_u32_e32 v23, v3, v7
	v_min_u32_e32 v3, v3, v7
	v_max_u32_e32 v7, v25, v53
	v_min_u32_e32 v25, v25, v53
	v_max_u32_e32 v53, v5, v55
	v_min_u32_e32 v5, v5, v55
	v_max_u32_e32 v55, v39, v37
	v_min_u32_e32 v37, v39, v37
	v_max_u32_e32 v39, v23, v21
	v_min_u32_e32 v21, v23, v21
	v_max_u32_e32 v23, v52, v56
	v_min_u32_e32 v52, v52, v56
	v_max_u32_e32 v56, v51, v9
	v_min_u32_e32 v9, v51, v9
	v_max_u32_e32 v51, v36, v40
	v_min_u32_e32 v36, v36, v40
	v_max_u32_e32 v40, v20, v24
	v_min_u32_e32 v20, v20, v24
	v_max_u32_e32 v24, v34, v38
	v_min_u32_e32 v34, v34, v38
	v_max_u32_e32 v38, v18, v22
	v_min_u32_e32 v18, v18, v22
	v_max_u32_e32 v22, v2, v6
	v_min_u32_e32 v2, v2, v6
	v_max_u32_e32 v6, v50, v54
	v_min_u32_e32 v50, v50, v54
	v_max_u32_e32 v54, v24, v52
	v_min_u32_e32 v24, v24, v52
	v_max_u32_e32 v52, v38, v9
	v_min_u32_e32 v9, v38, v9
	v_max_u32_e32 v38, v22, v36
	v_min_u32_e32 v22, v22, v36
	v_max_u32_e32 v36, v6, v20
	v_min_u32_e32 v6, v6, v20
	v_max_u32_e32 v20, v23, v7
	v_min_u32_e32 v7, v23, v7
	v_max_u32_e32 v23, v56, v53
	v_min_u32_e32 v53, v56, v53
	v_max_u32_e32 v56, v51, v55
	v_min_u32_e32 v51, v51, v55
	v_max_u32_e32 v55, v40, v39
	v_min_u32_e32 v39, v40, v39
	v_max_u32_e32 v40, v54, v25
	v_min_u32_e32 v25, v54, v25
	v_max_u32_e32 v54, v52, v5
	v_min_u32_e32 v5, v52, v5
	v_max_u32_e32 v52, v38, v37
	v_min_u32_e32 v37, v38, v37
	v_max_u32_e32 v38, v36, v21
	v_min_u32_e32 v21, v36, v21
	v_max_u32_e32 v36, v24, v4
	v_min_u32_e32 v4, v24, v4
	v_max_u32_e32 v24, v9, v35
	v_min_u32_e32 v9, v9, v35
	v_max_u32_e32 v35, v22, v19
	v_min_u32_e32 v19, v22, v19
	v_max_u32_e32 v22, v6, v3
	v_min_u32_e32 v3, v6, v3
	v_max_u32_e32 v6, v42, v43
	v_min_u32_e32 v42, v42, v43
	v_max_u32_e32 v43, v26, v27
	v_min_u32_e32 v26, v26, v27
	v_max_u32_e32 v27, v10, v11
	v_min_u32_e32 v10, v10, v11
	v_max_u32_e32 v11, v58, v59
	v_min_u32_e32 v58, v58, v59
	v_max_u32_e32 v59, v44, v45
	v_min_u32_e32 v44, v44, v45
	v_max_u32_e32 v45, v28, v29
	v_min_u32_e32 v28, v28, v29
	v_max_u32_e32 v29, v12, v13
	v_min_u32_e32 v12, v12, v13
	v_max_u32_e32 v13, v60, v61
	v_min_u32_e32 v60, v60, v61
	v_and_or_b32 v65, v65, s42, v153
	v_max_u32_e32 v61, v6, v59
	v_min_u32_e32 v6, v6, v59
	v_max_u32_e32 v59, v43, v45
	v_min_u32_e32 v43, v43, v45
	v_max_u32_e32 v45, v27, v29
	v_min_u32_e32 v27, v27, v29
	v_max_u32_e32 v29, v11, v13
	v_min_u32_e32 v11, v11, v13
	v_max_u32_e32 v13, v42, v44
	v_min_u32_e32 v42, v42, v44
	v_max_u32_e32 v44, v26, v28
	v_min_u32_e32 v26, v26, v28
	v_max_u32_e32 v28, v10, v12
	v_min_u32_e32 v10, v10, v12
	v_max_u32_e32 v12, v58, v60
	v_min_u32_e32 v58, v58, v60
	v_max_u32_e32 v60, v13, v6
	v_min_u32_e32 v6, v13, v6
	v_max_u32_e32 v13, v44, v43
	v_min_u32_e32 v43, v44, v43
	v_max_u32_e32 v44, v28, v27
	v_min_u32_e32 v27, v28, v27
	v_max_u32_e32 v28, v12, v11
	v_min_u32_e32 v11, v12, v11
	v_max_u32_e32 v12, v46, v47
	v_min_u32_e32 v46, v46, v47
	v_max_u32_e32 v47, v30, v31
	v_min_u32_e32 v30, v30, v31
	v_max_u32_e32 v31, v14, v15
	v_min_u32_e32 v14, v14, v15
	v_max_u32_e32 v15, v62, v63
	v_min_u32_e32 v62, v62, v63
	v_max_u32_e32 v63, v48, v49
	v_min_u32_e32 v48, v48, v49
	v_max_u32_e32 v49, v32, v33
	v_min_u32_e32 v32, v32, v33
	v_max_u32_e32 v33, v16, v17
	v_min_u32_e32 v16, v16, v17
	v_max_u32_e32 v17, v64, v65
	v_min_u32_e32 v64, v64, v65
	v_max_u32_e32 v65, v12, v63
	v_min_u32_e32 v12, v12, v63
	v_max_u32_e32 v63, v47, v49
	v_min_u32_e32 v47, v47, v49
; DI void merge_top16(unsigned (&A)[16], const unsigned (&B)[16]) {
; #pragma unroll
;     for (int i = 0; i < 16; ++i) A[i] = max(A[i], B[15 - i]);
; #pragma unroll
;     for (int n = 0; n < 32; ++n) cex(A[BMERGE16[n][0]], A[BMERGE16[n][1]]);
; }
; DI void peer_topk_phase(const bf16_t* __restrict__ qpk, const bf16_t* __restrict__ subk, int* __restrict__ eidx, float* __restrict__ gout) {
;     ...
;             for (int n = 0; n < 63; ++n) { cex(g0[SORT16[n][0]], g0[SORT16[n][1]]); cex(g1[SORT16[n][0]], g1[SORT16[n][1]]); cex(g2[SORT16[n][0]], g2[SORT16[n][1]]); cex(g3[SORT16[n][0]], g3[SORT16[n][1]]); }
;             merge_top16(g0, g1); merge_top16(g2, g3); merge_top16(g0, g2);
	v_max_u32_e32 v49, v31, v33
	v_min_u32_e32 v31, v31, v33
	v_max_u32_e32 v33, v15, v17
	v_min_u32_e32 v15, v15, v17
	v_max_u32_e32 v17, v46, v48
	v_min_u32_e32 v46, v46, v48
	v_max_u32_e32 v48, v30, v32
	v_min_u32_e32 v30, v30, v32
	v_max_u32_e32 v32, v14, v16
	v_min_u32_e32 v14, v14, v16
	v_max_u32_e32 v16, v62, v64
	v_min_u32_e32 v62, v62, v64
	v_max_u32_e32 v64, v17, v12
	v_min_u32_e32 v12, v17, v12
	v_max_u32_e32 v17, v48, v47
	v_min_u32_e32 v47, v48, v47
	v_max_u32_e32 v48, v32, v31
	v_min_u32_e32 v31, v32, v31
	v_max_u32_e32 v32, v16, v15
	v_min_u32_e32 v15, v16, v15
	v_max_u32_e32 v16, v61, v65
	v_min_u32_e32 v61, v61, v65
	v_max_u32_e32 v65, v59, v63
	v_min_u32_e32 v59, v59, v63
	v_max_u32_e32 v63, v45, v49
	v_min_u32_e32 v45, v45, v49
	v_max_u32_e32 v49, v29, v33
	v_min_u32_e32 v29, v29, v33
	v_max_u32_e32 v33, v6, v12
	v_min_u32_e32 v6, v6, v12
	v_max_u32_e32 v12, v43, v47
	v_min_u32_e32 v43, v43, v47
	v_max_u32_e32 v47, v27, v31
	v_min_u32_e32 v27, v27, v31
	v_max_u32_e32 v31, v11, v15
	v_min_u32_e32 v11, v11, v15
	v_max_u32_e32 v15, v33, v61
	v_min_u32_e32 v33, v33, v61
	v_max_u32_e32 v61, v12, v59
	v_min_u32_e32 v12, v12, v59
	v_max_u32_e32 v59, v47, v45
	v_min_u32_e32 v45, v47, v45
	v_max_u32_e32 v47, v31, v29
	v_min_u32_e32 v29, v31, v29
	v_max_u32_e32 v31, v60, v64
	v_min_u32_e32 v60, v60, v64
	v_max_u32_e32 v64, v13, v17
	v_min_u32_e32 v13, v13, v17
	v_max_u32_e32 v17, v44, v48
	v_min_u32_e32 v44, v44, v48
	v_max_u32_e32 v48, v28, v32
	v_min_u32_e32 v28, v28, v32
	v_max_u32_e32 v32, v42, v46
	v_min_u32_e32 v42, v42, v46
	v_max_u32_e32 v46, v26, v30
	v_min_u32_e32 v26, v26, v30
	v_max_u32_e32 v30, v10, v14
	v_min_u32_e32 v10, v10, v14
	v_max_u32_e32 v14, v58, v62
	v_min_u32_e32 v58, v58, v62
	v_max_u32_e32 v62, v32, v60
	v_min_u32_e32 v32, v32, v60
	v_max_u32_e32 v60, v46, v13
	v_min_u32_e32 v13, v46, v13
	v_max_u32_e32 v46, v30, v44
	v_min_u32_e32 v30, v30, v44
	v_max_u32_e32 v44, v14, v28
	v_min_u32_e32 v14, v14, v28
	v_max_u32_e32 v28, v31, v15
	v_min_u32_e32 v15, v31, v15
	v_max_u32_e32 v31, v64, v61
	v_min_u32_e32 v61, v64, v61
	v_max_u32_e32 v64, v17, v59
	v_min_u32_e32 v17, v17, v59
	v_max_u32_e32 v59, v48, v47
	v_min_u32_e32 v47, v48, v47
	v_max_u32_e32 v48, v62, v33
	v_min_u32_e32 v33, v62, v33
	v_max_u32_e32 v62, v60, v12
	v_min_u32_e32 v12, v60, v12
	v_max_u32_e32 v60, v46, v45
	v_min_u32_e32 v45, v46, v45
	v_max_u32_e32 v46, v44, v29
	v_min_u32_e32 v29, v44, v29
	v_max_u32_e32 v44, v32, v6
	v_min_u32_e32 v6, v32, v6
	v_max_u32_e32 v32, v13, v43
	v_min_u32_e32 v13, v13, v43
	v_max_u32_e32 v43, v30, v27
	v_min_u32_e32 v27, v30, v27
	v_max_u32_e32 v30, v14, v11
	v_min_u32_e32 v11, v14, v11
	v_min_u32_e32 v14, v8, v16
	v_min_u32_e32 v67, v57, v65
	v_min_u32_e32 v68, v66, v63
	v_min_u32_e32 v69, v41, v49
	v_max_u32_e32 v70, v25, v33
	v_min_u32_e32 v25, v25, v33
	v_max_u32_e32 v33, v5, v12
	v_min_u32_e32 v5, v5, v12
	v_max_u32_e32 v12, v37, v45
	v_min_u32_e32 v37, v37, v45
	v_max_u32_e32 v45, v21, v29
	v_min_u32_e32 v21, v21, v29
	v_max_u32_e32 v29, v70, v14
	v_min_u32_e32 v14, v70, v14
	v_max_u32_e32 v70, v33, v67
	v_min_u32_e32 v33, v33, v67
	v_max_u32_e32 v67, v12, v68
	v_min_u32_e32 v12, v12, v68
	v_max_u32_e32 v68, v45, v69
	v_min_u32_e32 v45, v45, v69
	v_max_u32_e32 v69, v7, v15
	v_min_u32_e32 v7, v7, v15
	v_max_u32_e32 v15, v53, v61
	v_min_u32_e32 v53, v53, v61
	v_max_u32_e32 v61, v51, v17
	v_min_u32_e32 v17, v51, v17
	v_max_u32_e32 v51, v39, v47
	v_min_u32_e32 v39, v39, v47
	v_max_u32_e32 v47, v4, v6
	v_min_u32_e32 v4, v4, v6
	v_max_u32_e32 v6, v9, v13
	v_min_u32_e32 v9, v9, v13
	v_max_u32_e32 v13, v19, v27
	v_min_u32_e32 v19, v19, v27
	v_max_u32_e32 v27, v3, v11
	v_min_u32_e32 v3, v3, v11
	v_max_u32_e32 v11, v47, v7
	v_min_u32_e32 v7, v47, v7
	v_max_u32_e32 v47, v6, v53
	v_min_u32_e32 v6, v6, v53
	v_max_u32_e32 v53, v13, v17
	v_min_u32_e32 v13, v13, v17
	v_max_u32_e32 v17, v27, v39
	v_min_u32_e32 v27, v27, v39
	v_max_u32_e32 v39, v69, v29
	v_min_u32_e32 v29, v69, v29
	v_max_u32_e32 v69, v15, v70
	v_min_u32_e32 v15, v15, v70
	v_max_u32_e32 v70, v61, v67
	v_min_u32_e32 v61, v61, v67
	v_max_u32_e32 v67, v51, v68
	v_min_u32_e32 v51, v51, v68
	v_max_u32_e32 v68, v11, v14
	v_min_u32_e32 v11, v11, v14
	v_max_u32_e32 v14, v47, v33
	v_min_u32_e32 v33, v47, v33
	v_max_u32_e32 v47, v53, v12
	v_min_u32_e32 v12, v53, v12
	v_max_u32_e32 v53, v17, v45
	v_min_u32_e32 v17, v17, v45
	v_max_u32_e32 v45, v7, v25
	v_min_u32_e32 v7, v7, v25
	v_max_u32_e32 v25, v6, v5
	v_min_u32_e32 v5, v6, v5
	v_max_u32_e32 v6, v13, v37
	v_min_u32_e32 v13, v13, v37
	v_max_u32_e32 v37, v27, v21
	v_min_u32_e32 v21, v27, v21
	v_max_u32_e32 v27, v20, v28
	v_min_u32_e32 v20, v20, v28
	v_max_u32_e32 v28, v23, v31
	v_min_u32_e32 v23, v23, v31
	v_max_u32_e32 v31, v56, v64
	v_min_u32_e32 v56, v56, v64
	v_max_u32_e32 v64, v55, v59
	v_min_u32_e32 v55, v55, v59
	v_max_u32_e32 v59, v36, v44
	v_min_u32_e32 v36, v36, v44
	v_max_u32_e32 v44, v24, v32
	v_min_u32_e32 v24, v24, v32
	v_max_u32_e32 v32, v35, v43
	v_min_u32_e32 v35, v35, v43
	v_max_u32_e32 v43, v22, v30
	v_min_u32_e32 v22, v22, v30
	v_max_u32_e32 v30, v59, v20
	v_min_u32_e32 v20, v59, v20
	v_max_u32_e32 v59, v44, v23
	v_min_u32_e32 v23, v44, v23
	v_max_u32_e32 v44, v32, v56
	v_min_u32_e32 v32, v32, v56
	v_max_u32_e32 v56, v43, v55
	v_min_u32_e32 v43, v43, v55
	v_max_u32_e32 v55, v40, v48
	v_min_u32_e32 v40, v40, v48
	v_max_u32_e32 v48, v54, v62
	v_min_u32_e32 v54, v54, v62
	v_max_u32_e32 v62, v52, v60
	v_min_u32_e32 v52, v52, v60
	v_max_u32_e32 v60, v38, v46
	v_min_u32_e32 v38, v38, v46
	v_max_u32_e32 v46, v34, v42
	v_min_u32_e32 v34, v34, v42
	v_max_u32_e32 v42, v18, v26
	v_min_u32_e32 v18, v18, v26
; DI void merge_top16(unsigned (&A)[16], const unsigned (&B)[16]) {
; #pragma unroll
;     for (int i = 0; i < 16; ++i) A[i] = max(A[i], B[15 - i]);
; #pragma unroll
;     for (int n = 0; n < 32; ++n) cex(A[BMERGE16[n][0]], A[BMERGE16[n][1]]);
; }
; DI void peer_topk_phase(const bf16_t* __restrict__ qpk, const bf16_t* __restrict__ subk, int* __restrict__ eidx, float* __restrict__ gout) {
;     ...
;             merge_top16(g0, g1); merge_top16(g2, g3); merge_top16(g0, g2);
	v_max_u32_e32 v26, v2, v10
	v_min_u32_e32 v2, v2, v10
	v_max_u32_e32 v10, v50, v58
	v_min_u32_e32 v50, v50, v58
	v_max_u32_e32 v58, v46, v40
	v_min_u32_e32 v40, v46, v40
	v_max_u32_e32 v46, v42, v54
	v_min_u32_e32 v42, v42, v54
	v_max_u32_e32 v54, v26, v52
	v_min_u32_e32 v26, v26, v52
	v_max_u32_e32 v52, v10, v38
	v_min_u32_e32 v10, v10, v38
	v_max_u32_e32 v38, v55, v30
	v_min_u32_e32 v30, v55, v30
	v_max_u32_e32 v55, v48, v59
	v_min_u32_e32 v48, v48, v59
	v_max_u32_e32 v59, v62, v44
	v_min_u32_e32 v44, v62, v44
	v_max_u32_e32 v62, v60, v56
	v_min_u32_e32 v56, v60, v56
	v_max_u32_e32 v60, v58, v20
	v_min_u32_e32 v20, v58, v20
	v_max_u32_e32 v58, v46, v23
	v_min_u32_e32 v23, v46, v23
	v_max_u32_e32 v46, v54, v32
	v_min_u32_e32 v32, v54, v32
	v_max_u32_e32 v54, v52, v43
	v_min_u32_e32 v43, v52, v43
	v_max_u32_e32 v52, v40, v36
	v_min_u32_e32 v36, v40, v36
	v_max_u32_e32 v40, v42, v24
	v_min_u32_e32 v24, v42, v24
	v_max_u32_e32 v42, v26, v35
	v_min_u32_e32 v26, v26, v35
	v_max_u32_e32 v35, v10, v22
	v_min_u32_e32 v10, v10, v22
	v_min_u32_e32 v22, v27, v39
	v_min_u32_e32 v71, v28, v69
	v_min_u32_e32 v72, v31, v70
	v_min_u32_e32 v73, v64, v67
	v_min_u32_e32 v82, v38, v29
	v_min_u32_e32 v83, v55, v15
	v_min_u32_e32 v183, v59, v61
	v_min_u32_e32 v184, v62, v51
	v_min_u32_e32 v185, v30, v68
	v_min_u32_e32 v186, v48, v14
	v_min_u32_e32 v187, v44, v47
	v_min_u32_e32 v188, v56, v53
	v_min_u32_e32 v189, v60, v11
	v_min_u32_e32 v190, v58, v33
	v_min_u32_e32 v191, v46, v12
	v_min_u32_e32 v198, v54, v17
	v_min_u32_e32 v199, v20, v45
	v_min_u32_e32 v200, v23, v25
	v_min_u32_e32 v201, v32, v6
	v_min_u32_e32 v202, v43, v37
	v_min_u32_e32 v203, v52, v7
	v_min_u32_e32 v210, v40, v5
	v_min_u32_e32 v211, v42, v13
	v_min_u32_e32 v212, v35, v21
	v_min_u32_e32 v213, v36, v4
	v_min_u32_e32 v214, v24, v9
	v_min_u32_e32 v215, v26, v19
	v_min_u32_e32 v216, v10, v3
	v_max3_u32 v8, v8, v16, v18
	v_max3_u32 v16, v27, v39, v214
	v_max3_u32 v9, v22, v24, v9
	v_max3_u32 v18, v38, v29, v210
	v_max3_u32 v5, v82, v40, v5
	v_max3_u32 v22, v30, v68, v200
	v_max3_u32 v23, v185, v23, v25
	v_max3_u32 v11, v60, v11, v190
	v_max3_u32 v24, v189, v58, v33
	v_max3_u32 v20, v20, v45, v186
	v_max3_u32 v14, v199, v48, v14
	v_max3_u32 v7, v52, v7, v83
	v_max3_u32 v15, v203, v55, v15
	v_max3_u32 v4, v36, v4, v71
	v_max3_u32 v25, v213, v28, v69
	v_max3_u32 v27, v34, v57, v65
	v_max3_u32 v40, v66, v63, v50
	v_max3_u32 v31, v31, v70, v216
	v_max3_u32 v3, v72, v10, v3
	v_max3_u32 v10, v59, v61, v212
	v_max3_u32 v21, v183, v35, v21
	v_max3_u32 v35, v44, v47, v202
	v_max3_u32 v37, v187, v43, v37
	v_max3_u32 v12, v46, v12, v198
	v_max3_u32 v17, v191, v54, v17
	v_max3_u32 v6, v32, v6, v188
	v_max3_u32 v32, v201, v56, v53
	v_max3_u32 v13, v42, v13, v184
	v_max3_u32 v42, v211, v62, v51
	v_max3_u32 v19, v26, v19, v73
	v_max3_u32 v26, v215, v64, v67
	v_max3_u32 v2, v2, v41, v49
	v_max_u32_e32 v28, v8, v24
	v_min_u32_e32 v8, v8, v24
	v_max_u32_e32 v24, v16, v20
	v_min_u32_e32 v16, v16, v20
	v_max_u32_e32 v20, v9, v14
	v_min_u32_e32 v9, v9, v14
	v_max_u32_e32 v14, v18, v7
	v_min_u32_e32 v7, v18, v7
	v_max_u32_e32 v18, v5, v15
	v_min_u32_e32 v5, v5, v15
	v_max_u32_e32 v15, v22, v4
	v_min_u32_e32 v4, v22, v4
	v_max_u32_e32 v22, v23, v25
	v_min_u32_e32 v23, v23, v25
	v_max_u32_e32 v25, v11, v27
	v_min_u32_e32 v11, v11, v27
	v_max_u32_e32 v41, v40, v17
	v_min_u32_e32 v17, v40, v17
	v_max_u32_e32 v40, v31, v6
	v_min_u32_e32 v6, v31, v6
	v_max_u32_e32 v31, v3, v32
	v_min_u32_e32 v3, v3, v32
	v_max_u32_e32 v32, v10, v13
	v_min_u32_e32 v10, v10, v13
	v_max_u32_e32 v13, v21, v42
	v_min_u32_e32 v21, v21, v42
	v_max_u32_e32 v42, v35, v19
	v_min_u32_e32 v19, v35, v19
	v_max_u32_e32 v35, v37, v26
	v_min_u32_e32 v26, v37, v26
	v_max_u32_e32 v37, v12, v2
	v_min_u32_e32 v2, v12, v2
	v_max_u32_e32 v27, v28, v18
	v_min_u32_e32 v18, v28, v18
	v_max_u32_e32 v28, v24, v15
	v_min_u32_e32 v15, v24, v15
	v_max_u32_e32 v24, v20, v22
	v_min_u32_e32 v20, v20, v22
	v_max_u32_e32 v22, v14, v25
	v_min_u32_e32 v14, v14, v25
	v_max_u32_e32 v25, v8, v5
	v_min_u32_e32 v5, v8, v5
	v_max_u32_e32 v8, v16, v4
	v_min_u32_e32 v4, v16, v4
	v_max_u32_e32 v16, v9, v23
	v_min_u32_e32 v9, v9, v23
	v_max_u32_e32 v23, v7, v11
	v_min_u32_e32 v7, v7, v11
	v_max_u32_e32 v12, v41, v13
	v_min_u32_e32 v13, v41, v13
	v_max_u32_e32 v41, v40, v42
	v_min_u32_e32 v40, v40, v42
	v_max_u32_e32 v42, v31, v35
	v_min_u32_e32 v31, v31, v35
	v_max_u32_e32 v35, v32, v37
	v_min_u32_e32 v32, v32, v37
	v_max_u32_e32 v37, v17, v21
	v_min_u32_e32 v17, v17, v21
	v_max_u32_e32 v21, v6, v19
	v_min_u32_e32 v6, v6, v19
	v_max_u32_e32 v19, v3, v26
	v_min_u32_e32 v3, v3, v26
	v_max_u32_e32 v26, v10, v2
	v_min_u32_e32 v2, v10, v2
	v_max_u32_e32 v11, v27, v24
	v_min_u32_e32 v24, v27, v24
	v_max_u32_e32 v27, v28, v22
	v_min_u32_e32 v22, v28, v22
	v_max_u32_e32 v28, v18, v20
	v_min_u32_e32 v18, v18, v20
	v_max_u32_e32 v20, v15, v14
	v_min_u32_e32 v14, v15, v14
	v_max_u32_e32 v15, v25, v16
	v_min_u32_e32 v16, v25, v16
	v_max_u32_e32 v25, v8, v23
	v_min_u32_e32 v8, v8, v23
	v_max_u32_e32 v23, v5, v9
	v_min_u32_e32 v5, v5, v9
	v_max_u32_e32 v9, v4, v7
	v_min_u32_e32 v4, v4, v7
	v_max_u32_e32 v10, v12, v42
	v_min_u32_e32 v12, v12, v42
	v_max_u32_e32 v42, v41, v35
	v_min_u32_e32 v35, v41, v35
	v_max_u32_e32 v41, v13, v31
	v_min_u32_e32 v13, v13, v31
	v_max_u32_e32 v31, v40, v32
	v_min_u32_e32 v32, v40, v32
	v_max_u32_e32 v40, v37, v19
	v_min_u32_e32 v19, v37, v19
	v_max_u32_e32 v37, v21, v26
	v_min_u32_e32 v21, v21, v26
	v_max_u32_e32 v26, v17, v3
	v_min_u32_e32 v3, v17, v3
	v_max_u32_e32 v17, v6, v2
	v_min_u32_e32 v2, v6, v2
	v_min_u32_e32 v7, v11, v27
	v_min_u32_e32 v29, v24, v22
; DI float ord2f(unsigned o) { const unsigned u = (o & 0x80000000u) ? (o & 0x7fffffffu) : ~o; return __uint_as_float(u); }
; DI void peer_topk_phase(const bf16_t* __restrict__ qpk, const bf16_t* __restrict__ subk, int* __restrict__ eidx, float* __restrict__ gout) {
;     ...
;             merge_top16(g0, g1); merge_top16(g2, g3); merge_top16(g0, g2);
;             unsigned pb[16];
; #pragma unroll
;             for (int i = 0; i < 16; ++i) pb[i] = (unsigned)__shfl_xor((int)g0[i], 32);
;             merge_top16(g0, pb);
; #pragma unroll
;             for (int i = 0; i < 16; ++i) top[c][i] = g0[i];
;         }
;         unsigned ck[50];
; #pragma unroll
;         for (int a = 0; a < 16; ++a)
; #pragma unroll
;             for (int b = 0; b < 16 / (a + 1); ++b) {
;                 const float cv = ord2f(top[0][a] & ~127u) + ord2f(top[1][b] & ~127u);
	v_min_u32_e32 v30, v28, v20
	v_min_u32_e32 v33, v18, v14
	v_min_u32_e32 v34, v15, v25
	v_min_u32_e32 v36, v16, v8
	v_min_u32_e32 v38, v23, v9
	v_min_u32_e32 v39, v5, v4
	v_min_u32_e32 v6, v10, v42
	v_min_u32_e32 v43, v12, v35
	v_min_u32_e32 v44, v41, v31
	v_min_u32_e32 v45, v13, v32
	v_min_u32_e32 v46, v40, v37
	v_min_u32_e32 v47, v19, v21
	v_min_u32_e32 v48, v26, v17
	v_min_u32_e32 v49, v3, v2
	v_max3_u32 v11, v11, v27, v49
	v_max3_u32 v2, v7, v3, v2
	v_max3_u32 v3, v24, v22, v48
	v_max3_u32 v7, v29, v26, v17
	v_max3_u32 v17, v28, v20, v47
	v_max3_u32 v19, v30, v19, v21
	v_max3_u32 v14, v18, v14, v46
	v_max3_u32 v18, v33, v40, v37
	v_max3_u32 v15, v15, v25, v45
	v_max3_u32 v13, v34, v13, v32
	v_max3_u32 v8, v16, v8, v44
	v_max3_u32 v16, v36, v41, v31
	v_max3_u32 v9, v23, v9, v43
	v_max3_u32 v12, v38, v12, v35
	v_max3_u32 v4, v5, v4, v6
	v_max3_u32 v5, v39, v10, v42
	v_max_u32_e32 v6, v11, v15
	v_min_u32_e32 v10, v11, v15
	v_max_u32_e32 v11, v2, v13
	v_min_u32_e32 v2, v2, v13
	v_max_u32_e32 v13, v3, v8
	v_min_u32_e32 v3, v3, v8
	v_max_u32_e32 v8, v7, v16
	v_min_u32_e32 v7, v7, v16
	v_max_u32_e32 v15, v17, v9
	v_min_u32_e32 v9, v17, v9
	v_max_u32_e32 v16, v19, v12
	v_min_u32_e32 v12, v19, v12
	v_max_u32_e32 v17, v14, v4
	v_min_u32_e32 v4, v14, v4
	v_max_u32_e32 v14, v18, v5
	v_min_u32_e32 v5, v18, v5
	v_max_u32_e32 v18, v6, v15
	v_min_u32_e32 v6, v6, v15
	v_max_u32_e32 v15, v11, v16
	v_min_u32_e32 v11, v11, v16
	v_max_u32_e32 v16, v13, v17
	v_min_u32_e32 v13, v13, v17
	v_max_u32_e32 v17, v8, v14
	v_min_u32_e32 v8, v8, v14
	v_max_u32_e32 v14, v10, v9
	v_min_u32_e32 v9, v10, v9
	v_max_u32_e32 v10, v2, v12
	v_min_u32_e32 v2, v2, v12
	v_max_u32_e32 v12, v3, v4
	v_min_u32_e32 v3, v3, v4
	v_max_u32_e32 v4, v7, v5
	v_min_u32_e32 v5, v7, v5
	v_max_u32_e32 v7, v18, v16
	v_min_u32_e32 v16, v18, v16
	v_max_u32_e32 v18, v15, v17
	v_min_u32_e32 v15, v15, v17
	v_max_u32_e32 v17, v6, v13
	v_min_u32_e32 v6, v6, v13
	v_max_u32_e32 v13, v11, v8
	v_min_u32_e32 v8, v11, v8
	v_max_u32_e32 v11, v14, v12
	v_min_u32_e32 v12, v14, v12
	v_max_u32_e32 v14, v10, v4
	v_min_u32_e32 v4, v10, v4
	v_max_u32_e32 v10, v9, v3
	v_min_u32_e32 v3, v9, v3
	v_max_u32_e32 v9, v2, v5
	v_min_u32_e32 v2, v2, v5
	v_max_u32_e32 v5, v7, v18
	v_min_u32_e32 v7, v7, v18
	v_max_u32_e32 v18, v16, v15
	v_min_u32_e32 v15, v16, v15
	v_max_u32_e32 v16, v17, v13
	v_min_u32_e32 v13, v17, v13
	v_max_u32_e32 v17, v6, v8
	v_min_u32_e32 v6, v6, v8
	v_max_u32_e32 v8, v11, v14
	v_min_u32_e32 v11, v11, v14
	v_max_u32_e32 v14, v12, v4
	v_min_u32_e32 v4, v12, v4
	v_max_u32_e32 v12, v10, v9
	v_min_u32_e32 v9, v10, v9
	v_max_u32_e32 v10, v3, v2
	v_min_u32_e32 v2, v3, v2
	ds_bpermute_b32 v3, v173, v5
	ds_bpermute_b32 v19, v173, v7
	ds_bpermute_b32 v20, v173, v18
	ds_bpermute_b32 v21, v173, v15
	ds_bpermute_b32 v22, v173, v16
	ds_bpermute_b32 v23, v173, v13
	ds_bpermute_b32 v24, v173, v17
	ds_bpermute_b32 v25, v173, v6
	ds_bpermute_b32 v26, v173, v8
	ds_bpermute_b32 v27, v173, v11
	ds_bpermute_b32 v28, v173, v14
	ds_bpermute_b32 v29, v173, v4
	ds_bpermute_b32 v30, v173, v12
	ds_bpermute_b32 v31, v173, v9
	ds_bpermute_b32 v32, v173, v10
	ds_bpermute_b32 v33, v173, v2
	s_waitcnt lgkmcnt(4)
	v_max_u32_e32 v16, v16, v29
	s_waitcnt lgkmcnt(3)
	v_max_u32_e32 v15, v15, v30
	s_waitcnt lgkmcnt(2)
	v_max_u32_e32 v18, v18, v31
	s_waitcnt lgkmcnt(1)
	v_max_u32_e32 v7, v7, v32
	s_waitcnt lgkmcnt(0)
	v_max_u32_e32 v5, v5, v33
	v_max_u32_e32 v13, v13, v28
	v_max_u32_e32 v17, v17, v27
	v_max_u32_e32 v6, v6, v26
	v_max_u32_e32 v8, v8, v25
	v_max_u32_e32 v11, v11, v24
	v_max_u32_e32 v14, v14, v23
	v_max_u32_e32 v4, v4, v22
	v_max_u32_e32 v12, v12, v21
	v_max_u32_e32 v9, v9, v20
	v_max_u32_e32 v10, v10, v19
	v_max_u32_e32 v2, v2, v3
	v_max_u32_e32 v3, v5, v8
	v_min_u32_e32 v5, v5, v8
	v_max_u32_e32 v8, v7, v11
	v_min_u32_e32 v7, v7, v11
	v_max_u32_e32 v11, v18, v14
	v_min_u32_e32 v14, v18, v14
	v_max_u32_e32 v18, v15, v4
	v_min_u32_e32 v4, v15, v4
	v_max_u32_e32 v15, v16, v12
	v_min_u32_e32 v12, v16, v12
	v_max_u32_e32 v16, v13, v9
	v_min_u32_e32 v9, v13, v9
	v_max_u32_e32 v13, v17, v10
	v_min_u32_e32 v10, v17, v10
	v_max_u32_e32 v17, v6, v2
	v_min_u32_e32 v2, v6, v2
	v_max_u32_e32 v6, v3, v15
	v_min_u32_e32 v3, v3, v15
	v_max_u32_e32 v15, v8, v16
	v_min_u32_e32 v8, v8, v16
	v_max_u32_e32 v16, v11, v13
	v_min_u32_e32 v11, v11, v13
	v_max_u32_e32 v13, v18, v17
	v_min_u32_e32 v17, v18, v17
	v_max_u32_e32 v18, v5, v12
	v_min_u32_e32 v5, v5, v12
	v_max_u32_e32 v12, v7, v9
	v_min_u32_e32 v7, v7, v9
	v_max_u32_e32 v9, v14, v10
	v_min_u32_e32 v10, v14, v10
	v_max_u32_e32 v14, v4, v2
	v_min_u32_e32 v2, v4, v2
	v_max_u32_e32 v4, v6, v16
	v_min_u32_e32 v6, v6, v16
	v_max_u32_e32 v16, v15, v13
	v_min_u32_e32 v13, v15, v13
	v_max_u32_e32 v15, v3, v11
	v_min_u32_e32 v3, v3, v11
	v_max_u32_e32 v11, v8, v17
	v_min_u32_e32 v8, v8, v17
	v_max_u32_e32 v23, v18, v9
	v_min_u32_e32 v9, v18, v9
	v_max_u32_e32 v18, v15, v11
	v_min_u32_e32 v17, v15, v11
	v_max_u32_e32 v24, v12, v14
	v_min_u32_e32 v25, v12, v14
	v_max_u32_e32 v26, v5, v10
	v_min_u32_e32 v27, v5, v10
	v_max_u32_e32 v5, v7, v2
	v_min_u32_e32 v2, v7, v2
	v_max_u32_e32 v21, v6, v13
	v_min_u32_e32 v19, v6, v13
	v_and_b32_e32 v6, 0xffffff80, v18
	v_and_b32_e32 v7, 0xffffff80, v17
	v_max_u32_e32 v20, v4, v16
	v_min_u32_e32 v22, v4, v16
	v_max_u32_e32 v16, v3, v8
	v_min_u32_e32 v15, v3, v8
	v_max_u32_e32 v14, v23, v24
	v_min_u32_e32 v13, v23, v24
	v_max_u32_e32 v12, v9, v25
	v_min_u32_e32 v11, v9, v25
	v_max_u32_e32 v10, v26, v5
	v_min_u32_e32 v9, v26, v5
	v_max_u32_e32 v5, v27, v2
	v_min_u32_e32 v3, v27, v2
	v_cmp_gt_i32_e32 vcc, 0, v17
	v_cmp_gt_i32_e64 s[0:1], 0, v18
	v_and_b32_e32 v2, 0x7fffff80, v18
; DI unsigned f2ord(float f) { const unsigned u = __float_as_uint(f); return (u & 0x80000000u) ? ~u : (u | 0x80000000u); }
; DI float ord2f(unsigned o) { const unsigned u = (o & 0x80000000u) ? (o & 0x7fffffffu) : ~o; return __uint_as_float(u); }
; DI void peer_topk_phase(const bf16_t* __restrict__ qpk, const bf16_t* __restrict__ subk, int* __restrict__ eidx, float* __restrict__ gout) {
;     ...
; #pragma unroll
;         for (int a = 0; a < 16; ++a)
; #pragma unroll
;             for (int b = 0; b < 16 / (a + 1); ++b) {
;                 const float cv = ord2f(top[0][a] & ~127u) + ord2f(top[1][b] & ~127u);
;                 ck[combo_row_start(a) + b] = (f2ord(cv) & ~255u) | (unsigned)(((15 - a) << 4) | (15 - b));
;             }
	v_and_b32_e32 v4, 0x7fffff80, v17
	v_xor_b32_e32 v6, -1, v6
	v_xor_b32_e32 v8, -1, v7
	v_cndmask_b32_e64 v7, v6, v2, s[0:1]
	v_cndmask_b32_e32 v6, v8, v4, vcc
	v_cmp_gt_i32_e32 vcc, 0, v15
	v_and_b32_e32 v2, 0x7fffff80, v15
	v_bitop3_b32 v4, v15, s5, v15 bitop3:0xcf
	v_and_b32_e32 v8, 0xffffff80, v14
	v_and_b32_e32 v23, 0xffffff80, v13
	v_cndmask_b32_e32 v36, v4, v2, vcc
	v_cmp_gt_i32_e32 vcc, 0, v13
	v_cmp_gt_i32_e64 s[0:1], 0, v14
	v_and_b32_e32 v2, 0x7fffff80, v14
	v_and_b32_e32 v4, 0x7fffff80, v13
	v_xor_b32_e32 v8, -1, v8
	v_xor_b32_e32 v23, -1, v23
	v_cndmask_b32_e64 v27, v8, v2, s[0:1]
	v_cndmask_b32_e32 v26, v23, v4, vcc
	v_and_b32_e32 v8, 0xffffff80, v12
	v_and_b32_e32 v23, 0xffffff80, v11
	v_cmp_gt_i32_e32 vcc, 0, v11
	v_cmp_gt_i32_e64 s[0:1], 0, v12
	v_and_b32_e32 v2, 0x7fffff80, v12
	v_and_b32_e32 v4, 0x7fffff80, v11
	v_xor_b32_e32 v8, -1, v8
	v_xor_b32_e32 v23, -1, v23
	v_cndmask_b32_e64 v29, v8, v2, s[0:1]
	v_cndmask_b32_e32 v28, v23, v4, vcc
	v_and_b32_e32 v8, 0xffffff80, v10
	v_and_b32_e32 v23, 0xffffff80, v9
	v_cmp_gt_i32_e32 vcc, 0, v9
	v_cmp_gt_i32_e64 s[0:1], 0, v10
	v_and_b32_e32 v2, 0x7fffff80, v10
	v_and_b32_e32 v4, 0x7fffff80, v9
	v_xor_b32_e32 v8, -1, v8
	v_xor_b32_e32 v23, -1, v23
	v_cndmask_b32_e64 v31, v8, v2, s[0:1]
	v_cndmask_b32_e32 v30, v23, v4, vcc
	v_cmp_gt_i32_e32 vcc, 0, v5
	v_and_b32_e32 v2, 0x7fffff80, v5
	v_bitop3_b32 v4, v5, s5, v5 bitop3:0xcf
	v_and_b32_e32 v8, 0xffffff80, v3
	v_and_b32_e32 v23, 0xffffff80, v168
	v_cndmask_b32_e32 v33, v4, v2, vcc
	v_cmp_gt_i32_e32 vcc, 0, v168
	v_cmp_gt_i32_e64 s[0:1], 0, v3
	v_and_b32_e32 v2, 0x7fffff80, v3
	v_and_b32_e32 v4, 0x7fffff80, v168
	v_xor_b32_e32 v8, -1, v8
	v_xor_b32_e32 v23, -1, v23
	v_cndmask_b32_e64 v32, v8, v2, s[0:1]
	v_cndmask_b32_e32 v2, v23, v4, vcc
	v_pk_add_f32 v[24:25], v[2:3], v[6:7] op_sel_hi:[0,1]
	v_not_b32_e32 v4, v25
	v_or_b32_e32 v8, 0x80000000, v25
	v_cmp_gt_i32_e64 s[0:1], 0, v25
	v_cmp_gt_i32_e32 vcc, 0, v24
	v_pk_add_f32 v[34:35], v[2:3], v[26:27] op_sel_hi:[0,1]
	v_cndmask_b32_e64 v4, v8, v4, s[0:1]
	v_and_b32_e32 v4, 0xffffff00, v4
	v_or_b32_e32 v23, 0xfb, v4
	v_not_b32_e32 v4, v24
	v_or_b32_e32 v8, 0x80000000, v24
	v_cndmask_b32_e32 v4, v8, v4, vcc
	v_and_b32_e32 v4, 0xffffff00, v4
	v_or_b32_e32 v24, 0xfa, v4
	v_add_f32_e32 v4, v2, v36
	v_cmp_gt_i32_e32 vcc, 0, v4
	v_not_b32_e32 v8, v4
	v_or_b32_e32 v4, 0x80000000, v4
	v_cndmask_b32_e32 v4, v4, v8, vcc
	v_and_b32_e32 v4, 0xffffff00, v4
	v_or_b32_e32 v25, 0xf8, v4
	v_not_b32_e32 v4, v35
	v_or_b32_e32 v8, 0x80000000, v35
	v_cmp_gt_i32_e64 s[0:1], 0, v35
	v_cmp_gt_i32_e32 vcc, 0, v34
	v_and_b32_e32 v43, 0x7fffff80, v159
	v_cndmask_b32_e64 v4, v8, v4, s[0:1]
	v_and_b32_e32 v4, 0xffffff00, v4
	v_or_b32_e32 v26, 0xf7, v4
	v_not_b32_e32 v4, v34
	v_or_b32_e32 v8, 0x80000000, v34
	v_cndmask_b32_e32 v4, v8, v4, vcc
	v_and_b32_e32 v4, 0xffffff00, v4
	v_pk_add_f32 v[34:35], v[2:3], v[28:29] op_sel_hi:[0,1]
	v_or_b32_e32 v27, 0xf6, v4
	v_not_b32_e32 v4, v35
	v_or_b32_e32 v8, 0x80000000, v35
	v_cmp_gt_i32_e64 s[0:1], 0, v35
	v_cmp_gt_i32_e32 vcc, 0, v34
	v_and_b32_e32 v45, 0x7fffff80, v157
	v_cndmask_b32_e64 v4, v8, v4, s[0:1]
	v_and_b32_e32 v4, 0xffffff00, v4
	v_or_b32_e32 v28, 0xf5, v4
	v_not_b32_e32 v4, v34
	v_or_b32_e32 v8, 0x80000000, v34
	v_cndmask_b32_e32 v4, v8, v4, vcc
	v_and_b32_e32 v4, 0xffffff00, v4
	v_pk_add_f32 v[34:35], v[2:3], v[30:31] op_sel_hi:[0,1]
	v_or_b32_e32 v29, 0xf4, v4
	v_not_b32_e32 v4, v35
	v_or_b32_e32 v8, 0x80000000, v35
	v_cmp_gt_i32_e64 s[0:1], 0, v35
	v_cmp_gt_i32_e32 vcc, 0, v34
	v_and_b32_e32 v69, 0x7fffff80, v20
	v_cndmask_b32_e64 v4, v8, v4, s[0:1]
	v_and_b32_e32 v4, 0xffffff00, v4
	v_or_b32_e32 v30, 0xf3, v4
	v_not_b32_e32 v4, v34
	v_or_b32_e32 v8, 0x80000000, v34
	v_cndmask_b32_e32 v4, v8, v4, vcc
	v_and_b32_e32 v4, 0xffffff00, v4
	v_pk_add_f32 v[34:35], v[2:3], v[32:33] op_sel_hi:[0,1]
	v_or_b32_e32 v31, 0xf2, v4
	v_not_b32_e32 v4, v35
	v_or_b32_e32 v8, 0x80000000, v35
	v_cmp_gt_i32_e64 s[0:1], 0, v35
	v_cmp_gt_i32_e32 vcc, 0, v34
	v_and_b32_e32 v35, 0x7fffff80, v182
	v_cndmask_b32_e64 v4, v8, v4, s[0:1]
	v_and_b32_e32 v4, 0xffffff00, v4
	v_or_b32_e32 v32, 0xf1, v4
	v_not_b32_e32 v4, v34
	v_or_b32_e32 v8, 0x80000000, v34
	v_cndmask_b32_e32 v4, v8, v4, vcc
	v_and_b32_e32 v4, 0xffffff00, v4
	v_or_b32_e32 v33, 0xf0, v4
	v_and_b32_e32 v4, 0xffffff80, v16
	v_cmp_gt_i32_e32 vcc, 0, v16
	v_and_b32_e32 v34, 0x7fffff80, v16
	v_xor_b32_e32 v37, -1, v4
	v_and_b32_e32 v8, 0xffffff80, v182
	v_cndmask_b32_e32 v37, v37, v34, vcc
	v_xor_b32_e32 v4, -1, v8
	v_add_f32_e32 v8, v37, v2
	v_cmp_gt_i32_e64 s[0:1], 0, v182
	v_cmp_gt_i32_e32 vcc, 0, v8
	v_not_b32_e32 v34, v8
	v_or_b32_e32 v8, 0x80000000, v8
	v_cndmask_b32_e64 v4, v4, v35, s[0:1]
	v_cndmask_b32_e32 v8, v8, v34, vcc
	v_and_b32_e32 v8, 0xffffff00, v8
	v_pk_add_f32 v[38:39], v[4:5], v[6:7] op_sel_hi:[0,1]
	v_or_b32_e32 v34, 0xf9, v8
	v_not_b32_e32 v6, v39
	v_or_b32_e32 v8, 0x80000000, v39
	v_cmp_gt_i32_e64 s[0:1], 0, v39
	v_cmp_gt_i32_e32 vcc, 0, v38
	v_pk_add_f32 v[36:37], v[4:5], v[36:37] op_sel_hi:[0,1]
	v_cndmask_b32_e64 v6, v8, v6, s[0:1]
	v_and_b32_e32 v6, 0xffffff00, v6
	v_or_b32_e32 v47, 0xeb, v6
	v_not_b32_e32 v6, v38
	v_or_b32_e32 v8, 0x80000000, v38
	v_cndmask_b32_e32 v6, v8, v6, vcc
	v_and_b32_e32 v6, 0xffffff00, v6
	v_or_b32_e32 v48, 0xea, v6
	v_not_b32_e32 v6, v37
	v_or_b32_e32 v8, 0x80000000, v37
	v_cmp_gt_i32_e64 s[0:1], 0, v37
	v_cmp_gt_i32_e32 vcc, 0, v36
	v_and_b32_e32 v35, 0x7fffff80, v19
	v_cndmask_b32_e64 v6, v8, v6, s[0:1]
	v_and_b32_e32 v6, 0xffffff00, v6
	v_or_b32_e32 v49, 0xe9, v6
	v_not_b32_e32 v6, v36
	v_or_b32_e32 v8, 0x80000000, v36
	v_cndmask_b32_e32 v6, v8, v6, vcc
; DI unsigned f2ord(float f) { const unsigned u = __float_as_uint(f); return (u & 0x80000000u) ? ~u : (u | 0x80000000u); }
; DI float ord2f(unsigned o) { const unsigned u = (o & 0x80000000u) ? (o & 0x7fffffffu) : ~o; return __uint_as_float(u); }
; DI void peer_topk_phase(const bf16_t* __restrict__ qpk, const bf16_t* __restrict__ subk, int* __restrict__ eidx, float* __restrict__ gout) {
;     ...
; #pragma unroll
;         for (int a = 0; a < 16; ++a)
; #pragma unroll
;             for (int b = 0; b < 16 / (a + 1); ++b) {
;                 const float cv = ord2f(top[0][a] & ~127u) + ord2f(top[1][b] & ~127u);
;                 ck[combo_row_start(a) + b] = (f2ord(cv) & ~255u) | (unsigned)(((15 - a) << 4) | (15 - b));
;             }
	v_and_b32_e32 v6, 0xffffff00, v6
	v_or_b32_e32 v50, 0xe8, v6
	v_and_b32_e32 v6, 0xffffff80, v19
	v_and_b32_e32 v8, 0xffffff80, v169
	v_cmp_gt_i32_e64 s[0:1], 0, v19
	v_xor_b32_e32 v6, -1, v6
	v_cmp_gt_i32_e32 vcc, 0, v169
	v_and_b32_e32 v36, 0x7fffff80, v169
	v_xor_b32_e32 v8, -1, v8
	v_cndmask_b32_e64 v37, v6, v35, s[0:1]
	v_cndmask_b32_e32 v6, v8, v36, vcc
	v_add_f32_e32 v8, v37, v2
	v_cmp_gt_i32_e32 vcc, 0, v8
	v_not_b32_e32 v35, v8
	v_or_b32_e32 v8, 0x80000000, v8
	v_cndmask_b32_e32 v8, v8, v35, vcc
	v_and_b32_e32 v8, 0xffffff00, v8
	v_or_b32_e32 v35, 0xfc, v8
	v_add_f32_e32 v8, v37, v4
	v_not_b32_e32 v36, v8
	v_or_b32_e32 v38, 0x80000000, v8
	v_cmp_gt_i32_e32 vcc, 0, v8
	v_and_b32_e32 v70, 0x7fffff80, v74
	s_nop 0
	v_cndmask_b32_e32 v8, v38, v36, vcc
	v_mov_b32_e32 v36, v7
	v_and_b32_e32 v8, 0xffffff00, v8
	v_pk_add_f32 v[38:39], v[6:7], v[36:37] op_sel_hi:[0,1]
	v_or_b32_e32 v51, 0xec, v8
	v_not_b32_e32 v7, v39
	v_or_b32_e32 v8, 0x80000000, v39
	v_cmp_gt_i32_e64 s[0:1], 0, v39
	v_cmp_gt_i32_e32 vcc, 0, v38
	v_and_b32_e32 v36, 0x7fffff80, v21
	v_cndmask_b32_e64 v7, v8, v7, s[0:1]
	v_and_b32_e32 v7, 0xffffff00, v7
	v_or_b32_e32 v52, 0xdc, v7
	v_not_b32_e32 v7, v38
	v_or_b32_e32 v8, 0x80000000, v38
	v_cndmask_b32_e32 v7, v8, v7, vcc
	v_and_b32_e32 v7, 0xffffff00, v7
	v_or_b32_e32 v53, 0xdb, v7
	v_and_b32_e32 v7, 0xffffff80, v21
	v_cmp_gt_i32_e64 s[0:1], 0, v21
	v_xor_b32_e32 v7, -1, v7
	v_and_b32_e32 v8, 0xffffff80, v167
	v_cndmask_b32_e64 v39, v7, v36, s[0:1]
	v_cmp_gt_i32_e32 vcc, 0, v167
	v_and_b32_e32 v38, 0x7fffff80, v167
	v_xor_b32_e32 v8, -1, v8
	v_add_f32_e32 v7, v39, v2
	v_cndmask_b32_e32 v8, v8, v38, vcc
	v_cmp_gt_i32_e32 vcc, 0, v7
	v_not_b32_e32 v36, v7
	v_or_b32_e32 v7, 0x80000000, v7
	v_cndmask_b32_e32 v7, v7, v36, vcc
	v_add_f32_e32 v36, v39, v4
	v_not_b32_e32 v38, v36
	v_or_b32_e32 v40, 0x80000000, v36
	v_cmp_gt_i32_e32 vcc, 0, v36
	v_and_b32_e32 v7, 0xffffff00, v7
	v_or_b32_e32 v7, 0xfd, v7
	v_cndmask_b32_e32 v36, v40, v38, vcc
	v_and_b32_e32 v36, 0xffffff00, v36
	v_or_b32_e32 v54, 0xed, v36
	v_add_f32_e32 v36, v39, v6
	v_not_b32_e32 v38, v36
	v_or_b32_e32 v40, 0x80000000, v36
	v_cmp_gt_i32_e32 vcc, 0, v36
	s_nop 1
	v_cndmask_b32_e32 v36, v40, v38, vcc
	v_and_b32_e32 v36, 0xffffff00, v36
	v_mov_b32_e32 v38, v37
	v_or_b32_e32 v55, 0xdd, v36
	v_pk_add_f32 v[36:37], v[8:9], v[38:39] op_sel_hi:[0,1]
	v_not_b32_e32 v38, v37
	v_or_b32_e32 v40, 0x80000000, v37
	v_cmp_gt_i32_e64 s[0:1], 0, v37
	v_cmp_gt_i32_e32 vcc, 0, v36
	s_nop 0
	v_cndmask_b32_e64 v37, v40, v38, s[0:1]
	v_not_b32_e32 v38, v36
	v_or_b32_e32 v36, 0x80000000, v36
	v_cndmask_b32_e32 v36, v36, v38, vcc
	v_and_b32_e32 v36, 0xffffff00, v36
	v_or_b32_e32 v56, 0xcc, v36
	v_cmp_gt_i32_e32 vcc, 0, v166
	v_and_b32_e32 v36, 0x7fffff80, v166
	v_bitop3_b32 v38, v166, s5, v166 bitop3:0xcf
	v_cndmask_b32_e32 v57, v38, v36, vcc
	v_add_f32_e32 v36, v39, v57
	v_not_b32_e32 v38, v36
	v_or_b32_e32 v39, 0x80000000, v36
	v_cmp_gt_i32_e32 vcc, 0, v36
	v_cmp_gt_i32_e64 s[0:1], 0, v164
	v_and_b32_e32 v40, 0x7fffff80, v164
	v_cndmask_b32_e32 v36, v39, v38, vcc
	v_and_b32_e32 v36, 0xffffff00, v36
	v_or_b32_e32 v58, 0xbd, v36
	v_cmp_gt_i32_e32 vcc, 0, v165
	v_and_b32_e32 v36, 0x7fffff80, v165
	v_bitop3_b32 v38, v165, s5, v165 bitop3:0xcf
	v_cndmask_b32_e32 v59, v38, v36, vcc
	v_and_b32_e32 v36, 0xffffff80, v22
	v_and_b32_e32 v38, 0xffffff80, v164
	v_cmp_gt_i32_e32 vcc, 0, v22
	v_and_b32_e32 v39, 0x7fffff80, v22
	v_xor_b32_e32 v36, -1, v36
	v_xor_b32_e32 v38, -1, v38
	v_cndmask_b32_e64 v60, v38, v40, s[0:1]
	v_cndmask_b32_e32 v38, v36, v39, vcc
	v_add_f32_e32 v36, v38, v2
	v_cmp_gt_i32_e32 vcc, 0, v36
	v_not_b32_e32 v39, v36
	v_or_b32_e32 v36, 0x80000000, v36
	v_cndmask_b32_e32 v36, v36, v39, vcc
	v_add_f32_e32 v39, v38, v4
	v_not_b32_e32 v40, v39
	v_or_b32_e32 v41, 0x80000000, v39
	v_cmp_gt_i32_e32 vcc, 0, v39
	v_cmp_gt_i32_e64 s[0:1], 0, v162
	v_and_b32_e32 v37, 0xffffff00, v37
	v_cndmask_b32_e32 v39, v41, v40, vcc
	v_and_b32_e32 v39, 0xffffff00, v39
	v_or_b32_e32 v61, 0xee, v39
	v_add_f32_e32 v39, v38, v6
	v_not_b32_e32 v40, v39
	v_or_b32_e32 v41, 0x80000000, v39
	v_cmp_gt_i32_e32 vcc, 0, v39
	v_or_b32_e32 v37, 0xcd, v37
	v_and_b32_e32 v36, 0xffffff00, v36
	v_cndmask_b32_e32 v39, v41, v40, vcc
	v_and_b32_e32 v39, 0xffffff00, v39
	v_or_b32_e32 v62, 0xde, v39
	v_add_f32_e32 v39, v38, v8
	v_not_b32_e32 v40, v39
	v_or_b32_e32 v41, 0x80000000, v39
	v_cmp_gt_i32_e32 vcc, 0, v39
	v_or_b32_e32 v36, 0xfe, v36
	s_nop 0
	v_cndmask_b32_e32 v39, v41, v40, vcc
	v_and_b32_e32 v39, 0xffffff00, v39
	v_or_b32_e32 v63, 0xce, v39
	v_add_f32_e32 v39, v38, v57
	v_not_b32_e32 v40, v39
	v_or_b32_e32 v41, 0x80000000, v39
	v_cmp_gt_i32_e32 vcc, 0, v39
	s_nop 1
	v_cndmask_b32_e32 v39, v41, v40, vcc
	v_and_b32_e32 v39, 0xffffff00, v39
	v_or_b32_e32 v64, 0xbe, v39
	v_add_f32_e32 v39, v38, v59
	v_not_b32_e32 v40, v39
	v_or_b32_e32 v41, 0x80000000, v39
	v_cmp_gt_i32_e32 vcc, 0, v39
	s_nop 1
	v_cndmask_b32_e32 v39, v41, v40, vcc
	v_and_b32_e32 v39, 0xffffff00, v39
	v_or_b32_e32 v65, 0xae, v39
	v_add_f32_e32 v39, v38, v60
	v_not_b32_e32 v40, v39
	v_or_b32_e32 v41, 0x80000000, v39
	v_cmp_gt_i32_e32 vcc, 0, v39
	s_nop 1
	v_cndmask_b32_e32 v39, v41, v40, vcc
	v_and_b32_e32 v39, 0xffffff00, v39
	v_or_b32_e32 v66, 0x9e, v39
	v_cmp_gt_i32_e32 vcc, 0, v163
	v_and_b32_e32 v39, 0x7fffff80, v163
	v_bitop3_b32 v40, v163, s5, v163 bitop3:0xcf
	v_cndmask_b32_e32 v67, v40, v39, vcc
	v_add_f32_e32 v38, v38, v67
	v_not_b32_e32 v39, v38
	v_or_b32_e32 v40, 0x80000000, v38
	v_cmp_gt_i32_e32 vcc, 0, v38
	v_and_b32_e32 v41, 0x7fffff80, v161
	s_nop 0
	v_cndmask_b32_e32 v38, v40, v39, vcc
	v_and_b32_e32 v38, 0xffffff00, v38
; DI unsigned f2ord(float f) { const unsigned u = __float_as_uint(f); return (u & 0x80000000u) ? ~u : (u | 0x80000000u); }
; DI float ord2f(unsigned o) { const unsigned u = (o & 0x80000000u) ? (o & 0x7fffffffu) : ~o; return __uint_as_float(u); }
; DI void peer_topk_phase(const bf16_t* __restrict__ qpk, const bf16_t* __restrict__ subk, int* __restrict__ eidx, float* __restrict__ gout) {
;     ...
; #pragma unroll
;         for (int a = 0; a < 16; ++a)
; #pragma unroll
;             for (int b = 0; b < 16 / (a + 1); ++b) {
;                 const float cv = ord2f(top[0][a] & ~127u) + ord2f(top[1][b] & ~127u);
;                 ck[combo_row_start(a) + b] = (f2ord(cv) & ~255u) | (unsigned)(((15 - a) << 4) | (15 - b));
;             }
;         unsigned c0[16], c1[16], c2[16], c3[16];
; #pragma unroll
;         for (int i = 0; i < 16; ++i) { c0[i] = ck[i]; c1[i] = ck[16 + i]; c2[i] = ck[32 + i]; c3[i] = (i < 2) ? ck[48 + i] : 0u; }
; #pragma unroll
;         for (int n = 0; n < 63; ++n) { cex(c1[SORT16[n][0]], c1[SORT16[n][1]]); cex(c2[SORT16[n][0]], c2[SORT16[n][1]]); }
;         merge_top16(c0, c1); merge_top16(c2, c3); merge_top16(c0, c2);
	v_or_b32_e32 v68, 0x8e, v38
	v_and_b32_e32 v38, 0xffffff80, v162
	v_and_b32_e32 v39, 0xffffff80, v161
	v_cmp_gt_i32_e32 vcc, 0, v161
	v_and_b32_e32 v40, 0x7fffff80, v162
	v_xor_b32_e32 v38, -1, v38
	v_xor_b32_e32 v42, -1, v39
	v_cndmask_b32_e64 v39, v38, v40, s[0:1]
	v_cndmask_b32_e32 v38, v42, v41, vcc
	v_and_b32_e32 v40, 0xffffff80, v160
	v_and_b32_e32 v41, 0xffffff80, v159
	v_cmp_gt_i32_e32 vcc, 0, v159
	v_cmp_gt_i32_e64 s[0:1], 0, v160
	v_and_b32_e32 v42, 0x7fffff80, v160
	v_xor_b32_e32 v40, -1, v40
	v_xor_b32_e32 v44, -1, v41
	v_cndmask_b32_e64 v41, v40, v42, s[0:1]
	v_cndmask_b32_e32 v40, v44, v43, vcc
	v_and_b32_e32 v42, 0xffffff80, v158
	v_and_b32_e32 v43, 0xffffff80, v157
	v_cmp_gt_i32_e32 vcc, 0, v157
	v_cmp_gt_i32_e64 s[0:1], 0, v158
	v_and_b32_e32 v44, 0x7fffff80, v158
	v_xor_b32_e32 v42, -1, v42
	v_xor_b32_e32 v46, -1, v43
	v_cndmask_b32_e64 v43, v42, v44, s[0:1]
	v_cndmask_b32_e32 v42, v46, v45, vcc
	v_cmp_gt_i32_e32 vcc, 0, v79
	v_and_b32_e32 v44, 0x7fffff80, v79
	v_bitop3_b32 v45, v79, s5, v79 bitop3:0xcf
	v_cndmask_b32_e32 v45, v45, v44, vcc
	v_and_b32_e32 v44, 0xffffff80, v20
	v_and_b32_e32 v46, 0xffffff80, v74
	v_cmp_gt_i32_e32 vcc, 0, v20
	v_xor_b32_e32 v71, -1, v44
	v_xor_b32_e32 v44, -1, v46
	v_cndmask_b32_e32 v46, v71, v69, vcc
	v_cmp_gt_i32_e64 s[0:1], 0, v74
	v_add_f32_e32 v2, v46, v2
	v_not_b32_e32 v69, v2
	v_cndmask_b32_e64 v44, v44, v70, s[0:1]
	v_or_b32_e32 v70, 0x80000000, v2
	v_cmp_gt_i32_e32 vcc, 0, v2
	v_add_f32_e32 v4, v46, v4
	v_add_f32_e32 v6, v46, v6
	v_cndmask_b32_e32 v2, v70, v69, vcc
	v_not_b32_e32 v69, v4
	v_or_b32_e32 v70, 0x80000000, v4
	v_cmp_gt_i32_e32 vcc, 0, v4
	v_add_f32_e32 v8, v46, v8
	v_add_f32_e32 v57, v46, v57
	v_cndmask_b32_e32 v4, v70, v69, vcc
	v_not_b32_e32 v69, v6
	v_or_b32_e32 v70, 0x80000000, v6
	v_cmp_gt_i32_e32 vcc, 0, v6
	v_add_f32_e32 v59, v46, v59
	v_add_f32_e32 v60, v46, v60
	v_cndmask_b32_e32 v6, v70, v69, vcc
	v_not_b32_e32 v69, v8
	v_or_b32_e32 v70, 0x80000000, v8
	v_cmp_gt_i32_e32 vcc, 0, v8
	v_add_f32_e32 v67, v46, v67
	v_pk_add_f32 v[38:39], v[46:47], v[38:39] op_sel_hi:[0,1]
	v_cndmask_b32_e32 v8, v70, v69, vcc
	v_not_b32_e32 v69, v57
	v_or_b32_e32 v70, 0x80000000, v57
	v_cmp_gt_i32_e32 vcc, 0, v57
	v_cmp_gt_i32_e64 s[0:1], 0, v39
	v_and_b32_e32 v4, 0xffffff00, v4
	v_cndmask_b32_e32 v57, v70, v69, vcc
	v_not_b32_e32 v69, v59
	v_or_b32_e32 v70, 0x80000000, v59
	v_cmp_gt_i32_e32 vcc, 0, v59
	v_and_b32_e32 v57, 0xffffff00, v57
	v_or_b32_e32 v4, 0xef, v4
	v_cndmask_b32_e32 v59, v70, v69, vcc
	v_not_b32_e32 v69, v60
	v_or_b32_e32 v70, 0x80000000, v60
	v_cmp_gt_i32_e32 vcc, 0, v60
	v_or_b32_e32 v57, 0xbf, v57
	v_and_b32_e32 v59, 0xffffff00, v59
	v_cndmask_b32_e32 v60, v70, v69, vcc
	v_not_b32_e32 v69, v67
	v_or_b32_e32 v70, 0x80000000, v67
	v_cmp_gt_i32_e32 vcc, 0, v67
	v_and_b32_e32 v60, 0xffffff00, v60
	v_or_b32_e32 v59, 0xaf, v59
	v_cndmask_b32_e32 v67, v70, v69, vcc
	v_not_b32_e32 v69, v39
	v_or_b32_e32 v70, 0x80000000, v39
	v_cndmask_b32_e64 v39, v70, v69, s[0:1]
	v_and_b32_e32 v39, 0xffffff00, v39
	v_cmp_gt_i32_e32 vcc, 0, v38
	v_or_b32_e32 v69, 0x7f, v39
	v_not_b32_e32 v39, v38
	v_or_b32_e32 v38, 0x80000000, v38
	v_cndmask_b32_e32 v38, v38, v39, vcc
	v_and_b32_e32 v38, 0xffffff00, v38
	v_or_b32_e32 v70, 0x6f, v38
	v_pk_add_f32 v[38:39], v[46:47], v[40:41] op_sel_hi:[0,1]
	v_not_b32_e32 v40, v39
	v_or_b32_e32 v41, 0x80000000, v39
	v_cmp_gt_i32_e64 s[0:1], 0, v39
	v_cmp_gt_i32_e32 vcc, 0, v38
	v_or_b32_e32 v60, 0x9f, v60
	v_cndmask_b32_e64 v39, v41, v40, s[0:1]
	v_and_b32_e32 v39, 0xffffff00, v39
	v_or_b32_e32 v40, 0x5f, v39
	v_not_b32_e32 v39, v38
	v_or_b32_e32 v38, 0x80000000, v38
	v_cndmask_b32_e32 v38, v38, v39, vcc
	v_and_b32_e32 v38, 0xffffff00, v38
	v_or_b32_e32 v41, 0x4f, v38
	v_pk_add_f32 v[38:39], v[46:47], v[42:43] op_sel_hi:[0,1]
	v_not_b32_e32 v42, v39
	v_or_b32_e32 v43, 0x80000000, v39
	v_cmp_gt_i32_e64 s[0:1], 0, v39
	v_cmp_gt_i32_e32 vcc, 0, v38
	v_and_b32_e32 v6, 0xffffff00, v6
	v_cndmask_b32_e64 v39, v43, v42, s[0:1]
	v_and_or_b32 v42, v39, s54, 63
	v_not_b32_e32 v39, v38
	v_or_b32_e32 v38, 0x80000000, v38
	v_cndmask_b32_e32 v38, v38, v39, vcc
	v_and_or_b32 v43, v38, s54, 47
	v_pk_add_f32 v[38:39], v[46:47], v[44:45] op_sel_hi:[0,1]
	v_not_b32_e32 v44, v39
	v_or_b32_e32 v45, 0x80000000, v39
	v_cmp_gt_i32_e64 s[0:1], 0, v39
	v_cmp_gt_i32_e32 vcc, 0, v38
	v_min_u32_e32 v46, v56, v57
	v_cndmask_b32_e64 v39, v45, v44, s[0:1]
	v_not_b32_e32 v44, v38
	v_or_b32_e32 v38, 0x80000000, v38
	v_cndmask_b32_e32 v38, v38, v44, vcc
	v_max_u32_e32 v44, v4, v61
	v_min_u32_e32 v4, v4, v61
	v_max_u32_e32 v45, v56, v57
	v_max_u32_e32 v56, v54, v51
	v_min_u32_e32 v51, v54, v51
	v_max_u32_e32 v54, v64, v58
	v_min_u32_e32 v57, v64, v58
	v_max_u32_e32 v58, v44, v56
	v_min_u32_e32 v44, v44, v56
	v_max_u32_e32 v56, v45, v54
	v_min_u32_e32 v45, v45, v54
	v_max_u32_e32 v54, v4, v51
	v_min_u32_e32 v4, v4, v51
	v_max_u32_e32 v51, v46, v57
	v_min_u32_e32 v46, v46, v57
	v_max_u32_e32 v57, v54, v44
	v_min_u32_e32 v44, v54, v44
	v_max_u32_e32 v54, v51, v45
	v_min_u32_e32 v45, v51, v45
	v_max_u32_e32 v51, v47, v48
	v_min_u32_e32 v47, v47, v48
	v_max_u32_e32 v48, v59, v65
	v_min_u32_e32 v59, v59, v65
	v_max_u32_e32 v61, v49, v50
	v_min_u32_e32 v49, v49, v50
	v_max_u32_e32 v50, v60, v66
	v_min_u32_e32 v60, v60, v66
	v_max_u32_e32 v64, v51, v61
	v_min_u32_e32 v51, v51, v61
	v_max_u32_e32 v61, v48, v50
	v_min_u32_e32 v48, v48, v50
	v_max_u32_e32 v50, v47, v49
	v_min_u32_e32 v47, v47, v49
	v_max_u32_e32 v49, v59, v60
	v_min_u32_e32 v59, v59, v60
	v_max_u32_e32 v60, v50, v51
	v_min_u32_e32 v50, v50, v51
	v_max_u32_e32 v51, v49, v48
	v_min_u32_e32 v48, v49, v48
	v_max_u32_e32 v49, v58, v64
; DI void peer_topk_phase(const bf16_t* __restrict__ qpk, const bf16_t* __restrict__ subk, int* __restrict__ eidx, float* __restrict__ gout) {
;     ...
;         for (int i = 0; i < 16; ++i) { c0[i] = ck[i]; c1[i] = ck[16 + i]; c2[i] = ck[32 + i]; c3[i] = (i < 2) ? ck[48 + i] : 0u; }
; #pragma unroll
;         for (int n = 0; n < 63; ++n) { cex(c1[SORT16[n][0]], c1[SORT16[n][1]]); cex(c2[SORT16[n][0]], c2[SORT16[n][1]]); }
;         merge_top16(c0, c1); merge_top16(c2, c3); merge_top16(c0, c2);
	v_min_u32_e32 v58, v58, v64
	v_max_u32_e32 v64, v56, v61
	v_min_u32_e32 v56, v56, v61
	v_max_u32_e32 v61, v44, v50
	v_min_u32_e32 v44, v44, v50
	v_max_u32_e32 v50, v45, v48
	v_and_b32_e32 v67, 0xffffff00, v67
	v_min_u32_e32 v45, v45, v48
	v_max_u32_e32 v48, v61, v58
	v_min_u32_e32 v58, v61, v58
	v_max_u32_e32 v61, v50, v56
	v_min_u32_e32 v50, v50, v56
	v_max_u32_e32 v56, v57, v60
	v_min_u32_e32 v57, v57, v60
	v_max_u32_e32 v60, v54, v51
	v_min_u32_e32 v51, v54, v51
	v_max_u32_e32 v54, v4, v47
	v_min_u32_e32 v4, v4, v47
	v_max_u32_e32 v47, v46, v59
	v_or_b32_e32 v6, 0xdf, v6
	v_or_b32_e32 v67, 0x8f, v67
	v_min_u32_e32 v46, v46, v59
	v_max_u32_e32 v59, v54, v57
	v_min_u32_e32 v54, v54, v57
	v_max_u32_e32 v57, v47, v51
	v_min_u32_e32 v47, v47, v51
	v_and_b32_e32 v8, 0xffffff00, v8
	v_max_u32_e32 v51, v56, v48
	v_min_u32_e32 v48, v56, v48
	v_max_u32_e32 v56, v60, v61
	v_min_u32_e32 v60, v60, v61
	v_max_u32_e32 v61, v59, v58
	v_min_u32_e32 v58, v59, v58
	v_max_u32_e32 v59, v57, v50
	v_min_u32_e32 v50, v57, v50
	v_max_u32_e32 v57, v54, v44
	v_min_u32_e32 v44, v54, v44
	v_max_u32_e32 v54, v47, v45
	v_min_u32_e32 v45, v47, v45
	v_max_u32_e32 v47, v6, v62
	v_min_u32_e32 v6, v6, v62
	v_max_u32_e32 v62, v67, v68
	v_min_u32_e32 v65, v67, v68
	v_max_u32_e32 v66, v55, v52
	v_min_u32_e32 v52, v55, v52
	v_max_u32_e32 v55, v69, v70
	v_min_u32_e32 v67, v69, v70
	v_or_b32_e32 v8, 0xcf, v8
	v_max_u32_e32 v68, v47, v66
	v_min_u32_e32 v47, v47, v66
	v_max_u32_e32 v66, v62, v55
	v_min_u32_e32 v55, v62, v55
	v_max_u32_e32 v62, v6, v52
	v_min_u32_e32 v6, v6, v52
	v_max_u32_e32 v52, v65, v67
	v_min_u32_e32 v65, v65, v67
	v_max_u32_e32 v67, v62, v47
	v_min_u32_e32 v47, v62, v47
	v_max_u32_e32 v62, v52, v55
	v_min_u32_e32 v52, v52, v55
	v_max_u32_e32 v55, v53, v8
	v_min_u32_e32 v8, v53, v8
	v_max_u32_e32 v53, v40, v41
	v_min_u32_e32 v40, v40, v41
	v_max_u32_e32 v41, v63, v37
	v_min_u32_e32 v37, v63, v37
	v_max_u32_e32 v63, v42, v43
	v_min_u32_e32 v42, v42, v43
	v_max_u32_e32 v43, v55, v41
	v_min_u32_e32 v41, v55, v41
	v_max_u32_e32 v55, v53, v63
	v_min_u32_e32 v53, v53, v63
	v_max_u32_e32 v63, v8, v37
	v_min_u32_e32 v8, v8, v37
	v_max_u32_e32 v37, v40, v42
	v_min_u32_e32 v40, v40, v42
	v_max_u32_e32 v42, v63, v41
	v_min_u32_e32 v41, v63, v41
	v_max_u32_e32 v63, v37, v53
	v_min_u32_e32 v37, v37, v53
	v_max_u32_e32 v53, v68, v43
	v_min_u32_e32 v43, v68, v43
	v_max_u32_e32 v68, v66, v55
	v_min_u32_e32 v55, v66, v55
	v_max_u32_e32 v66, v47, v41
	v_min_u32_e32 v41, v47, v41
	v_max_u32_e32 v47, v52, v37
	v_min_u32_e32 v37, v52, v37
	v_max_u32_e32 v52, v66, v43
	v_min_u32_e32 v43, v66, v43
	v_max_u32_e32 v66, v47, v55
	v_min_u32_e32 v47, v47, v55
	v_max_u32_e32 v55, v67, v42
	v_min_u32_e32 v42, v67, v42
	v_max_u32_e32 v67, v62, v63
	v_min_u32_e32 v62, v62, v63
	v_max_u32_e32 v63, v6, v8
	v_min_u32_e32 v6, v6, v8
	v_max_u32_e32 v8, v65, v40
	v_min_u32_e32 v40, v65, v40
	v_max_u32_e32 v65, v63, v42
	v_min_u32_e32 v42, v63, v42
	v_max_u32_e32 v63, v8, v62
	v_min_u32_e32 v8, v8, v62
	v_max_u32_e32 v62, v55, v52
	v_min_u32_e32 v52, v55, v52
	v_max_u32_e32 v55, v67, v66
	v_min_u32_e32 v66, v67, v66
	v_max_u32_e32 v67, v65, v43
	v_min_u32_e32 v43, v65, v43
	v_max_u32_e32 v65, v63, v47
	v_min_u32_e32 v47, v63, v47
	v_max_u32_e32 v63, v42, v41
	v_min_u32_e32 v41, v42, v41
	v_max_u32_e32 v42, v8, v37
	v_min_u32_e32 v8, v8, v37
	v_min_u32_e32 v37, v49, v53
	v_max_u32_e32 v69, v64, v68
	v_min_u32_e32 v64, v64, v68
	v_max_u32_e32 v68, v58, v43
	v_min_u32_e32 v43, v58, v43
	v_max_u32_e32 v58, v50, v47
	v_min_u32_e32 v47, v50, v47
	v_max_u32_e32 v50, v68, v37
	v_min_u32_e32 v37, v68, v37
	v_max_u32_e32 v68, v58, v64
	v_min_u32_e32 v58, v58, v64
	v_max_u32_e32 v64, v48, v52
	v_min_u32_e32 v48, v48, v52
	v_max_u32_e32 v52, v60, v66
	v_min_u32_e32 v60, v60, v66
	v_max_u32_e32 v66, v44, v41
	v_min_u32_e32 v41, v44, v41
	v_max_u32_e32 v44, v45, v8
	v_min_u32_e32 v8, v45, v8
	v_max_u32_e32 v45, v66, v48
	v_min_u32_e32 v48, v66, v48
	v_max_u32_e32 v66, v44, v60
	v_min_u32_e32 v44, v44, v60
	v_max_u32_e32 v60, v64, v50
	v_min_u32_e32 v50, v64, v50
	v_max_u32_e32 v64, v52, v68
	v_min_u32_e32 v52, v52, v68
	v_max_u32_e32 v68, v45, v37
	v_min_u32_e32 v37, v45, v37
	v_max_u32_e32 v45, v66, v58
	v_min_u32_e32 v58, v66, v58
	v_max_u32_e32 v66, v48, v43
	v_min_u32_e32 v43, v48, v43
	v_max_u32_e32 v48, v44, v47
	v_min_u32_e32 v44, v44, v47
	v_max_u32_e32 v47, v51, v62
	v_min_u32_e32 v51, v51, v62
	v_max_u32_e32 v62, v56, v55
	v_min_u32_e32 v55, v56, v55
	v_max_u32_e32 v56, v57, v63
	v_min_u32_e32 v57, v57, v63
	v_max_u32_e32 v63, v54, v42
	v_min_u32_e32 v42, v54, v42
	v_max_u32_e32 v54, v56, v51
	v_min_u32_e32 v51, v56, v51
	v_max_u32_e32 v56, v63, v55
	v_min_u32_e32 v55, v63, v55
	v_max_u32_e32 v63, v61, v67
	v_min_u32_e32 v61, v61, v67
	v_max_u32_e32 v67, v59, v65
	v_min_u32_e32 v59, v59, v65
	v_max_u32_e32 v65, v4, v6
	v_min_u32_e32 v4, v4, v6
	v_max_u32_e32 v6, v46, v40
	v_min_u32_e32 v40, v46, v40
	v_max_u32_e32 v46, v65, v61
	v_min_u32_e32 v61, v65, v61
	v_max_u32_e32 v65, v6, v59
	v_min_u32_e32 v6, v6, v59
	v_max_u32_e32 v59, v63, v54
	v_min_u32_e32 v54, v63, v54
	v_max_u32_e32 v63, v67, v56
	v_min_u32_e32 v56, v67, v56
	v_max_u32_e32 v67, v46, v51
	v_min_u32_e32 v46, v46, v51
	v_max_u32_e32 v51, v65, v55
	v_min_u32_e32 v55, v65, v55
	v_max_u32_e32 v65, v61, v57
	v_min_u32_e32 v57, v61, v57
	v_max_u32_e32 v61, v6, v42
	v_min_u32_e32 v6, v6, v42
	v_or_b32_e32 v2, 0xff, v2
	v_and_or_b32 v39, v39, s54, 31
	v_and_or_b32 v38, v38, s54, 15
	v_min_u32_e32 v42, v47, v60
	v_max_u32_e32 v70, v62, v64
	v_min_u32_e32 v62, v62, v64
	v_min_u32_e32 v64, v59, v50
	v_max_u32_e32 v71, v63, v52
	v_min_u32_e32 v52, v63, v52
; DI void merge_top16(unsigned (&A)[16], const unsigned (&B)[16]) {
; #pragma unroll
;     for (int i = 0; i < 16; ++i) A[i] = max(A[i], B[15 - i]);
; #pragma unroll
;     for (int n = 0; n < 32; ++n) cex(A[BMERGE16[n][0]], A[BMERGE16[n][1]]);
; }
; DI void peer_topk_phase(const bf16_t* __restrict__ qpk, const bf16_t* __restrict__ subk, int* __restrict__ eidx, float* __restrict__ gout) {
;     ...
;         merge_top16(c0, c1); merge_top16(c2, c3); merge_top16(c0, c2);
;         float sv[16]; int se[16];
; #pragma unroll
;         for (int rd = 0; rd < 16; ++rd) {
;             const unsigned m = c0[rd];
;             const int asel = 15 - (int)((m >> 4) & 15u), bsel = 15 - (int)(m & 15u);
;             unsigned ka = top[0][0], kb = top[1][0];
; #pragma unroll
;             for (int i = 1; i < 16; ++i) { ka = (asel == i) ? top[0][i] : ka; kb = (bsel == i) ? top[1][i] : kb; }
	v_min_u32_e32 v63, v54, v68
	v_max_u32_e32 v72, v56, v45
	v_min_u32_e32 v45, v56, v45
	v_min_u32_e32 v56, v67, v37
	v_max_u32_e32 v73, v51, v58
	v_min_u32_e32 v51, v51, v58
	v_min_u32_e32 v58, v46, v66
	v_max_u32_e32 v82, v55, v48
	v_min_u32_e32 v48, v55, v48
	v_min_u32_e32 v55, v65, v43
	v_max_u32_e32 v83, v61, v44
	v_min_u32_e32 v44, v61, v44
	v_min_u32_e32 v61, v57, v41
	v_max_u32_e32 v183, v6, v8
	v_min_u32_e32 v6, v6, v8
	v_max_u32_e32 v2, v2, v4
	v_max_u32_e32 v4, v36, v61
	v_max3_u32 v7, v7, v57, v41
	v_max_u32_e32 v8, v35, v55
	v_max3_u32 v23, v23, v65, v43
	v_max_u32_e32 v24, v24, v58
	v_max3_u32 v34, v34, v46, v66
	v_max_u32_e32 v25, v25, v56
	v_max3_u32 v26, v26, v67, v37
	v_max_u32_e32 v27, v27, v63
	v_max3_u32 v28, v28, v54, v68
	v_max_u32_e32 v29, v29, v64
	v_max3_u32 v30, v30, v59, v50
	v_max_u32_e32 v31, v31, v42
	v_max3_u32 v32, v32, v47, v60
	v_max3_u32 v33, v33, v49, v53
	v_max_u32_e32 v6, v6, v38
	v_max_u32_e32 v38, v40, v39
	v_max_u32_e32 v35, v2, v26
	v_min_u32_e32 v2, v2, v26
	v_max_u32_e32 v26, v4, v27
	v_min_u32_e32 v4, v4, v27
	v_max_u32_e32 v27, v7, v28
	v_min_u32_e32 v7, v7, v28
	v_max_u32_e32 v28, v8, v29
	v_min_u32_e32 v8, v8, v29
	v_max_u32_e32 v29, v23, v30
	v_min_u32_e32 v23, v23, v30
	v_max_u32_e32 v30, v24, v31
	v_min_u32_e32 v24, v24, v31
	v_max_u32_e32 v31, v34, v32
	v_min_u32_e32 v32, v34, v32
	v_max_u32_e32 v34, v25, v33
	v_min_u32_e32 v25, v25, v33
	v_max_u32_e32 v39, v69, v51
	v_min_u32_e32 v40, v69, v51
	v_max_u32_e32 v49, v70, v82
	v_min_u32_e32 v50, v70, v82
	v_max_u32_e32 v51, v62, v48
	v_min_u32_e32 v48, v62, v48
	v_max_u32_e32 v53, v71, v83
	v_min_u32_e32 v54, v71, v83
	v_max_u32_e32 v55, v52, v44
	v_min_u32_e32 v44, v52, v44
	v_max_u32_e32 v52, v72, v183
	v_min_u32_e32 v56, v72, v183
	v_max_u32_e32 v57, v45, v6
	v_min_u32_e32 v6, v45, v6
	v_max_u32_e32 v45, v73, v38
	v_min_u32_e32 v38, v73, v38
	v_max_u32_e32 v33, v35, v29
	v_min_u32_e32 v29, v35, v29
	v_max_u32_e32 v35, v26, v30
	v_min_u32_e32 v26, v26, v30
	v_max_u32_e32 v30, v27, v31
	v_min_u32_e32 v27, v27, v31
	v_max_u32_e32 v31, v28, v34
	v_min_u32_e32 v28, v28, v34
	v_max_u32_e32 v34, v2, v23
	v_min_u32_e32 v2, v2, v23
	v_max_u32_e32 v23, v4, v24
	v_min_u32_e32 v4, v4, v24
	v_max_u32_e32 v24, v7, v32
	v_min_u32_e32 v7, v7, v32
	v_max_u32_e32 v32, v8, v25
	v_min_u32_e32 v8, v8, v25
	v_max_u32_e32 v58, v39, v55
	v_min_u32_e32 v39, v39, v55
	v_max_u32_e32 v55, v49, v52
	v_min_u32_e32 v49, v49, v52
	v_max_u32_e32 v52, v51, v57
	v_min_u32_e32 v51, v51, v57
	v_max_u32_e32 v57, v53, v45
	v_min_u32_e32 v45, v53, v45
	v_max_u32_e32 v53, v40, v44
	v_min_u32_e32 v40, v40, v44
	v_max_u32_e32 v44, v50, v56
	v_min_u32_e32 v50, v50, v56
	v_max_u32_e32 v56, v48, v6
	v_min_u32_e32 v6, v48, v6
	v_max_u32_e32 v48, v54, v38
	v_min_u32_e32 v38, v54, v38
	v_max_u32_e32 v25, v33, v30
	v_min_u32_e32 v30, v33, v30
	v_max_u32_e32 v33, v35, v31
	v_min_u32_e32 v31, v35, v31
	v_max_u32_e32 v35, v29, v27
	v_min_u32_e32 v27, v29, v27
	v_max_u32_e32 v29, v26, v28
	v_min_u32_e32 v26, v26, v28
	v_max_u32_e32 v28, v34, v24
	v_min_u32_e32 v24, v34, v24
	v_max_u32_e32 v34, v23, v32
	v_min_u32_e32 v23, v23, v32
	v_max_u32_e32 v32, v2, v7
	v_min_u32_e32 v2, v2, v7
	v_max_u32_e32 v7, v4, v8
	v_min_u32_e32 v4, v4, v8
	v_max_u32_e32 v54, v58, v52
	v_min_u32_e32 v52, v58, v52
	v_max_u32_e32 v58, v55, v57
	v_min_u32_e32 v55, v55, v57
	v_max_u32_e32 v57, v39, v51
	v_min_u32_e32 v39, v39, v51
	v_max_u32_e32 v51, v49, v45
	v_min_u32_e32 v45, v49, v45
	v_max_u32_e32 v49, v53, v56
	v_min_u32_e32 v53, v53, v56
	v_max_u32_e32 v56, v44, v48
	v_min_u32_e32 v44, v44, v48
	v_max_u32_e32 v48, v40, v6
	v_min_u32_e32 v6, v40, v6
	v_max_u32_e32 v40, v50, v38
	v_min_u32_e32 v38, v50, v38
	v_min_u32_e32 v8, v25, v33
	v_min_u32_e32 v36, v30, v31
	v_min_u32_e32 v37, v35, v29
	v_min_u32_e32 v41, v27, v26
	v_min_u32_e32 v42, v28, v34
	v_min_u32_e32 v43, v24, v23
	v_min_u32_e32 v46, v32, v7
	v_min_u32_e32 v47, v2, v4
	v_min_u32_e32 v50, v54, v58
	v_min_u32_e32 v59, v52, v55
	v_min_u32_e32 v60, v57, v51
	v_min_u32_e32 v61, v39, v45
	v_min_u32_e32 v62, v49, v56
	v_min_u32_e32 v63, v53, v44
	v_min_u32_e32 v64, v48, v40
	v_min_u32_e32 v65, v6, v38
	v_max3_u32 v25, v25, v33, v65
	v_max3_u32 v6, v8, v6, v38
	v_max3_u32 v8, v30, v31, v64
	v_max3_u32 v30, v36, v48, v40
	v_max3_u32 v29, v35, v29, v63
	v_max3_u32 v31, v37, v53, v44
	v_max3_u32 v26, v27, v26, v62
	v_max3_u32 v27, v41, v49, v56
	v_max3_u32 v28, v28, v34, v61
	v_max3_u32 v33, v42, v39, v45
	v_max3_u32 v23, v24, v23, v60
	v_max3_u32 v24, v43, v57, v51
	v_max3_u32 v7, v32, v7, v59
	v_max3_u32 v32, v46, v52, v55
	v_max3_u32 v2, v2, v4, v50
	v_max3_u32 v4, v47, v54, v58
	v_max_u32_e32 v34, v25, v28
	v_min_u32_e32 v25, v25, v28
	v_max_u32_e32 v28, v6, v33
	v_min_u32_e32 v6, v6, v33
	v_max_u32_e32 v33, v8, v23
	v_min_u32_e32 v8, v8, v23
	v_max_u32_e32 v23, v30, v24
	v_min_u32_e32 v24, v30, v24
	v_max_u32_e32 v30, v29, v7
	v_min_u32_e32 v7, v29, v7
	v_max_u32_e32 v29, v31, v32
	v_min_u32_e32 v31, v31, v32
	v_max_u32_e32 v32, v26, v2
	v_min_u32_e32 v2, v26, v2
	v_max_u32_e32 v26, v27, v4
	v_min_u32_e32 v4, v27, v4
	v_max_u32_e32 v27, v34, v30
	v_min_u32_e32 v30, v34, v30
	v_max_u32_e32 v34, v28, v29
	v_min_u32_e32 v28, v28, v29
	v_max_u32_e32 v29, v33, v32
	v_min_u32_e32 v32, v33, v32
	v_max_u32_e32 v33, v23, v26
	v_min_u32_e32 v23, v23, v26
	v_max_u32_e32 v26, v25, v7
	v_min_u32_e32 v7, v25, v7
	v_max_u32_e32 v25, v6, v31
	v_min_u32_e32 v6, v6, v31
	v_max_u32_e32 v31, v8, v2
	v_min_u32_e32 v2, v8, v2
	v_max_u32_e32 v8, v24, v4
	v_min_u32_e32 v4, v24, v4
	v_max_u32_e32 v24, v27, v29
	v_min_u32_e32 v27, v27, v29
	v_max_u32_e32 v29, v34, v33
	v_min_u32_e32 v33, v34, v33
	v_max_u32_e32 v34, v30, v32
	v_min_u32_e32 v30, v30, v32
	v_max_u32_e32 v32, v28, v23
	v_min_u32_e32 v23, v28, v23
	v_max_u32_e32 v28, v26, v31
	v_min_u32_e32 v26, v26, v31
	v_max_u32_e32 v31, v25, v8
	v_min_u32_e32 v8, v25, v8
	v_max_u32_e32 v25, v7, v2
	v_min_u32_e32 v7, v7, v2
	v_max_u32_e32 v35, v6, v4
	v_min_u32_e32 v4, v6, v4
	v_min_u32_e32 v6, v24, v29
	v_max_u32_e32 v2, v24, v29
	v_max_u32_e32 v29, v34, v32
	v_min_u32_e32 v32, v34, v32
	v_max_u32_e32 v38, v28, v31
	v_min_u32_e32 v39, v28, v31
	v_max_u32_e32 v34, v7, v4
	v_min_u32_e32 v31, v7, v4
	v_max_u32_e32 v42, v26, v8
	v_min_u32_e32 v41, v26, v8
	v_max_u32_e32 v24, v27, v33
	v_min_u32_e32 v27, v27, v33
	v_max_u32_e32 v33, v30, v23
	v_min_u32_e32 v36, v30, v23
	v_max_u32_e32 v40, v25, v35
	v_min_u32_e32 v37, v25, v35
	v_lshrrev_b32_e32 v48, 6, v174
	v_lshlrev_b32_e32 v48, 13, v48
	v_lshl_or_b32 v48, v172, 2, v48
	v_mov_b32_e32 v49, 0xf00
	ds_write_b32 v48, v74
	ds_write_b32 v48, v79 offset:256
	ds_write_b32 v48, v157 offset:512
	ds_write_b32 v48, v158 offset:768
	ds_write_b32 v48, v159 offset:1024
	ds_write_b32 v48, v160 offset:1280
	ds_write_b32 v48, v161 offset:1536
	ds_write_b32 v48, v162 offset:1792
	s_waitcnt lgkmcnt(7)
; DI float ord2f(unsigned o) { const unsigned u = (o & 0x80000000u) ? (o & 0x7fffffffu) : ~o; return __uint_as_float(u); }
; DI void peer_topk_phase(const bf16_t* __restrict__ qpk, const bf16_t* __restrict__ subk, int* __restrict__ eidx, float* __restrict__ gout) {
;     ...
;         for (int rd = 0; rd < 16; ++rd) {
;             const unsigned m = c0[rd];
;             const int asel = 15 - (int)((m >> 4) & 15u), bsel = 15 - (int)(m & 15u);
;             unsigned ka = top[0][0], kb = top[1][0];
; #pragma unroll
;             for (int i = 1; i < 16; ++i) { ka = (asel == i) ? top[0][i] : ka; kb = (bsel == i) ? top[1][i] : kb; }
;             sv[rd] = ord2f(ka & ~127u) + ord2f(kb & ~127u);
;             se[rd] = (127 - (int)(ka & 127u)) * 128 + (127 - (int)(kb & 127u));
;         }
	ds_write_b32 v48, v163 offset:2048
	ds_write_b32 v48, v164 offset:2304
	ds_write_b32 v48, v165 offset:2560
	ds_write_b32 v48, v166 offset:2816
	ds_write_b32 v48, v167 offset:3072
	ds_write_b32 v48, v169 offset:3328
	ds_write_b32 v48, v182 offset:3584
	ds_write_b32 v48, v168 offset:3840
	s_waitcnt lgkmcnt(7)
	ds_write_b32 v48, v3 offset:4096
	ds_write_b32 v48, v5 offset:4352
	ds_write_b32 v48, v9 offset:4608
	ds_write_b32 v48, v10 offset:4864
	ds_write_b32 v48, v11 offset:5120
	ds_write_b32 v48, v12 offset:5376
	ds_write_b32 v48, v13 offset:5632
	ds_write_b32 v48, v14 offset:5888
	s_waitcnt lgkmcnt(7)
	ds_write_b32 v48, v15 offset:6144
	ds_write_b32 v48, v16 offset:6400
	ds_write_b32 v48, v17 offset:6656
	ds_write_b32 v48, v18 offset:6912
	ds_write_b32 v48, v19 offset:7168
	ds_write_b32 v48, v21 offset:7424
	ds_write_b32 v48, v22 offset:7680
	ds_write_b32 v48, v20 offset:7936
	s_waitcnt lgkmcnt(0)
	v_lshlrev_b32_e32 v4, 8, v6
	v_and_or_b32 v4, v4, v49, v48
	ds_read_b32 v4, v4 offset:4096
	v_lshlrev_b32_e32 v6, 4, v6
	v_and_or_b32 v6, v6, v49, v48
	ds_read_b32 v6, v6
	v_lshlrev_b32_e32 v8, 4, v24
	v_and_or_b32 v8, v8, v49, v48
	ds_read_b32 v8, v8
	v_lshlrev_b32_e32 v7, 8, v24
	v_and_or_b32 v7, v7, v49, v48
	ds_read_b32 v7, v7 offset:4096
	v_lshlrev_b32_e32 v24, 4, v27
	v_and_or_b32 v24, v24, v49, v48
	ds_read_b32 v24, v24
	v_lshlrev_b32_e32 v23, 8, v27
	v_and_or_b32 v23, v23, v49, v48
	ds_read_b32 v23, v23 offset:4096
	v_lshlrev_b32_e32 v26, 4, v29
	v_and_or_b32 v26, v26, v49, v48
	ds_read_b32 v26, v26
	v_lshlrev_b32_e32 v25, 8, v29
	v_and_or_b32 v25, v25, v49, v48
	ds_read_b32 v25, v25 offset:4096
	s_waitcnt lgkmcnt(7)
	v_lshlrev_b32_e32 v28, 4, v32
	v_and_or_b32 v28, v28, v49, v48
	ds_read_b32 v28, v28
	v_lshlrev_b32_e32 v27, 8, v32
	v_and_or_b32 v27, v27, v49, v48
	ds_read_b32 v27, v27 offset:4096
	v_lshlrev_b32_e32 v30, 4, v33
	v_and_or_b32 v30, v30, v49, v48
	ds_read_b32 v30, v30
	v_lshlrev_b32_e32 v29, 8, v33
	v_and_or_b32 v29, v29, v49, v48
	ds_read_b32 v29, v29 offset:4096
	v_lshlrev_b32_e32 v33, 4, v36
	v_and_or_b32 v33, v33, v49, v48
	ds_read_b32 v33, v33
	v_lshlrev_b32_e32 v32, 8, v36
	v_and_or_b32 v32, v32, v49, v48
	ds_read_b32 v32, v32 offset:4096
	v_lshlrev_b32_e32 v36, 4, v38
	v_and_or_b32 v36, v36, v49, v48
	ds_read_b32 v36, v36
	v_lshlrev_b32_e32 v35, 8, v38
	v_and_or_b32 v35, v35, v49, v48
	ds_read_b32 v35, v35 offset:4096
	s_waitcnt lgkmcnt(7)
	v_lshlrev_b32_e32 v38, 8, v39
	v_and_or_b32 v38, v38, v49, v48
	ds_read_b32 v38, v38 offset:4096
	v_lshlrev_b32_e32 v39, 4, v39
	v_and_or_b32 v39, v39, v49, v48
	ds_read_b32 v39, v39
	v_lshlrev_b32_e32 v43, 4, v42
	v_and_or_b32 v43, v43, v49, v48
	ds_read_b32 v43, v43
	v_lshlrev_b32_e32 v42, 8, v42
	v_and_or_b32 v42, v42, v49, v48
	ds_read_b32 v42, v42 offset:4096
	v_lshlrev_b32_e32 v44, 4, v41
	v_and_or_b32 v44, v44, v49, v48
	ds_read_b32 v44, v44
	v_lshlrev_b32_e32 v41, 8, v41
	v_and_or_b32 v41, v41, v49, v48
	ds_read_b32 v41, v41 offset:4096
	v_lshlrev_b32_e32 v45, 4, v40
	v_and_or_b32 v45, v45, v49, v48
	ds_read_b32 v45, v45
	v_lshlrev_b32_e32 v40, 8, v40
	v_and_or_b32 v40, v40, v49, v48
	ds_read_b32 v40, v40 offset:4096
	s_waitcnt lgkmcnt(7)
	v_lshlrev_b32_e32 v46, 4, v37
	v_and_or_b32 v46, v46, v49, v48
	ds_read_b32 v46, v46
	v_lshlrev_b32_e32 v37, 8, v37
	v_and_or_b32 v37, v37, v49, v48
	ds_read_b32 v37, v37 offset:4096
	v_lshlrev_b32_e32 v47, 4, v34
	v_and_or_b32 v47, v47, v49, v48
	ds_read_b32 v47, v47
	v_lshlrev_b32_e32 v34, 8, v34
	v_and_or_b32 v34, v34, v49, v48
	ds_read_b32 v34, v34 offset:4096
	v_lshlrev_b32_e32 v10, 4, v2
	v_and_or_b32 v10, v10, v49, v48
	ds_read_b32 v10, v10
	v_lshlrev_b32_e32 v11, 8, v2
	v_and_or_b32 v11, v11, v49, v48
	ds_read_b32 v11, v11 offset:4096
	v_lshlrev_b32_e32 v5, 4, v31
	v_and_or_b32 v5, v5, v49, v48
	ds_read_b32 v5, v5
	v_lshlrev_b32_e32 v9, 8, v31
	v_and_or_b32 v9, v9, v49, v48
	ds_read_b32 v9, v9 offset:4096
	s_waitcnt lgkmcnt(0)
	v_lshlrev_b64 v[2:3], 7, v[80:81]
	v_lshl_or_b32 v2, v156, 4, v2
	s_and_saveexec_b64 s[0:1], s[10:11]
	s_xor_b64 s[0:1], exec, s[0:1]
	s_cbranch_execz .LBB0_468
	v_and_b32_e32 v12, 0x7fffff80, v47
	v_bitop3_b32 v13, v47, s5, v47 bitop3:0xcf
	v_cmp_gt_i32_e32 vcc, 0, v47
	v_bitop3_b32 v14, v34, s5, v34 bitop3:0xcf
	v_bitop3_b32 v21, v32, s5, v32 bitop3:0xcf
	v_cndmask_b32_e32 v12, v13, v12, vcc
	v_and_b32_e32 v13, 0x7fffff80, v34
	v_cmp_gt_i32_e32 vcc, 0, v34
	v_bitop3_b32 v22, v29, s5, v29 bitop3:0xcf
	s_nop 0
	v_cndmask_b32_e32 v13, v14, v13, vcc
	v_add_f32_e32 v20, v13, v12
	v_and_b32_e32 v12, 0x7fffff80, v46
	v_bitop3_b32 v13, v46, s5, v46 bitop3:0xcf
	v_cmp_gt_i32_e32 vcc, 0, v46
	v_bitop3_b32 v14, v37, s5, v37 bitop3:0xcf
	s_nop 0
	v_cndmask_b32_e32 v12, v13, v12, vcc
	v_and_b32_e32 v13, 0x7fffff80, v37
	v_cmp_gt_i32_e32 vcc, 0, v37
	s_nop 1
	v_cndmask_b32_e32 v13, v14, v13, vcc
	v_add_f32_e32 v19, v13, v12
	v_and_b32_e32 v12, 0x7fffff80, v45
	v_bitop3_b32 v13, v45, s5, v45 bitop3:0xcf
	v_cmp_gt_i32_e32 vcc, 0, v45
	v_bitop3_b32 v14, v40, s5, v40 bitop3:0xcf
	s_nop 0
	v_cndmask_b32_e32 v12, v13, v12, vcc
	v_and_b32_e32 v13, 0x7fffff80, v40
	v_cmp_gt_i32_e32 vcc, 0, v40
	s_nop 1
	v_cndmask_b32_e32 v13, v14, v13, vcc
	v_add_f32_e32 v18, v13, v12
	v_and_b32_e32 v12, 0x7fffff80, v44
	v_bitop3_b32 v13, v44, s5, v44 bitop3:0xcf
	v_cmp_gt_i32_e32 vcc, 0, v44
	v_bitop3_b32 v14, v41, s5, v41 bitop3:0xcf
	s_nop 0
	v_cndmask_b32_e32 v12, v13, v12, vcc
	v_and_b32_e32 v13, 0x7fffff80, v41
	v_cmp_gt_i32_e32 vcc, 0, v41
	s_nop 1
	v_cndmask_b32_e32 v13, v14, v13, vcc
	v_add_f32_e32 v17, v13, v12
	v_and_b32_e32 v12, 0x7fffff80, v43
	v_bitop3_b32 v13, v43, s5, v43 bitop3:0xcf
	v_cmp_gt_i32_e32 vcc, 0, v43
; DI float ord2f(unsigned o) { const unsigned u = (o & 0x80000000u) ? (o & 0x7fffffffu) : ~o; return __uint_as_float(u); }
; DI void peer_topk_phase(const bf16_t* __restrict__ qpk, const bf16_t* __restrict__ subk, int* __restrict__ eidx, float* __restrict__ gout) {
;     ...
;             sv[rd] = ord2f(ka & ~127u) + ord2f(kb & ~127u);
;             se[rd] = (127 - (int)(ka & 127u)) * 128 + (127 - (int)(kb & 127u));
;         }
;         float den = 0.f;
;         const float mx0 = sv[0];
; #pragma unroll
;         for (int i = 0; i < 16; ++i) { sv[i] = __expf(sv[i] - mx0); den += sv[i]; }
;         const float inv = 1.0f / den;
;         const size_t ob = (size_t)(t0 + r) * 128 + hh * 16;
;         if (h == 0) {
; #pragma unroll
;             for (int i = 0; i < 4; ++i) { int4 v = make_int4(se[4 * i], se[4 * i + 1], se[4 * i + 2], se[4 * i + 3]); *(int4*)(eidx + ob + 4 * i) = v; }
;         } else {
; #pragma unroll
;             for (int i = 0; i < 4; ++i) { f32x4 v = {sv[4 * i] * inv, sv[4 * i + 1] * inv, sv[4 * i + 2] * inv, sv[4 * i + 3] * inv}; *(f32x4*)(gout + ob + 4 * i) = v; }
	v_bitop3_b32 v14, v42, s5, v42 bitop3:0xcf
	s_nop 0
	v_cndmask_b32_e32 v12, v13, v12, vcc
	v_and_b32_e32 v13, 0x7fffff80, v42
	v_cmp_gt_i32_e32 vcc, 0, v42
	s_nop 1
	v_cndmask_b32_e32 v13, v14, v13, vcc
	v_add_f32_e32 v16, v13, v12
	v_and_b32_e32 v12, 0x7fffff80, v39
	v_bitop3_b32 v13, v39, s5, v39 bitop3:0xcf
	v_cmp_gt_i32_e32 vcc, 0, v39
	v_bitop3_b32 v14, v38, s5, v38 bitop3:0xcf
	s_nop 0
	v_cndmask_b32_e32 v12, v13, v12, vcc
	v_and_b32_e32 v13, 0x7fffff80, v38
	v_cmp_gt_i32_e32 vcc, 0, v38
	s_nop 1
	v_cndmask_b32_e32 v13, v14, v13, vcc
	v_add_f32_e32 v15, v13, v12
	v_and_b32_e32 v12, 0x7fffff80, v36
	v_bitop3_b32 v13, v36, s5, v36 bitop3:0xcf
	v_cmp_gt_i32_e32 vcc, 0, v36
	v_bitop3_b32 v14, v35, s5, v35 bitop3:0xcf
	s_nop 0
	v_cndmask_b32_e32 v12, v13, v12, vcc
	v_and_b32_e32 v13, 0x7fffff80, v35
	v_cmp_gt_i32_e32 vcc, 0, v35
	s_nop 1
	v_cndmask_b32_e32 v13, v14, v13, vcc
	v_add_f32_e32 v14, v13, v12
	v_and_b32_e32 v12, 0x7fffff80, v33
	v_bitop3_b32 v13, v33, s5, v33 bitop3:0xcf
	v_cmp_gt_i32_e32 vcc, 0, v33
	s_nop 1
	v_cndmask_b32_e32 v12, v13, v12, vcc
	v_and_b32_e32 v13, 0x7fffff80, v32
	v_cmp_gt_i32_e32 vcc, 0, v32
	s_nop 1
	v_cndmask_b32_e32 v13, v21, v13, vcc
	v_add_f32_e32 v13, v13, v12
	v_and_b32_e32 v12, 0x7fffff80, v30
	v_bitop3_b32 v21, v30, s5, v30 bitop3:0xcf
	v_cmp_gt_i32_e32 vcc, 0, v30
	s_nop 1
	v_cndmask_b32_e32 v12, v21, v12, vcc
	v_and_b32_e32 v21, 0x7fffff80, v29
	v_cmp_gt_i32_e32 vcc, 0, v29
	v_and_b32_e32 v29, 0xffffff80, v9
	s_nop 0
	v_cndmask_b32_e32 v21, v22, v21, vcc
	v_add_f32_e32 v12, v21, v12
	v_and_b32_e32 v21, 0x7fffff80, v28
	v_bitop3_b32 v22, v28, s5, v28 bitop3:0xcf
	v_cmp_gt_i32_e32 vcc, 0, v28
	v_bitop3_b32 v28, v27, s5, v27 bitop3:0xcf
	s_nop 0
	v_cndmask_b32_e32 v21, v22, v21, vcc
	v_and_b32_e32 v22, 0x7fffff80, v27
	v_cmp_gt_i32_e32 vcc, 0, v27
	v_bitop3_b32 v27, v26, s5, v26 bitop3:0xcf
	s_nop 0
	v_cndmask_b32_e32 v22, v28, v22, vcc
	v_add_f32_e32 v21, v22, v21
	v_and_b32_e32 v22, 0x7fffff80, v26
	v_cmp_gt_i32_e32 vcc, 0, v26
	v_and_b32_e32 v26, 0x7fffff80, v25
	v_and_b32_e32 v28, 0xffffff80, v11
	v_cndmask_b32_e32 v22, v27, v22, vcc
	v_bitop3_b32 v27, v25, s5, v25 bitop3:0xcf
	v_cmp_gt_i32_e32 vcc, 0, v25
	s_nop 1
	v_cndmask_b32_e32 v25, v27, v26, vcc
	v_add_f32_e32 v22, v25, v22
	v_and_b32_e32 v25, 0x7fffff80, v24
	v_bitop3_b32 v26, v24, s5, v24 bitop3:0xcf
	v_cmp_gt_i32_e32 vcc, 0, v24
	v_and_b32_e32 v27, 0x7fffff80, v9
	s_nop 0
	v_cndmask_b32_e32 v24, v26, v25, vcc
	v_and_b32_e32 v25, 0x7fffff80, v23
	v_bitop3_b32 v26, v23, s5, v23 bitop3:0xcf
	v_cmp_gt_i32_e32 vcc, 0, v23
	s_nop 1
	v_cndmask_b32_e32 v23, v26, v25, vcc
	v_add_f32_e32 v23, v23, v24
	v_and_b32_e32 v24, 0x7fffff80, v8
	v_bitop3_b32 v25, v8, s5, v8 bitop3:0xcf
	v_cmp_gt_i32_e32 vcc, 0, v8
	v_and_b32_e32 v26, 0x7fffff80, v11
	s_nop 0
	v_cndmask_b32_e32 v8, v25, v24, vcc
	v_and_b32_e32 v24, 0x7fffff80, v7
	v_bitop3_b32 v25, v7, s5, v7 bitop3:0xcf
	v_cmp_gt_i32_e32 vcc, 0, v7
	s_nop 1
	v_cndmask_b32_e32 v7, v25, v24, vcc
	v_add_f32_e32 v8, v7, v8
	v_and_b32_e32 v7, 0x7fffff80, v6
	v_bitop3_b32 v24, v6, s5, v6 bitop3:0xcf
	v_cmp_gt_i32_e32 vcc, 0, v6
	v_and_b32_e32 v25, 0xffffff80, v5
	v_xor_b32_e32 v25, -1, v25
	v_cndmask_b32_e32 v6, v24, v7, vcc
	v_and_b32_e32 v7, 0x7fffff80, v4
	v_bitop3_b32 v24, v4, s5, v4 bitop3:0xcf
	v_cmp_gt_i32_e32 vcc, 0, v4
	s_nop 1
	v_cndmask_b32_e32 v4, v24, v7, vcc
	v_and_b32_e32 v7, 0xffffff80, v10
	v_add_f32_e32 v24, v4, v6
	v_and_b32_e32 v4, 0x7fffff80, v10
	v_xor_b32_e32 v7, -1, v7
	v_cmp_gt_i32_e32 vcc, 0, v10
	v_and_b32_e32 v6, 0x7fffff80, v5
	v_xor_b32_e32 v10, -1, v29
	v_cndmask_b32_e32 v7, v7, v4, vcc
	v_cmp_gt_i32_e32 vcc, 0, v5
	v_xor_b32_e32 v4, -1, v28
	s_nop 0
	v_cndmask_b32_e32 v6, v25, v6, vcc
	v_cmp_gt_i32_e32 vcc, 0, v11
	s_nop 1
	v_cndmask_b32_e32 v5, v4, v26, vcc
	v_cmp_gt_i32_e32 vcc, 0, v9
	s_nop 1
	v_cndmask_b32_e32 v4, v10, v27, vcc
	v_pk_add_f32 v[4:5], v[4:5], v[6:7]
	s_nop 0
	v_sub_f32_e32 v6, v5, v5
	v_mul_f32_e32 v6, 0x3fb8aa3b, v6
	v_sub_f32_e32 v7, v24, v5
	v_exp_f32_e32 v6, v6
	v_mul_f32_e32 v7, 0x3fb8aa3b, v7
	v_sub_f32_e32 v8, v8, v5
	v_exp_f32_e32 v7, v7
	v_mul_f32_e32 v8, 0x3fb8aa3b, v8
	v_sub_f32_e32 v9, v23, v5
	v_exp_f32_e32 v8, v8
	v_mul_f32_e32 v9, 0x3fb8aa3b, v9
	v_exp_f32_e32 v9, v9
	v_add_f32_e32 v10, 0, v6
	v_add_f32_e32 v10, v7, v10
	v_add_f32_e32 v10, v8, v10
	v_add_f32_e32 v23, v9, v10
	v_sub_f32_e32 v10, v22, v5
	v_mul_f32_e32 v10, 0x3fb8aa3b, v10
	v_sub_f32_e32 v11, v21, v5
	v_exp_f32_e32 v10, v10
	v_mul_f32_e32 v11, 0x3fb8aa3b, v11
	v_sub_f32_e32 v12, v12, v5
	v_exp_f32_e32 v11, v11
	v_mul_f32_e32 v12, 0x3fb8aa3b, v12
	v_sub_f32_e32 v13, v13, v5
	v_exp_f32_e32 v12, v12
	v_mul_f32_e32 v13, 0x3fb8aa3b, v13
	v_sub_f32_e32 v14, v14, v5
	v_exp_f32_e32 v13, v13
	v_mul_f32_e32 v14, 0x3fb8aa3b, v14
	v_sub_f32_e32 v15, v15, v5
	v_add_f32_e32 v21, v10, v23
	v_exp_f32_e32 v14, v14
	v_mul_f32_e32 v15, 0x3fb8aa3b, v15
	v_sub_f32_e32 v16, v16, v5
	v_add_f32_e32 v21, v11, v21
	v_exp_f32_e32 v15, v15
	v_mul_f32_e32 v16, 0x3fb8aa3b, v16
	v_sub_f32_e32 v17, v17, v5
	v_add_f32_e32 v21, v12, v21
	v_exp_f32_e32 v16, v16
	v_mul_f32_e32 v17, 0x3fb8aa3b, v17
	v_sub_f32_e32 v18, v18, v5
	v_add_f32_e32 v21, v13, v21
	v_exp_f32_e32 v17, v17
	v_mul_f32_e32 v18, 0x3fb8aa3b, v18
	v_sub_f32_e32 v19, v19, v5
	v_add_f32_e32 v21, v14, v21
	v_exp_f32_e32 v18, v18
	v_mul_f32_e32 v19, 0x3fb8aa3b, v19
	v_sub_f32_e32 v20, v20, v5
	v_add_f32_e32 v21, v15, v21
	v_exp_f32_e32 v19, v19
	v_mul_f32_e32 v20, 0x3fb8aa3b, v20
	v_sub_f32_e32 v4, v4, v5
	v_add_f32_e32 v21, v16, v21
	v_exp_f32_e32 v20, v20
	v_mul_f32_e32 v4, 0x3fb8aa3b, v4
	v_add_f32_e32 v22, v17, v21
	v_exp_f32_e32 v21, v4
	v_add_f32_e32 v4, v18, v22
	v_add_f32_e32 v4, v19, v4
	v_add_f32_e32 v4, v20, v4
	v_add_f32_e32 v4, v21, v4
	v_div_scale_f32 v5, s[12:13], v4, v4, 1.0
	v_rcp_f32_e32 v22, v5
	v_readlane_b32 s12, v253, 18
	v_readlane_b32 s13, v253, 19
	v_fma_f32 v23, -v5, v22, 1.0
	v_fmac_f32_e32 v22, v23, v22
	v_div_scale_f32 v23, vcc, 1.0, v4, 1.0
	v_mul_f32_e32 v24, v23, v22
	v_fma_f32 v25, -v5, v24, v23
	v_fmac_f32_e32 v24, v25, v22
	v_fma_f32 v5, -v5, v24, v23
	v_div_fmas_f32 v5, v5, v22, v24
	v_div_fixup_f32 v22, v5, v4, 1.0
	v_lshl_add_u64 v[24:25], v[2:3], 2, s[12:13]
	v_pk_mul_f32 v[4:5], v[8:9], v[22:23] op_sel_hi:[1,0]
	v_pk_mul_f32 v[2:3], v[6:7], v[22:23] op_sel_hi:[1,0]
	global_store_dwordx4 v[24:25], v[2:5], off
	s_nop 1
	v_pk_mul_f32 v[4:5], v[12:13], v[22:23] op_sel_hi:[1,0]
	v_pk_mul_f32 v[2:3], v[10:11], v[22:23] op_sel_hi:[1,0]
	global_store_dwordx4 v[24:25], v[2:5], off offset:16
	s_nop 1
	v_pk_mul_f32 v[4:5], v[16:17], v[22:23] op_sel_hi:[1,0]
	v_pk_mul_f32 v[2:3], v[14:15], v[22:23] op_sel_hi:[1,0]
	global_store_dwordx4 v[24:25], v[2:5], off offset:32
	s_nop 1
	v_pk_mul_f32 v[4:5], v[20:21], v[22:23] op_sel_hi:[1,0]
	v_pk_mul_f32 v[2:3], v[18:19], v[22:23] op_sel_hi:[1,0]
	global_store_dwordx4 v[24:25], v[2:5], off offset:48

; #define U_ISSUE(SEG, E0, E1) { _Pragma("unroll") for (int b = 0; b < 16; ++b) { const int e = __shfl((b < 8) ? (E0) : (E1), (b & 7) * 8 + grp); SEG[b] = *(const u32x4*)(ub + (size_t)e * DM); } }
; DI void peer_u_phase(const bf16_t* __restrict__ x1, const int* __restrict__ eidx, const unsigned char* __restrict__ U8, float* __restrict__ ph) {
;     ...
;         const unsigned char* ub = U8 + 128 * j + 16 * l8;
;         const bf16_t* xb_ = x1 + 128 * j + 16 * l8;
;         float* pj = ph + (size_t)j * T_TOK * 128;
;         const int step = sm.nslot;
;         int t = sm.wslot;
;         if (t >= T_TOK) continue;
;         u32x4 sa[16], sb[16];
;         int e0n = 0, e1n = 0;
;         u32x4 xa, xb, xan, xbn;
;     ...
;         {
;             const int e0 = eidx[(size_t)t * 128 + lane], e1 = eidx[(size_t)t * 128 + 64 + lane];
;             xa = *(const u32x4*)(xb_ + (size_t)t * DM); xb = *(const u32x4*)(xb_ + (size_t)t * DM + 8);
;             U_ISSUE(sa, e0, e1)
;             if (t + step < T_TOK) { e0n = eidx[(size_t)(t + step) * 128 + lane]; e1n = eidx[(size_t)(t + step) * 128 + 64 + lane]; }
;         }
.LBB0_525:
	s_and_saveexec_b64 s[58:59], vcc
	s_cbranch_execz .LBB0_524
	global_load_dword v81, v[158:159], off
	global_load_dword v83, v[158:159], off offset:256
	s_lshl_b32 s56, s27, 7
	v_lshl_add_u64 v[168:169], v[154:155], 0, s[56:57]
	v_and_b32_e32 v252, 7, v172
	v_lshlrev_b32_e32 v252, 4, v252
	v_readfirstlane_b32 s98, v168
	v_readfirstlane_b32 s99, v169
	s_lshl_b32 s56, s27, 8
	v_lshl_add_u64 v[182:183], v[156:157], 0, s[56:57]
	v_lshl_add_u64 v[78:79], v[182:183], 0, v[160:161]
	global_load_dwordx4 v[74:77], v[78:79], off
	v_mov_b32_e32 v210, 0
	v_mov_b32_e32 v203, 0
	s_waitcnt vmcnt(2)
	ds_bpermute_b32 v80, v1, v81
	ds_bpermute_b32 v82, v149, v81
	ds_bpermute_b32 v84, v153, v81
	ds_bpermute_b32 v86, v198, v81
	ds_bpermute_b32 v88, v199, v81
	ds_bpermute_b32 v90, v200, v81
	ds_bpermute_b32 v92, v201, v81
	ds_bpermute_b32 v94, v202, v81
	s_waitcnt vmcnt(1)
	ds_bpermute_b32 v96, v1, v83
	ds_bpermute_b32 v98, v149, v83
	ds_bpermute_b32 v100, v153, v83
	ds_bpermute_b32 v102, v198, v83
	ds_bpermute_b32 v104, v199, v83
	ds_bpermute_b32 v106, v200, v83
	ds_bpermute_b32 v108, v201, v83
	ds_bpermute_b32 v110, v202, v83
	s_waitcnt lgkmcnt(0)
	v_lshl_add_u32 v80, v80, 10, v252
	v_lshl_add_u32 v82, v82, 10, v252
	v_lshl_add_u32 v84, v84, 10, v252
	v_lshl_add_u32 v86, v86, 10, v252
	v_lshl_add_u32 v88, v88, 10, v252
	v_lshl_add_u32 v90, v90, 10, v252
	v_lshl_add_u32 v92, v92, 10, v252
	v_lshl_add_u32 v94, v94, 10, v252
	v_lshl_add_u32 v96, v96, 10, v252
	v_lshl_add_u32 v98, v98, 10, v252
	v_lshl_add_u32 v100, v100, 10, v252
	v_lshl_add_u32 v102, v102, 10, v252
	v_lshl_add_u32 v104, v104, 10, v252
	v_lshl_add_u32 v106, v106, 10, v252
	v_lshl_add_u32 v108, v108, 10, v252
	v_lshl_add_u32 v110, v110, 10, v252
	v_mov_b32_e32 v112, v84
	v_mov_b32_e32 v114, v86
	v_mov_b32_e32 v116, v88
	v_mov_b32_e32 v118, v90
	v_mov_b32_e32 v120, v92
	v_mov_b32_e32 v122, v94
	v_mov_b32_e32 v124, v96
	v_mov_b32_e32 v126, v98
	v_mov_b32_e32 v128, v100
	v_mov_b32_e32 v130, v102
	v_mov_b32_e32 v132, v104
	v_mov_b32_e32 v134, v106
	v_mov_b32_e32 v136, v108
	v_mov_b32_e32 v138, v110
	global_load_dwordx4 v[142:145], v[78:79], off offset:16
	s_nop 0
	global_load_dwordx4 v[78:81], v80, s[98:99]
	s_nop 0
	global_load_dwordx4 v[82:85], v82, s[98:99]
	s_nop 0
	global_load_dwordx4 v[86:89], v112, s[98:99]
	global_load_dwordx4 v[90:93], v114, s[98:99]
	global_load_dwordx4 v[94:97], v116, s[98:99]
	global_load_dwordx4 v[98:101], v118, s[98:99]
	global_load_dwordx4 v[102:105], v120, s[98:99]
	global_load_dwordx4 v[106:109], v122, s[98:99]
	global_load_dwordx4 v[110:113], v124, s[98:99]
	s_nop 0
	global_load_dwordx4 v[114:117], v126, s[98:99]
	global_load_dwordx4 v[118:121], v128, s[98:99]
	global_load_dwordx4 v[122:125], v130, s[98:99]
	s_nop 0
	global_load_dwordx4 v[126:129], v132, s[98:99]
	s_nop 0
	global_load_dwordx4 v[130:133], v134, s[98:99]
	s_nop 0
	global_load_dwordx4 v[134:137], v136, s[98:99]
	s_nop 0
	global_load_dwordx4 v[138:141], v138, s[98:99]
	s_and_saveexec_b64 s[0:1], s[10:11]
	s_cbranch_execz .LBB0_528
	global_load_dword v203, v[162:163], off
	global_load_dword v210, v[162:163], off offset:256

; #define U_ISSUE(SEG, E0, E1) { _Pragma("unroll") for (int b = 0; b < 16; ++b) { const int e = __shfl((b < 8) ? (E0) : (E1), (b & 7) * 8 + grp); SEG[b] = *(const u32x4*)(ub + (size_t)e * DM); } }
; DI void peer_u_phase(const bf16_t* __restrict__ x1, const int* __restrict__ eidx, const unsigned char* __restrict__ U8, float* __restrict__ ph) {
;     ...
;         for (; t < T_TOK; t += 2 * step) {
;             int e0nn = 0, e1nn = 0;
;             const bool n1 = t + step < T_TOK, n2 = t + 2 * step < T_TOK, n3 = t + 3 * step < T_TOK;
;             if (n1) { U_ISSUE(sb, e0n, e1n) xan = *(const u32x4*)(xb_ + (size_t)(t + step) * DM); xbn = *(const u32x4*)(xb_ + (size_t)(t + step) * DM + 8); }
;             if (n2) { e0nn = eidx[(size_t)(t + 2 * step) * 128 + lane]; e1nn = eidx[(size_t)(t + 2 * step) * 128 + 64 + lane]; }
.LBB0_531:
	v_add_u32_e32 v186, s54, v188
	v_cmp_gt_i32_e64 s[18:19], s24, v186
	v_ashrrev_i32_e32 v187, 31, v186
	s_and_saveexec_b64 s[0:1], s[18:19]
	s_cbranch_execz .LBB0_533
	s_waitcnt vmcnt(1)
	ds_bpermute_b32 v2, v1, v203
	ds_bpermute_b32 v4, v149, v203
	ds_bpermute_b32 v10, v153, v203
	ds_bpermute_b32 v12, v198, v203
	ds_bpermute_b32 v18, v199, v203
	ds_bpermute_b32 v20, v200, v203
	ds_bpermute_b32 v26, v201, v203
	ds_bpermute_b32 v28, v202, v203
	s_waitcnt vmcnt(0)
	ds_bpermute_b32 v34, v1, v210
	ds_bpermute_b32 v36, v149, v210
	ds_bpermute_b32 v42, v153, v210
	ds_bpermute_b32 v44, v198, v210
	ds_bpermute_b32 v50, v199, v210
	ds_bpermute_b32 v52, v200, v210
	ds_bpermute_b32 v58, v201, v210
	ds_bpermute_b32 v60, v202, v210
	s_waitcnt lgkmcnt(0)
	v_lshl_add_u32 v2, v2, 10, v252
	v_lshl_add_u32 v4, v4, 10, v252
	v_lshl_add_u32 v10, v10, 10, v252
	v_lshl_add_u32 v12, v12, 10, v252
	v_lshl_add_u32 v18, v18, 10, v252
	v_lshl_add_u32 v20, v20, 10, v252
	v_lshl_add_u32 v26, v26, 10, v252
	v_lshl_add_u32 v28, v28, 10, v252
	v_lshl_add_u32 v34, v34, 10, v252
	v_lshl_add_u32 v36, v36, 10, v252
	v_lshl_add_u32 v42, v42, 10, v252
	v_lshl_add_u32 v44, v44, 10, v252
	v_lshl_add_u32 v50, v50, 10, v252
	v_lshl_add_u32 v52, v52, 10, v252
	v_lshl_add_u32 v58, v58, 10, v252
	v_lshl_add_u32 v60, v60, 10, v252
	v_lshlrev_b64 v[66:67], 11, v[186:187]
	v_lshl_add_u64 v[66:67], v[182:183], 0, v[66:67]
	global_load_dwordx4 v[6:9], v2, s[98:99]
	s_nop 0
	global_load_dwordx4 v[2:5], v4, s[98:99]
	s_nop 0
	global_load_dwordx4 v[14:17], v10, s[98:99]
	s_nop 0
	global_load_dwordx4 v[10:13], v12, s[98:99]
	s_nop 0
	global_load_dwordx4 v[22:25], v18, s[98:99]
	s_nop 0
	global_load_dwordx4 v[18:21], v20, s[98:99]
	s_nop 0
	global_load_dwordx4 v[30:33], v26, s[98:99]
	s_nop 0
	global_load_dwordx4 v[26:29], v28, s[98:99]
	s_nop 0
	global_load_dwordx4 v[38:41], v34, s[98:99]
	s_nop 0
	global_load_dwordx4 v[34:37], v36, s[98:99]
	s_nop 0
	global_load_dwordx4 v[46:49], v42, s[98:99]
	s_nop 0
	global_load_dwordx4 v[42:45], v44, s[98:99]
	s_nop 0
	global_load_dwordx4 v[54:57], v50, s[98:99]
	s_nop 0
	global_load_dwordx4 v[50:53], v52, s[98:99]
	s_nop 0
	global_load_dwordx4 v[62:65], v58, s[98:99]
	s_nop 0
	global_load_dwordx4 v[58:61], v60, s[98:99]
	s_nop 0
	global_load_dwordx4 v[70:73], v[66:67], off offset:16
	s_nop 0
	global_load_dwordx4 v[66:69], v[66:67], off

; DI float dot16(const unsigned (&a)[8], u32x4 b0, u32x4 b1) {
;     float acc;
;     asm volatile("v_dot2_f32_bf16 %0, %1, %9, 0\n\tv_dot2_f32_bf16 %0, %2, %10, %0\n\tv_dot2_f32_bf16 %0, %3, %11, %0\n\tv_dot2_f32_bf16 %0, %4, %12, %0\n\t"
;                  "v_dot2_f32_bf16 %0, %5, %13, %0\n\tv_dot2_f32_bf16 %0, %6, %14, %0\n\tv_dot2_f32_bf16 %0, %7, %15, %0\n\tv_dot2_f32_bf16 %0, %8, %16, %0\n\ts_nop 2"
;                  : "=&v"(acc)
;                  : "v"(a[0]), "v"(a[1]), "v"(a[2]), "v"(a[3]), "v"(a[4]), "v"(a[5]), "v"(a[6]), "v"(a[7]),
;                    "v"(b0.x), "v"(b0.y), "v"(b0.z), "v"(b0.w), "v"(b1.x), "v"(b1.y), "v"(b1.z), "v"(b1.w));
;     return acc;
; }
; DI float dot_fp8_row(u32x4 u, u32x4 xa, u32x4 xb) {
;     unsigned a[8];
; #pragma unroll
;     for (int j = 0; j < 4; ++j) {
;         a[2 * j] = __builtin_bit_cast(unsigned, __builtin_amdgcn_cvt_scalef32_pk_bf16_fp8(u[j], 1.0f, false));
;         a[2 * j + 1] = __builtin_bit_cast(unsigned, __builtin_amdgcn_cvt_scalef32_pk_bf16_fp8(u[j], 1.0f, true));
;     }
;     return dot16(a, xa, xb);
; }
.LBB0_535:
	s_or_b64 exec, exec, s[0:1]
	s_setprio 1
	s_waitcnt vmcnt(15)
	v_cvt_scalef32_pk_bf16_fp8 v213, v79, 1.0
	v_cvt_scalef32_pk_bf16_fp8 v189, v78, 1.0
	v_cvt_scalef32_pk_bf16_fp8 v212, v78, 1.0 op_sel:[1,0,0]
	v_cvt_scalef32_pk_bf16_fp8 v214, v79, 1.0 op_sel:[1,0,0]
	v_cvt_scalef32_pk_bf16_fp8 v215, v80, 1.0
	v_cvt_scalef32_pk_bf16_fp8 v216, v80, 1.0 op_sel:[1,0,0]
	v_cvt_scalef32_pk_bf16_fp8 v217, v81, 1.0
	v_cvt_scalef32_pk_bf16_fp8 v218, v81, 1.0 op_sel:[1,0,0]
	v_dot2_f32_bf16 v219, v189, v74, 0
	v_dot2_f32_bf16 v219, v212, v75, v219
	v_dot2_f32_bf16 v219, v213, v76, v219
	v_dot2_f32_bf16 v219, v214, v77, v219
	v_dot2_f32_bf16 v219, v215, v142, v219
	v_dot2_f32_bf16 v219, v216, v143, v219
	v_dot2_f32_bf16 v219, v217, v144, v219
	v_dot2_f32_bf16 v219, v218, v145, v219
	s_nop 2
	s_waitcnt vmcnt(14)
	v_cvt_scalef32_pk_bf16_fp8 v213, v83, 1.0
	v_cvt_scalef32_pk_bf16_fp8 v189, v82, 1.0
	v_cvt_scalef32_pk_bf16_fp8 v212, v82, 1.0 op_sel:[1,0,0]
	v_cvt_scalef32_pk_bf16_fp8 v214, v83, 1.0 op_sel:[1,0,0]
	v_cvt_scalef32_pk_bf16_fp8 v215, v84, 1.0
	v_cvt_scalef32_pk_bf16_fp8 v216, v84, 1.0 op_sel:[1,0,0]
	v_cvt_scalef32_pk_bf16_fp8 v217, v85, 1.0
	v_cvt_scalef32_pk_bf16_fp8 v218, v85, 1.0 op_sel:[1,0,0]
	v_dot2_f32_bf16 v220, v189, v74, 0
	v_dot2_f32_bf16 v220, v212, v75, v220
	v_dot2_f32_bf16 v220, v213, v76, v220
	v_dot2_f32_bf16 v220, v214, v77, v220
	v_dot2_f32_bf16 v220, v215, v142, v220
	v_dot2_f32_bf16 v220, v216, v143, v220
	v_dot2_f32_bf16 v220, v217, v144, v220
	v_dot2_f32_bf16 v220, v218, v145, v220
	s_nop 2
	s_waitcnt vmcnt(13)
	v_cvt_scalef32_pk_bf16_fp8 v213, v87, 1.0
	v_cvt_scalef32_pk_bf16_fp8 v189, v86, 1.0
	v_cvt_scalef32_pk_bf16_fp8 v212, v86, 1.0 op_sel:[1,0,0]
	v_cvt_scalef32_pk_bf16_fp8 v214, v87, 1.0 op_sel:[1,0,0]
	v_cvt_scalef32_pk_bf16_fp8 v215, v88, 1.0
	v_cvt_scalef32_pk_bf16_fp8 v216, v88, 1.0 op_sel:[1,0,0]
	v_cvt_scalef32_pk_bf16_fp8 v217, v89, 1.0
	v_cvt_scalef32_pk_bf16_fp8 v218, v89, 1.0 op_sel:[1,0,0]
	v_dot2_f32_bf16 v221, v189, v74, 0
	v_dot2_f32_bf16 v221, v212, v75, v221
	v_dot2_f32_bf16 v221, v213, v76, v221
	v_dot2_f32_bf16 v221, v214, v77, v221
	v_dot2_f32_bf16 v221, v215, v142, v221
	v_dot2_f32_bf16 v221, v216, v143, v221
	v_dot2_f32_bf16 v221, v217, v144, v221
	v_dot2_f32_bf16 v221, v218, v145, v221
	s_nop 2
	s_waitcnt vmcnt(12)
	v_cvt_scalef32_pk_bf16_fp8 v213, v91, 1.0
	v_cvt_scalef32_pk_bf16_fp8 v189, v90, 1.0
	v_cvt_scalef32_pk_bf16_fp8 v212, v90, 1.0 op_sel:[1,0,0]
	v_cvt_scalef32_pk_bf16_fp8 v214, v91, 1.0 op_sel:[1,0,0]
	v_cvt_scalef32_pk_bf16_fp8 v215, v92, 1.0
	v_cvt_scalef32_pk_bf16_fp8 v216, v92, 1.0 op_sel:[1,0,0]
	v_cvt_scalef32_pk_bf16_fp8 v217, v93, 1.0
	v_cvt_scalef32_pk_bf16_fp8 v218, v93, 1.0 op_sel:[1,0,0]
	v_dot2_f32_bf16 v222, v189, v74, 0
	v_dot2_f32_bf16 v222, v212, v75, v222
	v_dot2_f32_bf16 v222, v213, v76, v222
	v_dot2_f32_bf16 v222, v214, v77, v222
	v_dot2_f32_bf16 v222, v215, v142, v222
	v_dot2_f32_bf16 v222, v216, v143, v222
	v_dot2_f32_bf16 v222, v217, v144, v222
	v_dot2_f32_bf16 v222, v218, v145, v222
	s_nop 2
	s_waitcnt vmcnt(11)
	v_cvt_scalef32_pk_bf16_fp8 v213, v95, 1.0
	v_cvt_scalef32_pk_bf16_fp8 v189, v94, 1.0
	v_cvt_scalef32_pk_bf16_fp8 v212, v94, 1.0 op_sel:[1,0,0]
	v_cvt_scalef32_pk_bf16_fp8 v214, v95, 1.0 op_sel:[1,0,0]
	v_cvt_scalef32_pk_bf16_fp8 v215, v96, 1.0
	v_cvt_scalef32_pk_bf16_fp8 v216, v96, 1.0 op_sel:[1,0,0]
	v_cvt_scalef32_pk_bf16_fp8 v217, v97, 1.0
	v_cvt_scalef32_pk_bf16_fp8 v218, v97, 1.0 op_sel:[1,0,0]
	v_dot2_f32_bf16 v223, v189, v74, 0
	v_dot2_f32_bf16 v223, v212, v75, v223
	v_dot2_f32_bf16 v223, v213, v76, v223
	v_dot2_f32_bf16 v223, v214, v77, v223
	v_dot2_f32_bf16 v223, v215, v142, v223
	v_dot2_f32_bf16 v223, v216, v143, v223
	v_dot2_f32_bf16 v223, v217, v144, v223
	v_dot2_f32_bf16 v223, v218, v145, v223
	s_nop 2
	s_waitcnt vmcnt(10)
	v_cvt_scalef32_pk_bf16_fp8 v213, v99, 1.0
	v_cvt_scalef32_pk_bf16_fp8 v189, v98, 1.0
	v_cvt_scalef32_pk_bf16_fp8 v212, v98, 1.0 op_sel:[1,0,0]
	v_cvt_scalef32_pk_bf16_fp8 v214, v99, 1.0 op_sel:[1,0,0]
	v_cvt_scalef32_pk_bf16_fp8 v215, v100, 1.0
	v_cvt_scalef32_pk_bf16_fp8 v216, v100, 1.0 op_sel:[1,0,0]
	v_cvt_scalef32_pk_bf16_fp8 v217, v101, 1.0
	v_cvt_scalef32_pk_bf16_fp8 v218, v101, 1.0 op_sel:[1,0,0]
	v_dot2_f32_bf16 v224, v189, v74, 0
	v_dot2_f32_bf16 v224, v212, v75, v224
	v_dot2_f32_bf16 v224, v213, v76, v224
	v_dot2_f32_bf16 v224, v214, v77, v224
	v_dot2_f32_bf16 v224, v215, v142, v224
	v_dot2_f32_bf16 v224, v216, v143, v224
	v_dot2_f32_bf16 v224, v217, v144, v224
	v_dot2_f32_bf16 v224, v218, v145, v224
	s_nop 2
	s_waitcnt vmcnt(9)
	v_cvt_scalef32_pk_bf16_fp8 v213, v103, 1.0
	v_cvt_scalef32_pk_bf16_fp8 v189, v102, 1.0
	v_cvt_scalef32_pk_bf16_fp8 v212, v102, 1.0 op_sel:[1,0,0]
	v_cvt_scalef32_pk_bf16_fp8 v214, v103, 1.0 op_sel:[1,0,0]
	v_cvt_scalef32_pk_bf16_fp8 v215, v104, 1.0
	v_cvt_scalef32_pk_bf16_fp8 v216, v104, 1.0 op_sel:[1,0,0]
	v_cvt_scalef32_pk_bf16_fp8 v217, v105, 1.0
	v_cvt_scalef32_pk_bf16_fp8 v218, v105, 1.0 op_sel:[1,0,0]
	v_dot2_f32_bf16 v225, v189, v74, 0
	v_dot2_f32_bf16 v225, v212, v75, v225
	v_dot2_f32_bf16 v225, v213, v76, v225
	v_dot2_f32_bf16 v225, v214, v77, v225
	v_dot2_f32_bf16 v225, v215, v142, v225
	v_dot2_f32_bf16 v225, v216, v143, v225
	v_dot2_f32_bf16 v225, v217, v144, v225
	v_dot2_f32_bf16 v225, v218, v145, v225
	s_nop 2
	s_waitcnt vmcnt(8)
	v_cvt_scalef32_pk_bf16_fp8 v213, v107, 1.0
	v_cvt_scalef32_pk_bf16_fp8 v189, v106, 1.0
	v_cvt_scalef32_pk_bf16_fp8 v212, v106, 1.0 op_sel:[1,0,0]
	v_cvt_scalef32_pk_bf16_fp8 v214, v107, 1.0 op_sel:[1,0,0]
	v_cvt_scalef32_pk_bf16_fp8 v215, v108, 1.0
	v_cvt_scalef32_pk_bf16_fp8 v216, v108, 1.0 op_sel:[1,0,0]
	v_cvt_scalef32_pk_bf16_fp8 v218, v109, 1.0
	v_cvt_scalef32_pk_bf16_fp8 v226, v109, 1.0 op_sel:[1,0,0]
	v_dot2_f32_bf16 v227, v189, v74, 0
	v_dot2_f32_bf16 v227, v212, v75, v227
	v_dot2_f32_bf16 v227, v213, v76, v227
	v_dot2_f32_bf16 v227, v214, v77, v227
	v_dot2_f32_bf16 v227, v215, v142, v227
	v_dot2_f32_bf16 v227, v216, v143, v227
	v_dot2_f32_bf16 v227, v218, v144, v227
	v_dot2_f32_bf16 v227, v226, v145, v227
	s_nop 2
	v_cndmask_b32_e64 v213, v220, v224, s[12:13]
	ds_bpermute_b32 v213, v193, v213
	v_cndmask_b32_e64 v214, v221, v225, s[12:13]
	ds_bpermute_b32 v214, v193, v214
	v_cndmask_b32_e64 v215, v222, v227, s[12:13]
	v_cndmask_b32_e64 v217, v219, v223, s[12:13]
	ds_bpermute_b32 v215, v193, v215
	ds_bpermute_b32 v217, v193, v217
	v_cndmask_b32_e64 v212, v224, v220, s[12:13]
	s_waitcnt lgkmcnt(3)
	v_add_f32_e32 v212, v212, v213
	v_cndmask_b32_e64 v213, v225, v221, s[12:13]
	s_waitcnt lgkmcnt(2)
	v_add_f32_e32 v213, v213, v214
	v_cndmask_b32_e64 v214, v227, v222, s[12:13]
	v_cndmask_b32_e64 v189, v223, v219, s[12:13]
	s_waitcnt lgkmcnt(1)
	v_add_f32_e32 v214, v214, v215
	s_waitcnt lgkmcnt(0)
	v_add_f32_e32 v189, v189, v217
	v_cndmask_b32_e64 v216, v212, v214, s[14:15]
	v_cndmask_b32_e64 v215, v189, v213, s[14:15]
	ds_bpermute_b32 v216, v194, v216
	ds_bpermute_b32 v215, v194, v215
	v_cndmask_b32_e64 v212, v214, v212, s[14:15]
	v_cndmask_b32_e64 v189, v213, v189, s[14:15]
	s_waitcnt vmcnt(7)
	v_cvt_scalef32_pk_bf16_fp8 v214, v110, 1.0
	s_waitcnt lgkmcnt(1)
	v_add_f32_e32 v212, v212, v216
	v_cvt_scalef32_pk_bf16_fp8 v216, v111, 1.0
	s_waitcnt lgkmcnt(0)
	v_add_f32_e32 v189, v189, v215
	v_cvt_scalef32_pk_bf16_fp8 v215, v110, 1.0 op_sel:[1,0,0]
	v_cvt_scalef32_pk_bf16_fp8 v217, v111, 1.0 op_sel:[1,0,0]
	v_cvt_scalef32_pk_bf16_fp8 v218, v112, 1.0
	v_cvt_scalef32_pk_bf16_fp8 v219, v112, 1.0 op_sel:[1,0,0]
	v_cvt_scalef32_pk_bf16_fp8 v220, v113, 1.0
	v_cvt_scalef32_pk_bf16_fp8 v221, v113, 1.0 op_sel:[1,0,0]
	v_dot2_f32_bf16 v222, v214, v74, 0
	v_dot2_f32_bf16 v222, v215, v75, v222
	v_dot2_f32_bf16 v222, v216, v76, v222
	v_dot2_f32_bf16 v222, v217, v77, v222
	v_dot2_f32_bf16 v222, v218, v142, v222
	v_dot2_f32_bf16 v222, v219, v143, v222
	v_dot2_f32_bf16 v222, v220, v144, v222
	v_dot2_f32_bf16 v222, v221, v145, v222
	s_nop 2
	s_waitcnt vmcnt(6)
	v_cvt_scalef32_pk_bf16_fp8 v216, v115, 1.0
	v_cvt_scalef32_pk_bf16_fp8 v214, v114, 1.0
	v_cvt_scalef32_pk_bf16_fp8 v215, v114, 1.0 op_sel:[1,0,0]
	v_cvt_scalef32_pk_bf16_fp8 v217, v115, 1.0 op_sel:[1,0,0]
	v_cvt_scalef32_pk_bf16_fp8 v218, v116, 1.0
	v_cvt_scalef32_pk_bf16_fp8 v219, v116, 1.0 op_sel:[1,0,0]
	v_cvt_scalef32_pk_bf16_fp8 v220, v117, 1.0
	v_cvt_scalef32_pk_bf16_fp8 v221, v117, 1.0 op_sel:[1,0,0]
	v_dot2_f32_bf16 v223, v214, v74, 0
	v_dot2_f32_bf16 v223, v215, v75, v223
	v_dot2_f32_bf16 v223, v216, v76, v223
	v_dot2_f32_bf16 v223, v217, v77, v223
	v_dot2_f32_bf16 v223, v218, v142, v223
	v_dot2_f32_bf16 v223, v219, v143, v223
	v_dot2_f32_bf16 v223, v220, v144, v223
	v_dot2_f32_bf16 v223, v221, v145, v223
	s_nop 2
	s_waitcnt vmcnt(5)
	v_cvt_scalef32_pk_bf16_fp8 v216, v119, 1.0
	v_cvt_scalef32_pk_bf16_fp8 v214, v118, 1.0
	v_cvt_scalef32_pk_bf16_fp8 v215, v118, 1.0 op_sel:[1,0,0]
	v_cvt_scalef32_pk_bf16_fp8 v217, v119, 1.0 op_sel:[1,0,0]
	v_cvt_scalef32_pk_bf16_fp8 v218, v120, 1.0
	v_cvt_scalef32_pk_bf16_fp8 v219, v120, 1.0 op_sel:[1,0,0]
	v_cvt_scalef32_pk_bf16_fp8 v220, v121, 1.0
	v_cvt_scalef32_pk_bf16_fp8 v221, v121, 1.0 op_sel:[1,0,0]
	v_dot2_f32_bf16 v224, v214, v74, 0
	v_dot2_f32_bf16 v224, v215, v75, v224
	v_dot2_f32_bf16 v224, v216, v76, v224
	v_dot2_f32_bf16 v224, v217, v77, v224
	v_dot2_f32_bf16 v224, v218, v142, v224
	v_dot2_f32_bf16 v224, v219, v143, v224
	v_dot2_f32_bf16 v224, v220, v144, v224
	v_dot2_f32_bf16 v224, v221, v145, v224
	s_nop 2
	s_waitcnt vmcnt(4)
	v_cvt_scalef32_pk_bf16_fp8 v216, v123, 1.0
	v_cvt_scalef32_pk_bf16_fp8 v214, v122, 1.0
	v_cvt_scalef32_pk_bf16_fp8 v215, v122, 1.0 op_sel:[1,0,0]
	v_cvt_scalef32_pk_bf16_fp8 v217, v123, 1.0 op_sel:[1,0,0]
	v_cvt_scalef32_pk_bf16_fp8 v218, v124, 1.0
	v_cvt_scalef32_pk_bf16_fp8 v219, v124, 1.0 op_sel:[1,0,0]
	v_cvt_scalef32_pk_bf16_fp8 v220, v125, 1.0
	v_cvt_scalef32_pk_bf16_fp8 v221, v125, 1.0 op_sel:[1,0,0]
	v_dot2_f32_bf16 v225, v214, v74, 0
	v_dot2_f32_bf16 v225, v215, v75, v225
	v_dot2_f32_bf16 v225, v216, v76, v225
	v_dot2_f32_bf16 v225, v217, v77, v225
	v_dot2_f32_bf16 v225, v218, v142, v225
	v_dot2_f32_bf16 v225, v219, v143, v225
	v_dot2_f32_bf16 v225, v220, v144, v225
	v_dot2_f32_bf16 v225, v221, v145, v225
	s_nop 2
	s_waitcnt vmcnt(3)
	v_cvt_scalef32_pk_bf16_fp8 v216, v127, 1.0
	v_cvt_scalef32_pk_bf16_fp8 v214, v126, 1.0
	v_cvt_scalef32_pk_bf16_fp8 v215, v126, 1.0 op_sel:[1,0,0]
	v_cvt_scalef32_pk_bf16_fp8 v217, v127, 1.0 op_sel:[1,0,0]
	v_cvt_scalef32_pk_bf16_fp8 v218, v128, 1.0
	v_cvt_scalef32_pk_bf16_fp8 v219, v128, 1.0 op_sel:[1,0,0]
	v_cvt_scalef32_pk_bf16_fp8 v220, v129, 1.0
	v_cvt_scalef32_pk_bf16_fp8 v221, v129, 1.0 op_sel:[1,0,0]
	v_dot2_f32_bf16 v226, v214, v74, 0
	v_dot2_f32_bf16 v226, v215, v75, v226
	v_dot2_f32_bf16 v226, v216, v76, v226
	v_dot2_f32_bf16 v226, v217, v77, v226
	v_dot2_f32_bf16 v226, v218, v142, v226
	v_dot2_f32_bf16 v226, v219, v143, v226
	v_dot2_f32_bf16 v226, v220, v144, v226
	v_dot2_f32_bf16 v226, v221, v145, v226
	s_nop 2
	s_waitcnt vmcnt(2)
; #define U_ISSUE(SEG, E0, E1) { _Pragma("unroll") for (int b = 0; b < 16; ++b) { const int e = __shfl((b < 8) ? (E0) : (E1), (b & 7) * 8 + grp); SEG[b] = *(const u32x4*)(ub + (size_t)e * DM); } }
; DI void peer_u_phase(const bf16_t* __restrict__ x1, const int* __restrict__ eidx, const unsigned char* __restrict__ U8, float* __restrict__ ph) {
;     ...
;         {
;             const int e0 = eidx[(size_t)t * 128 + lane], e1 = eidx[(size_t)t * 128 + 64 + lane];
;             xa = *(const u32x4*)(xb_ + (size_t)t * DM); xb = *(const u32x4*)(xb_ + (size_t)t * DM + 8);
;             U_ISSUE(sa, e0, e1)
;             if (t + step < T_TOK) { e0n = eidx[(size_t)(t + step) * 128 + lane]; e1n = eidx[(size_t)(t + step) * 128 + 64 + lane]; }
;         }
;         for (; t < T_TOK; t += 2 * step) {
;             int e0nn = 0, e1nn = 0;
;             const bool n1 = t + step < T_TOK, n2 = t + 2 * step < T_TOK, n3 = t + 3 * step < T_TOK;
;             if (n1) { U_ISSUE(sb, e0n, e1n) xan = *(const u32x4*)(xb_ + (size_t)(t + step) * DM); xbn = *(const u32x4*)(xb_ + (size_t)(t + step) * DM + 8); }
;             if (n2) { e0nn = eidx[(size_t)(t + 2 * step) * 128 + lane]; e1nn = eidx[(size_t)(t + 2 * step) * 128 + 64 + lane]; }
;             U_COMPUTE(sa, t)
;             if (n1) {
;                 xa = xan; xb = xbn;
;                 if (n2) { U_ISSUE(sa, e0nn, e1nn) xan = *(const u32x4*)(xb_ + (size_t)(t + 2 * step) * DM); xbn = *(const u32x4*)(xb_ + (size_t)(t + 2 * step) * DM + 8); }
	v_cvt_scalef32_pk_bf16_fp8 v216, v131, 1.0
	v_cvt_scalef32_pk_bf16_fp8 v214, v130, 1.0
	v_cvt_scalef32_pk_bf16_fp8 v215, v130, 1.0 op_sel:[1,0,0]
	v_cvt_scalef32_pk_bf16_fp8 v217, v131, 1.0 op_sel:[1,0,0]
	v_cvt_scalef32_pk_bf16_fp8 v218, v132, 1.0
	v_cvt_scalef32_pk_bf16_fp8 v219, v132, 1.0 op_sel:[1,0,0]
	v_cvt_scalef32_pk_bf16_fp8 v220, v133, 1.0
	v_cvt_scalef32_pk_bf16_fp8 v221, v133, 1.0 op_sel:[1,0,0]
	v_dot2_f32_bf16 v227, v214, v74, 0
	v_dot2_f32_bf16 v227, v215, v75, v227
	v_dot2_f32_bf16 v227, v216, v76, v227
	v_dot2_f32_bf16 v227, v217, v77, v227
	v_dot2_f32_bf16 v227, v218, v142, v227
	v_dot2_f32_bf16 v227, v219, v143, v227
	v_dot2_f32_bf16 v227, v220, v144, v227
	v_dot2_f32_bf16 v227, v221, v145, v227
	s_nop 2
	s_waitcnt vmcnt(1)
	v_cvt_scalef32_pk_bf16_fp8 v216, v135, 1.0
	v_cvt_scalef32_pk_bf16_fp8 v214, v134, 1.0
	v_cvt_scalef32_pk_bf16_fp8 v215, v134, 1.0 op_sel:[1,0,0]
	v_cvt_scalef32_pk_bf16_fp8 v217, v135, 1.0 op_sel:[1,0,0]
	v_cvt_scalef32_pk_bf16_fp8 v218, v136, 1.0
	v_cvt_scalef32_pk_bf16_fp8 v219, v136, 1.0 op_sel:[1,0,0]
	v_cvt_scalef32_pk_bf16_fp8 v220, v137, 1.0
	v_cvt_scalef32_pk_bf16_fp8 v221, v137, 1.0 op_sel:[1,0,0]
	v_dot2_f32_bf16 v228, v214, v74, 0
	v_dot2_f32_bf16 v228, v215, v75, v228
	v_dot2_f32_bf16 v228, v216, v76, v228
	v_dot2_f32_bf16 v228, v217, v77, v228
	v_dot2_f32_bf16 v228, v218, v142, v228
	v_dot2_f32_bf16 v228, v219, v143, v228
	v_dot2_f32_bf16 v228, v220, v144, v228
	v_dot2_f32_bf16 v228, v221, v145, v228
	s_nop 2
	s_waitcnt vmcnt(0)
	v_cvt_scalef32_pk_bf16_fp8 v216, v139, 1.0
	v_cvt_scalef32_pk_bf16_fp8 v214, v138, 1.0
	v_cvt_scalef32_pk_bf16_fp8 v215, v138, 1.0 op_sel:[1,0,0]
	v_cvt_scalef32_pk_bf16_fp8 v217, v139, 1.0 op_sel:[1,0,0]
	v_cvt_scalef32_pk_bf16_fp8 v218, v140, 1.0
	v_cvt_scalef32_pk_bf16_fp8 v219, v140, 1.0 op_sel:[1,0,0]
	v_cvt_scalef32_pk_bf16_fp8 v221, v141, 1.0
	v_cvt_scalef32_pk_bf16_fp8 v229, v141, 1.0 op_sel:[1,0,0]
	v_dot2_f32_bf16 v230, v214, v74, 0
	v_dot2_f32_bf16 v230, v215, v75, v230
	v_dot2_f32_bf16 v230, v216, v76, v230
	v_dot2_f32_bf16 v230, v217, v77, v230
	v_dot2_f32_bf16 v230, v218, v142, v230
	v_dot2_f32_bf16 v230, v219, v143, v230
	v_dot2_f32_bf16 v230, v221, v144, v230
	v_dot2_f32_bf16 v230, v229, v145, v230
	s_nop 2
	v_cndmask_b32_e64 v216, v223, v227, s[12:13]
	ds_bpermute_b32 v216, v193, v216
	v_cndmask_b32_e64 v217, v224, v228, s[12:13]
	v_cndmask_b32_e64 v220, v222, v226, s[12:13]
	ds_bpermute_b32 v217, v193, v217
	v_cndmask_b32_e64 v218, v225, v230, s[12:13]
	ds_bpermute_b32 v220, v193, v220
	ds_bpermute_b32 v218, v193, v218
	v_cndmask_b32_e64 v215, v227, v223, s[12:13]
	s_waitcnt lgkmcnt(3)
	v_add_f32_e32 v215, v215, v216
	v_cndmask_b32_e64 v216, v228, v224, s[12:13]
	v_cndmask_b32_e64 v214, v226, v222, s[12:13]
	s_waitcnt lgkmcnt(2)
	v_add_f32_e32 v216, v216, v217
	v_cndmask_b32_e64 v217, v230, v225, s[12:13]
	s_waitcnt lgkmcnt(1)
	v_add_f32_e32 v214, v214, v220
	s_waitcnt lgkmcnt(0)
	v_add_f32_e32 v217, v217, v218
	v_cndmask_b32_e64 v218, v214, v216, s[14:15]
	v_cndmask_b32_e64 v219, v215, v217, s[14:15]
	ds_bpermute_b32 v218, v194, v218
	ds_bpermute_b32 v219, v194, v219
	v_cndmask_b32_e64 v214, v216, v214, s[14:15]
	v_cndmask_b32_e64 v215, v217, v215, s[14:15]
	v_cndmask_b32_e64 v213, v189, v212, s[16:17]
	s_waitcnt lgkmcnt(1)
	v_add_f32_e32 v214, v214, v218
	s_waitcnt lgkmcnt(0)
	v_add_f32_e32 v215, v215, v219
	ds_bpermute_b32 v213, v195, v213
	v_cndmask_b32_e64 v216, v214, v215, s[16:17]
	ds_bpermute_b32 v216, v195, v216
	v_cndmask_b32_e64 v189, v212, v189, s[16:17]
	s_waitcnt lgkmcnt(1)
	v_add_f32_e32 v217, v189, v213
	v_cndmask_b32_e64 v189, v215, v214, s[16:17]
	s_waitcnt lgkmcnt(0)
	v_add_f32_e32 v214, v189, v216
	s_setprio 0
	v_ashrrev_i32_e32 v189, 31, v188
	v_lshlrev_b64 v[212:213], 9, v[188:189]
	v_lshl_add_u64 v[212:213], v[184:185], 0, v[212:213]
	global_store_dword v[212:213], v217, off
	global_store_dword v[212:213], v214, off offset:256
	s_and_saveexec_b64 s[74:75], s[18:19]
	s_cbranch_execz .LBB0_530
	v_mov_b64_e32 v[144:145], v[72:73]
	v_mov_b64_e32 v[76:77], v[68:69]
	v_mov_b64_e32 v[142:143], v[70:71]
	v_mov_b64_e32 v[74:75], v[66:67]
	s_and_saveexec_b64 s[0:1], s[20:21]
	s_cbranch_execz .LBB0_538
	ds_bpermute_b32 v74, v1, v211
	ds_bpermute_b32 v76, v149, v211
	ds_bpermute_b32 v86, v153, v211
	ds_bpermute_b32 v88, v198, v211
	ds_bpermute_b32 v94, v199, v211
	s_waitcnt lgkmcnt(4)
	ds_bpermute_b32 v96, v200, v211
	s_waitcnt lgkmcnt(4)
	v_lshl_add_u32 v74, v74, 10, v252
	ds_bpermute_b32 v102, v201, v211
	v_lshl_add_u32 v76, v76, 10, v252
	s_waitcnt lgkmcnt(4)
	ds_bpermute_b32 v104, v202, v211
	global_load_dwordx4 v[78:81], v74, s[98:99]
	global_load_dwordx4 v[82:85], v76, s[98:99]
	v_lshl_add_u32 v74, v86, 10, v252
	s_waitcnt lgkmcnt(4)
	ds_bpermute_b32 v110, v1, v191
	v_lshl_add_u32 v76, v88, 10, v252
	s_waitcnt lgkmcnt(4)
	ds_bpermute_b32 v112, v149, v191
	global_load_dwordx4 v[86:89], v74, s[98:99]
	global_load_dwordx4 v[90:93], v76, s[98:99]
	v_lshl_add_u32 v74, v94, 10, v252
	s_waitcnt lgkmcnt(4)
	ds_bpermute_b32 v118, v153, v191
	v_lshl_add_u32 v76, v96, 10, v252
	s_waitcnt lgkmcnt(4)
	ds_bpermute_b32 v120, v198, v191
	global_load_dwordx4 v[94:97], v74, s[98:99]
	global_load_dwordx4 v[98:101], v76, s[98:99]
	v_lshl_add_u32 v74, v102, 10, v252
	s_waitcnt lgkmcnt(4)
	ds_bpermute_b32 v126, v199, v191
	v_lshl_add_u32 v76, v104, 10, v252
	s_waitcnt lgkmcnt(4)
	ds_bpermute_b32 v128, v200, v191
	global_load_dwordx4 v[102:105], v74, s[98:99]
	global_load_dwordx4 v[106:109], v76, s[98:99]
	v_lshl_add_u32 v74, v110, 10, v252
	s_waitcnt lgkmcnt(4)
	ds_bpermute_b32 v134, v201, v191
	v_lshl_add_u32 v76, v112, 10, v252
	s_waitcnt lgkmcnt(4)
	ds_bpermute_b32 v136, v202, v191
	global_load_dwordx4 v[110:113], v74, s[98:99]
	global_load_dwordx4 v[114:117], v76, s[98:99]
	v_lshl_add_u32 v74, v118, 10, v252
	s_waitcnt lgkmcnt(4)
	v_lshl_add_u32 v76, v120, 10, v252
	s_waitcnt lgkmcnt(3)
	global_load_dwordx4 v[118:121], v74, s[98:99]
	global_load_dwordx4 v[122:125], v76, s[98:99]
	v_lshl_add_u32 v74, v126, 10, v252
	s_waitcnt lgkmcnt(2)
	v_lshl_add_u32 v76, v128, 10, v252
	s_waitcnt lgkmcnt(1)
	global_load_dwordx4 v[126:129], v74, s[98:99]
	global_load_dwordx4 v[130:133], v76, s[98:99]
	v_lshl_add_u32 v74, v134, 10, v252
	s_waitcnt lgkmcnt(0)
	v_lshl_add_u32 v76, v136, 10, v252
	v_ashrrev_i32_e32 v191, 31, v190
	global_load_dwordx4 v[134:137], v74, s[98:99]
	global_load_dwordx4 v[138:141], v76, s[98:99]
	v_lshlrev_b64 v[74:75], 11, v[190:191]
	v_lshl_add_u64 v[74:75], v[182:183], 0, v[74:75]
	global_load_dwordx4 v[142:145], v[74:75], off offset:16
	s_nop 0
	global_load_dwordx4 v[74:77], v[74:75], off

; #define V_ISSUE(SEG, E0, E1) { _Pragma("unroll") for (int b = 0; b < 16; ++b) { const int e = __shfl((b < 8) ? (E0) : (E1), (b & 7) * 8 + grp); SEG[b] = *(const u32x4*)(vb + (size_t)e * DM); } }
; DI void peer_v_phase(const bf16_t* __restrict__ x1, const int* __restrict__ eidx, const float* __restrict__ wgt, const unsigned char* __restrict__ V8, bf16_t* __restrict__ y) {
;     ...
;         const unsigned char* vb = V8 + 128 * j + 16 * l8;
;         const int col = 128 * j + 16 * l8 + 2 * grp;
;         const int step = sm.nslot;
;         int t = sm.wslot;
;         if (t >= T_TOK) continue;
;         u32x4 sa[16], sb[16];
;         int e0n = 0, e1n = 0;
;         float w0, w1, w0n = 0.f, w1n = 0.f;
;     ...
;         {
;             const int e0 = eidx[(size_t)t * 128 + lane], e1 = eidx[(size_t)t * 128 + 64 + lane];
;             w0 = wgt[(size_t)t * 128 + lane]; w1 = wgt[(size_t)t * 128 + 64 + lane];
;             V_ISSUE(sa, e0, e1)
;             if (t + step < T_TOK) { e0n = eidx[(size_t)(t + step) * 128 + lane]; e1n = eidx[(size_t)(t + step) * 128 + 64 + lane]; }
;         }
.LBB0_654:
	s_and_saveexec_b64 s[72:73], vcc
	s_cbranch_execz .LBB0_653
	global_load_dword v67, v[136:137], off
	global_load_dword v69, v[138:139], off
	s_lshl_b32 s56, s27, 7
	v_lshl_add_u64 v[158:159], v[134:135], 0, s[56:57]
	v_and_b32_e32 v252, 7, v172
	v_lshlrev_b32_e32 v252, 4, v252
	v_readfirstlane_b32 s98, v158
	v_readfirstlane_b32 s99, v159
	global_load_dword v189, v[140:141], off
	global_load_dword v191, v[142:143], off
	v_mov_b32_e32 v198, 0
	v_mov_b32_e32 v190, 0
	v_mov_b32_e32 v188, 0
	s_waitcnt vmcnt(3)
	ds_bpermute_b32 v66, v131, v67
	ds_bpermute_b32 v68, v149, v67
	ds_bpermute_b32 v70, v182, v67
	ds_bpermute_b32 v72, v183, v67
	ds_bpermute_b32 v74, v184, v67
	ds_bpermute_b32 v76, v185, v67
	ds_bpermute_b32 v78, v186, v67
	ds_bpermute_b32 v80, v187, v67
	s_waitcnt vmcnt(2)
	ds_bpermute_b32 v82, v131, v69
	ds_bpermute_b32 v84, v149, v69
	ds_bpermute_b32 v86, v182, v69
	ds_bpermute_b32 v88, v183, v69
	ds_bpermute_b32 v90, v184, v69
	ds_bpermute_b32 v92, v185, v69
	ds_bpermute_b32 v94, v186, v69
	ds_bpermute_b32 v96, v187, v69
	s_waitcnt lgkmcnt(0)
	v_lshl_add_u32 v66, v66, 10, v252
	v_lshl_add_u32 v68, v68, 10, v252
	v_lshl_add_u32 v70, v70, 10, v252
	v_lshl_add_u32 v72, v72, 10, v252
	v_lshl_add_u32 v74, v74, 10, v252
	v_lshl_add_u32 v76, v76, 10, v252
	v_lshl_add_u32 v78, v78, 10, v252
	v_lshl_add_u32 v80, v80, 10, v252
	v_lshl_add_u32 v82, v82, 10, v252
	v_lshl_add_u32 v84, v84, 10, v252
	v_lshl_add_u32 v86, v86, 10, v252
	v_lshl_add_u32 v88, v88, 10, v252
	v_lshl_add_u32 v90, v90, 10, v252
	v_lshl_add_u32 v92, v92, 10, v252
	v_lshl_add_u32 v94, v94, 10, v252
	v_lshl_add_u32 v96, v96, 10, v252
	v_mov_b32_e32 v98, v68
	v_mov_b32_e32 v100, v70
	v_mov_b32_e32 v102, v72
	v_mov_b32_e32 v104, v74
	v_mov_b32_e32 v106, v76
	v_mov_b32_e32 v108, v78
	v_mov_b32_e32 v110, v80
	v_mov_b32_e32 v112, v82
	v_mov_b32_e32 v114, v84
	v_mov_b32_e32 v116, v86
	v_mov_b32_e32 v118, v88
	v_mov_b32_e32 v120, v90
	v_mov_b32_e32 v122, v92
	v_mov_b32_e32 v124, v94
	v_mov_b32_e32 v126, v96
	global_load_dwordx4 v[66:69], v66, s[98:99]
	s_nop 0
	global_load_dwordx4 v[70:73], v98, s[98:99]
	global_load_dwordx4 v[74:77], v100, s[98:99]
	global_load_dwordx4 v[78:81], v102, s[98:99]
	global_load_dwordx4 v[82:85], v104, s[98:99]
	global_load_dwordx4 v[86:89], v106, s[98:99]
	global_load_dwordx4 v[90:93], v108, s[98:99]
	global_load_dwordx4 v[94:97], v110, s[98:99]
	global_load_dwordx4 v[98:101], v112, s[98:99]
	s_nop 0
	global_load_dwordx4 v[102:105], v114, s[98:99]
	global_load_dwordx4 v[106:109], v116, s[98:99]
	global_load_dwordx4 v[110:113], v118, s[98:99]
	s_nop 0
	global_load_dwordx4 v[114:117], v120, s[98:99]
	s_nop 0
	global_load_dwordx4 v[118:121], v122, s[98:99]
	s_nop 0
	global_load_dwordx4 v[122:125], v124, s[98:99]
	s_nop 0
	global_load_dwordx4 v[126:129], v126, s[98:99]
	s_and_saveexec_b64 s[0:1], s[10:11]
	s_cbranch_execz .LBB0_657
	global_load_dword v188, v[152:153], off
	global_load_dword v190, v[152:153], off offset:256

; #define V_ISSUE(SEG, E0, E1) { _Pragma("unroll") for (int b = 0; b < 16; ++b) { const int e = __shfl((b < 8) ? (E0) : (E1), (b & 7) * 8 + grp); SEG[b] = *(const u32x4*)(vb + (size_t)e * DM); } }
; DI void peer_v_phase(const bf16_t* __restrict__ x1, const int* __restrict__ eidx, const float* __restrict__ wgt, const unsigned char* __restrict__ V8, bf16_t* __restrict__ y) {
;     ...
;         for (; t < T_TOK; t += 2 * step) {
;             int e0nn = 0, e1nn = 0;
;             const bool n1 = t + step < T_TOK, n2 = t + 2 * step < T_TOK, n3 = t + 3 * step < T_TOK;
;             if (n1) { V_ISSUE(sb, e0n, e1n) w0n = wgt[(size_t)(t + step) * 128 + lane]; w1n = wgt[(size_t)(t + step) * 128 + 64 + lane]; }
;             if (n2) { e0nn = eidx[(size_t)(t + 2 * step) * 128 + lane]; e1nn = eidx[(size_t)(t + 2 * step) * 128 + 64 + lane]; }
.LBB0_660:
	v_add_u32_e32 v164, s54, v166
	v_cmp_gt_i32_e64 s[18:19], s24, v164
	v_ashrrev_i32_e32 v165, 31, v164
	s_and_saveexec_b64 s[0:1], s[18:19]
	s_cbranch_execz .LBB0_662
	s_waitcnt vmcnt(1)
	ds_bpermute_b32 v2, v131, v188
	ds_bpermute_b32 v4, v149, v188
	ds_bpermute_b32 v10, v182, v188
	ds_bpermute_b32 v12, v183, v188
	ds_bpermute_b32 v18, v184, v188
	ds_bpermute_b32 v20, v185, v188
	ds_bpermute_b32 v26, v186, v188
	ds_bpermute_b32 v28, v187, v188
	s_waitcnt vmcnt(0)
	ds_bpermute_b32 v34, v131, v190
	ds_bpermute_b32 v36, v149, v190
	ds_bpermute_b32 v42, v182, v190
	ds_bpermute_b32 v44, v183, v190
	ds_bpermute_b32 v50, v184, v190
	ds_bpermute_b32 v52, v185, v190
	ds_bpermute_b32 v58, v186, v190
	ds_bpermute_b32 v60, v187, v190
	s_waitcnt lgkmcnt(0)
	v_lshl_add_u32 v2, v2, 10, v252
	v_lshl_add_u32 v4, v4, 10, v252
	v_lshl_add_u32 v10, v10, 10, v252
	v_lshl_add_u32 v12, v12, 10, v252
	v_lshl_add_u32 v18, v18, 10, v252
	v_lshl_add_u32 v20, v20, 10, v252
	v_lshl_add_u32 v26, v26, 10, v252
	v_lshl_add_u32 v28, v28, 10, v252
	v_lshl_add_u32 v34, v34, 10, v252
	v_lshl_add_u32 v36, v36, 10, v252
	v_lshl_add_u32 v42, v42, 10, v252
	v_lshl_add_u32 v44, v44, 10, v252
	v_lshl_add_u32 v50, v50, 10, v252
	v_lshl_add_u32 v52, v52, 10, v252
	v_lshl_add_u32 v58, v58, 10, v252
	v_lshl_add_u32 v60, v60, 10, v252
	v_lshlrev_b64 v[168:169], 9, v[164:165]
	v_mov_b32_e32 v22, v20
	v_mov_b32_e32 v30, v28
	v_mov_b32_e32 v38, v36
	v_mov_b32_e32 v46, v44
	v_mov_b32_e32 v54, v52
	v_mov_b32_e32 v62, v60
	v_lshl_add_u64 v[168:169], v[154:155], 0, v[168:169]
	global_load_dwordx4 v[6:9], v2, s[98:99]
	s_nop 0
	global_load_dwordx4 v[2:5], v4, s[98:99]
	s_nop 0
	global_load_dwordx4 v[14:17], v10, s[98:99]
	s_nop 0
	global_load_dwordx4 v[10:13], v12, s[98:99]
	s_nop 0
	global_load_dwordx4 v[18:21], v18, s[98:99]
	s_nop 0
	global_load_dwordx4 v[22:25], v22, s[98:99]
	s_nop 0
	global_load_dwordx4 v[26:29], v26, s[98:99]
	s_nop 0
	global_load_dwordx4 v[30:33], v30, s[98:99]
	s_nop 0
	global_load_dwordx4 v[34:37], v34, s[98:99]
	s_nop 0
	global_load_dwordx4 v[38:41], v38, s[98:99]
	s_nop 0
	global_load_dwordx4 v[42:45], v42, s[98:99]
	s_nop 0
	global_load_dwordx4 v[46:49], v46, s[98:99]
	s_nop 0
	global_load_dwordx4 v[50:53], v50, s[98:99]
	s_nop 0
	global_load_dwordx4 v[54:57], v54, s[98:99]
	s_nop 0
	global_load_dwordx4 v[58:61], v58, s[98:99]
	s_nop 0
	global_load_dwordx4 v[62:65], v62, s[98:99]
	s_nop 0
	global_load_dword v198, v[168:169], off
	global_load_dword v132, v[168:169], off offset:256

; DI void axpy_fp8_row(f32x2 (&o)[8], float wgt, u32x4 v) {
;     const f32x2 w2 = {wgt, wgt};
; #pragma unroll
;     for (int j = 0; j < 4; ++j) {
;         const f32x2 lo = __builtin_amdgcn_cvt_pk_f32_fp8(v[j], false), hi = __builtin_amdgcn_cvt_pk_f32_fp8(v[j], true);
;         o[2 * j] = __builtin_elementwise_fma(w2, lo, o[2 * j]);
;         o[2 * j + 1] = __builtin_elementwise_fma(w2, hi, o[2 * j + 1]);
;     }
; }
.LBB0_664:
	s_or_b64 exec, exec, s[0:1]
	s_setprio 1
	s_waitcnt vmcnt(17)
	ds_bpermute_b32 v200, v131, v189
	s_waitcnt vmcnt(15)
	v_cvt_pk_f32_fp8_e32 v[202:203], v66
	v_cvt_pk_f32_fp8_sdwa v[210:211], v66 src0_sel:WORD_1
	v_cvt_pk_f32_fp8_e32 v[212:213], v67
	v_cvt_pk_f32_fp8_sdwa v[214:215], v67 src0_sel:WORD_1
	v_cvt_pk_f32_fp8_e32 v[216:217], v68
	v_cvt_pk_f32_fp8_sdwa v[218:219], v68 src0_sel:WORD_1
	v_cvt_pk_f32_fp8_e32 v[220:221], v69
	v_cvt_pk_f32_fp8_sdwa v[222:223], v69 src0_sel:WORD_1
	s_waitcnt lgkmcnt(0)
	v_pk_fma_f32 v[202:203], v[200:201], v[202:203], 0 op_sel_hi:[0,1,0]
	v_pk_fma_f32 v[210:211], v[200:201], v[210:211], 0 op_sel_hi:[0,1,0]
	v_pk_fma_f32 v[212:213], v[200:201], v[212:213], 0 op_sel_hi:[0,1,0]
	v_pk_fma_f32 v[214:215], v[200:201], v[214:215], 0 op_sel_hi:[0,1,0]
	v_pk_fma_f32 v[216:217], v[200:201], v[216:217], 0 op_sel_hi:[0,1,0]
	v_pk_fma_f32 v[218:219], v[200:201], v[218:219], 0 op_sel_hi:[0,1,0]
	v_pk_fma_f32 v[220:221], v[200:201], v[220:221], 0 op_sel_hi:[0,1,0]
	v_pk_fma_f32 v[200:201], v[200:201], v[222:223], 0 op_sel_hi:[0,1,0]
	ds_bpermute_b32 v222, v149, v189
	s_waitcnt vmcnt(14)
	v_cvt_pk_f32_fp8_e32 v[224:225], v70
	v_cvt_pk_f32_fp8_sdwa v[226:227], v70 src0_sel:WORD_1
	v_cvt_pk_f32_fp8_e32 v[228:229], v71
	v_cvt_pk_f32_fp8_sdwa v[230:231], v71 src0_sel:WORD_1
	s_waitcnt lgkmcnt(0)
	v_pk_fma_f32 v[202:203], v[222:223], v[224:225], v[202:203] op_sel_hi:[0,1,1]
	v_pk_fma_f32 v[210:211], v[222:223], v[226:227], v[210:211] op_sel_hi:[0,1,1]
	v_pk_fma_f32 v[212:213], v[222:223], v[228:229], v[212:213] op_sel_hi:[0,1,1]
	v_pk_fma_f32 v[214:215], v[222:223], v[230:231], v[214:215] op_sel_hi:[0,1,1]
	v_cvt_pk_f32_fp8_e32 v[224:225], v72
	v_cvt_pk_f32_fp8_sdwa v[226:227], v72 src0_sel:WORD_1
	v_cvt_pk_f32_fp8_e32 v[228:229], v73
	v_cvt_pk_f32_fp8_sdwa v[230:231], v73 src0_sel:WORD_1
	v_pk_fma_f32 v[216:217], v[222:223], v[224:225], v[216:217] op_sel_hi:[0,1,1]
	v_pk_fma_f32 v[218:219], v[222:223], v[226:227], v[218:219] op_sel_hi:[0,1,1]
	v_pk_fma_f32 v[220:221], v[222:223], v[228:229], v[220:221] op_sel_hi:[0,1,1]
	v_pk_fma_f32 v[200:201], v[222:223], v[230:231], v[200:201] op_sel_hi:[0,1,1]
	ds_bpermute_b32 v222, v182, v189
	s_waitcnt vmcnt(13)
	v_cvt_pk_f32_fp8_e32 v[224:225], v74
	v_cvt_pk_f32_fp8_sdwa v[226:227], v74 src0_sel:WORD_1
	v_cvt_pk_f32_fp8_e32 v[228:229], v75
	v_cvt_pk_f32_fp8_sdwa v[230:231], v75 src0_sel:WORD_1
	s_waitcnt lgkmcnt(0)
	v_pk_fma_f32 v[202:203], v[222:223], v[224:225], v[202:203] op_sel_hi:[0,1,1]
	v_pk_fma_f32 v[210:211], v[222:223], v[226:227], v[210:211] op_sel_hi:[0,1,1]
	v_pk_fma_f32 v[212:213], v[222:223], v[228:229], v[212:213] op_sel_hi:[0,1,1]
	v_pk_fma_f32 v[214:215], v[222:223], v[230:231], v[214:215] op_sel_hi:[0,1,1]
	v_cvt_pk_f32_fp8_e32 v[224:225], v76
	v_cvt_pk_f32_fp8_sdwa v[226:227], v76 src0_sel:WORD_1
	v_cvt_pk_f32_fp8_e32 v[228:229], v77
	v_cvt_pk_f32_fp8_sdwa v[230:231], v77 src0_sel:WORD_1
	v_pk_fma_f32 v[216:217], v[222:223], v[224:225], v[216:217] op_sel_hi:[0,1,1]
	v_pk_fma_f32 v[218:219], v[222:223], v[226:227], v[218:219] op_sel_hi:[0,1,1]
	v_pk_fma_f32 v[220:221], v[222:223], v[228:229], v[220:221] op_sel_hi:[0,1,1]
	v_pk_fma_f32 v[200:201], v[222:223], v[230:231], v[200:201] op_sel_hi:[0,1,1]
	ds_bpermute_b32 v222, v183, v189
	s_waitcnt vmcnt(12)
	v_cvt_pk_f32_fp8_e32 v[224:225], v78
	v_cvt_pk_f32_fp8_sdwa v[226:227], v78 src0_sel:WORD_1
	v_cvt_pk_f32_fp8_e32 v[228:229], v79
	v_cvt_pk_f32_fp8_sdwa v[230:231], v79 src0_sel:WORD_1
	s_waitcnt lgkmcnt(0)
	v_pk_fma_f32 v[202:203], v[222:223], v[224:225], v[202:203] op_sel_hi:[0,1,1]
	v_pk_fma_f32 v[210:211], v[222:223], v[226:227], v[210:211] op_sel_hi:[0,1,1]
	v_pk_fma_f32 v[212:213], v[222:223], v[228:229], v[212:213] op_sel_hi:[0,1,1]
	v_pk_fma_f32 v[214:215], v[222:223], v[230:231], v[214:215] op_sel_hi:[0,1,1]
	v_cvt_pk_f32_fp8_e32 v[224:225], v80
	v_cvt_pk_f32_fp8_sdwa v[226:227], v80 src0_sel:WORD_1
	v_cvt_pk_f32_fp8_e32 v[228:229], v81
	v_cvt_pk_f32_fp8_sdwa v[230:231], v81 src0_sel:WORD_1
	v_pk_fma_f32 v[216:217], v[222:223], v[224:225], v[216:217] op_sel_hi:[0,1,1]
	v_pk_fma_f32 v[218:219], v[222:223], v[226:227], v[218:219] op_sel_hi:[0,1,1]
	v_pk_fma_f32 v[220:221], v[222:223], v[228:229], v[220:221] op_sel_hi:[0,1,1]
	v_pk_fma_f32 v[200:201], v[222:223], v[230:231], v[200:201] op_sel_hi:[0,1,1]
	ds_bpermute_b32 v222, v184, v189
	s_waitcnt vmcnt(11)
	v_cvt_pk_f32_fp8_e32 v[224:225], v82
	v_cvt_pk_f32_fp8_sdwa v[226:227], v82 src0_sel:WORD_1
	v_cvt_pk_f32_fp8_e32 v[228:229], v83
	v_cvt_pk_f32_fp8_sdwa v[230:231], v83 src0_sel:WORD_1
	s_waitcnt lgkmcnt(0)
	v_pk_fma_f32 v[202:203], v[222:223], v[224:225], v[202:203] op_sel_hi:[0,1,1]
	v_pk_fma_f32 v[210:211], v[222:223], v[226:227], v[210:211] op_sel_hi:[0,1,1]
	v_pk_fma_f32 v[212:213], v[222:223], v[228:229], v[212:213] op_sel_hi:[0,1,1]
	v_pk_fma_f32 v[214:215], v[222:223], v[230:231], v[214:215] op_sel_hi:[0,1,1]
	v_cvt_pk_f32_fp8_e32 v[224:225], v84
	v_cvt_pk_f32_fp8_sdwa v[226:227], v84 src0_sel:WORD_1
	v_cvt_pk_f32_fp8_e32 v[228:229], v85
	v_cvt_pk_f32_fp8_sdwa v[230:231], v85 src0_sel:WORD_1
	v_pk_fma_f32 v[216:217], v[222:223], v[224:225], v[216:217] op_sel_hi:[0,1,1]
	v_pk_fma_f32 v[218:219], v[222:223], v[226:227], v[218:219] op_sel_hi:[0,1,1]
	v_pk_fma_f32 v[220:221], v[222:223], v[228:229], v[220:221] op_sel_hi:[0,1,1]
	v_pk_fma_f32 v[200:201], v[222:223], v[230:231], v[200:201] op_sel_hi:[0,1,1]
	ds_bpermute_b32 v222, v185, v189
	s_waitcnt vmcnt(10)
	v_cvt_pk_f32_fp8_e32 v[224:225], v86
	v_cvt_pk_f32_fp8_sdwa v[226:227], v86 src0_sel:WORD_1
	v_cvt_pk_f32_fp8_e32 v[228:229], v87
	v_cvt_pk_f32_fp8_sdwa v[230:231], v87 src0_sel:WORD_1
	s_waitcnt lgkmcnt(0)
; DI void axpy_fp8_row(f32x2 (&o)[8], float wgt, u32x4 v) {
;     const f32x2 w2 = {wgt, wgt};
; #pragma unroll
;     for (int j = 0; j < 4; ++j) {
;         const f32x2 lo = __builtin_amdgcn_cvt_pk_f32_fp8(v[j], false), hi = __builtin_amdgcn_cvt_pk_f32_fp8(v[j], true);
;         o[2 * j] = __builtin_elementwise_fma(w2, lo, o[2 * j]);
;         o[2 * j + 1] = __builtin_elementwise_fma(w2, hi, o[2 * j + 1]);
;     }
; }
	v_pk_fma_f32 v[202:203], v[222:223], v[224:225], v[202:203] op_sel_hi:[0,1,1]
	v_pk_fma_f32 v[210:211], v[222:223], v[226:227], v[210:211] op_sel_hi:[0,1,1]
	v_pk_fma_f32 v[212:213], v[222:223], v[228:229], v[212:213] op_sel_hi:[0,1,1]
	v_pk_fma_f32 v[214:215], v[222:223], v[230:231], v[214:215] op_sel_hi:[0,1,1]
	v_cvt_pk_f32_fp8_e32 v[224:225], v88
	v_cvt_pk_f32_fp8_sdwa v[226:227], v88 src0_sel:WORD_1
	v_cvt_pk_f32_fp8_e32 v[228:229], v89
	v_cvt_pk_f32_fp8_sdwa v[230:231], v89 src0_sel:WORD_1
	v_pk_fma_f32 v[216:217], v[222:223], v[224:225], v[216:217] op_sel_hi:[0,1,1]
	v_pk_fma_f32 v[218:219], v[222:223], v[226:227], v[218:219] op_sel_hi:[0,1,1]
	v_pk_fma_f32 v[220:221], v[222:223], v[228:229], v[220:221] op_sel_hi:[0,1,1]
	v_pk_fma_f32 v[200:201], v[222:223], v[230:231], v[200:201] op_sel_hi:[0,1,1]
	ds_bpermute_b32 v222, v186, v189
	s_waitcnt vmcnt(9)
	v_cvt_pk_f32_fp8_e32 v[224:225], v90
	v_cvt_pk_f32_fp8_sdwa v[226:227], v90 src0_sel:WORD_1
	v_cvt_pk_f32_fp8_e32 v[228:229], v91
	v_cvt_pk_f32_fp8_sdwa v[230:231], v91 src0_sel:WORD_1
	s_waitcnt lgkmcnt(0)
	v_pk_fma_f32 v[202:203], v[222:223], v[224:225], v[202:203] op_sel_hi:[0,1,1]
	v_pk_fma_f32 v[210:211], v[222:223], v[226:227], v[210:211] op_sel_hi:[0,1,1]
	v_pk_fma_f32 v[212:213], v[222:223], v[228:229], v[212:213] op_sel_hi:[0,1,1]
	v_pk_fma_f32 v[214:215], v[222:223], v[230:231], v[214:215] op_sel_hi:[0,1,1]
	v_cvt_pk_f32_fp8_e32 v[224:225], v92
	v_cvt_pk_f32_fp8_sdwa v[226:227], v92 src0_sel:WORD_1
	v_cvt_pk_f32_fp8_e32 v[228:229], v93
	v_cvt_pk_f32_fp8_sdwa v[230:231], v93 src0_sel:WORD_1
	v_pk_fma_f32 v[216:217], v[222:223], v[224:225], v[216:217] op_sel_hi:[0,1,1]
	v_pk_fma_f32 v[218:219], v[222:223], v[226:227], v[218:219] op_sel_hi:[0,1,1]
	v_pk_fma_f32 v[220:221], v[222:223], v[228:229], v[220:221] op_sel_hi:[0,1,1]
	v_pk_fma_f32 v[200:201], v[222:223], v[230:231], v[200:201] op_sel_hi:[0,1,1]
	ds_bpermute_b32 v222, v187, v189
	s_waitcnt vmcnt(8)
	v_cvt_pk_f32_fp8_e32 v[224:225], v94
	v_cvt_pk_f32_fp8_sdwa v[226:227], v94 src0_sel:WORD_1
	v_cvt_pk_f32_fp8_e32 v[228:229], v95
	v_cvt_pk_f32_fp8_sdwa v[230:231], v95 src0_sel:WORD_1
	s_waitcnt lgkmcnt(0)
	v_pk_fma_f32 v[202:203], v[222:223], v[224:225], v[202:203] op_sel_hi:[0,1,1]
	v_pk_fma_f32 v[210:211], v[222:223], v[226:227], v[210:211] op_sel_hi:[0,1,1]
	v_pk_fma_f32 v[212:213], v[222:223], v[228:229], v[212:213] op_sel_hi:[0,1,1]
	v_pk_fma_f32 v[214:215], v[222:223], v[230:231], v[214:215] op_sel_hi:[0,1,1]
	v_cvt_pk_f32_fp8_e32 v[224:225], v96
	v_cvt_pk_f32_fp8_sdwa v[226:227], v96 src0_sel:WORD_1
	v_cvt_pk_f32_fp8_e32 v[228:229], v97
	v_cvt_pk_f32_fp8_sdwa v[230:231], v97 src0_sel:WORD_1
	v_pk_fma_f32 v[216:217], v[222:223], v[224:225], v[216:217] op_sel_hi:[0,1,1]
	v_pk_fma_f32 v[218:219], v[222:223], v[226:227], v[218:219] op_sel_hi:[0,1,1]
	v_pk_fma_f32 v[220:221], v[222:223], v[228:229], v[220:221] op_sel_hi:[0,1,1]
	v_pk_fma_f32 v[200:201], v[222:223], v[230:231], v[200:201] op_sel_hi:[0,1,1]
	ds_bpermute_b32 v222, v131, v191
	s_waitcnt vmcnt(7)
	v_cvt_pk_f32_fp8_e32 v[224:225], v98
	v_cvt_pk_f32_fp8_sdwa v[226:227], v98 src0_sel:WORD_1
	v_cvt_pk_f32_fp8_e32 v[228:229], v99
	v_cvt_pk_f32_fp8_sdwa v[230:231], v99 src0_sel:WORD_1
	s_waitcnt lgkmcnt(0)
	v_pk_fma_f32 v[202:203], v[222:223], v[224:225], v[202:203] op_sel_hi:[0,1,1]
	v_pk_fma_f32 v[210:211], v[222:223], v[226:227], v[210:211] op_sel_hi:[0,1,1]
	v_pk_fma_f32 v[212:213], v[222:223], v[228:229], v[212:213] op_sel_hi:[0,1,1]
	v_pk_fma_f32 v[214:215], v[222:223], v[230:231], v[214:215] op_sel_hi:[0,1,1]
	v_cvt_pk_f32_fp8_e32 v[224:225], v100
	v_cvt_pk_f32_fp8_sdwa v[226:227], v100 src0_sel:WORD_1
	v_cvt_pk_f32_fp8_e32 v[228:229], v101
	v_cvt_pk_f32_fp8_sdwa v[230:231], v101 src0_sel:WORD_1
	v_pk_fma_f32 v[216:217], v[222:223], v[224:225], v[216:217] op_sel_hi:[0,1,1]
	v_pk_fma_f32 v[218:219], v[222:223], v[226:227], v[218:219] op_sel_hi:[0,1,1]
	v_pk_fma_f32 v[220:221], v[222:223], v[228:229], v[220:221] op_sel_hi:[0,1,1]
	v_pk_fma_f32 v[200:201], v[222:223], v[230:231], v[200:201] op_sel_hi:[0,1,1]
	ds_bpermute_b32 v222, v149, v191
	s_waitcnt vmcnt(6)
	v_cvt_pk_f32_fp8_e32 v[224:225], v102
	v_cvt_pk_f32_fp8_sdwa v[226:227], v102 src0_sel:WORD_1
	v_cvt_pk_f32_fp8_e32 v[228:229], v103
	v_cvt_pk_f32_fp8_sdwa v[230:231], v103 src0_sel:WORD_1
	s_waitcnt lgkmcnt(0)
	v_pk_fma_f32 v[202:203], v[222:223], v[224:225], v[202:203] op_sel_hi:[0,1,1]
	v_pk_fma_f32 v[210:211], v[222:223], v[226:227], v[210:211] op_sel_hi:[0,1,1]
	v_pk_fma_f32 v[212:213], v[222:223], v[228:229], v[212:213] op_sel_hi:[0,1,1]
	v_pk_fma_f32 v[214:215], v[222:223], v[230:231], v[214:215] op_sel_hi:[0,1,1]
	v_cvt_pk_f32_fp8_e32 v[224:225], v104
	v_cvt_pk_f32_fp8_sdwa v[226:227], v104 src0_sel:WORD_1
	v_cvt_pk_f32_fp8_e32 v[228:229], v105
	v_cvt_pk_f32_fp8_sdwa v[230:231], v105 src0_sel:WORD_1
	v_pk_fma_f32 v[216:217], v[222:223], v[224:225], v[216:217] op_sel_hi:[0,1,1]
	v_pk_fma_f32 v[218:219], v[222:223], v[226:227], v[218:219] op_sel_hi:[0,1,1]
	v_pk_fma_f32 v[220:221], v[222:223], v[228:229], v[220:221] op_sel_hi:[0,1,1]
	v_pk_fma_f32 v[200:201], v[222:223], v[230:231], v[200:201] op_sel_hi:[0,1,1]
	ds_bpermute_b32 v222, v182, v191
	s_waitcnt vmcnt(5)
	v_cvt_pk_f32_fp8_e32 v[224:225], v106
	v_cvt_pk_f32_fp8_sdwa v[226:227], v106 src0_sel:WORD_1
	v_cvt_pk_f32_fp8_e32 v[228:229], v107
	v_cvt_pk_f32_fp8_sdwa v[230:231], v107 src0_sel:WORD_1
	s_waitcnt lgkmcnt(0)
; DI void axpy_fp8_row(f32x2 (&o)[8], float wgt, u32x4 v) {
;     const f32x2 w2 = {wgt, wgt};
; #pragma unroll
;     for (int j = 0; j < 4; ++j) {
;         const f32x2 lo = __builtin_amdgcn_cvt_pk_f32_fp8(v[j], false), hi = __builtin_amdgcn_cvt_pk_f32_fp8(v[j], true);
;         o[2 * j] = __builtin_elementwise_fma(w2, lo, o[2 * j]);
;         o[2 * j + 1] = __builtin_elementwise_fma(w2, hi, o[2 * j + 1]);
;     }
; }
	v_pk_fma_f32 v[202:203], v[222:223], v[224:225], v[202:203] op_sel_hi:[0,1,1]
	v_pk_fma_f32 v[210:211], v[222:223], v[226:227], v[210:211] op_sel_hi:[0,1,1]
	v_pk_fma_f32 v[212:213], v[222:223], v[228:229], v[212:213] op_sel_hi:[0,1,1]
	v_pk_fma_f32 v[214:215], v[222:223], v[230:231], v[214:215] op_sel_hi:[0,1,1]
	v_cvt_pk_f32_fp8_e32 v[224:225], v108
	v_cvt_pk_f32_fp8_sdwa v[226:227], v108 src0_sel:WORD_1
	v_cvt_pk_f32_fp8_e32 v[228:229], v109
	v_cvt_pk_f32_fp8_sdwa v[230:231], v109 src0_sel:WORD_1
	v_pk_fma_f32 v[216:217], v[222:223], v[224:225], v[216:217] op_sel_hi:[0,1,1]
	v_pk_fma_f32 v[218:219], v[222:223], v[226:227], v[218:219] op_sel_hi:[0,1,1]
	v_pk_fma_f32 v[220:221], v[222:223], v[228:229], v[220:221] op_sel_hi:[0,1,1]
	v_pk_fma_f32 v[200:201], v[222:223], v[230:231], v[200:201] op_sel_hi:[0,1,1]
	ds_bpermute_b32 v222, v183, v191
	s_waitcnt vmcnt(4)
	v_cvt_pk_f32_fp8_e32 v[224:225], v110
	v_cvt_pk_f32_fp8_sdwa v[226:227], v110 src0_sel:WORD_1
	v_cvt_pk_f32_fp8_e32 v[228:229], v111
	v_cvt_pk_f32_fp8_sdwa v[230:231], v111 src0_sel:WORD_1
	s_waitcnt lgkmcnt(0)
	v_pk_fma_f32 v[202:203], v[222:223], v[224:225], v[202:203] op_sel_hi:[0,1,1]
	v_pk_fma_f32 v[210:211], v[222:223], v[226:227], v[210:211] op_sel_hi:[0,1,1]
	v_pk_fma_f32 v[212:213], v[222:223], v[228:229], v[212:213] op_sel_hi:[0,1,1]
	v_pk_fma_f32 v[214:215], v[222:223], v[230:231], v[214:215] op_sel_hi:[0,1,1]
	v_cvt_pk_f32_fp8_e32 v[224:225], v112
	v_cvt_pk_f32_fp8_sdwa v[226:227], v112 src0_sel:WORD_1
	v_cvt_pk_f32_fp8_e32 v[228:229], v113
	v_cvt_pk_f32_fp8_sdwa v[230:231], v113 src0_sel:WORD_1
	v_pk_fma_f32 v[216:217], v[222:223], v[224:225], v[216:217] op_sel_hi:[0,1,1]
	v_pk_fma_f32 v[218:219], v[222:223], v[226:227], v[218:219] op_sel_hi:[0,1,1]
	v_pk_fma_f32 v[220:221], v[222:223], v[228:229], v[220:221] op_sel_hi:[0,1,1]
	v_pk_fma_f32 v[200:201], v[222:223], v[230:231], v[200:201] op_sel_hi:[0,1,1]
	ds_bpermute_b32 v222, v184, v191
	s_waitcnt vmcnt(3)
	v_cvt_pk_f32_fp8_e32 v[224:225], v114
	v_cvt_pk_f32_fp8_sdwa v[226:227], v114 src0_sel:WORD_1
	v_cvt_pk_f32_fp8_e32 v[228:229], v115
	v_cvt_pk_f32_fp8_sdwa v[230:231], v115 src0_sel:WORD_1
	s_waitcnt lgkmcnt(0)
	v_pk_fma_f32 v[202:203], v[222:223], v[224:225], v[202:203] op_sel_hi:[0,1,1]
	v_pk_fma_f32 v[210:211], v[222:223], v[226:227], v[210:211] op_sel_hi:[0,1,1]
	v_pk_fma_f32 v[212:213], v[222:223], v[228:229], v[212:213] op_sel_hi:[0,1,1]
	v_pk_fma_f32 v[214:215], v[222:223], v[230:231], v[214:215] op_sel_hi:[0,1,1]
	v_cvt_pk_f32_fp8_e32 v[224:225], v116
	v_cvt_pk_f32_fp8_sdwa v[226:227], v116 src0_sel:WORD_1
	v_cvt_pk_f32_fp8_e32 v[228:229], v117
	v_cvt_pk_f32_fp8_sdwa v[230:231], v117 src0_sel:WORD_1
	v_pk_fma_f32 v[216:217], v[222:223], v[224:225], v[216:217] op_sel_hi:[0,1,1]
	v_pk_fma_f32 v[218:219], v[222:223], v[226:227], v[218:219] op_sel_hi:[0,1,1]
	v_pk_fma_f32 v[220:221], v[222:223], v[228:229], v[220:221] op_sel_hi:[0,1,1]
	v_pk_fma_f32 v[200:201], v[222:223], v[230:231], v[200:201] op_sel_hi:[0,1,1]
	ds_bpermute_b32 v222, v185, v191
	s_waitcnt vmcnt(2)
	v_cvt_pk_f32_fp8_e32 v[224:225], v118
	v_cvt_pk_f32_fp8_sdwa v[226:227], v118 src0_sel:WORD_1
	v_cvt_pk_f32_fp8_e32 v[228:229], v119
	v_cvt_pk_f32_fp8_sdwa v[230:231], v119 src0_sel:WORD_1
	s_waitcnt lgkmcnt(0)
	v_pk_fma_f32 v[202:203], v[222:223], v[224:225], v[202:203] op_sel_hi:[0,1,1]
	v_pk_fma_f32 v[210:211], v[222:223], v[226:227], v[210:211] op_sel_hi:[0,1,1]
	v_pk_fma_f32 v[212:213], v[222:223], v[228:229], v[212:213] op_sel_hi:[0,1,1]
	v_pk_fma_f32 v[214:215], v[222:223], v[230:231], v[214:215] op_sel_hi:[0,1,1]
	v_cvt_pk_f32_fp8_e32 v[224:225], v120
	v_cvt_pk_f32_fp8_sdwa v[226:227], v120 src0_sel:WORD_1
	v_cvt_pk_f32_fp8_e32 v[228:229], v121
	v_cvt_pk_f32_fp8_sdwa v[230:231], v121 src0_sel:WORD_1
	v_pk_fma_f32 v[216:217], v[222:223], v[224:225], v[216:217] op_sel_hi:[0,1,1]
	v_pk_fma_f32 v[218:219], v[222:223], v[226:227], v[218:219] op_sel_hi:[0,1,1]
	v_pk_fma_f32 v[220:221], v[222:223], v[228:229], v[220:221] op_sel_hi:[0,1,1]
	v_pk_fma_f32 v[200:201], v[222:223], v[230:231], v[200:201] op_sel_hi:[0,1,1]
	ds_bpermute_b32 v222, v186, v191
	s_waitcnt vmcnt(1)
	v_cvt_pk_f32_fp8_e32 v[224:225], v122
	v_cvt_pk_f32_fp8_sdwa v[226:227], v122 src0_sel:WORD_1
	v_cvt_pk_f32_fp8_e32 v[228:229], v123
	v_cvt_pk_f32_fp8_sdwa v[230:231], v123 src0_sel:WORD_1
	s_waitcnt lgkmcnt(0)
	v_pk_fma_f32 v[202:203], v[222:223], v[224:225], v[202:203] op_sel_hi:[0,1,1]
	v_pk_fma_f32 v[210:211], v[222:223], v[226:227], v[210:211] op_sel_hi:[0,1,1]
	v_pk_fma_f32 v[212:213], v[222:223], v[228:229], v[212:213] op_sel_hi:[0,1,1]
	v_pk_fma_f32 v[214:215], v[222:223], v[230:231], v[214:215] op_sel_hi:[0,1,1]
	v_cvt_pk_f32_fp8_e32 v[224:225], v124
	v_cvt_pk_f32_fp8_sdwa v[226:227], v124 src0_sel:WORD_1
	v_cvt_pk_f32_fp8_e32 v[228:229], v125
	v_cvt_pk_f32_fp8_sdwa v[230:231], v125 src0_sel:WORD_1
	v_pk_fma_f32 v[216:217], v[222:223], v[224:225], v[216:217] op_sel_hi:[0,1,1]
	v_pk_fma_f32 v[218:219], v[222:223], v[226:227], v[218:219] op_sel_hi:[0,1,1]
	v_pk_fma_f32 v[220:221], v[222:223], v[228:229], v[220:221] op_sel_hi:[0,1,1]
	v_pk_fma_f32 v[200:201], v[222:223], v[230:231], v[200:201] op_sel_hi:[0,1,1]
	ds_bpermute_b32 v222, v187, v191
	s_waitcnt vmcnt(0)
	v_cvt_pk_f32_fp8_e32 v[224:225], v126
	v_cvt_pk_f32_fp8_sdwa v[226:227], v126 src0_sel:WORD_1
	v_cvt_pk_f32_fp8_e32 v[228:229], v127
	v_cvt_pk_f32_fp8_sdwa v[230:231], v127 src0_sel:WORD_1
	s_waitcnt lgkmcnt(0)
; #define V_ISSUE(SEG, E0, E1) { _Pragma("unroll") for (int b = 0; b < 16; ++b) { const int e = __shfl((b < 8) ? (E0) : (E1), (b & 7) * 8 + grp); SEG[b] = *(const u32x4*)(vb + (size_t)e * DM); } }
; DI void peer_v_phase(const bf16_t* __restrict__ x1, const int* __restrict__ eidx, const float* __restrict__ wgt, const unsigned char* __restrict__ V8, bf16_t* __restrict__ y) {
;     ...
;         {
;             const int e0 = eidx[(size_t)t * 128 + lane], e1 = eidx[(size_t)t * 128 + 64 + lane];
;             w0 = wgt[(size_t)t * 128 + lane]; w1 = wgt[(size_t)t * 128 + 64 + lane];
;             V_ISSUE(sa, e0, e1)
;             if (t + step < T_TOK) { e0n = eidx[(size_t)(t + step) * 128 + lane]; e1n = eidx[(size_t)(t + step) * 128 + 64 + lane]; }
;         }
;         for (; t < T_TOK; t += 2 * step) {
;             int e0nn = 0, e1nn = 0;
;             const bool n1 = t + step < T_TOK, n2 = t + 2 * step < T_TOK, n3 = t + 3 * step < T_TOK;
;             if (n1) { V_ISSUE(sb, e0n, e1n) w0n = wgt[(size_t)(t + step) * 128 + lane]; w1n = wgt[(size_t)(t + step) * 128 + 64 + lane]; }
;             if (n2) { e0nn = eidx[(size_t)(t + 2 * step) * 128 + lane]; e1nn = eidx[(size_t)(t + 2 * step) * 128 + 64 + lane]; }
;             V_COMPUTE(sa, t)
;             if (n1) {
;                 w0 = w0n; w1 = w1n;
;                 if (n2) { V_ISSUE(sa, e0nn, e1nn) w0n = wgt[(size_t)(t + 2 * step) * 128 + lane]; w1n = wgt[(size_t)(t + 2 * step) * 128 + 64 + lane]; }
;                 if (n3) { e0n = eidx[(size_t)(t + 3 * step) * 128 + lane]; e1n = eidx[(size_t)(t + 3 * step) * 128 + 64 + lane]; }
;                 V_COMPUTE(sb, t + step)
	v_pk_fma_f32 v[202:203], v[222:223], v[224:225], v[202:203] op_sel_hi:[0,1,1]
	v_cvt_pk_f32_fp8_e32 v[224:225], v128
	v_pk_fma_f32 v[210:211], v[222:223], v[226:227], v[210:211] op_sel_hi:[0,1,1]
	v_pk_fma_f32 v[212:213], v[222:223], v[228:229], v[212:213] op_sel_hi:[0,1,1]
	v_pk_fma_f32 v[214:215], v[222:223], v[230:231], v[214:215] op_sel_hi:[0,1,1]
	v_cvt_pk_f32_fp8_sdwa v[226:227], v128 src0_sel:WORD_1
	v_cvt_pk_f32_fp8_e32 v[228:229], v129
	v_cvt_pk_f32_fp8_sdwa v[230:231], v129 src0_sel:WORD_1
	v_pk_fma_f32 v[216:217], v[222:223], v[224:225], v[216:217] op_sel_hi:[0,1,1]
	v_cndmask_b32_e64 v167, v202, v216, s[12:13]
	v_pk_fma_f32 v[218:219], v[222:223], v[226:227], v[218:219] op_sel_hi:[0,1,1]
	v_pk_fma_f32 v[220:221], v[222:223], v[228:229], v[220:221] op_sel_hi:[0,1,1]
	v_pk_fma_f32 v[200:201], v[222:223], v[230:231], v[200:201] op_sel_hi:[0,1,1]
	ds_bpermute_b32 v222, v173, v167
	v_cndmask_b32_e64 v167, v203, v217, s[12:13]
	ds_bpermute_b32 v223, v173, v167
	v_cndmask_b32_e64 v167, v210, v218, s[12:13]
	ds_bpermute_b32 v224, v173, v167
	v_cndmask_b32_e64 v167, v211, v219, s[12:13]
	ds_bpermute_b32 v225, v173, v167
	v_cndmask_b32_e64 v167, v212, v220, s[12:13]
	ds_bpermute_b32 v226, v173, v167
	v_cndmask_b32_e64 v167, v213, v221, s[12:13]
	ds_bpermute_b32 v227, v173, v167
	v_cndmask_b32_e64 v167, v214, v200, s[12:13]
	ds_bpermute_b32 v228, v173, v167
	v_cndmask_b32_e64 v167, v215, v201, s[12:13]
	ds_bpermute_b32 v229, v173, v167
	s_setprio 0
	v_ashrrev_i32_e32 v167, 31, v166
	v_lshlrev_b64 v[230:231], 11, v[166:167]
	v_lshl_add_u64 v[232:233], v[160:161], 0, v[230:231]
	global_load_dword v167, v[232:233], off
	v_cndmask_b32_e64 v203, v217, v203, s[12:13]
	v_cndmask_b32_e64 v202, v216, v202, s[12:13]
	v_cndmask_b32_e64 v211, v219, v211, s[12:13]
	v_cndmask_b32_e64 v210, v218, v210, s[12:13]
	v_cndmask_b32_e64 v213, v221, v213, s[12:13]
	v_cndmask_b32_e64 v212, v220, v212, s[12:13]
	v_cndmask_b32_e64 v201, v201, v215, s[12:13]
	v_cndmask_b32_e64 v200, v200, v214, s[12:13]
	s_waitcnt lgkmcnt(6)
	v_pk_add_f32 v[202:203], v[202:203], v[222:223]
	s_waitcnt lgkmcnt(4)
	v_pk_add_f32 v[210:211], v[210:211], v[224:225]
	s_waitcnt lgkmcnt(2)
	v_pk_add_f32 v[212:213], v[212:213], v[226:227]
	s_waitcnt lgkmcnt(0)
	v_pk_add_f32 v[200:201], v[200:201], v[228:229]
	v_cndmask_b32_e64 v214, v202, v212, s[14:15]
	v_cndmask_b32_e64 v215, v213, v203, s[14:15]
	v_cndmask_b32_e64 v203, v203, v213, s[14:15]
	v_cndmask_b32_e64 v213, v210, v200, s[14:15]
	v_cndmask_b32_e64 v219, v211, v201, s[14:15]
	ds_bpermute_b32 v216, v175, v214
	ds_bpermute_b32 v217, v175, v203
	ds_bpermute_b32 v218, v175, v213
	ds_bpermute_b32 v219, v175, v219
	v_cndmask_b32_e64 v214, v212, v202, s[14:15]
	v_cndmask_b32_e64 v201, v201, v211, s[14:15]
	v_cndmask_b32_e64 v200, v200, v210, s[14:15]
	s_waitcnt lgkmcnt(2)
	v_pk_add_f32 v[202:203], v[214:215], v[216:217]
	s_waitcnt lgkmcnt(0)
	v_pk_add_f32 v[200:201], v[200:201], v[218:219]
	s_nop 0
	v_cndmask_b32_e64 v210, v202, v200, s[16:17]
	v_cndmask_b32_e64 v211, v203, v201, s[16:17]
	ds_bpermute_b32 v210, v192, v210
	ds_bpermute_b32 v211, v192, v211
	v_cndmask_b32_e64 v201, v201, v203, s[16:17]
	v_cndmask_b32_e64 v200, v200, v202, s[16:17]
	s_waitcnt lgkmcnt(0)
	v_pk_add_f32 v[200:201], v[200:201], v[210:211]
	s_waitcnt vmcnt(0)
	v_lshlrev_b32_e32 v202, 16, v167
	v_and_b32_e32 v203, 0xffff0000, v167
	v_pk_fma_f32 v[200:201], v[202:203], s[58:59], v[200:201] op_sel_hi:[1,0,1]
	s_nop 0
	v_cvt_pk_bf16_f32 v167, v200, v201
	v_lshl_add_u64 v[200:201], v[162:163], 0, v[230:231]
	global_store_dword v[200:201], v167, off
	s_and_saveexec_b64 s[76:77], s[18:19]
	s_cbranch_execz .LBB0_659
	v_mov_b32_e32 v191, v132
	v_mov_b32_e32 v189, v198
	s_and_saveexec_b64 s[0:1], s[20:21]
	s_cbranch_execz .LBB0_667
	ds_bpermute_b32 v66, v131, v199
	ds_bpermute_b32 v68, v149, v199
	ds_bpermute_b32 v74, v182, v199
	ds_bpermute_b32 v76, v183, v199
	ds_bpermute_b32 v82, v184, v199
	ds_bpermute_b32 v84, v185, v199
	ds_bpermute_b32 v90, v186, v199
	ds_bpermute_b32 v92, v187, v199
	ds_bpermute_b32 v98, v131, v169
	ds_bpermute_b32 v100, v149, v169
	ds_bpermute_b32 v106, v182, v169
	ds_bpermute_b32 v108, v183, v169
	ds_bpermute_b32 v114, v184, v169
	ds_bpermute_b32 v116, v185, v169
	ds_bpermute_b32 v122, v186, v169
	ds_bpermute_b32 v124, v187, v169
	s_waitcnt lgkmcnt(0)
	v_ashrrev_i32_e32 v169, 31, v168
	v_lshl_add_u32 v66, v66, 10, v252
	v_lshl_add_u32 v68, v68, 10, v252
	v_lshl_add_u32 v74, v74, 10, v252
	v_lshl_add_u32 v76, v76, 10, v252
	v_lshl_add_u32 v82, v82, 10, v252
	v_lshl_add_u32 v84, v84, 10, v252
	v_lshl_add_u32 v90, v90, 10, v252
	v_lshl_add_u32 v92, v92, 10, v252
	v_lshl_add_u32 v98, v98, 10, v252
	v_lshl_add_u32 v100, v100, 10, v252
	v_lshl_add_u32 v106, v106, 10, v252
	v_lshl_add_u32 v108, v108, 10, v252
	v_lshl_add_u32 v114, v114, 10, v252
	v_lshl_add_u32 v116, v116, 10, v252
	v_lshl_add_u32 v122, v122, 10, v252
	v_lshl_add_u32 v124, v124, 10, v252
	v_lshlrev_b64 v[168:169], 9, v[168:169]
	v_mov_b32_e32 v70, v68
	v_mov_b32_e32 v78, v76
	v_mov_b32_e32 v86, v84
	v_mov_b32_e32 v94, v92
	v_mov_b32_e32 v102, v100
	v_mov_b32_e32 v110, v108
	v_mov_b32_e32 v118, v116
	v_mov_b32_e32 v126, v124
	v_lshl_add_u64 v[168:169], v[154:155], 0, v[168:169]
	global_load_dwordx4 v[66:69], v66, s[98:99]
	s_nop 0
	global_load_dwordx4 v[70:73], v70, s[98:99]
	s_nop 0
	global_load_dwordx4 v[74:77], v74, s[98:99]
	s_nop 0
	global_load_dwordx4 v[78:81], v78, s[98:99]
	s_nop 0
	global_load_dwordx4 v[82:85], v82, s[98:99]
	s_nop 0
	global_load_dwordx4 v[86:89], v86, s[98:99]
	s_nop 0
	global_load_dwordx4 v[90:93], v90, s[98:99]
	s_nop 0
	global_load_dwordx4 v[94:97], v94, s[98:99]
	s_nop 0
	global_load_dwordx4 v[98:101], v98, s[98:99]
	s_nop 0
	global_load_dwordx4 v[102:105], v102, s[98:99]
	s_nop 0
	global_load_dwordx4 v[106:109], v106, s[98:99]
	s_nop 0
	global_load_dwordx4 v[110:113], v110, s[98:99]
	s_nop 0
	global_load_dwordx4 v[114:117], v114, s[98:99]
	s_nop 0
	global_load_dwordx4 v[118:121], v118, s[98:99]
	s_nop 0
	global_load_dwordx4 v[122:125], v122, s[98:99]
	s_nop 0
	global_load_dwordx4 v[126:129], v126, s[98:99]
	s_nop 0
	global_load_dword v189, v[168:169], off
	global_load_dword v191, v[168:169], off offset:256

; #define MFMA(a, b, c) __builtin_amdgcn_mfma_f32_32x32x16_bf16((a), (b), (c), 0, 0, 0)
; DI unsigned f2ord(float f) { const unsigned u = __float_as_uint(f); return (u & 0x80000000u) ? ~u : (u | 0x80000000u); }
; DI void peer_topk_phase(const bf16_t* __restrict__ qpk, const bf16_t* __restrict__ subk, int* __restrict__ eidx, float* __restrict__ gout) {
;     ...
;             f32x16 acc[4];
; #pragma unroll
;             for (int nb = 0; nb < 4; ++nb)
; #pragma unroll
;                 for (int i = 0; i < 16; ++i) acc[nb][i] = 0.f;
;             const bf16_t* qp = qpk + (size_t)(t0 + r) * 1024 + hh * 128 + c * 64 + h * 8;
;             const bf16_t* kp = subk + ((size_t)(hh * 2 + c) * 128 + r) * 64 + h * 8;
; #pragma unroll
;             for (int ks = 0; ks < 4; ++ks) {
;                 const bf16x8 qfr = *(const bf16x8*)(qp + ks * 16);
; #pragma unroll
;                 for (int nb = 0; nb < 4; ++nb) {
;                     const bf16x8 kf = *(const bf16x8*)(kp + nb * 32 * 64 + ks * 16);
;                     acc[nb] = MFMA(kf, qfr, acc[nb]);
;                 }
;             }
;             unsigned key[64];
; #pragma unroll
;             for (int nb = 0; nb < 4; ++nb)
; #pragma unroll
;                 for (int i = 0; i < 16; ++i) {
;                     const int n = nb * 32 + (i & 3) + 8 * (i >> 2) + 4 * h;
;                     key[nb * 16 + i] = (f2ord(acc[nb][i]) & ~127u) | (unsigned)(127 - n);
;                 }
.LBB0_1164:
	v_and_or_b32 v86, v169, s13, v99
	v_ashrrev_i32_e32 v87, 31, v86
	v_and_b32_e32 v179, 7, v98
	v_lshlrev_b64 v[0:1], 11, v[86:87]
	v_lshl_add_u64 v[0:1], s[36:37], 0, v[0:1]
	v_lshlrev_b32_e32 v80, 8, v179
	v_lshl_add_u64 v[4:5], v[0:1], 0, v[80:81]
	v_lshl_or_b32 v80, v179, 15, v178
	v_lshl_add_u64 v[90:91], v[82:83], 0, v[80:81]
	v_mov_b32_e32 v85, v81
	v_add_co_u32_e32 v92, vcc, s15, v90
	v_lshl_add_u64 v[88:89], v[4:5], 0, v[84:85]
	s_nop 0
	v_addc_co_u32_e32 v93, vcc, 0, v91, vcc
	global_load_dwordx4 v[0:3], v[90:91], off
	global_load_dwordx4 v[16:19], v[88:89], off
	global_load_dwordx4 v[64:67], v[88:89], off offset:32
	global_load_dwordx4 v[68:71], v[90:91], off offset:32
	global_load_dwordx4 v[20:23], v[92:93], off offset:-4096
	global_load_dwordx4 v[180:183], v[92:93], off offset:32
	v_add_co_u32_e32 v94, vcc, s20, v90
	s_waitcnt vmcnt(4)
	v_mfma_f32_32x32x16_bf16 v[0:15], v[0:3], v[16:19], 0
	v_addc_co_u32_e32 v95, vcc, 0, v91, vcc
	global_load_dwordx4 v[72:75], v[94:95], off offset:96
	v_add_co_u32_e32 v96, vcc, s10, v90
	s_nop 1
	v_addc_co_u32_e32 v97, vcc, 0, v91, vcc
	s_waitcnt vmcnt(2)
	v_mfma_f32_32x32x16_bf16 v[48:63], v[20:23], v[16:19], 0
	global_load_dwordx4 v[20:23], v[92:93], off
	v_add_co_u32_e32 v184, vcc, s14, v90
	s_nop 1
	v_addc_co_u32_e32 v185, vcc, 0, v91, vcc
	v_add_co_u32_e32 v206, vcc, s16, v90
	v_mfma_f32_32x32x16_bf16 v[0:15], v[68:71], v[64:67], v[0:15]
	s_nop 0
	v_addc_co_u32_e32 v207, vcc, 0, v91, vcc
	s_waitcnt vmcnt(0)
	v_mfma_f32_32x32x16_bf16 v[32:47], v[20:23], v[16:19], 0
	global_load_dwordx4 v[20:23], v[96:97], off offset:-4096
	global_load_dwordx4 v[76:79], v[96:97], off
	global_load_dwordx4 v[68:71], v[184:185], off offset:32
	global_load_dwordx4 v[188:191], v[184:185], off offset:64
	v_mfma_f32_32x32x16_bf16 v[32:47], v[180:183], v[64:67], v[32:47]
	s_waitcnt vmcnt(1)
	v_mfma_f32_32x32x16_bf16 v[48:63], v[68:71], v[64:67], v[48:63]
	global_load_dwordx4 v[68:71], v[206:207], off offset:32
	global_load_dwordx4 v[180:183], v[90:91], off offset:64
	global_load_dwordx4 v[198:201], v[184:185], off offset:96
	v_mfma_f32_32x32x16_bf16 v[16:31], v[20:23], v[16:19], 0
	s_waitcnt vmcnt(2)
	v_mfma_f32_32x32x16_bf16 v[16:31], v[68:71], v[64:67], v[16:31]
	global_load_dwordx4 v[64:67], v[88:89], off offset:64
	global_load_dwordx4 v[68:71], v[88:89], off offset:96
	global_load_dwordx4 v[202:205], v[90:91], off offset:96
	s_waitcnt vmcnt(2)
	v_mfma_f32_32x32x16_bf16 v[0:15], v[180:183], v[64:67], v[0:15]
	v_mfma_f32_32x32x16_bf16 v[48:63], v[188:191], v[64:67], v[48:63]
	global_load_dwordx4 v[180:183], v[92:93], off offset:64
	global_load_dwordx4 v[188:191], v[92:93], off offset:96
	s_waitcnt vmcnt(2)
	v_mfma_f32_32x32x16_bf16 v[0:15], v[202:205], v[68:71], v[0:15]
	v_mfma_f32_32x32x16_bf16 v[48:63], v[198:201], v[68:71], v[48:63]
	s_nop 10
	v_cmp_gt_i32_e32 vcc, 0, v0
	v_not_b32_e32 v80, v2
	v_or_b32_e32 v85, 0x80000000, v2
	v_not_b32_e32 v92, v3
	v_or_b32_e32 v93, 0x80000000, v3
	v_not_b32_e32 v184, v6
	v_or_b32_e32 v185, 0x80000000, v6
	v_not_b32_e32 v187, v7
	v_or_b32_e32 v198, 0x80000000, v9
	v_not_b32_e32 v199, v10
	v_or_b32_e32 v200, 0x80000000, v10
	v_not_b32_e32 v201, v11
	v_or_b32_e32 v202, 0x80000000, v11
	s_waitcnt vmcnt(1)
	v_mfma_f32_32x32x16_bf16 v[32:47], v[180:183], v[64:67], v[32:47]
	global_load_dwordx4 v[180:183], v[206:207], off offset:64
	s_nop 0
	global_load_dwordx4 v[206:209], v[206:207], off offset:96
	s_nop 0
	global_load_dwordx4 v[214:217], v[88:89], off offset:224
	s_waitcnt vmcnt(2)
	v_mfma_f32_32x32x16_bf16 v[16:31], v[180:183], v[64:67], v[16:31]
	v_not_b32_e32 v64, v0
	v_or_b32_e32 v65, 0x80000000, v0
	v_not_b32_e32 v66, v1
	v_or_b32_e32 v67, 0x80000000, v1
	v_cndmask_b32_e32 v0, v65, v64, vcc
	v_cmp_gt_i32_e32 vcc, 0, v1
	v_not_b32_e32 v180, v4
	v_or_b32_e32 v181, 0x80000000, v4
	v_cndmask_b32_e32 v1, v67, v66, vcc
	v_cmp_gt_i32_e32 vcc, 0, v2
	v_not_b32_e32 v182, v5
	v_or_b32_e32 v183, 0x80000000, v5
	v_cndmask_b32_e32 v2, v85, v80, vcc
	v_cmp_gt_i32_e32 vcc, 0, v3
	v_mfma_f32_32x32x16_bf16 v[32:47], v[188:191], v[68:71], v[32:47]
	v_or_b32_e32 v188, 0x80000000, v7
	v_cndmask_b32_e32 v3, v93, v92, vcc
	v_cmp_gt_i32_e32 vcc, 0, v4
	v_not_b32_e32 v189, v8
	v_or_b32_e32 v190, 0x80000000, v8
	v_cndmask_b32_e32 v4, v181, v180, vcc
	v_cmp_gt_i32_e32 vcc, 0, v5
	v_not_b32_e32 v191, v9
	v_not_b32_e32 v64, v12
	v_cndmask_b32_e32 v5, v183, v182, vcc
	v_cmp_gt_i32_e32 vcc, 0, v6
	v_or_b32_e32 v65, 0x80000000, v12
	s_waitcnt vmcnt(1)
; DI unsigned f2ord(float f) { const unsigned u = __float_as_uint(f); return (u & 0x80000000u) ? ~u : (u | 0x80000000u); }
; DI void peer_topk_phase(const bf16_t* __restrict__ qpk, const bf16_t* __restrict__ subk, int* __restrict__ eidx, float* __restrict__ gout) {
;     ...
; #pragma unroll
;             for (int nb = 0; nb < 4; ++nb)
; #pragma unroll
;                 for (int i = 0; i < 16; ++i) {
;                     const int n = nb * 32 + (i & 3) + 8 * (i >> 2) + 4 * h;
;                     key[nb * 16 + i] = (f2ord(acc[nb][i]) & ~127u) | (unsigned)(127 - n);
;                 }
	v_mfma_f32_32x32x16_bf16 v[16:31], v[206:209], v[68:71], v[16:31]
	v_cndmask_b32_e32 v6, v185, v184, vcc
	v_cmp_gt_i32_e32 vcc, 0, v7
	v_and_or_b32 v0, v0, s17, v100
	v_and_or_b32 v1, v1, s17, v101
	v_cndmask_b32_e32 v7, v188, v187, vcc
	v_cmp_gt_i32_e32 vcc, 0, v8
	v_and_or_b32 v2, v2, s17, v102
	v_and_or_b32 v3, v3, s17, v103
	v_cndmask_b32_e32 v8, v190, v189, vcc
	v_cmp_gt_i32_e32 vcc, 0, v9
	v_and_or_b32 v4, v4, s17, v104
	v_and_or_b32 v5, v5, s17, v105
	v_cndmask_b32_e32 v9, v198, v191, vcc
	v_cmp_gt_i32_e32 vcc, 0, v10
	v_and_or_b32 v6, v6, s17, v106
	v_and_or_b32 v7, v7, s17, v107
	v_cndmask_b32_e32 v10, v200, v199, vcc
	v_cmp_gt_i32_e32 vcc, 0, v11
	v_and_or_b32 v8, v8, s17, v108
	v_and_or_b32 v9, v9, s17, v109
	v_cndmask_b32_e32 v11, v202, v201, vcc
	v_cmp_gt_i32_e32 vcc, 0, v12
	v_and_or_b32 v10, v10, s17, v110
	v_and_or_b32 v11, v11, s17, v111
	v_cndmask_b32_e32 v12, v65, v64, vcc
	v_not_b32_e32 v64, v13
	v_or_b32_e32 v65, 0x80000000, v13
	v_cmp_gt_i32_e32 vcc, 0, v13
	v_and_or_b32 v12, v12, s17, v112
	s_nop 0
	v_cndmask_b32_e32 v13, v65, v64, vcc
	v_not_b32_e32 v64, v14
	v_or_b32_e32 v65, 0x80000000, v14
	v_cmp_gt_i32_e32 vcc, 0, v14
	v_and_or_b32 v13, v13, s17, v113
	s_nop 0
	v_cndmask_b32_e32 v14, v65, v64, vcc
	v_not_b32_e32 v64, v15
	v_or_b32_e32 v65, 0x80000000, v15
	v_cmp_gt_i32_e32 vcc, 0, v15
	v_and_or_b32 v14, v14, s17, v114
	s_nop 0
	v_cndmask_b32_e32 v15, v65, v64, vcc
	v_not_b32_e32 v64, v48
	v_or_b32_e32 v65, 0x80000000, v48
	v_cmp_gt_i32_e32 vcc, 0, v48
	v_and_or_b32 v15, v15, s17, v115
	s_nop 0
	v_cndmask_b32_e32 v48, v65, v64, vcc
	v_not_b32_e32 v64, v49
	v_or_b32_e32 v65, 0x80000000, v49
	v_cmp_gt_i32_e32 vcc, 0, v49
	v_and_or_b32 v48, v48, s17, v116
	s_nop 0
	v_cndmask_b32_e32 v49, v65, v64, vcc
	v_not_b32_e32 v64, v50
	v_or_b32_e32 v65, 0x80000000, v50
	v_cmp_gt_i32_e32 vcc, 0, v50
	v_and_or_b32 v49, v49, s17, v117
	s_nop 0
	v_cndmask_b32_e32 v50, v65, v64, vcc
	v_not_b32_e32 v64, v51
	v_or_b32_e32 v65, 0x80000000, v51
	v_cmp_gt_i32_e32 vcc, 0, v51
	v_and_or_b32 v50, v50, s17, v118
	s_nop 0
	v_cndmask_b32_e32 v51, v65, v64, vcc
	v_not_b32_e32 v64, v52
	v_or_b32_e32 v65, 0x80000000, v52
	v_cmp_gt_i32_e32 vcc, 0, v52
	v_and_or_b32 v51, v51, s17, v119
	s_nop 0
	v_cndmask_b32_e32 v52, v65, v64, vcc
	v_not_b32_e32 v64, v53
	v_or_b32_e32 v65, 0x80000000, v53
	v_cmp_gt_i32_e32 vcc, 0, v53
	v_and_or_b32 v52, v52, s17, v120
	s_nop 0
	v_cndmask_b32_e32 v53, v65, v64, vcc
	v_not_b32_e32 v64, v54
	v_or_b32_e32 v65, 0x80000000, v54
	v_cmp_gt_i32_e32 vcc, 0, v54
	v_and_or_b32 v53, v53, s17, v121
	s_nop 0
	v_cndmask_b32_e32 v54, v65, v64, vcc
	v_not_b32_e32 v64, v55
	v_or_b32_e32 v65, 0x80000000, v55
	v_cmp_gt_i32_e32 vcc, 0, v55
	v_and_or_b32 v54, v54, s17, v122
	s_nop 0
	v_cndmask_b32_e32 v55, v65, v64, vcc
	v_not_b32_e32 v64, v56
	v_or_b32_e32 v65, 0x80000000, v56
	v_cmp_gt_i32_e32 vcc, 0, v56
	v_and_or_b32 v55, v55, s17, v123
	s_nop 0
	v_cndmask_b32_e32 v56, v65, v64, vcc
	v_not_b32_e32 v64, v57
	v_or_b32_e32 v65, 0x80000000, v57
	v_cmp_gt_i32_e32 vcc, 0, v57
	v_and_or_b32 v56, v56, s17, v124
	s_nop 0
	v_cndmask_b32_e32 v57, v65, v64, vcc
	v_not_b32_e32 v64, v58
	v_or_b32_e32 v65, 0x80000000, v58
	v_cmp_gt_i32_e32 vcc, 0, v58
	v_and_or_b32 v57, v57, s17, v125
	s_nop 0
	v_cndmask_b32_e32 v58, v65, v64, vcc
	v_not_b32_e32 v64, v59
	v_or_b32_e32 v65, 0x80000000, v59
	v_cmp_gt_i32_e32 vcc, 0, v59
	v_and_or_b32 v58, v58, s17, v126
	s_nop 0
	v_cndmask_b32_e32 v59, v65, v64, vcc
	v_not_b32_e32 v64, v60
	v_or_b32_e32 v65, 0x80000000, v60
	v_cmp_gt_i32_e32 vcc, 0, v60
	v_and_or_b32 v59, v59, s17, v127
	s_nop 0
	v_cndmask_b32_e32 v60, v65, v64, vcc
	v_not_b32_e32 v64, v61
	v_or_b32_e32 v65, 0x80000000, v61
	v_cmp_gt_i32_e32 vcc, 0, v61
	v_and_or_b32 v60, v60, s17, v128
	s_nop 0
	v_cndmask_b32_e32 v61, v65, v64, vcc
	v_not_b32_e32 v64, v62
	v_or_b32_e32 v65, 0x80000000, v62
	v_cmp_gt_i32_e32 vcc, 0, v62
	v_and_or_b32 v61, v61, s17, v129
	s_nop 0
	v_cndmask_b32_e32 v62, v65, v64, vcc
	v_not_b32_e32 v64, v63
	v_or_b32_e32 v65, 0x80000000, v63
	v_cmp_gt_i32_e32 vcc, 0, v63
	v_and_or_b32 v62, v62, s17, v130
	s_nop 0
	v_cndmask_b32_e32 v63, v65, v64, vcc
	v_not_b32_e32 v64, v32
	v_or_b32_e32 v65, 0x80000000, v32
	v_cmp_gt_i32_e32 vcc, 0, v32
	v_and_or_b32 v63, v63, s17, v131
	s_nop 0
	v_cndmask_b32_e32 v32, v65, v64, vcc
	v_not_b32_e32 v64, v33
	v_or_b32_e32 v65, 0x80000000, v33
	v_cmp_gt_i32_e32 vcc, 0, v33
	v_and_or_b32 v32, v32, s17, v132
	s_nop 0
	v_cndmask_b32_e32 v33, v65, v64, vcc
	v_not_b32_e32 v64, v34
	v_or_b32_e32 v65, 0x80000000, v34
	v_cmp_gt_i32_e32 vcc, 0, v34
	v_and_or_b32 v33, v33, s17, v133
	s_nop 0
	v_cndmask_b32_e32 v34, v65, v64, vcc
	v_not_b32_e32 v64, v35
	v_or_b32_e32 v65, 0x80000000, v35
	v_cmp_gt_i32_e32 vcc, 0, v35
	v_and_or_b32 v34, v34, s17, v134
	s_nop 0
	v_cndmask_b32_e32 v35, v65, v64, vcc
	v_not_b32_e32 v64, v36
	v_or_b32_e32 v65, 0x80000000, v36
	v_cmp_gt_i32_e32 vcc, 0, v36
	v_and_or_b32 v35, v35, s17, v135
	s_nop 0
	v_cndmask_b32_e32 v36, v65, v64, vcc
	v_not_b32_e32 v64, v37
	v_or_b32_e32 v65, 0x80000000, v37
	v_cmp_gt_i32_e32 vcc, 0, v37
	v_and_or_b32 v36, v36, s17, v136
	s_nop 0
	v_cndmask_b32_e32 v37, v65, v64, vcc
	v_not_b32_e32 v64, v38
	v_or_b32_e32 v65, 0x80000000, v38
	v_cmp_gt_i32_e32 vcc, 0, v38
	v_and_or_b32 v37, v37, s17, v137
	s_nop 0
	v_cndmask_b32_e32 v38, v65, v64, vcc
	v_not_b32_e32 v64, v39
	v_or_b32_e32 v65, 0x80000000, v39
	v_cmp_gt_i32_e32 vcc, 0, v39
	v_and_or_b32 v38, v38, s17, v138
	s_nop 0
	v_cndmask_b32_e32 v39, v65, v64, vcc
	v_not_b32_e32 v64, v40
	v_or_b32_e32 v65, 0x80000000, v40
	v_cmp_gt_i32_e32 vcc, 0, v40
	v_and_or_b32 v39, v39, s17, v139
	s_nop 0
; DI unsigned f2ord(float f) { const unsigned u = __float_as_uint(f); return (u & 0x80000000u) ? ~u : (u | 0x80000000u); }
; DI void peer_topk_phase(const bf16_t* __restrict__ qpk, const bf16_t* __restrict__ subk, int* __restrict__ eidx, float* __restrict__ gout) {
;     ...
; #pragma unroll
;             for (int nb = 0; nb < 4; ++nb)
; #pragma unroll
;                 for (int i = 0; i < 16; ++i) {
;                     const int n = nb * 32 + (i & 3) + 8 * (i >> 2) + 4 * h;
;                     key[nb * 16 + i] = (f2ord(acc[nb][i]) & ~127u) | (unsigned)(127 - n);
;                 }
;             unsigned g0[16], g1[16], g2[16], g3[16];
; #pragma unroll
;             for (int i = 0; i < 16; ++i) { g0[i] = key[i]; g1[i] = key[16 + i]; g2[i] = key[32 + i]; g3[i] = key[48 + i]; }
; #pragma unroll
;             for (int n = 0; n < 63; ++n) { cex(g0[SORT16[n][0]], g0[SORT16[n][1]]); cex(g1[SORT16[n][0]], g1[SORT16[n][1]]); cex(g2[SORT16[n][0]], g2[SORT16[n][1]]); cex(g3[SORT16[n][0]], g3[SORT16[n][1]]); }
	v_cndmask_b32_e32 v40, v65, v64, vcc
	v_not_b32_e32 v64, v41
	v_or_b32_e32 v65, 0x80000000, v41
	v_cmp_gt_i32_e32 vcc, 0, v41
	v_and_or_b32 v40, v40, s17, v140
	s_nop 0
	v_cndmask_b32_e32 v41, v65, v64, vcc
	v_not_b32_e32 v64, v42
	v_or_b32_e32 v65, 0x80000000, v42
	v_cmp_gt_i32_e32 vcc, 0, v42
	v_and_or_b32 v41, v41, s17, v141
	s_nop 0
	v_cndmask_b32_e32 v42, v65, v64, vcc
	v_not_b32_e32 v64, v43
	v_or_b32_e32 v65, 0x80000000, v43
	v_cmp_gt_i32_e32 vcc, 0, v43
	v_and_or_b32 v42, v42, s17, v142
	s_nop 0
	v_cndmask_b32_e32 v43, v65, v64, vcc
	v_not_b32_e32 v64, v44
	v_or_b32_e32 v65, 0x80000000, v44
	v_cmp_gt_i32_e32 vcc, 0, v44
	v_and_or_b32 v43, v43, s17, v143
	s_nop 0
	v_cndmask_b32_e32 v44, v65, v64, vcc
	v_not_b32_e32 v64, v45
	v_or_b32_e32 v65, 0x80000000, v45
	v_cmp_gt_i32_e32 vcc, 0, v45
	v_and_or_b32 v44, v44, s17, v149
	s_nop 0
	v_cndmask_b32_e32 v45, v65, v64, vcc
	v_not_b32_e32 v64, v46
	v_or_b32_e32 v65, 0x80000000, v46
	v_cmp_gt_i32_e32 vcc, 0, v46
	v_and_or_b32 v45, v45, s17, v150
	s_nop 0
	v_cndmask_b32_e32 v46, v65, v64, vcc
	v_not_b32_e32 v64, v47
	v_or_b32_e32 v65, 0x80000000, v47
	v_cmp_gt_i32_e32 vcc, 0, v47
	v_and_or_b32 v46, v46, s17, v151
	s_nop 0
	v_cndmask_b32_e32 v47, v65, v64, vcc
	v_not_b32_e32 v64, v16
	v_or_b32_e32 v65, 0x80000000, v16
	v_cmp_gt_i32_e32 vcc, 0, v16
	v_and_or_b32 v47, v47, s17, v152
	s_nop 0
	v_cndmask_b32_e32 v16, v65, v64, vcc
	v_not_b32_e32 v64, v17
	v_or_b32_e32 v65, 0x80000000, v17
	v_cmp_gt_i32_e32 vcc, 0, v17
	v_and_or_b32 v16, v16, s17, v153
	s_nop 0
	v_cndmask_b32_e32 v17, v65, v64, vcc
	v_not_b32_e32 v64, v18
	v_or_b32_e32 v65, 0x80000000, v18
	v_cmp_gt_i32_e32 vcc, 0, v18
	v_and_or_b32 v17, v17, s17, v154
	s_nop 0
	v_cndmask_b32_e32 v18, v65, v64, vcc
	v_not_b32_e32 v64, v19
	v_or_b32_e32 v65, 0x80000000, v19
	v_cmp_gt_i32_e32 vcc, 0, v19
	v_and_or_b32 v18, v18, s17, v155
	s_nop 0
	v_cndmask_b32_e32 v19, v65, v64, vcc
	v_not_b32_e32 v64, v20
	v_or_b32_e32 v65, 0x80000000, v20
	v_cmp_gt_i32_e32 vcc, 0, v20
	v_and_or_b32 v19, v19, s17, v156
	s_nop 0
	v_cndmask_b32_e32 v20, v65, v64, vcc
	v_not_b32_e32 v64, v21
	v_or_b32_e32 v65, 0x80000000, v21
	v_cmp_gt_i32_e32 vcc, 0, v21
	v_and_or_b32 v20, v20, s17, v157
	s_nop 0
	v_cndmask_b32_e32 v21, v65, v64, vcc
	v_not_b32_e32 v64, v22
	v_or_b32_e32 v65, 0x80000000, v22
	v_cmp_gt_i32_e32 vcc, 0, v22
	v_and_or_b32 v21, v21, s17, v158
	s_nop 0
	v_cndmask_b32_e32 v22, v65, v64, vcc
	v_not_b32_e32 v64, v23
	v_or_b32_e32 v65, 0x80000000, v23
	v_cmp_gt_i32_e32 vcc, 0, v23
	v_and_or_b32 v22, v22, s17, v159
	s_nop 0
	v_cndmask_b32_e32 v23, v65, v64, vcc
	v_not_b32_e32 v64, v24
	v_or_b32_e32 v65, 0x80000000, v24
	v_cmp_gt_i32_e32 vcc, 0, v24
	v_and_or_b32 v23, v23, s17, v160
	s_nop 0
	v_cndmask_b32_e32 v24, v65, v64, vcc
	v_not_b32_e32 v64, v25
	v_or_b32_e32 v65, 0x80000000, v25
	v_cmp_gt_i32_e32 vcc, 0, v25
	v_and_or_b32 v24, v24, s17, v161
	s_nop 0
	v_cndmask_b32_e32 v25, v65, v64, vcc
	v_not_b32_e32 v64, v26
	v_or_b32_e32 v65, 0x80000000, v26
	v_cmp_gt_i32_e32 vcc, 0, v26
	v_and_or_b32 v25, v25, s17, v162
	s_nop 0
	v_cndmask_b32_e32 v26, v65, v64, vcc
	v_not_b32_e32 v64, v27
	v_or_b32_e32 v65, 0x80000000, v27
	v_cmp_gt_i32_e32 vcc, 0, v27
	v_and_or_b32 v26, v26, s17, v163
	s_nop 0
	v_cndmask_b32_e32 v27, v65, v64, vcc
	v_not_b32_e32 v64, v28
	v_or_b32_e32 v65, 0x80000000, v28
	v_cmp_gt_i32_e32 vcc, 0, v28
	v_and_or_b32 v27, v27, s17, v164
	s_nop 0
	v_cndmask_b32_e32 v28, v65, v64, vcc
	v_not_b32_e32 v64, v29
	v_or_b32_e32 v65, 0x80000000, v29
	v_cmp_gt_i32_e32 vcc, 0, v29
	v_and_or_b32 v28, v28, s17, v165
	s_nop 0
	v_cndmask_b32_e32 v29, v65, v64, vcc
	v_not_b32_e32 v64, v30
	v_or_b32_e32 v65, 0x80000000, v30
	v_cmp_gt_i32_e32 vcc, 0, v30
	v_and_or_b32 v29, v29, s17, v166
	s_nop 0
	v_cndmask_b32_e32 v30, v65, v64, vcc
	v_not_b32_e32 v64, v31
	v_or_b32_e32 v65, 0x80000000, v31
	v_cmp_gt_i32_e32 vcc, 0, v31
	v_and_or_b32 v30, v30, s17, v167
	s_nop 0
	v_cndmask_b32_e32 v31, v65, v64, vcc
	v_max_u32_e32 v64, v0, v1
	v_min_u32_e32 v0, v0, v1
	v_max_u32_e32 v1, v48, v49
	v_min_u32_e32 v48, v48, v49
	v_max_u32_e32 v49, v32, v33
	v_min_u32_e32 v32, v32, v33
	v_max_u32_e32 v33, v16, v17
	v_min_u32_e32 v16, v16, v17
	v_max_u32_e32 v17, v2, v3
	v_min_u32_e32 v2, v2, v3
	v_max_u32_e32 v3, v50, v51
	v_min_u32_e32 v50, v50, v51
	v_max_u32_e32 v51, v34, v35
	v_min_u32_e32 v34, v34, v35
	v_max_u32_e32 v35, v18, v19
	v_min_u32_e32 v18, v18, v19
	v_max_u32_e32 v19, v64, v17
	v_min_u32_e32 v17, v64, v17
	v_max_u32_e32 v64, v1, v3
	v_min_u32_e32 v1, v1, v3
	v_max_u32_e32 v3, v49, v51
	v_min_u32_e32 v49, v49, v51
	v_max_u32_e32 v51, v33, v35
	v_min_u32_e32 v33, v33, v35
	v_max_u32_e32 v35, v0, v2
	v_min_u32_e32 v0, v0, v2
	v_max_u32_e32 v2, v48, v50
	v_min_u32_e32 v48, v48, v50
	v_max_u32_e32 v50, v32, v34
	v_min_u32_e32 v32, v32, v34
	v_max_u32_e32 v34, v16, v18
	v_min_u32_e32 v16, v16, v18
	v_max_u32_e32 v18, v35, v17
	v_min_u32_e32 v17, v35, v17
	v_max_u32_e32 v35, v2, v1
	v_min_u32_e32 v1, v2, v1
	v_max_u32_e32 v2, v50, v49
	v_min_u32_e32 v49, v50, v49
	v_max_u32_e32 v50, v34, v33
	v_min_u32_e32 v33, v34, v33
	v_max_u32_e32 v34, v4, v5
	v_min_u32_e32 v4, v4, v5
	v_max_u32_e32 v5, v52, v53
	v_min_u32_e32 v52, v52, v53
	v_max_u32_e32 v53, v36, v37
	v_min_u32_e32 v36, v36, v37
	v_max_u32_e32 v37, v20, v21
	v_min_u32_e32 v20, v20, v21
	v_max_u32_e32 v21, v6, v7
	v_min_u32_e32 v6, v6, v7
	v_max_u32_e32 v7, v54, v55
	v_min_u32_e32 v54, v54, v55
	v_max_u32_e32 v55, v38, v39
	v_min_u32_e32 v38, v38, v39
	v_max_u32_e32 v39, v22, v23
	v_min_u32_e32 v22, v22, v23
	v_max_u32_e32 v23, v34, v21
	v_min_u32_e32 v21, v34, v21
	v_max_u32_e32 v34, v5, v7
	v_min_u32_e32 v5, v5, v7
; DI void peer_topk_phase(const bf16_t* __restrict__ qpk, const bf16_t* __restrict__ subk, int* __restrict__ eidx, float* __restrict__ gout) {
;     ...
;             unsigned g0[16], g1[16], g2[16], g3[16];
; #pragma unroll
;             for (int i = 0; i < 16; ++i) { g0[i] = key[i]; g1[i] = key[16 + i]; g2[i] = key[32 + i]; g3[i] = key[48 + i]; }
; #pragma unroll
;             for (int n = 0; n < 63; ++n) { cex(g0[SORT16[n][0]], g0[SORT16[n][1]]); cex(g1[SORT16[n][0]], g1[SORT16[n][1]]); cex(g2[SORT16[n][0]], g2[SORT16[n][1]]); cex(g3[SORT16[n][0]], g3[SORT16[n][1]]); }
	v_max_u32_e32 v7, v53, v55
	v_min_u32_e32 v53, v53, v55
	v_max_u32_e32 v55, v37, v39
	v_min_u32_e32 v37, v37, v39
	v_max_u32_e32 v39, v4, v6
	v_min_u32_e32 v4, v4, v6
	v_max_u32_e32 v6, v52, v54
	v_min_u32_e32 v52, v52, v54
	v_max_u32_e32 v54, v36, v38
	v_min_u32_e32 v36, v36, v38
	v_max_u32_e32 v38, v20, v22
	v_min_u32_e32 v20, v20, v22
	v_max_u32_e32 v22, v39, v21
	v_min_u32_e32 v21, v39, v21
	v_max_u32_e32 v39, v6, v5
	v_min_u32_e32 v5, v6, v5
	v_max_u32_e32 v6, v54, v53
	v_min_u32_e32 v53, v54, v53
	v_max_u32_e32 v54, v38, v37
	v_min_u32_e32 v37, v38, v37
	v_max_u32_e32 v38, v19, v23
	v_min_u32_e32 v19, v19, v23
	v_max_u32_e32 v23, v64, v34
	v_min_u32_e32 v34, v64, v34
	v_max_u32_e32 v64, v3, v7
	v_min_u32_e32 v3, v3, v7
	v_max_u32_e32 v7, v51, v55
	v_min_u32_e32 v51, v51, v55
	v_max_u32_e32 v55, v17, v21
	v_min_u32_e32 v17, v17, v21
	v_max_u32_e32 v21, v1, v5
	v_min_u32_e32 v1, v1, v5
	v_max_u32_e32 v5, v49, v53
	v_min_u32_e32 v49, v49, v53
	v_max_u32_e32 v53, v33, v37
	v_min_u32_e32 v33, v33, v37
	v_max_u32_e32 v37, v55, v19
	v_min_u32_e32 v19, v55, v19
	v_max_u32_e32 v55, v21, v34
	v_min_u32_e32 v21, v21, v34
	v_max_u32_e32 v34, v5, v3
	v_min_u32_e32 v3, v5, v3
	v_max_u32_e32 v5, v53, v51
	v_min_u32_e32 v51, v53, v51
	v_max_u32_e32 v53, v18, v22
	v_min_u32_e32 v18, v18, v22
	v_max_u32_e32 v22, v35, v39
	v_min_u32_e32 v35, v35, v39
	v_max_u32_e32 v39, v2, v6
	v_min_u32_e32 v2, v2, v6
	v_max_u32_e32 v6, v50, v54
	v_min_u32_e32 v50, v50, v54
	v_max_u32_e32 v54, v0, v4
	v_min_u32_e32 v0, v0, v4
	v_max_u32_e32 v4, v48, v52
	v_min_u32_e32 v48, v48, v52
	v_max_u32_e32 v52, v32, v36
	v_min_u32_e32 v32, v32, v36
	v_max_u32_e32 v36, v16, v20
	v_min_u32_e32 v16, v16, v20
	v_max_u32_e32 v20, v54, v18
	v_min_u32_e32 v18, v54, v18
	v_max_u32_e32 v54, v4, v35
	v_min_u32_e32 v4, v4, v35
	v_max_u32_e32 v35, v52, v2
	v_min_u32_e32 v2, v52, v2
	v_max_u32_e32 v52, v36, v50
	v_min_u32_e32 v36, v36, v50
	v_max_u32_e32 v50, v53, v37
	v_min_u32_e32 v37, v53, v37
	v_max_u32_e32 v53, v22, v55
	v_min_u32_e32 v22, v22, v55
	v_max_u32_e32 v55, v39, v34
	v_min_u32_e32 v34, v39, v34
	v_max_u32_e32 v39, v6, v5
	v_min_u32_e32 v5, v6, v5
	v_max_u32_e32 v6, v20, v19
	v_min_u32_e32 v19, v20, v19
	v_max_u32_e32 v20, v54, v21
	v_min_u32_e32 v21, v54, v21
	v_max_u32_e32 v54, v35, v3
	v_min_u32_e32 v3, v35, v3
	v_max_u32_e32 v35, v52, v51
	v_min_u32_e32 v51, v52, v51
	v_max_u32_e32 v52, v18, v17
	v_min_u32_e32 v17, v18, v17
	v_max_u32_e32 v18, v4, v1
	v_min_u32_e32 v1, v4, v1
	v_max_u32_e32 v4, v2, v49
	v_min_u32_e32 v2, v2, v49
	v_max_u32_e32 v49, v36, v33
	v_min_u32_e32 v33, v36, v33
	v_max_u32_e32 v36, v8, v9
	v_min_u32_e32 v8, v8, v9
	v_max_u32_e32 v9, v56, v57
	v_min_u32_e32 v56, v56, v57
	v_max_u32_e32 v57, v40, v41
	v_min_u32_e32 v40, v40, v41
	v_max_u32_e32 v41, v24, v25
	v_min_u32_e32 v24, v24, v25
	v_max_u32_e32 v25, v10, v11
	v_min_u32_e32 v10, v10, v11
	v_max_u32_e32 v11, v58, v59
	v_min_u32_e32 v58, v58, v59
	v_max_u32_e32 v59, v42, v43
	v_min_u32_e32 v42, v42, v43
	v_max_u32_e32 v43, v26, v27
	v_min_u32_e32 v26, v26, v27
	v_and_or_b32 v31, v31, s17, v168
	v_max_u32_e32 v27, v36, v25
	v_min_u32_e32 v25, v36, v25
	v_max_u32_e32 v36, v9, v11
	v_min_u32_e32 v9, v9, v11
	v_max_u32_e32 v11, v57, v59
	v_min_u32_e32 v57, v57, v59
	v_max_u32_e32 v59, v41, v43
	v_min_u32_e32 v41, v41, v43
	v_max_u32_e32 v43, v8, v10
	v_min_u32_e32 v8, v8, v10
	v_max_u32_e32 v10, v56, v58
	v_min_u32_e32 v56, v56, v58
	v_max_u32_e32 v58, v40, v42
	v_min_u32_e32 v40, v40, v42
	v_max_u32_e32 v42, v24, v26
	v_min_u32_e32 v24, v24, v26
	v_max_u32_e32 v26, v43, v25
	v_min_u32_e32 v25, v43, v25
	v_max_u32_e32 v43, v10, v9
	v_min_u32_e32 v9, v10, v9
	v_max_u32_e32 v10, v58, v57
	v_min_u32_e32 v57, v58, v57
	v_max_u32_e32 v58, v42, v41
	v_min_u32_e32 v41, v42, v41
	v_max_u32_e32 v42, v12, v13
	v_min_u32_e32 v12, v12, v13
	v_max_u32_e32 v13, v60, v61
	v_min_u32_e32 v60, v60, v61
	v_max_u32_e32 v61, v44, v45
	v_min_u32_e32 v44, v44, v45
	v_max_u32_e32 v45, v28, v29
	v_min_u32_e32 v28, v28, v29
	v_max_u32_e32 v29, v14, v15
	v_min_u32_e32 v14, v14, v15
	v_max_u32_e32 v15, v62, v63
	v_min_u32_e32 v62, v62, v63
	v_max_u32_e32 v63, v46, v47
	v_min_u32_e32 v46, v46, v47
	v_max_u32_e32 v47, v30, v31
	v_min_u32_e32 v30, v30, v31
	v_max_u32_e32 v31, v42, v29
	v_min_u32_e32 v29, v42, v29
	v_max_u32_e32 v42, v13, v15
	v_min_u32_e32 v13, v13, v15
	v_max_u32_e32 v15, v61, v63
	v_min_u32_e32 v61, v61, v63
	v_max_u32_e32 v63, v45, v47
	v_min_u32_e32 v45, v45, v47
	v_max_u32_e32 v47, v12, v14
	v_min_u32_e32 v12, v12, v14
	v_max_u32_e32 v14, v60, v62
	v_min_u32_e32 v60, v60, v62
	v_max_u32_e32 v62, v44, v46
	v_min_u32_e32 v44, v44, v46
	v_max_u32_e32 v46, v28, v30
	v_min_u32_e32 v28, v28, v30
	v_max_u32_e32 v30, v47, v29
	v_min_u32_e32 v29, v47, v29
	v_max_u32_e32 v47, v14, v13
	v_min_u32_e32 v13, v14, v13
	v_max_u32_e32 v14, v62, v61
	v_min_u32_e32 v61, v62, v61
	v_max_u32_e32 v62, v46, v45
	v_min_u32_e32 v45, v46, v45
	v_max_u32_e32 v46, v27, v31
	v_min_u32_e32 v27, v27, v31
	v_max_u32_e32 v31, v36, v42
	v_min_u32_e32 v36, v36, v42
	v_max_u32_e32 v42, v11, v15
	v_min_u32_e32 v11, v11, v15
	v_max_u32_e32 v15, v59, v63
	v_min_u32_e32 v59, v59, v63
	v_max_u32_e32 v63, v25, v29
	v_min_u32_e32 v25, v25, v29
	v_max_u32_e32 v29, v9, v13
	v_min_u32_e32 v9, v9, v13
	v_max_u32_e32 v13, v57, v61
	v_min_u32_e32 v57, v57, v61
	v_max_u32_e32 v61, v41, v45
	v_min_u32_e32 v41, v41, v45
	v_max_u32_e32 v45, v63, v27
	v_min_u32_e32 v27, v63, v27
	v_max_u32_e32 v63, v29, v36
	v_min_u32_e32 v29, v29, v36
	v_max_u32_e32 v36, v13, v11
	v_min_u32_e32 v11, v13, v11
	v_max_u32_e32 v13, v61, v59
	v_min_u32_e32 v59, v61, v59
; DI void merge_top16(unsigned (&A)[16], const unsigned (&B)[16]) {
; #pragma unroll
;     for (int i = 0; i < 16; ++i) A[i] = max(A[i], B[15 - i]);
; #pragma unroll
;     for (int n = 0; n < 32; ++n) cex(A[BMERGE16[n][0]], A[BMERGE16[n][1]]);
; }
; DI void peer_topk_phase(const bf16_t* __restrict__ qpk, const bf16_t* __restrict__ subk, int* __restrict__ eidx, float* __restrict__ gout) {
;     ...
;             unsigned g0[16], g1[16], g2[16], g3[16];
; #pragma unroll
;             for (int i = 0; i < 16; ++i) { g0[i] = key[i]; g1[i] = key[16 + i]; g2[i] = key[32 + i]; g3[i] = key[48 + i]; }
; #pragma unroll
;             for (int n = 0; n < 63; ++n) { cex(g0[SORT16[n][0]], g0[SORT16[n][1]]); cex(g1[SORT16[n][0]], g1[SORT16[n][1]]); cex(g2[SORT16[n][0]], g2[SORT16[n][1]]); cex(g3[SORT16[n][0]], g3[SORT16[n][1]]); }
;             merge_top16(g0, g1); merge_top16(g2, g3); merge_top16(g0, g2);
;             unsigned pb[16];
; #pragma unroll
;             for (int i = 0; i < 16; ++i) pb[i] = (unsigned)__shfl_xor((int)g0[i], 32);
;             merge_top16(g0, pb);
	v_max_u32_e32 v61, v26, v30
	v_min_u32_e32 v26, v26, v30
	v_max_u32_e32 v30, v43, v47
	v_min_u32_e32 v43, v43, v47
	v_max_u32_e32 v47, v10, v14
	v_min_u32_e32 v10, v10, v14
	v_max_u32_e32 v14, v58, v62
	v_min_u32_e32 v58, v58, v62
	v_max_u32_e32 v62, v8, v12
	v_min_u32_e32 v8, v8, v12
	v_max_u32_e32 v12, v56, v60
	v_min_u32_e32 v56, v56, v60
	v_max_u32_e32 v60, v40, v44
	v_min_u32_e32 v40, v40, v44
	v_max_u32_e32 v44, v24, v28
	v_min_u32_e32 v24, v24, v28
	v_max_u32_e32 v28, v62, v26
	v_min_u32_e32 v26, v62, v26
	v_max_u32_e32 v62, v12, v43
	v_min_u32_e32 v12, v12, v43
	v_max_u32_e32 v43, v60, v10
	v_min_u32_e32 v10, v60, v10
	v_max_u32_e32 v60, v44, v58
	v_min_u32_e32 v44, v44, v58
	v_max_u32_e32 v58, v61, v45
	v_min_u32_e32 v45, v61, v45
	v_max_u32_e32 v61, v30, v63
	v_min_u32_e32 v30, v30, v63
	v_max_u32_e32 v63, v47, v36
	v_min_u32_e32 v36, v47, v36
	v_max_u32_e32 v47, v14, v13
	v_min_u32_e32 v13, v14, v13
	v_max_u32_e32 v14, v28, v27
	v_min_u32_e32 v27, v28, v27
	v_max_u32_e32 v28, v62, v29
	v_min_u32_e32 v29, v62, v29
	v_max_u32_e32 v62, v43, v11
	v_min_u32_e32 v11, v43, v11
	v_max_u32_e32 v43, v60, v59
	v_min_u32_e32 v59, v60, v59
	v_max_u32_e32 v60, v26, v25
	v_min_u32_e32 v25, v26, v25
	v_max_u32_e32 v26, v12, v9
	v_min_u32_e32 v9, v12, v9
	v_max_u32_e32 v12, v10, v57
	v_min_u32_e32 v10, v10, v57
	v_max_u32_e32 v57, v44, v41
	v_min_u32_e32 v41, v44, v41
	v_min_u32_e32 v44, v38, v46
	v_min_u32_e32 v65, v23, v31
	v_min_u32_e32 v66, v64, v42
	v_min_u32_e32 v67, v7, v15
	v_max_u32_e32 v68, v19, v27
	v_min_u32_e32 v19, v19, v27
	v_max_u32_e32 v27, v21, v29
	v_min_u32_e32 v21, v21, v29
	v_max_u32_e32 v29, v3, v11
	v_min_u32_e32 v3, v3, v11
	v_max_u32_e32 v11, v51, v59
	v_min_u32_e32 v51, v51, v59
	v_max_u32_e32 v59, v68, v44
	v_min_u32_e32 v44, v68, v44
	v_max_u32_e32 v68, v27, v65
	v_min_u32_e32 v27, v27, v65
	v_max_u32_e32 v65, v29, v66
	v_min_u32_e32 v29, v29, v66
	v_max_u32_e32 v66, v11, v67
	v_min_u32_e32 v11, v11, v67
	v_max_u32_e32 v67, v37, v45
	v_min_u32_e32 v37, v37, v45
	v_max_u32_e32 v45, v22, v30
	v_min_u32_e32 v22, v22, v30
	v_max_u32_e32 v30, v34, v36
	v_min_u32_e32 v34, v34, v36
	v_max_u32_e32 v36, v5, v13
	v_min_u32_e32 v5, v5, v13
	v_max_u32_e32 v13, v17, v25
	v_min_u32_e32 v17, v17, v25
	v_max_u32_e32 v25, v1, v9
	v_min_u32_e32 v1, v1, v9
	v_max_u32_e32 v9, v2, v10
	v_min_u32_e32 v2, v2, v10
	v_max_u32_e32 v10, v33, v41
	v_min_u32_e32 v33, v33, v41
	v_max_u32_e32 v41, v13, v37
	v_min_u32_e32 v13, v13, v37
	v_max_u32_e32 v37, v25, v22
	v_min_u32_e32 v22, v25, v22
	v_max_u32_e32 v25, v9, v34
	v_min_u32_e32 v9, v9, v34
	v_max_u32_e32 v34, v10, v5
	v_min_u32_e32 v5, v10, v5
	v_max_u32_e32 v10, v67, v59
	v_min_u32_e32 v59, v67, v59
	v_max_u32_e32 v67, v45, v68
	v_min_u32_e32 v45, v45, v68
	v_max_u32_e32 v68, v30, v65
	v_min_u32_e32 v30, v30, v65
	v_max_u32_e32 v65, v36, v66
	v_min_u32_e32 v36, v36, v66
	v_max_u32_e32 v66, v41, v44
	v_min_u32_e32 v41, v41, v44
	v_max_u32_e32 v44, v37, v27
	v_min_u32_e32 v27, v37, v27
	v_max_u32_e32 v37, v25, v29
	v_min_u32_e32 v25, v25, v29
	v_max_u32_e32 v29, v34, v11
	v_min_u32_e32 v11, v34, v11
	v_max_u32_e32 v34, v13, v19
	v_min_u32_e32 v13, v13, v19
	v_max_u32_e32 v19, v22, v21
	v_min_u32_e32 v21, v22, v21
	v_max_u32_e32 v22, v9, v3
	v_min_u32_e32 v3, v9, v3
	v_max_u32_e32 v9, v5, v51
	v_min_u32_e32 v5, v5, v51
	v_max_u32_e32 v51, v50, v58
	v_min_u32_e32 v50, v50, v58
	v_max_u32_e32 v58, v53, v61
	v_min_u32_e32 v53, v53, v61
	v_max_u32_e32 v61, v55, v63
	v_min_u32_e32 v55, v55, v63
	v_max_u32_e32 v63, v39, v47
	v_min_u32_e32 v39, v39, v47
	v_max_u32_e32 v47, v52, v60
	v_min_u32_e32 v52, v52, v60
	v_max_u32_e32 v60, v18, v26
	v_min_u32_e32 v18, v18, v26
	v_max_u32_e32 v26, v4, v12
	v_min_u32_e32 v4, v4, v12
	v_max_u32_e32 v12, v49, v57
	v_min_u32_e32 v49, v49, v57
	v_max_u32_e32 v57, v47, v50
	v_min_u32_e32 v47, v47, v50
	v_max_u32_e32 v50, v60, v53
	v_min_u32_e32 v53, v60, v53
	v_max_u32_e32 v60, v26, v55
	v_min_u32_e32 v26, v26, v55
	v_max_u32_e32 v55, v12, v39
	v_min_u32_e32 v12, v12, v39
	v_max_u32_e32 v39, v6, v14
	v_min_u32_e32 v6, v6, v14
	v_max_u32_e32 v14, v20, v28
	v_min_u32_e32 v20, v20, v28
	v_max_u32_e32 v28, v54, v62
	v_min_u32_e32 v54, v54, v62
	v_max_u32_e32 v62, v35, v43
	v_min_u32_e32 v35, v35, v43
	v_max_u32_e32 v43, v0, v8
	v_min_u32_e32 v0, v0, v8
	v_max_u32_e32 v8, v48, v56
	v_min_u32_e32 v48, v48, v56
	v_max_u32_e32 v56, v32, v40
	v_min_u32_e32 v32, v32, v40
	v_max_u32_e32 v40, v16, v24
	v_min_u32_e32 v16, v16, v24
	v_max_u32_e32 v24, v43, v6
	v_min_u32_e32 v6, v43, v6
	v_max_u32_e32 v43, v8, v20
	v_min_u32_e32 v8, v8, v20
	v_max_u32_e32 v20, v56, v54
	v_min_u32_e32 v54, v56, v54
	v_max_u32_e32 v56, v40, v35
	v_min_u32_e32 v35, v40, v35
	v_max_u32_e32 v40, v39, v57
	v_min_u32_e32 v39, v39, v57
	v_max_u32_e32 v57, v14, v50
	v_min_u32_e32 v14, v14, v50
	v_max_u32_e32 v50, v28, v60
	v_min_u32_e32 v28, v28, v60
	v_max_u32_e32 v60, v62, v55
	v_min_u32_e32 v55, v62, v55
	v_max_u32_e32 v62, v24, v47
	v_min_u32_e32 v24, v24, v47
	v_max_u32_e32 v47, v43, v53
	v_min_u32_e32 v43, v43, v53
	v_max_u32_e32 v53, v20, v26
	v_min_u32_e32 v20, v20, v26
	v_max_u32_e32 v26, v56, v12
	v_min_u32_e32 v12, v56, v12
	v_max_u32_e32 v56, v6, v52
	v_min_u32_e32 v6, v6, v52
	v_max_u32_e32 v52, v8, v18
	v_min_u32_e32 v8, v8, v18
	v_max_u32_e32 v18, v54, v4
	v_min_u32_e32 v4, v54, v4
	v_max_u32_e32 v54, v35, v49
	v_min_u32_e32 v35, v35, v49
	v_min_u32_e32 v49, v51, v10
	v_min_u32_e32 v69, v58, v67
	v_min_u32_e32 v70, v61, v68
	v_min_u32_e32 v71, v63, v65
	v_min_u32_e32 v80, v40, v59
	v_min_u32_e32 v85, v57, v45
	v_min_u32_e32 v92, v50, v30
	v_min_u32_e32 v93, v60, v36
	v_min_u32_e32 v180, v39, v66
; #define MFMA(a, b, c) __builtin_amdgcn_mfma_f32_32x32x16_bf16((a), (b), (c), 0, 0, 0)
; DI void peer_topk_phase(const bf16_t* __restrict__ qpk, const bf16_t* __restrict__ subk, int* __restrict__ eidx, float* __restrict__ gout) {
;     ...
;             const bf16_t* qp = qpk + (size_t)(t0 + r) * 1024 + hh * 128 + c * 64 + h * 8;
;             const bf16_t* kp = subk + ((size_t)(hh * 2 + c) * 128 + r) * 64 + h * 8;
; #pragma unroll
;             for (int ks = 0; ks < 4; ++ks) {
;                 const bf16x8 qfr = *(const bf16x8*)(qp + ks * 16);
; #pragma unroll
;                 for (int nb = 0; nb < 4; ++nb) {
;                     const bf16x8 kf = *(const bf16x8*)(kp + nb * 32 * 64 + ks * 16);
;                     acc[nb] = MFMA(kf, qfr, acc[nb]);
;                 }
;     ...
;             unsigned g0[16], g1[16], g2[16], g3[16];
; #pragma unroll
;             for (int i = 0; i < 16; ++i) { g0[i] = key[i]; g1[i] = key[16 + i]; g2[i] = key[32 + i]; g3[i] = key[48 + i]; }
; #pragma unroll
;             for (int n = 0; n < 63; ++n) { cex(g0[SORT16[n][0]], g0[SORT16[n][1]]); cex(g1[SORT16[n][0]], g1[SORT16[n][1]]); cex(g2[SORT16[n][0]], g2[SORT16[n][1]]); cex(g3[SORT16[n][0]], g3[SORT16[n][1]]); }
;             merge_top16(g0, g1); merge_top16(g2, g3); merge_top16(g0, g2);
;             unsigned pb[16];
; #pragma unroll
;             for (int i = 0; i < 16; ++i) pb[i] = (unsigned)__shfl_xor((int)g0[i], 32);
;             merge_top16(g0, pb);
	v_min_u32_e32 v181, v14, v44
	v_min_u32_e32 v182, v28, v37
	v_min_u32_e32 v183, v55, v29
	v_min_u32_e32 v184, v62, v41
	v_min_u32_e32 v185, v47, v27
	v_min_u32_e32 v187, v53, v25
	v_min_u32_e32 v188, v26, v11
	v_min_u32_e32 v189, v24, v34
	v_min_u32_e32 v190, v43, v19
	v_min_u32_e32 v191, v20, v22
	v_min_u32_e32 v198, v12, v9
	v_min_u32_e32 v199, v56, v13
	v_min_u32_e32 v200, v52, v21
	v_min_u32_e32 v201, v18, v3
	v_min_u32_e32 v202, v54, v5
	v_min_u32_e32 v203, v6, v17
	v_min_u32_e32 v204, v8, v1
	v_min_u32_e32 v205, v4, v2
	v_min_u32_e32 v206, v35, v33
	v_max3_u32 v38, v38, v46, v48
	v_max3_u32 v10, v51, v10, v204
	v_max3_u32 v1, v49, v8, v1
	v_max3_u32 v8, v40, v59, v200
	v_max3_u32 v21, v80, v52, v21
	v_max3_u32 v39, v39, v66, v190
	v_max3_u32 v19, v180, v43, v19
	v_max3_u32 v40, v62, v41, v185
	v_max3_u32 v27, v184, v47, v27
	v_max3_u32 v24, v24, v34, v181
	v_max3_u32 v14, v189, v14, v44
	v_max3_u32 v13, v56, v13, v85
	v_max3_u32 v34, v199, v57, v45
	v_max3_u32 v6, v6, v17, v69
	v_max3_u32 v17, v203, v58, v67
	v_max3_u32 v0, v0, v23, v31
	v_max3_u32 v16, v64, v42, v16
	v_max3_u32 v42, v61, v68, v206
	v_max3_u32 v33, v70, v35, v33
	v_max3_u32 v30, v50, v30, v202
	v_max3_u32 v5, v92, v54, v5
	v_max3_u32 v28, v28, v37, v198
	v_max3_u32 v9, v182, v12, v9
	v_max3_u32 v12, v53, v25, v188
	v_max3_u32 v11, v187, v26, v11
	v_max3_u32 v20, v20, v22, v183
	v_max3_u32 v22, v191, v55, v29
	v_max3_u32 v3, v18, v3, v93
	v_max3_u32 v18, v201, v60, v36
	v_max3_u32 v2, v4, v2, v71
	v_max3_u32 v4, v205, v63, v65
	v_max3_u32 v7, v32, v7, v15
	v_max_u32_e32 v23, v38, v27
	v_min_u32_e32 v27, v38, v27
	v_max_u32_e32 v31, v10, v24
	v_min_u32_e32 v10, v10, v24
	v_max_u32_e32 v24, v1, v14
	v_min_u32_e32 v1, v1, v14
	v_max_u32_e32 v14, v8, v13
	v_min_u32_e32 v8, v8, v13
	v_max_u32_e32 v13, v21, v34
	v_min_u32_e32 v21, v21, v34
	v_max_u32_e32 v34, v39, v6
	v_min_u32_e32 v6, v39, v6
	v_max_u32_e32 v38, v19, v17
	v_min_u32_e32 v17, v19, v17
	v_max_u32_e32 v19, v40, v0
	v_min_u32_e32 v0, v40, v0
	v_max_u32_e32 v15, v16, v11
	v_min_u32_e32 v11, v16, v11
	v_max_u32_e32 v16, v42, v20
	v_min_u32_e32 v20, v42, v20
	v_max_u32_e32 v25, v33, v22
	v_min_u32_e32 v22, v33, v22
	v_max_u32_e32 v26, v30, v3
	v_min_u32_e32 v3, v30, v3
	v_max_u32_e32 v29, v5, v18
	v_min_u32_e32 v5, v5, v18
	v_max_u32_e32 v18, v28, v2
	v_min_u32_e32 v2, v28, v2
	v_max_u32_e32 v28, v9, v4
	v_min_u32_e32 v4, v9, v4
	v_max_u32_e32 v9, v12, v7
	v_min_u32_e32 v7, v12, v7
	v_max_u32_e32 v39, v23, v13
	v_min_u32_e32 v13, v23, v13
	v_max_u32_e32 v23, v31, v34
	v_min_u32_e32 v31, v31, v34
	v_max_u32_e32 v34, v24, v38
	v_min_u32_e32 v24, v24, v38
	v_max_u32_e32 v38, v14, v19
	v_min_u32_e32 v14, v14, v19
	v_max_u32_e32 v19, v27, v21
	v_min_u32_e32 v21, v27, v21
	v_max_u32_e32 v27, v10, v6
	v_min_u32_e32 v6, v10, v6
	v_max_u32_e32 v10, v1, v17
	v_min_u32_e32 v1, v1, v17
	v_max_u32_e32 v17, v8, v0
	v_min_u32_e32 v0, v8, v0
	v_max_u32_e32 v12, v15, v29
	v_min_u32_e32 v15, v15, v29
	v_max_u32_e32 v29, v16, v18
	v_min_u32_e32 v16, v16, v18
	v_max_u32_e32 v18, v25, v28
	v_min_u32_e32 v25, v25, v28
	v_max_u32_e32 v28, v26, v9
	v_min_u32_e32 v9, v26, v9
	v_max_u32_e32 v26, v11, v5
	v_min_u32_e32 v5, v11, v5
	v_max_u32_e32 v11, v20, v2
	v_min_u32_e32 v2, v20, v2
	v_max_u32_e32 v20, v22, v4
	v_min_u32_e32 v4, v22, v4
	v_max_u32_e32 v22, v3, v7
	v_min_u32_e32 v3, v3, v7
	v_max_u32_e32 v8, v39, v34
	v_min_u32_e32 v34, v39, v34
	v_max_u32_e32 v39, v23, v38
	v_min_u32_e32 v23, v23, v38
	v_max_u32_e32 v38, v13, v24
	v_min_u32_e32 v13, v13, v24
	v_max_u32_e32 v24, v31, v14
	v_min_u32_e32 v14, v31, v14
	v_max_u32_e32 v31, v19, v10
	v_min_u32_e32 v10, v19, v10
	v_max_u32_e32 v19, v27, v17
	v_min_u32_e32 v17, v27, v17
	v_max_u32_e32 v27, v21, v1
	v_min_u32_e32 v1, v21, v1
	v_max_u32_e32 v21, v6, v0
	v_max_u32_e32 v30, v12, v18
	v_min_u32_e32 v7, v12, v18
	v_max_u32_e32 v12, v29, v28
	v_min_u32_e32 v18, v29, v28
	v_max_u32_e32 v28, v15, v25
	v_min_u32_e32 v15, v15, v25
	v_max_u32_e32 v25, v16, v9
	v_min_u32_e32 v9, v16, v9
	v_max_u32_e32 v16, v26, v20
	v_min_u32_e32 v20, v26, v20
	v_max_u32_e32 v26, v11, v22
	v_min_u32_e32 v11, v11, v22
	v_max_u32_e32 v22, v5, v4
	v_min_u32_e32 v4, v5, v4
	v_max_u32_e32 v5, v2, v3
	v_min_u32_e32 v2, v2, v3
	v_min_u32_e32 v0, v6, v0
	v_min_u32_e32 v6, v8, v39
	v_min_u32_e32 v46, v27, v21
	v_min_u32_e32 v3, v30, v12
	v_min_u32_e32 v32, v28, v25
	v_min_u32_e32 v42, v4, v2
	v_min_u32_e32 v45, v10, v17
	v_min_u32_e32 v47, v1, v0
	v_min_u32_e32 v29, v7, v18
	v_max3_u32 v8, v8, v39, v42
	v_max3_u32 v39, v6, v4, v2
	v_max3_u32 v10, v10, v17, v32
	v_max3_u32 v17, v46, v7, v18
	v_max3_u32 v18, v1, v0, v3
	global_load_dwordx4 v[0:3], v[88:89], off offset:128
	global_load_dwordx4 v[68:71], v[88:89], off offset:160
	v_min_u32_e32 v40, v34, v23
	v_min_u32_e32 v41, v38, v24
	v_min_u32_e32 v44, v31, v19
	v_min_u32_e32 v33, v15, v9
	v_min_u32_e32 v35, v16, v26
	v_min_u32_e32 v36, v20, v11
	v_min_u32_e32 v37, v22, v5
	v_add_co_u32_e32 v184, vcc, s19, v90
	v_min_u32_e32 v43, v13, v14
	v_max3_u32 v23, v34, v23, v37
	v_max3_u32 v22, v40, v22, v5
	v_max3_u32 v24, v38, v24, v36
	v_max3_u32 v20, v41, v20, v11
	v_max3_u32 v13, v13, v14, v35
	v_max3_u32 v11, v31, v19, v33
	v_max3_u32 v9, v44, v15, v9
	v_max3_u32 v14, v45, v28, v25
	v_max3_u32 v15, v27, v21, v29
	v_addc_co_u32_e32 v185, vcc, 0, v91, vcc
	v_max3_u32 v16, v43, v16, v26
	global_load_dwordx4 v[4:7], v[184:185], off offset:-4096
	global_load_dwordx4 v[198:201], v[96:97], off offset:64
	v_max3_u32 v19, v47, v30, v12
	v_max_u32_e32 v21, v8, v11
	v_min_u32_e32 v25, v8, v11
	v_max_u32_e32 v26, v39, v9
	v_min_u32_e32 v27, v39, v9
	v_max_u32_e32 v28, v23, v10
	v_min_u32_e32 v23, v23, v10
	global_load_dwordx4 v[8:11], v[184:185], off
	v_max_u32_e32 v29, v22, v14
	v_min_u32_e32 v22, v22, v14
	v_max_u32_e32 v30, v24, v15
	v_min_u32_e32 v24, v24, v15
	v_max_u32_e32 v31, v20, v17
	v_min_u32_e32 v17, v20, v17
	v_max_u32_e32 v20, v13, v18
	v_min_u32_e32 v18, v13, v18
	global_load_dwordx4 v[12:15], v[94:95], off
	global_load_dwordx4 v[188:191], v[94:95], off offset:32
	global_load_dwordx4 v[64:67], v[96:97], off offset:32
	global_load_dwordx4 v[202:205], v[88:89], off offset:192
	v_add_co_u32_e32 v218, vcc, s18, v90
	s_waitcnt vmcnt(8)
; #define MFMA(a, b, c) __builtin_amdgcn_mfma_f32_32x32x16_bf16((a), (b), (c), 0, 0, 0)
; DI unsigned f2ord(float f) { const unsigned u = __float_as_uint(f); return (u & 0x80000000u) ? ~u : (u | 0x80000000u); }
; DI void peer_topk_phase(const bf16_t* __restrict__ qpk, const bf16_t* __restrict__ subk, int* __restrict__ eidx, float* __restrict__ gout) {
;     ...
;             const bf16_t* qp = qpk + (size_t)(t0 + r) * 1024 + hh * 128 + c * 64 + h * 8;
;             const bf16_t* kp = subk + ((size_t)(hh * 2 + c) * 128 + r) * 64 + h * 8;
; #pragma unroll
;             for (int ks = 0; ks < 4; ++ks) {
;                 const bf16x8 qfr = *(const bf16x8*)(qp + ks * 16);
; #pragma unroll
;                 for (int nb = 0; nb < 4; ++nb) {
;                     const bf16x8 kf = *(const bf16x8*)(kp + nb * 32 * 64 + ks * 16);
;                     acc[nb] = MFMA(kf, qfr, acc[nb]);
;                 }
;             }
;             unsigned key[64];
; #pragma unroll
;             for (int nb = 0; nb < 4; ++nb)
; #pragma unroll
;                 for (int i = 0; i < 16; ++i) {
;                     const int n = nb * 32 + (i & 3) + 8 * (i >> 2) + 4 * h;
;                     key[nb * 16 + i] = (f2ord(acc[nb][i]) & ~127u) | (unsigned)(127 - n);
;     ...
;             for (int i = 0; i < 16; ++i) pb[i] = (unsigned)__shfl_xor((int)g0[i], 32);
;             merge_top16(g0, pb);
	v_mfma_f32_32x32x16_bf16 v[48:63], v[76:79], v[0:3], 0
	v_addc_co_u32_e32 v219, vcc, 0, v91, vcc
	global_load_dwordx4 v[90:93], v[218:219], off offset:32
	global_load_dwordx4 v[222:225], v[184:185], off offset:96
	global_load_dwordx4 v[76:79], v[94:95], off offset:64
	global_load_dwordx4 v[206:209], v[218:219], off offset:64
	global_load_dwordx4 v[180:183], v[184:185], off offset:32
	global_load_dwordx4 v[210:213], v[184:185], off offset:64
	v_max_u32_e32 v32, v16, v19
	global_load_dwordx4 v[94:97], v[96:97], off offset:96
	v_min_u32_e32 v16, v16, v19
	global_load_dwordx4 v[218:221], v[218:219], off offset:96
	v_max_u32_e32 v19, v21, v30
	v_min_u32_e32 v21, v21, v30
	v_max_u32_e32 v30, v26, v31
	v_min_u32_e32 v26, v26, v31
	v_max_u32_e32 v31, v28, v20
	v_min_u32_e32 v20, v28, v20
	v_max_u32_e32 v28, v29, v32
	v_min_u32_e32 v29, v29, v32
	v_max_u32_e32 v32, v25, v24
	v_min_u32_e32 v24, v25, v24
	v_max_u32_e32 v25, v27, v17
	v_min_u32_e32 v17, v27, v17
	v_max_u32_e32 v27, v23, v18
	v_min_u32_e32 v18, v23, v18
	v_max_u32_e32 v23, v22, v16
	v_min_u32_e32 v16, v22, v16
	v_max_u32_e32 v22, v19, v31
	v_min_u32_e32 v19, v19, v31
	v_max_u32_e32 v31, v30, v28
	v_min_u32_e32 v28, v30, v28
	v_max_u32_e32 v30, v21, v20
	v_min_u32_e32 v20, v21, v20
	v_max_u32_e32 v21, v26, v29
	v_min_u32_e32 v26, v26, v29
	v_max_u32_e32 v29, v32, v27
	v_min_u32_e32 v27, v32, v27
	v_max_u32_e32 v32, v25, v23
	v_min_u32_e32 v23, v25, v23
	v_max_u32_e32 v25, v24, v18
	v_min_u32_e32 v18, v24, v18
	v_max_u32_e32 v24, v17, v16
	v_min_u32_e32 v16, v17, v16
	v_max_u32_e32 v80, v22, v31
	v_min_u32_e32 v85, v22, v31
	v_max_u32_e32 v187, v19, v28
	v_min_u32_e32 v226, v19, v28
	v_max_u32_e32 v227, v30, v21
	v_min_u32_e32 v228, v30, v21
	v_max_u32_e32 v229, v20, v26
	v_min_u32_e32 v230, v20, v26
	v_max_u32_e32 v231, v29, v32
	v_min_u32_e32 v232, v29, v32
	v_max_u32_e32 v233, v27, v23
	v_min_u32_e32 v234, v27, v23
	v_max_u32_e32 v235, v25, v24
	v_min_u32_e32 v236, v25, v24
	v_max_u32_e32 v237, v18, v16
	v_min_u32_e32 v238, v18, v16
	s_waitcnt vmcnt(14)
	v_mfma_f32_32x32x16_bf16 v[32:47], v[4:7], v[0:3], 0
	ds_bpermute_b32 v239, v173, v80
	ds_bpermute_b32 v240, v173, v85
	ds_bpermute_b32 v241, v173, v187
	ds_bpermute_b32 v242, v173, v226
	ds_bpermute_b32 v243, v173, v227
	ds_bpermute_b32 v244, v173, v228
	ds_bpermute_b32 v245, v173, v229
	s_waitcnt vmcnt(12)
	v_mfma_f32_32x32x16_bf16 v[16:31], v[8:11], v[0:3], 0
	ds_bpermute_b32 v88, v173, v230
	ds_bpermute_b32 v89, v173, v231
	ds_bpermute_b32 v246, v173, v232
	ds_bpermute_b32 v247, v173, v233
	ds_bpermute_b32 v248, v173, v234
	ds_bpermute_b32 v249, v173, v238
	ds_bpermute_b32 v250, v173, v237
	s_waitcnt vmcnt(11)
	v_mfma_f32_32x32x16_bf16 v[0:15], v[12:15], v[0:3], 0
	ds_bpermute_b32 v251, v173, v236
	ds_bpermute_b32 v252, v173, v235
	s_waitcnt lgkmcnt(3)
	v_max_u32_e32 v80, v80, v249
	s_waitcnt lgkmcnt(2)
	v_max_u32_e32 v85, v85, v250
	v_max_u32_e32 v89, v230, v89
	s_waitcnt lgkmcnt(1)
	v_max_u32_e32 v184, v187, v251
	v_max_u32_e32 v88, v231, v88
	s_waitcnt vmcnt(9)
	v_mfma_f32_32x32x16_bf16 v[48:63], v[64:67], v[68:71], v[48:63]
	s_waitcnt lgkmcnt(0)
	v_max_u32_e32 v64, v226, v252
	v_max_u32_e32 v65, v227, v248
	v_max_u32_e32 v66, v228, v247
	v_max_u32_e32 v67, v229, v246
	v_max_u32_e32 v185, v232, v245
	v_max_u32_e32 v187, v237, v240
	v_max_u32_e32 v226, v238, v239
	v_mfma_f32_32x32x16_bf16 v[0:15], v[188:191], v[68:71], v[0:15]
	v_max_u32_e32 v227, v80, v88
	v_min_u32_e32 v80, v80, v88
	v_max_u32_e32 v88, v85, v185
	v_min_u32_e32 v85, v85, v185
	s_waitcnt vmcnt(8)
	v_mfma_f32_32x32x16_bf16 v[48:63], v[198:201], v[202:205], v[48:63]
	s_waitcnt vmcnt(7)
	v_mfma_f32_32x32x16_bf16 v[32:47], v[90:93], v[68:71], v[32:47]
	v_max_u32_e32 v90, v233, v244
	v_max_u32_e32 v91, v234, v243
	v_max_u32_e32 v92, v235, v242
	v_max_u32_e32 v93, v236, v241
	s_waitcnt vmcnt(5)
	v_mfma_f32_32x32x16_bf16 v[0:15], v[76:79], v[202:205], v[0:15]
	s_waitcnt vmcnt(1)
	v_mfma_f32_32x32x16_bf16 v[48:63], v[94:97], v[214:217], v[48:63]
	v_mfma_f32_32x32x16_bf16 v[32:47], v[206:209], v[202:205], v[32:47]
	s_nop 10
	v_cmp_gt_i32_e32 vcc, 0, v48
	v_mfma_f32_32x32x16_bf16 v[0:15], v[72:75], v[214:217], v[0:15]
	v_not_b32_e32 v72, v48
	v_or_b32_e32 v73, 0x80000000, v48
	v_cndmask_b32_e32 v48, v73, v72, vcc
	v_not_b32_e32 v72, v49
	v_or_b32_e32 v73, 0x80000000, v49
	v_cmp_gt_i32_e32 vcc, 0, v49
	v_and_or_b32 v48, v48, s17, v100
	v_mfma_f32_32x32x16_bf16 v[16:31], v[180:183], v[68:71], v[16:31]
	v_cndmask_b32_e32 v49, v73, v72, vcc
	v_not_b32_e32 v72, v50
	v_or_b32_e32 v73, 0x80000000, v50
	v_cmp_gt_i32_e32 vcc, 0, v50
	v_and_or_b32 v49, v49, s17, v101
	v_max_u32_e32 v180, v184, v90
	v_cndmask_b32_e32 v50, v73, v72, vcc
	v_not_b32_e32 v72, v51
	v_or_b32_e32 v73, 0x80000000, v51
	v_cmp_gt_i32_e32 vcc, 0, v51
	s_waitcnt vmcnt(0)
; DI unsigned f2ord(float f) { const unsigned u = __float_as_uint(f); return (u & 0x80000000u) ? ~u : (u | 0x80000000u); }
; DI void merge_top16(unsigned (&A)[16], const unsigned (&B)[16]) {
; #pragma unroll
;     for (int i = 0; i < 16; ++i) A[i] = max(A[i], B[15 - i]);
; #pragma unroll
;     for (int n = 0; n < 32; ++n) cex(A[BMERGE16[n][0]], A[BMERGE16[n][1]]);
; }
; DI void peer_topk_phase(const bf16_t* __restrict__ qpk, const bf16_t* __restrict__ subk, int* __restrict__ eidx, float* __restrict__ gout) {
;     ...
;             for (int nb = 0; nb < 4; ++nb)
; #pragma unroll
;                 for (int i = 0; i < 16; ++i) {
;                     const int n = nb * 32 + (i & 3) + 8 * (i >> 2) + 4 * h;
;                     key[nb * 16 + i] = (f2ord(acc[nb][i]) & ~127u) | (unsigned)(127 - n);
	v_mfma_f32_32x32x16_bf16 v[32:47], v[218:221], v[214:217], v[32:47]
	v_and_or_b32 v50, v50, s17, v102
	v_cndmask_b32_e32 v51, v73, v72, vcc
	v_not_b32_e32 v72, v52
	v_or_b32_e32 v73, 0x80000000, v52
	v_cmp_gt_i32_e32 vcc, 0, v52
	v_and_or_b32 v51, v51, s17, v103
	v_min_u32_e32 v90, v184, v90
	v_cndmask_b32_e32 v52, v73, v72, vcc
	v_not_b32_e32 v72, v53
	v_or_b32_e32 v73, 0x80000000, v53
	v_cmp_gt_i32_e32 vcc, 0, v53
	v_mfma_f32_32x32x16_bf16 v[16:31], v[210:213], v[202:205], v[16:31]
	v_and_or_b32 v52, v52, s17, v104
	v_cndmask_b32_e32 v53, v73, v72, vcc
	v_not_b32_e32 v72, v54
	v_or_b32_e32 v73, 0x80000000, v54
	v_cmp_gt_i32_e32 vcc, 0, v54
	v_and_or_b32 v53, v53, s17, v105
	v_max_u32_e32 v181, v64, v91
	v_cndmask_b32_e32 v54, v73, v72, vcc
	v_not_b32_e32 v72, v55
	v_or_b32_e32 v73, 0x80000000, v55
	v_cmp_gt_i32_e32 vcc, 0, v55
	v_mfma_f32_32x32x16_bf16 v[16:31], v[222:225], v[214:217], v[16:31]
	v_and_or_b32 v54, v54, s17, v106
	v_cndmask_b32_e32 v55, v73, v72, vcc
	v_not_b32_e32 v72, v56
	v_or_b32_e32 v73, 0x80000000, v56
	v_cmp_gt_i32_e32 vcc, 0, v56
	v_and_or_b32 v55, v55, s17, v107
	v_min_u32_e32 v64, v64, v91
	v_cndmask_b32_e32 v56, v73, v72, vcc
	v_not_b32_e32 v72, v57
	v_or_b32_e32 v73, 0x80000000, v57
	v_cmp_gt_i32_e32 vcc, 0, v57
	v_and_or_b32 v56, v56, s17, v108
	v_max_u32_e32 v68, v65, v92
	v_cndmask_b32_e32 v57, v73, v72, vcc
	v_not_b32_e32 v72, v58
	v_or_b32_e32 v73, 0x80000000, v58
	v_cmp_gt_i32_e32 vcc, 0, v58
	v_and_or_b32 v57, v57, s17, v109
	v_min_u32_e32 v65, v65, v92
	v_cndmask_b32_e32 v58, v73, v72, vcc
	v_not_b32_e32 v72, v59
	v_or_b32_e32 v73, 0x80000000, v59
	v_cmp_gt_i32_e32 vcc, 0, v59
	v_and_or_b32 v58, v58, s17, v110
	v_max_u32_e32 v69, v66, v93
	v_cndmask_b32_e32 v59, v73, v72, vcc
	v_not_b32_e32 v72, v60
	v_or_b32_e32 v73, 0x80000000, v60
	v_cmp_gt_i32_e32 vcc, 0, v60
	v_and_or_b32 v59, v59, s17, v111
	v_min_u32_e32 v66, v66, v93
	v_cndmask_b32_e32 v60, v73, v72, vcc
	v_not_b32_e32 v72, v61
	v_or_b32_e32 v73, 0x80000000, v61
	v_cmp_gt_i32_e32 vcc, 0, v61
	v_and_or_b32 v60, v60, s17, v112
	v_max_u32_e32 v70, v67, v187
	v_cndmask_b32_e32 v61, v73, v72, vcc
	v_not_b32_e32 v72, v62
	v_or_b32_e32 v73, 0x80000000, v62
	v_cmp_gt_i32_e32 vcc, 0, v62
	v_and_or_b32 v61, v61, s17, v113
	v_min_u32_e32 v67, v67, v187
	v_cndmask_b32_e32 v62, v73, v72, vcc
	v_not_b32_e32 v72, v63
	v_or_b32_e32 v73, 0x80000000, v63
	v_cmp_gt_i32_e32 vcc, 0, v63
	v_and_or_b32 v62, v62, s17, v114
	v_max_u32_e32 v71, v89, v226
	v_cndmask_b32_e32 v63, v73, v72, vcc
	v_not_b32_e32 v72, v32
	v_or_b32_e32 v73, 0x80000000, v32
	v_cmp_gt_i32_e32 vcc, 0, v32
	v_and_or_b32 v63, v63, s17, v115
	v_min_u32_e32 v89, v89, v226
	v_cndmask_b32_e32 v32, v73, v72, vcc
	v_not_b32_e32 v72, v33
	v_or_b32_e32 v73, 0x80000000, v33
	v_cmp_gt_i32_e32 vcc, 0, v33
	v_and_or_b32 v32, v32, s17, v116
	v_max_u32_e32 v91, v227, v68
	v_cndmask_b32_e32 v33, v73, v72, vcc
	v_not_b32_e32 v72, v34
	v_or_b32_e32 v73, 0x80000000, v34
	v_cmp_gt_i32_e32 vcc, 0, v34
	v_and_or_b32 v33, v33, s17, v117
	v_min_u32_e32 v68, v227, v68
	v_cndmask_b32_e32 v34, v73, v72, vcc
	v_not_b32_e32 v72, v35
	v_or_b32_e32 v73, 0x80000000, v35
	v_cmp_gt_i32_e32 vcc, 0, v35
	v_and_or_b32 v34, v34, s17, v118
	v_max_u32_e32 v92, v88, v69
	v_cndmask_b32_e32 v35, v73, v72, vcc
	v_not_b32_e32 v72, v36
	v_or_b32_e32 v73, 0x80000000, v36
	v_cmp_gt_i32_e32 vcc, 0, v36
	v_and_or_b32 v35, v35, s17, v119
	v_min_u32_e32 v69, v88, v69
	v_cndmask_b32_e32 v36, v73, v72, vcc
	v_not_b32_e32 v72, v37
	v_or_b32_e32 v73, 0x80000000, v37
	v_cmp_gt_i32_e32 vcc, 0, v37
	v_and_or_b32 v36, v36, s17, v120
	v_max_u32_e32 v88, v180, v70
	v_cndmask_b32_e32 v37, v73, v72, vcc
	v_not_b32_e32 v72, v38
	v_or_b32_e32 v73, 0x80000000, v38
	v_cmp_gt_i32_e32 vcc, 0, v38
	v_and_or_b32 v37, v37, s17, v121
	v_min_u32_e32 v70, v180, v70
	v_cndmask_b32_e32 v38, v73, v72, vcc
	v_not_b32_e32 v72, v39
	v_or_b32_e32 v73, 0x80000000, v39
	v_cmp_gt_i32_e32 vcc, 0, v39
	v_and_or_b32 v38, v38, s17, v122
	v_max_u32_e32 v93, v181, v71
	v_cndmask_b32_e32 v39, v73, v72, vcc
	v_not_b32_e32 v72, v40
	v_or_b32_e32 v73, 0x80000000, v40
	v_cmp_gt_i32_e32 vcc, 0, v40
	v_and_or_b32 v39, v39, s17, v123
	v_min_u32_e32 v71, v181, v71
	v_cndmask_b32_e32 v40, v73, v72, vcc
	v_not_b32_e32 v72, v41
	v_or_b32_e32 v73, 0x80000000, v41
	v_cmp_gt_i32_e32 vcc, 0, v41
	v_and_or_b32 v40, v40, s17, v124
	v_max_u32_e32 v180, v80, v65
	v_cndmask_b32_e32 v41, v73, v72, vcc
	v_not_b32_e32 v72, v42
	v_or_b32_e32 v73, 0x80000000, v42
	v_cmp_gt_i32_e32 vcc, 0, v42
	v_and_or_b32 v41, v41, s17, v125
	v_min_u32_e32 v65, v80, v65
	v_cndmask_b32_e32 v42, v73, v72, vcc
	v_not_b32_e32 v72, v43
	v_or_b32_e32 v73, 0x80000000, v43
	v_cmp_gt_i32_e32 vcc, 0, v43
	v_and_or_b32 v42, v42, s17, v126
	v_max_u32_e32 v80, v85, v66
	v_cndmask_b32_e32 v43, v73, v72, vcc
	v_not_b32_e32 v72, v44
	v_or_b32_e32 v73, 0x80000000, v44
	v_cmp_gt_i32_e32 vcc, 0, v44
	v_and_or_b32 v43, v43, s17, v127
	v_min_u32_e32 v66, v85, v66
	v_cndmask_b32_e32 v44, v73, v72, vcc
	v_not_b32_e32 v72, v45
	v_or_b32_e32 v73, 0x80000000, v45
	v_cmp_gt_i32_e32 vcc, 0, v45
	v_and_or_b32 v44, v44, s17, v128
	v_max_u32_e32 v85, v90, v67
	v_cndmask_b32_e32 v45, v73, v72, vcc
	v_not_b32_e32 v72, v46
	v_or_b32_e32 v73, 0x80000000, v46
	v_cmp_gt_i32_e32 vcc, 0, v46
	v_and_or_b32 v45, v45, s17, v129
	v_min_u32_e32 v67, v90, v67
	v_cndmask_b32_e32 v46, v73, v72, vcc
	v_not_b32_e32 v72, v47
	v_or_b32_e32 v73, 0x80000000, v47
	v_cmp_gt_i32_e32 vcc, 0, v47
	v_and_or_b32 v46, v46, s17, v130
	v_max_u32_e32 v90, v64, v89
	v_cndmask_b32_e32 v47, v73, v72, vcc
	v_not_b32_e32 v72, v16
	v_or_b32_e32 v73, 0x80000000, v16
	v_cmp_gt_i32_e32 vcc, 0, v16
; DI unsigned f2ord(float f) { const unsigned u = __float_as_uint(f); return (u & 0x80000000u) ? ~u : (u | 0x80000000u); }
; DI void merge_top16(unsigned (&A)[16], const unsigned (&B)[16]) {
; #pragma unroll
;     for (int i = 0; i < 16; ++i) A[i] = max(A[i], B[15 - i]);
; #pragma unroll
;     for (int n = 0; n < 32; ++n) cex(A[BMERGE16[n][0]], A[BMERGE16[n][1]]);
; }
; DI void peer_topk_phase(const bf16_t* __restrict__ qpk, const bf16_t* __restrict__ subk, int* __restrict__ eidx, float* __restrict__ gout) {
;     ...
;             for (int nb = 0; nb < 4; ++nb)
; #pragma unroll
;                 for (int i = 0; i < 16; ++i) {
;                     const int n = nb * 32 + (i & 3) + 8 * (i >> 2) + 4 * h;
;                     key[nb * 16 + i] = (f2ord(acc[nb][i]) & ~127u) | (unsigned)(127 - n);
	v_and_or_b32 v47, v47, s17, v131
	v_min_u32_e32 v64, v64, v89
	v_cndmask_b32_e32 v16, v73, v72, vcc
	v_not_b32_e32 v72, v17
	v_or_b32_e32 v73, 0x80000000, v17
	v_cmp_gt_i32_e32 vcc, 0, v17
	v_and_or_b32 v16, v16, s17, v132
	v_max_u32_e32 v89, v91, v88
	v_cndmask_b32_e32 v17, v73, v72, vcc
	v_not_b32_e32 v72, v18
	v_or_b32_e32 v73, 0x80000000, v18
	v_cmp_gt_i32_e32 vcc, 0, v18
	v_and_or_b32 v17, v17, s17, v133
	v_min_u32_e32 v91, v91, v88
	v_cndmask_b32_e32 v18, v73, v72, vcc
	v_not_b32_e32 v72, v19
	v_or_b32_e32 v73, 0x80000000, v19
	v_cmp_gt_i32_e32 vcc, 0, v19
	v_and_or_b32 v18, v18, s17, v134
	v_max_u32_e32 v88, v92, v93
	v_cndmask_b32_e32 v19, v73, v72, vcc
	v_not_b32_e32 v72, v20
	v_or_b32_e32 v73, 0x80000000, v20
	v_cmp_gt_i32_e32 vcc, 0, v20
	v_and_or_b32 v19, v19, s17, v135
	v_min_u32_e32 v92, v92, v93
	v_cndmask_b32_e32 v20, v73, v72, vcc
	v_not_b32_e32 v72, v21
	v_or_b32_e32 v73, 0x80000000, v21
	v_cmp_gt_i32_e32 vcc, 0, v21
	v_and_or_b32 v20, v20, s17, v136
	v_max_u32_e32 v76, v68, v70
	v_cndmask_b32_e32 v21, v73, v72, vcc
	v_not_b32_e32 v72, v22
	v_or_b32_e32 v73, 0x80000000, v22
	v_cmp_gt_i32_e32 vcc, 0, v22
	v_and_or_b32 v21, v21, s17, v137
	v_min_u32_e32 v68, v68, v70
	v_cndmask_b32_e32 v22, v73, v72, vcc
	v_not_b32_e32 v72, v23
	v_or_b32_e32 v73, 0x80000000, v23
	v_cmp_gt_i32_e32 vcc, 0, v23
	v_and_or_b32 v22, v22, s17, v138
	v_max_u32_e32 v70, v69, v71
	v_cndmask_b32_e32 v23, v73, v72, vcc
	v_not_b32_e32 v72, v24
	v_or_b32_e32 v73, 0x80000000, v24
	v_cmp_gt_i32_e32 vcc, 0, v24
	v_and_or_b32 v23, v23, s17, v139
	v_min_u32_e32 v69, v69, v71
	v_cndmask_b32_e32 v24, v73, v72, vcc
	v_not_b32_e32 v72, v25
	v_or_b32_e32 v73, 0x80000000, v25
	v_cmp_gt_i32_e32 vcc, 0, v25
	v_and_or_b32 v24, v24, s17, v140
	v_max_u32_e32 v93, v180, v85
	v_cndmask_b32_e32 v25, v73, v72, vcc
	v_not_b32_e32 v72, v26
	v_or_b32_e32 v73, 0x80000000, v26
	v_cmp_gt_i32_e32 vcc, 0, v26
	v_and_or_b32 v25, v25, s17, v141
	v_min_u32_e32 v180, v180, v85
	v_cndmask_b32_e32 v26, v73, v72, vcc
	v_not_b32_e32 v72, v27
	v_or_b32_e32 v73, 0x80000000, v27
	v_cmp_gt_i32_e32 vcc, 0, v27
	v_and_or_b32 v26, v26, s17, v142
	v_max_u32_e32 v181, v80, v90
	v_cndmask_b32_e32 v27, v73, v72, vcc
	v_not_b32_e32 v72, v28
	v_or_b32_e32 v73, 0x80000000, v28
	v_cmp_gt_i32_e32 vcc, 0, v28
	v_and_or_b32 v27, v27, s17, v143
	v_min_u32_e32 v90, v80, v90
	v_cndmask_b32_e32 v28, v73, v72, vcc
	v_not_b32_e32 v72, v29
	v_or_b32_e32 v73, 0x80000000, v29
	v_cmp_gt_i32_e32 vcc, 0, v29
	v_and_or_b32 v28, v28, s17, v149
	v_max_u32_e32 v79, v76, v70
	v_cndmask_b32_e32 v29, v73, v72, vcc
	v_not_b32_e32 v72, v30
	v_or_b32_e32 v73, 0x80000000, v30
	v_cmp_gt_i32_e32 vcc, 0, v30
	v_and_or_b32 v29, v29, s17, v150
	v_min_u32_e32 v78, v76, v70
	v_cndmask_b32_e32 v30, v73, v72, vcc
	v_not_b32_e32 v72, v31
	v_or_b32_e32 v73, 0x80000000, v31
	v_cmp_gt_i32_e32 vcc, 0, v31
	v_and_or_b32 v30, v30, s17, v151
	v_max_u32_e32 v77, v68, v69
	v_cndmask_b32_e32 v31, v73, v72, vcc
	v_not_b32_e32 v72, v0
	v_or_b32_e32 v73, 0x80000000, v0
	v_cmp_gt_i32_e32 vcc, 0, v0
	v_and_or_b32 v31, v31, s17, v152
	v_min_u32_e32 v76, v68, v69
	v_cndmask_b32_e32 v0, v73, v72, vcc
	v_not_b32_e32 v72, v1
	v_or_b32_e32 v73, 0x80000000, v1
	v_cmp_gt_i32_e32 vcc, 0, v1
	v_and_or_b32 v0, v0, s17, v153
	v_max_u32_e32 v69, v180, v90
	v_cndmask_b32_e32 v1, v73, v72, vcc
	v_not_b32_e32 v72, v2
	v_or_b32_e32 v73, 0x80000000, v2
	v_cmp_gt_i32_e32 vcc, 0, v2
	v_and_or_b32 v1, v1, s17, v154
	v_min_u32_e32 v68, v180, v90
	v_cndmask_b32_e32 v2, v73, v72, vcc
	v_not_b32_e32 v72, v3
	v_or_b32_e32 v73, 0x80000000, v3
	v_cmp_gt_i32_e32 vcc, 0, v3
	v_and_or_b32 v2, v2, s17, v155
	v_max_u32_e32 v94, v65, v67
	v_cndmask_b32_e32 v3, v73, v72, vcc
	v_not_b32_e32 v72, v4
	v_or_b32_e32 v73, 0x80000000, v4
	v_cmp_gt_i32_e32 vcc, 0, v4
	v_and_or_b32 v3, v3, s17, v156
	v_min_u32_e32 v95, v65, v67
	v_cndmask_b32_e32 v4, v73, v72, vcc
	v_not_b32_e32 v72, v5
	v_or_b32_e32 v73, 0x80000000, v5
	v_cmp_gt_i32_e32 vcc, 0, v5
	v_and_or_b32 v4, v4, s17, v157
	v_max_u32_e32 v65, v66, v64
	v_cndmask_b32_e32 v5, v73, v72, vcc
	v_not_b32_e32 v72, v6
	v_or_b32_e32 v73, 0x80000000, v6
	v_cmp_gt_i32_e32 vcc, 0, v6
	v_and_or_b32 v5, v5, s17, v158
	v_min_u32_e32 v64, v66, v64
	v_cndmask_b32_e32 v6, v73, v72, vcc
	v_not_b32_e32 v72, v7
	v_or_b32_e32 v73, 0x80000000, v7
	v_cmp_gt_i32_e32 vcc, 0, v7
	v_and_or_b32 v6, v6, s17, v159
	v_max_u32_e32 v80, v89, v88
	v_cndmask_b32_e32 v7, v73, v72, vcc
	v_not_b32_e32 v72, v8
	v_or_b32_e32 v73, 0x80000000, v8
	v_cmp_gt_i32_e32 vcc, 0, v8
	v_and_or_b32 v7, v7, s17, v160
	v_min_u32_e32 v88, v89, v88
	v_cndmask_b32_e32 v8, v73, v72, vcc
	v_not_b32_e32 v72, v9
	v_or_b32_e32 v73, 0x80000000, v9
	v_cmp_gt_i32_e32 vcc, 0, v9
	v_and_or_b32 v8, v8, s17, v161
	v_max_u32_e32 v89, v91, v92
	v_cndmask_b32_e32 v9, v73, v72, vcc
	v_not_b32_e32 v72, v10
	v_or_b32_e32 v73, 0x80000000, v10
	v_cmp_gt_i32_e32 vcc, 0, v10
	v_and_or_b32 v9, v9, s17, v162
	v_min_u32_e32 v85, v91, v92
	v_cndmask_b32_e32 v10, v73, v72, vcc
	v_not_b32_e32 v72, v11
	v_or_b32_e32 v73, 0x80000000, v11
	v_cmp_gt_i32_e32 vcc, 0, v11
	v_and_or_b32 v10, v10, s17, v163
	v_max_u32_e32 v71, v93, v181
	v_cndmask_b32_e32 v11, v73, v72, vcc
	v_not_b32_e32 v72, v12
	v_or_b32_e32 v73, 0x80000000, v12
	v_cmp_gt_i32_e32 vcc, 0, v12
	v_and_or_b32 v11, v11, s17, v164
	v_min_u32_e32 v70, v93, v181
	v_cndmask_b32_e32 v12, v73, v72, vcc
	v_not_b32_e32 v72, v13
	v_or_b32_e32 v73, 0x80000000, v13
	v_cmp_gt_i32_e32 vcc, 0, v13
	v_and_or_b32 v12, v12, s17, v165
	v_max_u32_e32 v67, v94, v65
	v_cndmask_b32_e32 v13, v73, v72, vcc
	v_not_b32_e32 v72, v14
	v_or_b32_e32 v73, 0x80000000, v14
	v_cmp_gt_i32_e32 vcc, 0, v14
; DI unsigned f2ord(float f) { const unsigned u = __float_as_uint(f); return (u & 0x80000000u) ? ~u : (u | 0x80000000u); }
; DI void peer_topk_phase(const bf16_t* __restrict__ qpk, const bf16_t* __restrict__ subk, int* __restrict__ eidx, float* __restrict__ gout) {
;     ...
;             for (int nb = 0; nb < 4; ++nb)
; #pragma unroll
;                 for (int i = 0; i < 16; ++i) {
;                     const int n = nb * 32 + (i & 3) + 8 * (i >> 2) + 4 * h;
;                     key[nb * 16 + i] = (f2ord(acc[nb][i]) & ~127u) | (unsigned)(127 - n);
;                 }
;             unsigned g0[16], g1[16], g2[16], g3[16];
; #pragma unroll
;             for (int i = 0; i < 16; ++i) { g0[i] = key[i]; g1[i] = key[16 + i]; g2[i] = key[32 + i]; g3[i] = key[48 + i]; }
; #pragma unroll
;             for (int n = 0; n < 63; ++n) { cex(g0[SORT16[n][0]], g0[SORT16[n][1]]); cex(g1[SORT16[n][0]], g1[SORT16[n][1]]); cex(g2[SORT16[n][0]], g2[SORT16[n][1]]); cex(g3[SORT16[n][0]], g3[SORT16[n][1]]); }
	v_and_or_b32 v13, v13, s17, v166
	v_min_u32_e32 v66, v94, v65
	v_cndmask_b32_e32 v14, v73, v72, vcc
	v_not_b32_e32 v72, v15
	v_or_b32_e32 v73, 0x80000000, v15
	v_cmp_gt_i32_e32 vcc, 0, v15
	v_and_or_b32 v14, v14, s17, v167
	v_max_u32_e32 v65, v95, v64
	v_cndmask_b32_e32 v15, v73, v72, vcc
	v_max_u32_e32 v72, v48, v49
	v_min_u32_e32 v48, v48, v49
	v_max_u32_e32 v49, v32, v33
	v_min_u32_e32 v32, v32, v33
	v_max_u32_e32 v33, v16, v17
	v_min_u32_e32 v16, v16, v17
	v_max_u32_e32 v17, v0, v1
	v_min_u32_e32 v0, v0, v1
	v_max_u32_e32 v1, v50, v51
	v_min_u32_e32 v50, v50, v51
	v_max_u32_e32 v51, v34, v35
	v_min_u32_e32 v34, v34, v35
	v_max_u32_e32 v35, v18, v19
	v_min_u32_e32 v18, v18, v19
	v_max_u32_e32 v19, v2, v3
	v_min_u32_e32 v2, v2, v3
	v_max_u32_e32 v3, v72, v1
	v_min_u32_e32 v1, v72, v1
	v_max_u32_e32 v72, v49, v51
	v_min_u32_e32 v49, v49, v51
	v_max_u32_e32 v51, v33, v35
	v_min_u32_e32 v33, v33, v35
	v_max_u32_e32 v35, v17, v19
	v_min_u32_e32 v17, v17, v19
	v_max_u32_e32 v19, v48, v50
	v_min_u32_e32 v48, v48, v50
	v_max_u32_e32 v50, v32, v34
	v_min_u32_e32 v32, v32, v34
	v_max_u32_e32 v34, v16, v18
	v_min_u32_e32 v16, v16, v18
	v_max_u32_e32 v18, v0, v2
	v_min_u32_e32 v0, v0, v2
	v_max_u32_e32 v2, v19, v1
	v_min_u32_e32 v1, v19, v1
	v_max_u32_e32 v19, v50, v49
	v_min_u32_e32 v49, v50, v49
	v_max_u32_e32 v50, v34, v33
	v_min_u32_e32 v33, v34, v33
	v_max_u32_e32 v34, v18, v17
	v_min_u32_e32 v17, v18, v17
	v_max_u32_e32 v18, v52, v53
	v_min_u32_e32 v52, v52, v53
	v_max_u32_e32 v53, v36, v37
	v_min_u32_e32 v36, v36, v37
	v_max_u32_e32 v37, v20, v21
	v_min_u32_e32 v20, v20, v21
	v_max_u32_e32 v21, v4, v5
	v_min_u32_e32 v4, v4, v5
	v_max_u32_e32 v5, v54, v55
	v_min_u32_e32 v54, v54, v55
	v_max_u32_e32 v55, v38, v39
	v_min_u32_e32 v38, v38, v39
	v_max_u32_e32 v39, v22, v23
	v_min_u32_e32 v22, v22, v23
	v_max_u32_e32 v23, v6, v7
	v_min_u32_e32 v6, v6, v7
	v_max_u32_e32 v7, v18, v5
	v_min_u32_e32 v5, v18, v5
	v_max_u32_e32 v18, v53, v55
	v_min_u32_e32 v53, v53, v55
	v_max_u32_e32 v55, v37, v39
	v_min_u32_e32 v37, v37, v39
	v_max_u32_e32 v39, v21, v23
	v_min_u32_e32 v21, v21, v23
	v_max_u32_e32 v23, v52, v54
	v_min_u32_e32 v52, v52, v54
	v_max_u32_e32 v54, v36, v38
	v_min_u32_e32 v36, v36, v38
	v_max_u32_e32 v38, v20, v22
	v_min_u32_e32 v20, v20, v22
	v_max_u32_e32 v22, v4, v6
	v_min_u32_e32 v4, v4, v6
	v_max_u32_e32 v6, v23, v5
	v_min_u32_e32 v5, v23, v5
	v_max_u32_e32 v23, v54, v53
	v_min_u32_e32 v53, v54, v53
	v_max_u32_e32 v54, v38, v37
	v_min_u32_e32 v37, v38, v37
	v_max_u32_e32 v38, v22, v21
	v_min_u32_e32 v21, v22, v21
	v_max_u32_e32 v22, v3, v7
	v_min_u32_e32 v3, v3, v7
	v_max_u32_e32 v7, v72, v18
	v_min_u32_e32 v18, v72, v18
	v_max_u32_e32 v72, v51, v55
	v_min_u32_e32 v51, v51, v55
	v_max_u32_e32 v55, v35, v39
	v_min_u32_e32 v35, v35, v39
	v_max_u32_e32 v39, v1, v5
	v_min_u32_e32 v1, v1, v5
	v_max_u32_e32 v5, v49, v53
	v_min_u32_e32 v49, v49, v53
	v_max_u32_e32 v53, v33, v37
	v_min_u32_e32 v33, v33, v37
	v_max_u32_e32 v37, v17, v21
	v_min_u32_e32 v17, v17, v21
	v_max_u32_e32 v21, v39, v3
	v_min_u32_e32 v3, v39, v3
	v_max_u32_e32 v39, v5, v18
	v_min_u32_e32 v5, v5, v18
	v_max_u32_e32 v18, v53, v51
	v_min_u32_e32 v51, v53, v51
	v_max_u32_e32 v53, v37, v35
	v_min_u32_e32 v35, v37, v35
	v_max_u32_e32 v37, v2, v6
	v_min_u32_e32 v2, v2, v6
	v_max_u32_e32 v6, v19, v23
	v_min_u32_e32 v19, v19, v23
	v_max_u32_e32 v23, v50, v54
	v_min_u32_e32 v50, v50, v54
	v_max_u32_e32 v54, v34, v38
	v_min_u32_e32 v34, v34, v38
	v_max_u32_e32 v38, v48, v52
	v_min_u32_e32 v48, v48, v52
	v_max_u32_e32 v52, v32, v36
	v_min_u32_e32 v32, v32, v36
	v_max_u32_e32 v36, v16, v20
	v_min_u32_e32 v16, v16, v20
	v_max_u32_e32 v20, v0, v4
	v_min_u32_e32 v0, v0, v4
	v_max_u32_e32 v4, v38, v2
	v_min_u32_e32 v2, v38, v2
	v_max_u32_e32 v38, v52, v19
	v_min_u32_e32 v19, v52, v19
	v_max_u32_e32 v52, v36, v50
	v_min_u32_e32 v36, v36, v50
	v_max_u32_e32 v50, v20, v34
	v_min_u32_e32 v20, v20, v34
	v_max_u32_e32 v34, v37, v21
	v_min_u32_e32 v21, v37, v21
	v_max_u32_e32 v37, v6, v39
	v_min_u32_e32 v6, v6, v39
	v_max_u32_e32 v39, v23, v18
	v_min_u32_e32 v18, v23, v18
	v_max_u32_e32 v23, v54, v53
	v_min_u32_e32 v53, v54, v53
	v_max_u32_e32 v54, v4, v3
	v_min_u32_e32 v3, v4, v3
	v_max_u32_e32 v4, v38, v5
	v_min_u32_e32 v5, v38, v5
	v_max_u32_e32 v38, v52, v51
	v_min_u32_e32 v51, v52, v51
	v_max_u32_e32 v52, v50, v35
	v_min_u32_e32 v35, v50, v35
	v_max_u32_e32 v50, v2, v1
	v_min_u32_e32 v1, v2, v1
	v_max_u32_e32 v2, v19, v49
	v_min_u32_e32 v19, v19, v49
	v_max_u32_e32 v49, v36, v33
	v_min_u32_e32 v33, v36, v33
	v_max_u32_e32 v36, v20, v17
	v_min_u32_e32 v17, v20, v17
	v_max_u32_e32 v20, v56, v57
	v_min_u32_e32 v56, v56, v57
	v_max_u32_e32 v57, v40, v41
	v_min_u32_e32 v40, v40, v41
	v_max_u32_e32 v41, v24, v25
	v_min_u32_e32 v24, v24, v25
	v_max_u32_e32 v25, v8, v9
	v_min_u32_e32 v8, v8, v9
	v_max_u32_e32 v9, v58, v59
	v_min_u32_e32 v58, v58, v59
	v_max_u32_e32 v59, v42, v43
	v_min_u32_e32 v42, v42, v43
	v_max_u32_e32 v43, v26, v27
	v_min_u32_e32 v26, v26, v27
	v_max_u32_e32 v27, v10, v11
	v_min_u32_e32 v10, v10, v11
	v_and_or_b32 v15, v15, s17, v168
	v_max_u32_e32 v11, v20, v9
	v_min_u32_e32 v9, v20, v9
	v_max_u32_e32 v20, v57, v59
	v_min_u32_e32 v57, v57, v59
	v_max_u32_e32 v59, v41, v43
	v_min_u32_e32 v41, v41, v43
	v_max_u32_e32 v43, v25, v27
	v_min_u32_e32 v25, v25, v27
	v_max_u32_e32 v27, v56, v58
	v_min_u32_e32 v56, v56, v58
	v_max_u32_e32 v58, v40, v42
	v_min_u32_e32 v40, v40, v42
	v_max_u32_e32 v42, v24, v26
	v_min_u32_e32 v24, v24, v26
	v_max_u32_e32 v26, v8, v10
	v_min_u32_e32 v8, v8, v10
	v_max_u32_e32 v10, v27, v9
	v_min_u32_e32 v9, v27, v9
	v_max_u32_e32 v27, v58, v57
; DI void peer_topk_phase(const bf16_t* __restrict__ qpk, const bf16_t* __restrict__ subk, int* __restrict__ eidx, float* __restrict__ gout) {
;     ...
; #pragma unroll
;             for (int n = 0; n < 63; ++n) { cex(g0[SORT16[n][0]], g0[SORT16[n][1]]); cex(g1[SORT16[n][0]], g1[SORT16[n][1]]); cex(g2[SORT16[n][0]], g2[SORT16[n][1]]); cex(g3[SORT16[n][0]], g3[SORT16[n][1]]); }
;             merge_top16(g0, g1); merge_top16(g2, g3); merge_top16(g0, g2);
;             unsigned pb[16];
; #pragma unroll
;             for (int i = 0; i < 16; ++i) pb[i] = (unsigned)__shfl_xor((int)g0[i], 32);
;             merge_top16(g0, pb);
	v_min_u32_e32 v57, v58, v57
	v_max_u32_e32 v58, v42, v41
	v_min_u32_e32 v41, v42, v41
	v_max_u32_e32 v42, v26, v25
	v_min_u32_e32 v25, v26, v25
	v_max_u32_e32 v26, v60, v61
	v_min_u32_e32 v60, v60, v61
	v_max_u32_e32 v61, v44, v45
	v_min_u32_e32 v44, v44, v45
	v_max_u32_e32 v45, v28, v29
	v_min_u32_e32 v28, v28, v29
	v_max_u32_e32 v29, v12, v13
	v_min_u32_e32 v12, v12, v13
	v_max_u32_e32 v13, v62, v63
	v_min_u32_e32 v62, v62, v63
	v_max_u32_e32 v63, v46, v47
	v_min_u32_e32 v46, v46, v47
	v_max_u32_e32 v47, v30, v31
	v_min_u32_e32 v30, v30, v31
	v_max_u32_e32 v31, v14, v15
	v_min_u32_e32 v14, v14, v15
	v_max_u32_e32 v15, v26, v13
	v_min_u32_e32 v13, v26, v13
	v_max_u32_e32 v26, v61, v63
	v_min_u32_e32 v61, v61, v63
	v_max_u32_e32 v63, v45, v47
	v_min_u32_e32 v45, v45, v47
	v_max_u32_e32 v47, v29, v31
	v_min_u32_e32 v29, v29, v31
	v_max_u32_e32 v31, v60, v62
	v_min_u32_e32 v60, v60, v62
	v_max_u32_e32 v62, v44, v46
	v_min_u32_e32 v44, v44, v46
	v_max_u32_e32 v46, v28, v30
	v_min_u32_e32 v28, v28, v30
	v_max_u32_e32 v30, v12, v14
	v_min_u32_e32 v12, v12, v14
	v_max_u32_e32 v14, v31, v13
	v_min_u32_e32 v13, v31, v13
	v_max_u32_e32 v31, v62, v61
	v_min_u32_e32 v61, v62, v61
	v_max_u32_e32 v62, v46, v45
	v_min_u32_e32 v45, v46, v45
	v_max_u32_e32 v46, v30, v29
	v_min_u32_e32 v29, v30, v29
	v_max_u32_e32 v30, v11, v15
	v_min_u32_e32 v11, v11, v15
	v_max_u32_e32 v15, v20, v26
	v_min_u32_e32 v20, v20, v26
	v_max_u32_e32 v26, v59, v63
	v_min_u32_e32 v59, v59, v63
	v_max_u32_e32 v63, v43, v47
	v_min_u32_e32 v43, v43, v47
	v_max_u32_e32 v47, v9, v13
	v_min_u32_e32 v9, v9, v13
	v_max_u32_e32 v13, v57, v61
	v_min_u32_e32 v57, v57, v61
	v_max_u32_e32 v61, v41, v45
	v_min_u32_e32 v41, v41, v45
	v_max_u32_e32 v45, v25, v29
	v_min_u32_e32 v25, v25, v29
	v_max_u32_e32 v29, v47, v11
	v_min_u32_e32 v11, v47, v11
	v_max_u32_e32 v47, v13, v20
	v_min_u32_e32 v13, v13, v20
	v_max_u32_e32 v20, v61, v59
	v_min_u32_e32 v59, v61, v59
	v_max_u32_e32 v61, v45, v43
	v_min_u32_e32 v43, v45, v43
	v_max_u32_e32 v45, v10, v14
	v_min_u32_e32 v10, v10, v14
	v_max_u32_e32 v14, v27, v31
	v_min_u32_e32 v27, v27, v31
	v_max_u32_e32 v31, v58, v62
	v_min_u32_e32 v58, v58, v62
	v_max_u32_e32 v62, v42, v46
	v_min_u32_e32 v42, v42, v46
	v_max_u32_e32 v46, v56, v60
	v_min_u32_e32 v56, v56, v60
	v_max_u32_e32 v60, v40, v44
	v_min_u32_e32 v40, v40, v44
	v_max_u32_e32 v44, v24, v28
	v_min_u32_e32 v24, v24, v28
	v_max_u32_e32 v28, v8, v12
	v_min_u32_e32 v8, v8, v12
	v_max_u32_e32 v12, v46, v10
	v_min_u32_e32 v10, v46, v10
	v_max_u32_e32 v46, v60, v27
	v_min_u32_e32 v27, v60, v27
	v_max_u32_e32 v60, v44, v58
	v_min_u32_e32 v44, v44, v58
	v_max_u32_e32 v58, v28, v42
	v_min_u32_e32 v28, v28, v42
	v_max_u32_e32 v42, v45, v29
	v_min_u32_e32 v29, v45, v29
	v_max_u32_e32 v45, v14, v47
	v_min_u32_e32 v14, v14, v47
	v_max_u32_e32 v47, v31, v20
	v_min_u32_e32 v20, v31, v20
	v_max_u32_e32 v31, v62, v61
	v_min_u32_e32 v61, v62, v61
	v_max_u32_e32 v62, v12, v11
	v_min_u32_e32 v11, v12, v11
	v_max_u32_e32 v12, v46, v13
	v_min_u32_e32 v13, v46, v13
	v_max_u32_e32 v46, v60, v59
	v_min_u32_e32 v59, v60, v59
	v_max_u32_e32 v60, v58, v43
	v_min_u32_e32 v43, v58, v43
	v_max_u32_e32 v58, v10, v9
	v_min_u32_e32 v9, v10, v9
	v_max_u32_e32 v10, v27, v57
	v_min_u32_e32 v27, v27, v57
	v_max_u32_e32 v57, v44, v41
	v_min_u32_e32 v41, v44, v41
	v_max_u32_e32 v44, v28, v25
	v_min_u32_e32 v25, v28, v25
	v_min_u32_e32 v28, v22, v30
	v_min_u32_e32 v73, v7, v15
	v_min_u32_e32 v74, v72, v26
	v_min_u32_e32 v75, v55, v63
	v_max_u32_e32 v90, v3, v11
	v_min_u32_e32 v3, v3, v11
	v_max_u32_e32 v11, v5, v13
	v_min_u32_e32 v5, v5, v13
	v_max_u32_e32 v13, v51, v59
	v_min_u32_e32 v51, v51, v59
	v_max_u32_e32 v59, v35, v43
	v_min_u32_e32 v35, v35, v43
	v_max_u32_e32 v43, v90, v28
	v_min_u32_e32 v28, v90, v28
	v_max_u32_e32 v90, v11, v73
	v_min_u32_e32 v11, v11, v73
	v_max_u32_e32 v73, v13, v74
	v_min_u32_e32 v13, v13, v74
	v_max_u32_e32 v74, v59, v75
	v_min_u32_e32 v59, v59, v75
	v_max_u32_e32 v75, v21, v29
	v_min_u32_e32 v21, v21, v29
	v_max_u32_e32 v29, v6, v14
	v_min_u32_e32 v6, v6, v14
	v_max_u32_e32 v14, v18, v20
	v_min_u32_e32 v18, v18, v20
	v_max_u32_e32 v20, v53, v61
	v_min_u32_e32 v53, v53, v61
	v_max_u32_e32 v61, v1, v9
	v_min_u32_e32 v1, v1, v9
	v_max_u32_e32 v9, v19, v27
	v_min_u32_e32 v19, v19, v27
	v_max_u32_e32 v27, v33, v41
	v_min_u32_e32 v33, v33, v41
	v_max_u32_e32 v41, v17, v25
	v_min_u32_e32 v17, v17, v25
	v_max_u32_e32 v25, v61, v21
	v_min_u32_e32 v21, v61, v21
	v_max_u32_e32 v61, v9, v6
	v_min_u32_e32 v6, v9, v6
	v_max_u32_e32 v9, v27, v18
	v_min_u32_e32 v18, v27, v18
	v_max_u32_e32 v27, v41, v53
	v_min_u32_e32 v41, v41, v53
	v_max_u32_e32 v53, v75, v43
	v_min_u32_e32 v43, v75, v43
	v_max_u32_e32 v75, v29, v90
	v_min_u32_e32 v29, v29, v90
	v_max_u32_e32 v90, v14, v73
	v_min_u32_e32 v14, v14, v73
	v_max_u32_e32 v73, v20, v74
	v_min_u32_e32 v20, v20, v74
	v_max_u32_e32 v74, v25, v28
	v_min_u32_e32 v25, v25, v28
	v_max_u32_e32 v28, v61, v11
	v_min_u32_e32 v11, v61, v11
	v_max_u32_e32 v61, v9, v13
	v_min_u32_e32 v9, v9, v13
	v_max_u32_e32 v13, v27, v59
	v_min_u32_e32 v27, v27, v59
	v_max_u32_e32 v59, v21, v3
	v_min_u32_e32 v3, v21, v3
	v_max_u32_e32 v21, v6, v5
	v_min_u32_e32 v5, v6, v5
	v_max_u32_e32 v6, v18, v51
	v_min_u32_e32 v18, v18, v51
	v_max_u32_e32 v51, v41, v35
	v_min_u32_e32 v35, v41, v35
	v_max_u32_e32 v41, v34, v42
	v_min_u32_e32 v34, v34, v42
	v_max_u32_e32 v42, v37, v45
	v_min_u32_e32 v37, v37, v45
	v_max_u32_e32 v45, v39, v47
	v_min_u32_e32 v39, v39, v47
	v_max_u32_e32 v47, v23, v31
	v_min_u32_e32 v23, v23, v31
	v_max_u32_e32 v31, v50, v58
	v_min_u32_e32 v50, v50, v58
	v_max_u32_e32 v58, v2, v10
; DI void merge_top16(unsigned (&A)[16], const unsigned (&B)[16]) {
; #pragma unroll
;     for (int i = 0; i < 16; ++i) A[i] = max(A[i], B[15 - i]);
; #pragma unroll
;     for (int n = 0; n < 32; ++n) cex(A[BMERGE16[n][0]], A[BMERGE16[n][1]]);
; }
; DI void peer_topk_phase(const bf16_t* __restrict__ qpk, const bf16_t* __restrict__ subk, int* __restrict__ eidx, float* __restrict__ gout) {
;     ...
;             merge_top16(g0, g1); merge_top16(g2, g3); merge_top16(g0, g2);
;             unsigned pb[16];
; #pragma unroll
;             for (int i = 0; i < 16; ++i) pb[i] = (unsigned)__shfl_xor((int)g0[i], 32);
;             merge_top16(g0, pb);
	v_min_u32_e32 v2, v2, v10
	v_max_u32_e32 v10, v49, v57
	v_min_u32_e32 v49, v49, v57
	v_max_u32_e32 v57, v36, v44
	v_min_u32_e32 v36, v36, v44
	v_max_u32_e32 v44, v31, v34
	v_min_u32_e32 v31, v31, v34
	v_max_u32_e32 v34, v58, v37
	v_min_u32_e32 v37, v58, v37
	v_max_u32_e32 v58, v10, v39
	v_min_u32_e32 v10, v10, v39
	v_max_u32_e32 v39, v57, v23
	v_min_u32_e32 v23, v57, v23
	v_max_u32_e32 v57, v54, v62
	v_min_u32_e32 v54, v54, v62
	v_max_u32_e32 v62, v4, v12
	v_min_u32_e32 v4, v4, v12
	v_max_u32_e32 v12, v38, v46
	v_min_u32_e32 v38, v38, v46
	v_max_u32_e32 v46, v52, v60
	v_min_u32_e32 v52, v52, v60
	v_max_u32_e32 v60, v48, v56
	v_min_u32_e32 v48, v48, v56
	v_max_u32_e32 v56, v32, v40
	v_min_u32_e32 v32, v32, v40
	v_max_u32_e32 v40, v16, v24
	v_min_u32_e32 v16, v16, v24
	v_max_u32_e32 v24, v0, v8
	v_min_u32_e32 v0, v0, v8
	v_max_u32_e32 v8, v60, v54
	v_min_u32_e32 v54, v60, v54
	v_max_u32_e32 v60, v56, v4
	v_min_u32_e32 v4, v56, v4
	v_max_u32_e32 v56, v40, v38
	v_min_u32_e32 v38, v40, v38
	v_max_u32_e32 v40, v24, v52
	v_min_u32_e32 v24, v24, v52
	v_max_u32_e32 v52, v57, v44
	v_min_u32_e32 v44, v57, v44
	v_max_u32_e32 v57, v62, v34
	v_min_u32_e32 v34, v62, v34
	v_max_u32_e32 v62, v12, v58
	v_min_u32_e32 v12, v12, v58
	v_max_u32_e32 v58, v46, v39
	v_min_u32_e32 v39, v46, v39
	v_max_u32_e32 v46, v8, v31
	v_min_u32_e32 v8, v8, v31
	v_max_u32_e32 v31, v60, v37
	v_min_u32_e32 v37, v60, v37
	v_max_u32_e32 v60, v56, v10
	v_min_u32_e32 v10, v56, v10
	v_max_u32_e32 v56, v40, v23
	v_min_u32_e32 v23, v40, v23
	v_max_u32_e32 v40, v54, v50
	v_min_u32_e32 v50, v54, v50
	v_max_u32_e32 v54, v4, v2
	v_min_u32_e32 v2, v4, v2
	v_max_u32_e32 v4, v38, v49
	v_min_u32_e32 v38, v38, v49
	v_max_u32_e32 v49, v24, v36
	v_min_u32_e32 v24, v24, v36
	v_min_u32_e32 v64, v95, v64
	v_min_u32_e32 v36, v41, v53
	v_min_u32_e32 v91, v42, v75
	v_min_u32_e32 v92, v45, v90
	v_min_u32_e32 v93, v47, v73
	v_min_u32_e32 v94, v52, v43
	v_min_u32_e32 v95, v57, v29
	v_min_u32_e32 v96, v62, v14
	v_min_u32_e32 v97, v58, v20
	v_min_u32_e32 v180, v44, v74
	v_min_u32_e32 v181, v34, v28
	v_min_u32_e32 v182, v12, v61
	v_min_u32_e32 v183, v39, v13
	v_min_u32_e32 v184, v46, v25
	v_min_u32_e32 v185, v31, v11
	v_min_u32_e32 v187, v60, v9
	v_min_u32_e32 v188, v56, v27
	v_min_u32_e32 v189, v8, v59
	v_min_u32_e32 v190, v37, v21
	v_min_u32_e32 v191, v10, v6
	v_min_u32_e32 v198, v23, v51
	v_min_u32_e32 v199, v40, v3
	v_min_u32_e32 v200, v54, v5
	v_min_u32_e32 v201, v4, v18
	v_min_u32_e32 v202, v49, v35
	v_min_u32_e32 v203, v50, v1
	v_min_u32_e32 v204, v2, v19
	v_min_u32_e32 v205, v38, v33
	v_min_u32_e32 v206, v24, v17
	v_max3_u32 v22, v22, v30, v32
	v_max3_u32 v30, v41, v53, v204
	v_max3_u32 v2, v36, v2, v19
	v_max3_u32 v19, v52, v43, v200
	v_max3_u32 v5, v94, v54, v5
	v_max3_u32 v32, v44, v74, v190
	v_max3_u32 v21, v180, v37, v21
	v_max3_u32 v25, v46, v25, v185
	v_max3_u32 v11, v184, v31, v11
	v_max3_u32 v8, v8, v59, v181
	v_max3_u32 v28, v189, v34, v28
	v_max3_u32 v3, v40, v3, v95
	v_max3_u32 v29, v199, v57, v29
	v_max3_u32 v1, v50, v1, v91
	v_max3_u32 v31, v203, v42, v75
	v_max3_u32 v7, v48, v7, v15
	v_max3_u32 v0, v72, v26, v0
	v_max3_u32 v26, v45, v90, v206
	v_max3_u32 v17, v92, v24, v17
	v_max3_u32 v14, v62, v14, v202
	v_max3_u32 v24, v96, v49, v35
	v_max3_u32 v12, v12, v61, v198
	v_max3_u32 v23, v182, v23, v51
	v_max3_u32 v9, v60, v9, v188
	v_max3_u32 v27, v187, v56, v27
	v_max3_u32 v6, v10, v6, v183
	v_max3_u32 v10, v191, v39, v13
	v_max3_u32 v4, v4, v18, v97
	v_max3_u32 v13, v201, v58, v20
	v_max3_u32 v18, v38, v33, v93
	v_max3_u32 v20, v205, v47, v73
	v_max3_u32 v16, v16, v55, v63
	v_max_u32_e32 v15, v22, v11
	v_min_u32_e32 v11, v22, v11
	v_max_u32_e32 v22, v30, v8
	v_min_u32_e32 v8, v30, v8
	v_max_u32_e32 v30, v2, v28
	v_min_u32_e32 v2, v2, v28
	v_max_u32_e32 v28, v19, v3
	v_min_u32_e32 v3, v19, v3
	v_max_u32_e32 v19, v5, v29
	v_min_u32_e32 v5, v5, v29
	v_max_u32_e32 v29, v32, v1
	v_min_u32_e32 v1, v32, v1
	v_max_u32_e32 v32, v21, v31
	v_min_u32_e32 v21, v21, v31
	v_max_u32_e32 v31, v25, v7
	v_min_u32_e32 v7, v25, v7
	v_max_u32_e32 v33, v0, v27
	v_min_u32_e32 v0, v0, v27
	v_max_u32_e32 v27, v26, v6
	v_min_u32_e32 v6, v26, v6
	v_max_u32_e32 v26, v17, v10
	v_min_u32_e32 v10, v17, v10
	v_max_u32_e32 v17, v14, v4
	v_min_u32_e32 v4, v14, v4
	v_max_u32_e32 v14, v24, v13
	v_min_u32_e32 v13, v24, v13
	v_max_u32_e32 v24, v12, v18
	v_min_u32_e32 v12, v12, v18
	v_max_u32_e32 v18, v23, v20
	v_min_u32_e32 v20, v23, v20
	v_max_u32_e32 v23, v9, v16
	v_min_u32_e32 v9, v9, v16
	v_max_u32_e32 v25, v15, v19
	v_min_u32_e32 v15, v15, v19
	v_max_u32_e32 v19, v22, v29
	v_min_u32_e32 v22, v22, v29
	v_max_u32_e32 v29, v30, v32
	v_min_u32_e32 v30, v30, v32
	v_max_u32_e32 v32, v28, v31
	v_min_u32_e32 v28, v28, v31
	v_max_u32_e32 v31, v11, v5
	v_min_u32_e32 v5, v11, v5
	v_max_u32_e32 v11, v8, v1
	v_min_u32_e32 v1, v8, v1
	v_max_u32_e32 v8, v2, v21
	v_min_u32_e32 v2, v2, v21
	v_max_u32_e32 v21, v3, v7
	v_min_u32_e32 v3, v3, v7
	v_max_u32_e32 v16, v33, v14
	v_min_u32_e32 v14, v33, v14
	v_max_u32_e32 v33, v27, v24
	v_min_u32_e32 v24, v27, v24
	v_max_u32_e32 v27, v26, v18
	v_min_u32_e32 v18, v26, v18
	v_max_u32_e32 v26, v17, v23
	v_min_u32_e32 v17, v17, v23
	v_max_u32_e32 v23, v0, v13
	v_min_u32_e32 v0, v0, v13
	v_max_u32_e32 v13, v6, v12
	v_min_u32_e32 v6, v6, v12
	v_max_u32_e32 v12, v10, v20
	v_min_u32_e32 v10, v10, v20
	v_max_u32_e32 v20, v4, v9
	v_min_u32_e32 v4, v4, v9
	v_max_u32_e32 v7, v25, v29
	v_min_u32_e32 v25, v25, v29
	v_max_u32_e32 v29, v19, v32
	v_min_u32_e32 v19, v19, v32
	v_max_u32_e32 v32, v15, v30
	v_min_u32_e32 v15, v15, v30
	v_max_u32_e32 v30, v22, v28
	v_min_u32_e32 v22, v22, v28
	v_max_u32_e32 v28, v31, v8
; DI void merge_top16(unsigned (&A)[16], const unsigned (&B)[16]) {
; #pragma unroll
;     for (int i = 0; i < 16; ++i) A[i] = max(A[i], B[15 - i]);
; #pragma unroll
;     for (int n = 0; n < 32; ++n) cex(A[BMERGE16[n][0]], A[BMERGE16[n][1]]);
; }
; DI void peer_topk_phase(const bf16_t* __restrict__ qpk, const bf16_t* __restrict__ subk, int* __restrict__ eidx, float* __restrict__ gout) {
;     ...
;             merge_top16(g0, g1); merge_top16(g2, g3); merge_top16(g0, g2);
;             unsigned pb[16];
; #pragma unroll
;             for (int i = 0; i < 16; ++i) pb[i] = (unsigned)__shfl_xor((int)g0[i], 32);
;             merge_top16(g0, pb);
; #pragma unroll
;             for (int i = 0; i < 16; ++i) top[c][i] = g0[i];
	v_min_u32_e32 v8, v31, v8
	v_max_u32_e32 v31, v11, v21
	v_min_u32_e32 v11, v11, v21
	v_max_u32_e32 v21, v5, v2
	v_min_u32_e32 v2, v5, v2
	v_max_u32_e32 v5, v1, v3
	v_min_u32_e32 v1, v1, v3
	v_max_u32_e32 v9, v16, v27
	v_min_u32_e32 v16, v16, v27
	v_max_u32_e32 v27, v33, v26
	v_min_u32_e32 v26, v33, v26
	v_max_u32_e32 v33, v14, v18
	v_min_u32_e32 v14, v14, v18
	v_max_u32_e32 v18, v24, v17
	v_min_u32_e32 v17, v24, v17
	v_max_u32_e32 v24, v23, v12
	v_min_u32_e32 v12, v23, v12
	v_max_u32_e32 v23, v13, v20
	v_min_u32_e32 v13, v13, v20
	v_max_u32_e32 v20, v0, v10
	v_min_u32_e32 v0, v0, v10
	v_max_u32_e32 v10, v6, v4
	v_min_u32_e32 v4, v6, v4
	v_min_u32_e32 v3, v7, v29
	v_min_u32_e32 v34, v25, v19
	v_min_u32_e32 v36, v32, v30
	v_min_u32_e32 v37, v15, v22
	v_min_u32_e32 v40, v28, v31
	v_min_u32_e32 v41, v8, v11
	v_min_u32_e32 v42, v21, v5
	v_min_u32_e32 v43, v2, v1
	v_min_u32_e32 v6, v9, v27
	v_min_u32_e32 v35, v16, v26
	v_min_u32_e32 v38, v33, v18
	v_min_u32_e32 v39, v14, v17
	v_min_u32_e32 v44, v24, v23
	v_min_u32_e32 v45, v12, v13
	v_min_u32_e32 v46, v20, v10
	v_min_u32_e32 v47, v0, v4
	v_max3_u32 v7, v7, v29, v47
	v_max3_u32 v0, v3, v0, v4
	v_max3_u32 v3, v25, v19, v46
	v_max3_u32 v4, v34, v20, v10
	v_max3_u32 v10, v32, v30, v45
	v_max3_u32 v12, v36, v12, v13
	v_max3_u32 v13, v15, v22, v44
	v_max3_u32 v15, v37, v24, v23
	v_max3_u32 v19, v28, v31, v39
	v_max3_u32 v14, v40, v14, v17
	v_max3_u32 v8, v8, v11, v38
	v_max3_u32 v11, v41, v33, v18
	v_max3_u32 v5, v21, v5, v35
	v_max3_u32 v16, v42, v16, v26
	v_max3_u32 v1, v2, v1, v6
	v_max3_u32 v2, v43, v9, v27
	v_max_u32_e32 v6, v7, v19
	v_min_u32_e32 v7, v7, v19
	v_max_u32_e32 v9, v0, v14
	v_min_u32_e32 v0, v0, v14
	v_max_u32_e32 v14, v3, v8
	v_min_u32_e32 v3, v3, v8
	v_max_u32_e32 v8, v4, v11
	v_min_u32_e32 v4, v4, v11
	v_max_u32_e32 v11, v10, v5
	v_min_u32_e32 v5, v10, v5
	v_max_u32_e32 v10, v12, v16
	v_min_u32_e32 v12, v12, v16
	v_max_u32_e32 v16, v13, v1
	v_min_u32_e32 v1, v13, v1
	v_max_u32_e32 v13, v15, v2
	v_min_u32_e32 v2, v15, v2
	v_max_u32_e32 v15, v6, v11
	v_min_u32_e32 v6, v6, v11
	v_max_u32_e32 v11, v9, v10
	v_min_u32_e32 v9, v9, v10
	v_max_u32_e32 v10, v14, v16
	v_min_u32_e32 v14, v14, v16
	v_max_u32_e32 v16, v8, v13
	v_min_u32_e32 v8, v8, v13
	v_max_u32_e32 v13, v7, v5
	v_min_u32_e32 v5, v7, v5
	v_max_u32_e32 v7, v0, v12
	v_min_u32_e32 v0, v0, v12
	v_max_u32_e32 v12, v3, v1
	v_min_u32_e32 v1, v3, v1
	v_max_u32_e32 v3, v4, v2
	v_min_u32_e32 v2, v4, v2
	v_max_u32_e32 v4, v15, v10
	v_min_u32_e32 v10, v15, v10
	v_max_u32_e32 v15, v11, v16
	v_min_u32_e32 v11, v11, v16
	v_max_u32_e32 v16, v6, v14
	v_min_u32_e32 v6, v6, v14
	v_max_u32_e32 v14, v9, v8
	v_min_u32_e32 v8, v9, v8
	v_max_u32_e32 v9, v13, v12
	v_min_u32_e32 v12, v13, v12
	v_max_u32_e32 v13, v7, v3
	v_min_u32_e32 v3, v7, v3
	v_max_u32_e32 v7, v5, v1
	v_min_u32_e32 v1, v5, v1
	v_max_u32_e32 v5, v0, v2
	v_min_u32_e32 v0, v0, v2
	v_max_u32_e32 v2, v4, v15
	v_min_u32_e32 v4, v4, v15
	v_max_u32_e32 v15, v10, v11
	v_min_u32_e32 v10, v10, v11
	v_max_u32_e32 v11, v16, v14
	v_min_u32_e32 v14, v16, v14
	v_max_u32_e32 v16, v6, v8
	v_min_u32_e32 v6, v6, v8
	v_max_u32_e32 v8, v9, v13
	v_min_u32_e32 v9, v9, v13
	v_max_u32_e32 v13, v12, v3
	v_min_u32_e32 v3, v12, v3
	v_max_u32_e32 v12, v7, v5
	v_min_u32_e32 v5, v7, v5
	v_max_u32_e32 v7, v1, v0
	v_min_u32_e32 v0, v1, v0
	ds_bpermute_b32 v1, v173, v2
	ds_bpermute_b32 v17, v173, v4
	ds_bpermute_b32 v18, v173, v15
	ds_bpermute_b32 v19, v173, v10
	ds_bpermute_b32 v20, v173, v11
	ds_bpermute_b32 v21, v173, v14
	ds_bpermute_b32 v22, v173, v16
	ds_bpermute_b32 v23, v173, v6
	ds_bpermute_b32 v24, v173, v8
	ds_bpermute_b32 v25, v173, v9
	ds_bpermute_b32 v26, v173, v13
	ds_bpermute_b32 v27, v173, v0
	ds_bpermute_b32 v28, v173, v7
	ds_bpermute_b32 v29, v173, v5
	ds_bpermute_b32 v30, v173, v12
	ds_bpermute_b32 v31, v173, v3
	s_waitcnt lgkmcnt(4)
	v_max_u32_e32 v2, v2, v27
	s_waitcnt lgkmcnt(3)
	v_max_u32_e32 v4, v4, v28
	s_waitcnt lgkmcnt(2)
	v_max_u32_e32 v15, v15, v29
	s_waitcnt lgkmcnt(1)
	v_max_u32_e32 v10, v10, v30
	s_waitcnt lgkmcnt(0)
	v_max_u32_e32 v11, v11, v31
	v_max_u32_e32 v14, v14, v26
	v_max_u32_e32 v16, v16, v25
	v_max_u32_e32 v6, v6, v24
	v_max_u32_e32 v8, v8, v23
	v_max_u32_e32 v9, v9, v22
	v_max_u32_e32 v13, v13, v21
	v_max_u32_e32 v3, v3, v20
	v_max_u32_e32 v12, v12, v19
	v_max_u32_e32 v5, v5, v18
	v_max_u32_e32 v7, v7, v17
	v_max_u32_e32 v0, v0, v1
	v_max_u32_e32 v1, v2, v8
	v_min_u32_e32 v2, v2, v8
	v_max_u32_e32 v8, v4, v9
	v_min_u32_e32 v4, v4, v9
	v_max_u32_e32 v9, v15, v13
	v_min_u32_e32 v13, v15, v13
	v_max_u32_e32 v15, v10, v3
	v_min_u32_e32 v3, v10, v3
	v_max_u32_e32 v10, v11, v12
	v_min_u32_e32 v11, v11, v12
	v_max_u32_e32 v12, v14, v5
	v_min_u32_e32 v5, v14, v5
	v_max_u32_e32 v14, v16, v7
	v_min_u32_e32 v7, v16, v7
	v_max_u32_e32 v16, v6, v0
	v_min_u32_e32 v0, v6, v0
	v_max_u32_e32 v6, v1, v10
	v_min_u32_e32 v1, v1, v10
	v_max_u32_e32 v10, v8, v12
	v_min_u32_e32 v8, v8, v12
	v_max_u32_e32 v12, v9, v14
	v_min_u32_e32 v9, v9, v14
	v_max_u32_e32 v14, v15, v16
	v_min_u32_e32 v15, v15, v16
	v_max_u32_e32 v16, v2, v11
	v_min_u32_e32 v2, v2, v11
	v_max_u32_e32 v11, v4, v5
	v_min_u32_e32 v4, v4, v5
	v_max_u32_e32 v5, v13, v7
	v_min_u32_e32 v7, v13, v7
	v_max_u32_e32 v13, v3, v0
	v_max_u32_e32 v18, v1, v9
	v_min_u32_e32 v1, v1, v9
	v_max_u32_e32 v9, v8, v15
	v_min_u32_e32 v0, v3, v0
	v_max_u32_e32 v3, v6, v12
	v_min_u32_e32 v6, v6, v12
	v_max_u32_e32 v12, v10, v14
	v_max_u32_e32 v20, v11, v13
	v_min_u32_e32 v21, v11, v13
	v_max_u32_e32 v13, v18, v9
	v_min_u32_e32 v10, v10, v14
	v_min_u32_e32 v8, v8, v15
	v_max_u32_e32 v19, v16, v5
	v_max_u32_e32 v22, v2, v7
	v_min_u32_e32 v2, v2, v7
; DI unsigned f2ord(float f) { const unsigned u = __float_as_uint(f); return (u & 0x80000000u) ? ~u : (u | 0x80000000u); }
; DI float ord2f(unsigned o) { const unsigned u = (o & 0x80000000u) ? (o & 0x7fffffffu) : ~o; return __uint_as_float(u); }
; DI void peer_topk_phase(const bf16_t* __restrict__ qpk, const bf16_t* __restrict__ subk, int* __restrict__ eidx, float* __restrict__ gout) {
;     ...
;         unsigned ck[50];
; #pragma unroll
;         for (int a = 0; a < 16; ++a)
; #pragma unroll
;             for (int b = 0; b < 16 / (a + 1); ++b) {
;                 const float cv = ord2f(top[0][a] & ~127u) + ord2f(top[1][b] & ~127u);
;                 ck[combo_row_start(a) + b] = (f2ord(cv) & ~255u) | (unsigned)(((15 - a) << 4) | (15 - b));
;             }
	v_max_u32_e32 v23, v4, v0
	v_min_u32_e32 v0, v4, v0
	v_max_u32_e32 v15, v3, v12
	v_min_u32_e32 v17, v3, v12
	v_min_u32_e32 v12, v18, v9
	v_and_b32_e32 v18, 0xffffff80, v13
	v_min_u32_e32 v5, v16, v5
	v_max_u32_e32 v16, v6, v10
	v_min_u32_e32 v14, v6, v10
	v_max_u32_e32 v11, v1, v8
	v_min_u32_e32 v10, v1, v8
	v_max_u32_e32 v9, v19, v20
	v_min_u32_e32 v8, v19, v20
	v_max_u32_e32 v3, v2, v0
	v_min_u32_e32 v1, v2, v0
	v_and_b32_e32 v0, 0x7fffff80, v13
	v_and_b32_e32 v19, 0xffffff80, v12
	v_xor_b32_e32 v18, -1, v18
	v_cmp_gt_i32_e32 vcc, 0, v13
	v_and_b32_e32 v2, 0x7fffff80, v12
	v_xor_b32_e32 v19, -1, v19
	v_cndmask_b32_e32 v31, v18, v0, vcc
	v_cmp_gt_i32_e32 vcc, 0, v12
	v_and_b32_e32 v0, 0x7fffff80, v10
	v_and_b32_e32 v18, 0xffffff80, v9
	v_cndmask_b32_e32 v30, v19, v2, vcc
	v_bitop3_b32 v2, v10, s11, v10 bitop3:0xcf
	v_cmp_gt_i32_e32 vcc, 0, v10
	v_max_u32_e32 v7, v5, v21
	v_and_b32_e32 v19, 0xffffff80, v8
	v_cndmask_b32_e32 v32, v2, v0, vcc
	v_and_b32_e32 v0, 0x7fffff80, v9
	v_xor_b32_e32 v18, -1, v18
	v_cmp_gt_i32_e32 vcc, 0, v9
	v_min_u32_e32 v6, v5, v21
	v_max_u32_e32 v5, v22, v23
	v_min_u32_e32 v4, v22, v23
	v_and_b32_e32 v2, 0x7fffff80, v8
	v_xor_b32_e32 v19, -1, v19
	v_cndmask_b32_e32 v23, v18, v0, vcc
	v_cmp_gt_i32_e32 vcc, 0, v8
	v_and_b32_e32 v18, 0xffffff80, v7
	v_and_b32_e32 v0, 0x7fffff80, v7
	v_cndmask_b32_e32 v22, v19, v2, vcc
	v_and_b32_e32 v19, 0xffffff80, v6
	v_xor_b32_e32 v18, -1, v18
	v_cmp_gt_i32_e32 vcc, 0, v7
	v_and_b32_e32 v2, 0x7fffff80, v6
	v_xor_b32_e32 v19, -1, v19
	v_cndmask_b32_e32 v25, v18, v0, vcc
	v_cmp_gt_i32_e32 vcc, 0, v6
	v_and_b32_e32 v18, 0xffffff80, v5
	v_and_b32_e32 v0, 0x7fffff80, v5
	v_cndmask_b32_e32 v24, v19, v2, vcc
	v_and_b32_e32 v19, 0xffffff80, v4
	v_xor_b32_e32 v18, -1, v18
	v_cmp_gt_i32_e32 vcc, 0, v5
	v_and_b32_e32 v2, 0x7fffff80, v4
	v_xor_b32_e32 v19, -1, v19
	v_cndmask_b32_e32 v27, v18, v0, vcc
	v_cmp_gt_i32_e32 vcc, 0, v4
	v_and_b32_e32 v0, 0x7fffff80, v3
	v_and_b32_e32 v18, 0xffffff80, v1
	v_cndmask_b32_e32 v26, v19, v2, vcc
	v_bitop3_b32 v2, v3, s11, v3 bitop3:0xcf
	v_cmp_gt_i32_e32 vcc, 0, v3
	v_and_b32_e32 v19, 0xffffff80, v80
	v_xor_b32_e32 v18, -1, v18
	v_cndmask_b32_e32 v29, v2, v0, vcc
	v_and_b32_e32 v0, 0x7fffff80, v1
	v_cmp_gt_i32_e32 vcc, 0, v1
	v_and_b32_e32 v2, 0x7fffff80, v80
	v_xor_b32_e32 v19, -1, v19
	v_cndmask_b32_e32 v28, v18, v0, vcc
	v_cmp_gt_i32_e32 vcc, 0, v80
	v_and_b32_e32 v34, 0x7fffff80, v88
	v_and_b32_e32 v33, 0x7fffff80, v11
	v_cndmask_b32_e32 v0, v19, v2, vcc
	v_pk_add_f32 v[20:21], v[0:1], v[30:31] op_sel_hi:[0,1]
	v_not_b32_e32 v2, v21
	v_or_b32_e32 v18, 0x80000000, v21
	v_cmp_gt_i32_e32 vcc, 0, v21
	v_or_b32_e32 v19, 0x80000000, v20
	v_pk_add_f32 v[22:23], v[0:1], v[22:23] op_sel_hi:[0,1]
	v_cndmask_b32_e32 v2, v18, v2, vcc
	v_and_b32_e32 v2, 0xffffff00, v2
	v_or_b32_e32 v18, 0xfb, v2
	v_not_b32_e32 v2, v20
	v_cmp_gt_i32_e32 vcc, 0, v20
	v_pk_add_f32 v[24:25], v[0:1], v[24:25] op_sel_hi:[0,1]
	v_pk_add_f32 v[26:27], v[0:1], v[26:27] op_sel_hi:[0,1]
	v_cndmask_b32_e32 v2, v19, v2, vcc
	v_and_b32_e32 v2, 0xffffff00, v2
	v_or_b32_e32 v19, 0xfa, v2
	v_add_f32_e32 v2, v0, v32
	v_not_b32_e32 v20, v2
	v_or_b32_e32 v21, 0x80000000, v2
	v_cmp_gt_i32_e32 vcc, 0, v2
	v_pk_add_f32 v[28:29], v[0:1], v[28:29] op_sel_hi:[0,1]
	v_and_b32_e32 v38, 0x7fffff80, v85
	v_cndmask_b32_e32 v2, v21, v20, vcc
	v_and_b32_e32 v2, 0xffffff00, v2
	v_or_b32_e32 v20, 0xf8, v2
	v_not_b32_e32 v2, v23
	v_or_b32_e32 v21, 0x80000000, v23
	v_cmp_gt_i32_e32 vcc, 0, v23
	v_or_b32_e32 v23, 0x80000000, v22
	v_and_b32_e32 v41, 0x7fffff80, v68
	v_cndmask_b32_e32 v2, v21, v2, vcc
	v_and_b32_e32 v2, 0xffffff00, v2
	v_or_b32_e32 v21, 0xf7, v2
	v_not_b32_e32 v2, v22
	v_cmp_gt_i32_e32 vcc, 0, v22
	v_and_b32_e32 v43, 0x7fffff80, v66
	v_and_b32_e32 v90, 0x7fffff80, v64
	v_cndmask_b32_e32 v2, v23, v2, vcc
	v_and_b32_e32 v2, 0xffffff00, v2
	v_or_b32_e32 v22, 0xf6, v2
	v_not_b32_e32 v2, v25
	v_or_b32_e32 v23, 0x80000000, v25
	v_cmp_gt_i32_e32 vcc, 0, v25
	v_or_b32_e32 v25, 0x80000000, v24
	v_and_b32_e32 v75, 0x7fffff80, v15
	v_cndmask_b32_e32 v2, v23, v2, vcc
	v_and_b32_e32 v2, 0xffffff00, v2
	v_or_b32_e32 v23, 0xf5, v2
	v_not_b32_e32 v2, v24
	v_cmp_gt_i32_e32 vcc, 0, v24
	s_nop 1
	v_cndmask_b32_e32 v2, v25, v2, vcc
	v_and_b32_e32 v2, 0xffffff00, v2
	v_or_b32_e32 v24, 0xf4, v2
	v_not_b32_e32 v2, v27
	v_or_b32_e32 v25, 0x80000000, v27
	v_cmp_gt_i32_e32 vcc, 0, v27
	v_or_b32_e32 v27, 0x80000000, v26
	s_nop 0
	v_cndmask_b32_e32 v2, v25, v2, vcc
	v_and_b32_e32 v2, 0xffffff00, v2
	v_or_b32_e32 v25, 0xf3, v2
	v_not_b32_e32 v2, v26
	v_cmp_gt_i32_e32 vcc, 0, v26
	s_nop 1
	v_cndmask_b32_e32 v2, v27, v2, vcc
	v_and_b32_e32 v2, 0xffffff00, v2
	v_or_b32_e32 v26, 0xf2, v2
	v_not_b32_e32 v2, v29
	v_or_b32_e32 v27, 0x80000000, v29
	v_cmp_gt_i32_e32 vcc, 0, v29
	v_or_b32_e32 v29, 0x80000000, v28
	s_nop 0
	v_cndmask_b32_e32 v2, v27, v2, vcc
	v_and_b32_e32 v2, 0xffffff00, v2
	v_or_b32_e32 v27, 0xf1, v2
	v_not_b32_e32 v2, v28
	v_cmp_gt_i32_e32 vcc, 0, v28
	s_nop 1
	v_cndmask_b32_e32 v2, v29, v2, vcc
	v_and_b32_e32 v2, 0xffffff00, v2
	v_or_b32_e32 v28, 0xf0, v2
	v_and_b32_e32 v2, 0xffffff80, v11
	v_and_b32_e32 v29, 0xffffff80, v88
	v_xor_b32_e32 v35, -1, v2
	v_xor_b32_e32 v2, -1, v29
	v_cmp_gt_i32_e32 vcc, 0, v88
	s_nop 1
	v_cndmask_b32_e32 v2, v2, v34, vcc
	v_cmp_gt_i32_e32 vcc, 0, v11
	s_nop 1
	v_cndmask_b32_e32 v33, v35, v33, vcc
	v_add_f32_e32 v29, v33, v0
	v_not_b32_e32 v34, v29
	v_or_b32_e32 v35, 0x80000000, v29
	v_cmp_gt_i32_e32 vcc, 0, v29
	v_pk_add_f32 v[32:33], v[2:3], v[32:33] op_sel_hi:[0,1]
	s_nop 0
	v_cndmask_b32_e32 v29, v35, v34, vcc
	v_pk_add_f32 v[34:35], v[2:3], v[30:31] op_sel_hi:[0,1]
	v_not_b32_e32 v30, v35
; DI unsigned f2ord(float f) { const unsigned u = __float_as_uint(f); return (u & 0x80000000u) ? ~u : (u | 0x80000000u); }
; DI float ord2f(unsigned o) { const unsigned u = (o & 0x80000000u) ? (o & 0x7fffffffu) : ~o; return __uint_as_float(u); }
; DI void peer_topk_phase(const bf16_t* __restrict__ qpk, const bf16_t* __restrict__ subk, int* __restrict__ eidx, float* __restrict__ gout) {
;     ...
;         unsigned ck[50];
; #pragma unroll
;         for (int a = 0; a < 16; ++a)
; #pragma unroll
;             for (int b = 0; b < 16 / (a + 1); ++b) {
;                 const float cv = ord2f(top[0][a] & ~127u) + ord2f(top[1][b] & ~127u);
;                 ck[combo_row_start(a) + b] = (f2ord(cv) & ~255u) | (unsigned)(((15 - a) << 4) | (15 - b));
;             }
	v_or_b32_e32 v36, 0x80000000, v35
	v_cmp_gt_i32_e32 vcc, 0, v35
	v_and_b32_e32 v29, 0xffffff00, v29
	v_or_b32_e32 v29, 0xf9, v29
	v_cndmask_b32_e32 v30, v36, v30, vcc
	v_and_b32_e32 v30, 0xffffff00, v30
	v_or_b32_e32 v35, 0xeb, v30
	v_not_b32_e32 v30, v34
	v_or_b32_e32 v36, 0x80000000, v34
	v_cmp_gt_i32_e32 vcc, 0, v34
	v_or_b32_e32 v34, 0x80000000, v33
	s_nop 0
	v_cndmask_b32_e32 v30, v36, v30, vcc
	v_and_b32_e32 v30, 0xffffff00, v30
	v_or_b32_e32 v45, 0xea, v30
	v_not_b32_e32 v30, v33
	v_cmp_gt_i32_e32 vcc, 0, v33
	v_or_b32_e32 v33, 0x80000000, v32
	s_nop 0
	v_cndmask_b32_e32 v30, v34, v30, vcc
	v_and_b32_e32 v30, 0xffffff00, v30
	v_or_b32_e32 v46, 0xe9, v30
	v_not_b32_e32 v30, v32
	v_cmp_gt_i32_e32 vcc, 0, v32
	v_and_b32_e32 v32, 0xffffff80, v89
	v_and_b32_e32 v34, 0x7fffff80, v89
	v_cndmask_b32_e32 v30, v33, v30, vcc
	v_and_b32_e32 v30, 0xffffff00, v30
	v_or_b32_e32 v47, 0xe8, v30
	v_and_b32_e32 v30, 0xffffff80, v14
	v_and_b32_e32 v33, 0x7fffff80, v14
	v_xor_b32_e32 v30, -1, v30
	v_cmp_gt_i32_e32 vcc, 0, v14
	v_xor_b32_e32 v32, -1, v32
	s_nop 0
	v_cndmask_b32_e32 v33, v30, v33, vcc
	v_cmp_gt_i32_e32 vcc, 0, v89
	v_add_f32_e32 v30, v33, v0
	v_or_b32_e32 v36, 0x80000000, v30
	v_cndmask_b32_e32 v34, v32, v34, vcc
	v_not_b32_e32 v32, v30
	v_cmp_gt_i32_e32 vcc, 0, v30
	s_nop 1
	v_cndmask_b32_e32 v30, v36, v32, vcc
	v_add_f32_e32 v32, v33, v2
	v_not_b32_e32 v36, v32
	v_or_b32_e32 v37, 0x80000000, v32
	v_cmp_gt_i32_e32 vcc, 0, v32
	v_and_b32_e32 v30, 0xffffff00, v30
	v_or_b32_e32 v30, 0xfc, v30
	v_cndmask_b32_e32 v32, v37, v36, vcc
	v_and_b32_e32 v32, 0xffffff00, v32
	v_or_b32_e32 v48, 0xec, v32
	v_mov_b32_e32 v32, v31
	v_pk_add_f32 v[36:37], v[34:35], v[32:33] op_sel_hi:[0,1]
	v_not_b32_e32 v31, v37
	v_or_b32_e32 v32, 0x80000000, v37
	v_cmp_gt_i32_e32 vcc, 0, v37
	s_nop 1
	v_cndmask_b32_e32 v31, v32, v31, vcc
	v_and_b32_e32 v31, 0xffffff00, v31
	v_or_b32_e32 v49, 0xdc, v31
	v_not_b32_e32 v31, v36
	v_or_b32_e32 v32, 0x80000000, v36
	v_cmp_gt_i32_e32 vcc, 0, v36
	v_and_b32_e32 v36, 0x7fffff80, v16
	s_nop 0
	v_cndmask_b32_e32 v31, v32, v31, vcc
	v_and_b32_e32 v31, 0xffffff00, v31
	v_or_b32_e32 v50, 0xdb, v31
	v_and_b32_e32 v31, 0xffffff80, v16
	v_xor_b32_e32 v31, -1, v31
	v_cmp_gt_i32_e32 vcc, 0, v16
	v_and_b32_e32 v32, 0xffffff80, v85
	v_xor_b32_e32 v32, -1, v32
	v_cndmask_b32_e32 v37, v31, v36, vcc
	v_cmp_gt_i32_e32 vcc, 0, v85
	v_add_f32_e32 v31, v37, v0
	v_not_b32_e32 v36, v31
	v_cndmask_b32_e32 v32, v32, v38, vcc
	v_or_b32_e32 v38, 0x80000000, v31
	v_cmp_gt_i32_e32 vcc, 0, v31
	s_nop 1
	v_cndmask_b32_e32 v31, v38, v36, vcc
	v_add_f32_e32 v36, v37, v2
	v_not_b32_e32 v38, v36
	v_or_b32_e32 v39, 0x80000000, v36
	v_cmp_gt_i32_e32 vcc, 0, v36
	v_and_b32_e32 v31, 0xffffff00, v31
	v_or_b32_e32 v31, 0xfd, v31
	v_cndmask_b32_e32 v36, v39, v38, vcc
	v_and_b32_e32 v36, 0xffffff00, v36
	v_or_b32_e32 v51, 0xed, v36
	v_add_f32_e32 v36, v37, v34
	v_not_b32_e32 v38, v36
	v_or_b32_e32 v39, 0x80000000, v36
	v_cmp_gt_i32_e32 vcc, 0, v36
	s_nop 1
	v_cndmask_b32_e32 v36, v39, v38, vcc
	v_and_b32_e32 v36, 0xffffff00, v36
	v_or_b32_e32 v52, 0xdd, v36
	v_mov_b32_e32 v36, v33
	v_pk_add_f32 v[38:39], v[32:33], v[36:37] op_sel_hi:[0,1]
	v_not_b32_e32 v33, v39
	v_or_b32_e32 v36, 0x80000000, v39
	v_cmp_gt_i32_e32 vcc, 0, v39
	v_and_b32_e32 v39, 0x7fffff80, v77
	s_nop 0
	v_cndmask_b32_e32 v33, v36, v33, vcc
	v_and_b32_e32 v33, 0xffffff00, v33
	v_or_b32_e32 v53, 0xcd, v33
	v_not_b32_e32 v33, v38
	v_or_b32_e32 v36, 0x80000000, v38
	v_cmp_gt_i32_e32 vcc, 0, v38
	s_nop 1
	v_cndmask_b32_e32 v33, v36, v33, vcc
	v_and_b32_e32 v33, 0xffffff00, v33
	v_or_b32_e32 v54, 0xcc, v33
	v_and_b32_e32 v33, 0x7fffff80, v79
	v_bitop3_b32 v36, v79, s11, v79 bitop3:0xcf
	v_cmp_gt_i32_e32 vcc, 0, v79
	s_nop 1
	v_cndmask_b32_e32 v33, v36, v33, vcc
	v_add_f32_e32 v36, v37, v33
	v_not_b32_e32 v37, v36
	v_or_b32_e32 v38, 0x80000000, v36
	v_cmp_gt_i32_e32 vcc, 0, v36
	s_nop 1
	v_cndmask_b32_e32 v36, v38, v37, vcc
	v_and_b32_e32 v36, 0xffffff00, v36
	v_or_b32_e32 v55, 0xbd, v36
	v_and_b32_e32 v36, 0x7fffff80, v78
	v_bitop3_b32 v37, v78, s11, v78 bitop3:0xcf
	v_cmp_gt_i32_e32 vcc, 0, v78
	v_and_b32_e32 v38, 0x7fffff80, v17
	s_nop 0
	v_cndmask_b32_e32 v56, v37, v36, vcc
	v_and_b32_e32 v37, 0xffffff80, v77
	v_and_b32_e32 v36, 0xffffff80, v17
	v_xor_b32_e32 v37, -1, v37
	v_cmp_gt_i32_e32 vcc, 0, v77
	v_xor_b32_e32 v36, -1, v36
	s_nop 0
	v_cndmask_b32_e32 v57, v37, v39, vcc
	v_cmp_gt_i32_e32 vcc, 0, v17
	s_nop 1
	v_cndmask_b32_e32 v36, v36, v38, vcc
	v_add_f32_e32 v37, v36, v0
	v_not_b32_e32 v38, v37
	v_or_b32_e32 v39, 0x80000000, v37
	v_cmp_gt_i32_e32 vcc, 0, v37
	s_nop 1
	v_cndmask_b32_e32 v37, v39, v38, vcc
	v_and_b32_e32 v37, 0xffffff00, v37
	v_or_b32_e32 v58, 0xfe, v37
	v_add_f32_e32 v37, v36, v2
	v_not_b32_e32 v38, v37
	v_or_b32_e32 v39, 0x80000000, v37
	v_cmp_gt_i32_e32 vcc, 0, v37
	s_nop 1
	v_cndmask_b32_e32 v37, v39, v38, vcc
	v_and_b32_e32 v37, 0xffffff00, v37
	v_or_b32_e32 v59, 0xee, v37
	v_add_f32_e32 v37, v36, v34
	v_not_b32_e32 v38, v37
	v_or_b32_e32 v39, 0x80000000, v37
	v_cmp_gt_i32_e32 vcc, 0, v37
	s_nop 1
	v_cndmask_b32_e32 v37, v39, v38, vcc
	v_and_b32_e32 v37, 0xffffff00, v37
	v_or_b32_e32 v60, 0xde, v37
	v_add_f32_e32 v37, v36, v32
	v_not_b32_e32 v38, v37
	v_or_b32_e32 v39, 0x80000000, v37
	v_cmp_gt_i32_e32 vcc, 0, v37
	s_nop 1
	v_cndmask_b32_e32 v37, v39, v38, vcc
	v_and_b32_e32 v37, 0xffffff00, v37
	v_or_b32_e32 v61, 0xce, v37
	v_add_f32_e32 v37, v36, v33
	v_not_b32_e32 v38, v37
	v_or_b32_e32 v39, 0x80000000, v37
	v_cmp_gt_i32_e32 vcc, 0, v37
	s_nop 1
	v_cndmask_b32_e32 v37, v39, v38, vcc
	v_and_b32_e32 v37, 0xffffff00, v37
	v_or_b32_e32 v62, 0xbe, v37
	v_add_f32_e32 v37, v36, v56
; DI unsigned f2ord(float f) { const unsigned u = __float_as_uint(f); return (u & 0x80000000u) ? ~u : (u | 0x80000000u); }
; DI float ord2f(unsigned o) { const unsigned u = (o & 0x80000000u) ? (o & 0x7fffffffu) : ~o; return __uint_as_float(u); }
; DI void peer_topk_phase(const bf16_t* __restrict__ qpk, const bf16_t* __restrict__ subk, int* __restrict__ eidx, float* __restrict__ gout) {
;     ...
;         unsigned ck[50];
; #pragma unroll
;         for (int a = 0; a < 16; ++a)
; #pragma unroll
;             for (int b = 0; b < 16 / (a + 1); ++b) {
;                 const float cv = ord2f(top[0][a] & ~127u) + ord2f(top[1][b] & ~127u);
;                 ck[combo_row_start(a) + b] = (f2ord(cv) & ~255u) | (unsigned)(((15 - a) << 4) | (15 - b));
;             }
;         unsigned c0[16], c1[16], c2[16], c3[16];
; #pragma unroll
;         for (int i = 0; i < 16; ++i) { c0[i] = ck[i]; c1[i] = ck[16 + i]; c2[i] = ck[32 + i]; c3[i] = (i < 2) ? ck[48 + i] : 0u; }
; #pragma unroll
;         for (int n = 0; n < 63; ++n) { cex(c1[SORT16[n][0]], c1[SORT16[n][1]]); cex(c2[SORT16[n][0]], c2[SORT16[n][1]]); }
;         merge_top16(c0, c1); merge_top16(c2, c3); merge_top16(c0, c2);
	v_not_b32_e32 v38, v37
	v_or_b32_e32 v39, 0x80000000, v37
	v_cmp_gt_i32_e32 vcc, 0, v37
	s_nop 1
	v_cndmask_b32_e32 v37, v39, v38, vcc
	v_and_b32_e32 v37, 0xffffff00, v37
	v_or_b32_e32 v63, 0xae, v37
	v_add_f32_e32 v37, v36, v57
	v_not_b32_e32 v38, v37
	v_or_b32_e32 v39, 0x80000000, v37
	v_cmp_gt_i32_e32 vcc, 0, v37
	s_nop 1
	v_cndmask_b32_e32 v37, v39, v38, vcc
	v_and_b32_e32 v37, 0xffffff00, v37
	v_or_b32_e32 v72, 0x9e, v37
	v_and_b32_e32 v37, 0x7fffff80, v76
	v_bitop3_b32 v38, v76, s11, v76 bitop3:0xcf
	v_cmp_gt_i32_e32 vcc, 0, v76
	v_and_b32_e32 v39, 0x7fffff80, v70
	s_nop 0
	v_cndmask_b32_e32 v73, v38, v37, vcc
	v_add_f32_e32 v36, v36, v73
	v_not_b32_e32 v37, v36
	v_or_b32_e32 v38, 0x80000000, v36
	v_cmp_gt_i32_e32 vcc, 0, v36
	s_nop 1
	v_cndmask_b32_e32 v36, v38, v37, vcc
	v_and_b32_e32 v36, 0xffffff00, v36
	v_or_b32_e32 v74, 0x8e, v36
	v_and_b32_e32 v36, 0xffffff80, v71
	v_and_b32_e32 v37, 0xffffff80, v70
	v_and_b32_e32 v38, 0x7fffff80, v71
	v_xor_b32_e32 v36, -1, v36
	v_cmp_gt_i32_e32 vcc, 0, v71
	v_xor_b32_e32 v40, -1, v37
	s_nop 0
	v_cndmask_b32_e32 v37, v36, v38, vcc
	v_cmp_gt_i32_e32 vcc, 0, v70
	v_and_b32_e32 v38, 0xffffff80, v69
	v_xor_b32_e32 v38, -1, v38
	v_cndmask_b32_e32 v36, v40, v39, vcc
	v_and_b32_e32 v39, 0xffffff80, v68
	v_and_b32_e32 v40, 0x7fffff80, v69
	v_cmp_gt_i32_e32 vcc, 0, v69
	v_xor_b32_e32 v42, -1, v39
	s_nop 0
	v_cndmask_b32_e32 v39, v38, v40, vcc
	v_cmp_gt_i32_e32 vcc, 0, v68
	v_and_b32_e32 v40, 0xffffff80, v67
	v_xor_b32_e32 v40, -1, v40
	v_cndmask_b32_e32 v38, v42, v41, vcc
	v_and_b32_e32 v41, 0xffffff80, v66
	v_and_b32_e32 v42, 0x7fffff80, v67
	v_cmp_gt_i32_e32 vcc, 0, v67
	v_xor_b32_e32 v44, -1, v41
	s_nop 0
	v_cndmask_b32_e32 v41, v40, v42, vcc
	v_cmp_gt_i32_e32 vcc, 0, v66
	v_and_b32_e32 v42, 0x7fffff80, v65
	s_nop 0
	v_cndmask_b32_e32 v40, v44, v43, vcc
	v_bitop3_b32 v43, v65, s11, v65 bitop3:0xcf
	v_cmp_gt_i32_e32 vcc, 0, v65
	v_and_b32_e32 v44, 0xffffff80, v64
	s_nop 0
	v_cndmask_b32_e32 v43, v43, v42, vcc
	v_and_b32_e32 v42, 0xffffff80, v15
	v_xor_b32_e32 v91, -1, v42
	v_xor_b32_e32 v42, -1, v44
	v_cmp_gt_i32_e32 vcc, 0, v64
	s_nop 1
	v_cndmask_b32_e32 v42, v42, v90, vcc
	v_cmp_gt_i32_e32 vcc, 0, v15
	s_nop 1
	v_cndmask_b32_e32 v44, v91, v75, vcc
	v_add_f32_e32 v0, v44, v0
	v_not_b32_e32 v75, v0
	v_or_b32_e32 v90, 0x80000000, v0
	v_cmp_gt_i32_e32 vcc, 0, v0
	v_add_f32_e32 v2, v44, v2
	v_add_f32_e32 v34, v44, v34
	v_cndmask_b32_e32 v0, v90, v75, vcc
	v_not_b32_e32 v75, v2
	v_or_b32_e32 v90, 0x80000000, v2
	v_cmp_gt_i32_e32 vcc, 0, v2
	v_add_f32_e32 v32, v44, v32
	v_or_b32_e32 v0, 0xff, v0
	v_cndmask_b32_e32 v2, v90, v75, vcc
	v_not_b32_e32 v75, v34
	v_or_b32_e32 v90, 0x80000000, v34
	v_cmp_gt_i32_e32 vcc, 0, v34
	v_and_b32_e32 v2, 0xffffff00, v2
	v_or_b32_e32 v2, 0xef, v2
	v_cndmask_b32_e32 v34, v90, v75, vcc
	v_not_b32_e32 v75, v32
	v_or_b32_e32 v90, 0x80000000, v32
	v_cmp_gt_i32_e32 vcc, 0, v32
	v_and_b32_e32 v34, 0xffffff00, v34
	v_or_b32_e32 v34, 0xdf, v34
	v_cndmask_b32_e32 v32, v90, v75, vcc
	v_and_b32_e32 v32, 0xffffff00, v32
	v_or_b32_e32 v75, 0xcf, v32
	v_add_f32_e32 v32, v44, v33
	v_not_b32_e32 v33, v32
	v_or_b32_e32 v90, 0x80000000, v32
	v_cmp_gt_i32_e32 vcc, 0, v32
	s_nop 1
	v_cndmask_b32_e32 v32, v90, v33, vcc
	v_and_b32_e32 v32, 0xffffff00, v32
	v_or_b32_e32 v90, 0xbf, v32
	v_add_f32_e32 v32, v44, v56
	v_not_b32_e32 v33, v32
	v_or_b32_e32 v56, 0x80000000, v32
	v_cmp_gt_i32_e32 vcc, 0, v32
	s_nop 1
	v_cndmask_b32_e32 v32, v56, v33, vcc
	v_and_b32_e32 v32, 0xffffff00, v32
	v_or_b32_e32 v56, 0xaf, v32
	v_add_f32_e32 v32, v44, v57
	v_not_b32_e32 v33, v32
	v_or_b32_e32 v57, 0x80000000, v32
	v_cmp_gt_i32_e32 vcc, 0, v32
	s_nop 1
	v_cndmask_b32_e32 v32, v57, v33, vcc
	v_and_b32_e32 v32, 0xffffff00, v32
	v_or_b32_e32 v57, 0x9f, v32
	v_add_f32_e32 v32, v44, v73
	v_not_b32_e32 v33, v32
	v_or_b32_e32 v73, 0x80000000, v32
	v_cmp_gt_i32_e32 vcc, 0, v32
	s_nop 1
	v_cndmask_b32_e32 v32, v73, v33, vcc
	v_and_b32_e32 v32, 0xffffff00, v32
	v_or_b32_e32 v73, 0x8f, v32
	v_pk_add_f32 v[32:33], v[44:45], v[36:37] op_sel_hi:[0,1]
	v_not_b32_e32 v36, v33
	v_or_b32_e32 v37, 0x80000000, v33
	v_cmp_gt_i32_e32 vcc, 0, v33
	s_nop 1
	v_cndmask_b32_e32 v33, v37, v36, vcc
	v_and_b32_e32 v33, 0xffffff00, v33
	v_or_b32_e32 v36, 0x7f, v33
	v_not_b32_e32 v33, v32
	v_or_b32_e32 v37, 0x80000000, v32
	v_cmp_gt_i32_e32 vcc, 0, v32
	s_nop 1
	v_cndmask_b32_e32 v32, v37, v33, vcc
	v_and_b32_e32 v32, 0xffffff00, v32
	v_or_b32_e32 v37, 0x6f, v32
	v_pk_add_f32 v[32:33], v[44:45], v[38:39] op_sel_hi:[0,1]
	v_not_b32_e32 v38, v33
	v_or_b32_e32 v39, 0x80000000, v33
	v_cmp_gt_i32_e32 vcc, 0, v33
	s_nop 1
	v_cndmask_b32_e32 v33, v39, v38, vcc
	v_and_b32_e32 v33, 0xffffff00, v33
	v_or_b32_e32 v38, 0x5f, v33
	v_not_b32_e32 v33, v32
	v_or_b32_e32 v39, 0x80000000, v32
	v_cmp_gt_i32_e32 vcc, 0, v32
	s_nop 1
	v_cndmask_b32_e32 v32, v39, v33, vcc
	v_and_b32_e32 v32, 0xffffff00, v32
	v_or_b32_e32 v39, 0x4f, v32
	v_pk_add_f32 v[32:33], v[44:45], v[40:41] op_sel_hi:[0,1]
	v_not_b32_e32 v40, v33
	v_or_b32_e32 v41, 0x80000000, v33
	v_cmp_gt_i32_e32 vcc, 0, v33
	s_nop 1
	v_cndmask_b32_e32 v33, v41, v40, vcc
	v_and_or_b32 v40, v33, s21, 63
	v_not_b32_e32 v33, v32
	v_or_b32_e32 v41, 0x80000000, v32
	v_cmp_gt_i32_e32 vcc, 0, v32
	s_nop 1
	v_cndmask_b32_e32 v32, v41, v33, vcc
	v_and_or_b32 v41, v32, s21, 47
	v_pk_add_f32 v[32:33], v[44:45], v[42:43] op_sel_hi:[0,1]
	v_not_b32_e32 v42, v33
	v_or_b32_e32 v43, 0x80000000, v33
	v_cmp_gt_i32_e32 vcc, 0, v33
	v_min_u32_e32 v44, v54, v90
	s_nop 0
	v_cndmask_b32_e32 v33, v43, v42, vcc
	v_not_b32_e32 v42, v32
	v_or_b32_e32 v43, 0x80000000, v32
	v_cmp_gt_i32_e32 vcc, 0, v32
	v_and_or_b32 v33, v33, s21, 31
; DI void peer_topk_phase(const bf16_t* __restrict__ qpk, const bf16_t* __restrict__ subk, int* __restrict__ eidx, float* __restrict__ gout) {
;     ...
;         unsigned c0[16], c1[16], c2[16], c3[16];
; #pragma unroll
;         for (int i = 0; i < 16; ++i) { c0[i] = ck[i]; c1[i] = ck[16 + i]; c2[i] = ck[32 + i]; c3[i] = (i < 2) ? ck[48 + i] : 0u; }
; #pragma unroll
;         for (int n = 0; n < 63; ++n) { cex(c1[SORT16[n][0]], c1[SORT16[n][1]]); cex(c2[SORT16[n][0]], c2[SORT16[n][1]]); }
;         merge_top16(c0, c1); merge_top16(c2, c3); merge_top16(c0, c2);
	s_nop 0
	v_cndmask_b32_e32 v32, v43, v42, vcc
	v_max_u32_e32 v42, v2, v59
	v_min_u32_e32 v2, v2, v59
	v_max_u32_e32 v43, v54, v90
	v_max_u32_e32 v54, v51, v48
	v_min_u32_e32 v48, v51, v48
	v_max_u32_e32 v51, v62, v55
	v_min_u32_e32 v55, v62, v55
	v_max_u32_e32 v59, v42, v54
	v_min_u32_e32 v42, v42, v54
	v_max_u32_e32 v54, v43, v51
	v_min_u32_e32 v43, v43, v51
	v_max_u32_e32 v51, v2, v48
	v_min_u32_e32 v2, v2, v48
	v_max_u32_e32 v48, v44, v55
	v_min_u32_e32 v44, v44, v55
	v_max_u32_e32 v55, v51, v42
	v_min_u32_e32 v42, v51, v42
	v_max_u32_e32 v51, v48, v43
	v_min_u32_e32 v43, v48, v43
	v_max_u32_e32 v48, v35, v45
	v_min_u32_e32 v35, v35, v45
	v_max_u32_e32 v45, v56, v63
	v_min_u32_e32 v56, v56, v63
	v_max_u32_e32 v62, v46, v47
	v_min_u32_e32 v46, v46, v47
	v_max_u32_e32 v47, v57, v72
	v_min_u32_e32 v57, v57, v72
	v_max_u32_e32 v63, v48, v62
	v_min_u32_e32 v48, v48, v62
	v_max_u32_e32 v62, v45, v47
	v_min_u32_e32 v45, v45, v47
	v_max_u32_e32 v47, v35, v46
	v_min_u32_e32 v35, v35, v46
	v_max_u32_e32 v46, v56, v57
	v_min_u32_e32 v56, v56, v57
	v_max_u32_e32 v57, v47, v48
	v_min_u32_e32 v47, v47, v48
	v_max_u32_e32 v48, v46, v45
	v_min_u32_e32 v45, v46, v45
	v_max_u32_e32 v46, v59, v63
	v_min_u32_e32 v59, v59, v63
	v_max_u32_e32 v63, v54, v62
	v_min_u32_e32 v54, v54, v62
	v_max_u32_e32 v62, v42, v47
	v_min_u32_e32 v42, v42, v47
	v_max_u32_e32 v47, v43, v45
	v_min_u32_e32 v43, v43, v45
	v_max_u32_e32 v45, v62, v59
	v_min_u32_e32 v59, v62, v59
	v_max_u32_e32 v62, v47, v54
	v_min_u32_e32 v47, v47, v54
	v_max_u32_e32 v54, v55, v57
	v_min_u32_e32 v55, v55, v57
	v_max_u32_e32 v57, v51, v48
	v_min_u32_e32 v48, v51, v48
	v_max_u32_e32 v51, v2, v35
	v_min_u32_e32 v2, v2, v35
	v_max_u32_e32 v35, v44, v56
	v_min_u32_e32 v44, v44, v56
	v_max_u32_e32 v56, v51, v55
	v_min_u32_e32 v51, v51, v55
	v_max_u32_e32 v55, v35, v48
	v_min_u32_e32 v35, v35, v48
	v_max_u32_e32 v48, v54, v45
	v_min_u32_e32 v45, v54, v45
	v_max_u32_e32 v54, v57, v62
	v_min_u32_e32 v57, v57, v62
	v_max_u32_e32 v62, v56, v59
	v_min_u32_e32 v56, v56, v59
	v_max_u32_e32 v59, v55, v47
	v_min_u32_e32 v47, v55, v47
	v_max_u32_e32 v55, v51, v42
	v_min_u32_e32 v42, v51, v42
	v_max_u32_e32 v51, v35, v43
	v_min_u32_e32 v35, v35, v43
	v_max_u32_e32 v43, v34, v60
	v_min_u32_e32 v34, v34, v60
	v_max_u32_e32 v60, v73, v74
	v_min_u32_e32 v72, v73, v74
	v_max_u32_e32 v73, v52, v49
	v_min_u32_e32 v49, v52, v49
	v_max_u32_e32 v52, v36, v37
	v_min_u32_e32 v36, v36, v37
	v_max_u32_e32 v37, v43, v73
	v_min_u32_e32 v43, v43, v73
	v_max_u32_e32 v73, v60, v52
	v_min_u32_e32 v52, v60, v52
	v_max_u32_e32 v60, v34, v49
	v_min_u32_e32 v34, v34, v49
	v_max_u32_e32 v49, v72, v36
	v_min_u32_e32 v36, v72, v36
	v_max_u32_e32 v72, v60, v43
	v_min_u32_e32 v43, v60, v43
	v_max_u32_e32 v60, v49, v52
	v_min_u32_e32 v49, v49, v52
	v_max_u32_e32 v52, v50, v75
	v_min_u32_e32 v50, v50, v75
	v_max_u32_e32 v74, v38, v39
	v_min_u32_e32 v38, v38, v39
	v_max_u32_e32 v39, v61, v53
	v_min_u32_e32 v53, v61, v53
	v_max_u32_e32 v61, v40, v41
	v_min_u32_e32 v40, v40, v41
	v_max_u32_e32 v41, v52, v39
	v_min_u32_e32 v39, v52, v39
	v_max_u32_e32 v52, v74, v61
	v_min_u32_e32 v61, v74, v61
	v_max_u32_e32 v74, v50, v53
	v_min_u32_e32 v50, v50, v53
	v_max_u32_e32 v53, v38, v40
	v_min_u32_e32 v38, v38, v40
	v_max_u32_e32 v40, v74, v39
	v_min_u32_e32 v39, v74, v39
	v_max_u32_e32 v74, v53, v61
	v_min_u32_e32 v53, v53, v61
	v_max_u32_e32 v61, v37, v41
	v_min_u32_e32 v37, v37, v41
	v_max_u32_e32 v41, v73, v52
	v_min_u32_e32 v52, v73, v52
	v_max_u32_e32 v73, v43, v39
	v_min_u32_e32 v39, v43, v39
	v_max_u32_e32 v43, v49, v53
	v_min_u32_e32 v49, v49, v53
	v_max_u32_e32 v53, v73, v37
	v_min_u32_e32 v37, v73, v37
	v_max_u32_e32 v73, v43, v52
	v_min_u32_e32 v43, v43, v52
	v_max_u32_e32 v52, v72, v40
	v_min_u32_e32 v40, v72, v40
	v_max_u32_e32 v72, v60, v74
	v_min_u32_e32 v60, v60, v74
	v_max_u32_e32 v74, v34, v50
	v_min_u32_e32 v34, v34, v50
	v_max_u32_e32 v50, v36, v38
	v_min_u32_e32 v36, v36, v38
	v_max_u32_e32 v38, v74, v40
	v_min_u32_e32 v40, v74, v40
	v_max_u32_e32 v74, v50, v60
	v_min_u32_e32 v50, v50, v60
	v_max_u32_e32 v60, v52, v53
	v_min_u32_e32 v52, v52, v53
	v_max_u32_e32 v53, v72, v73
	v_min_u32_e32 v72, v72, v73
	v_max_u32_e32 v73, v38, v37
	v_min_u32_e32 v37, v38, v37
	v_max_u32_e32 v38, v74, v43
	v_min_u32_e32 v43, v74, v43
	v_max_u32_e32 v74, v40, v39
	v_min_u32_e32 v39, v40, v39
	v_max_u32_e32 v40, v50, v49
	v_min_u32_e32 v49, v50, v49
	v_min_u32_e32 v50, v46, v61
	v_max_u32_e32 v75, v63, v41
	v_min_u32_e32 v41, v63, v41
	v_max_u32_e32 v63, v56, v37
	v_min_u32_e32 v37, v56, v37
	v_max_u32_e32 v56, v47, v43
	v_min_u32_e32 v43, v47, v43
	v_max_u32_e32 v47, v63, v50
	v_min_u32_e32 v50, v63, v50
	v_max_u32_e32 v63, v56, v41
	v_min_u32_e32 v41, v56, v41
	v_max_u32_e32 v56, v45, v52
	v_min_u32_e32 v45, v45, v52
	v_max_u32_e32 v52, v57, v72
	v_min_u32_e32 v57, v57, v72
	v_max_u32_e32 v72, v42, v39
	v_min_u32_e32 v39, v42, v39
	v_max_u32_e32 v42, v35, v49
	v_min_u32_e32 v35, v35, v49
	v_max_u32_e32 v49, v72, v45
	v_min_u32_e32 v45, v72, v45
	v_max_u32_e32 v72, v42, v57
	v_min_u32_e32 v42, v42, v57
	v_max_u32_e32 v57, v56, v47
	v_min_u32_e32 v47, v56, v47
	v_max_u32_e32 v56, v52, v63
	v_min_u32_e32 v52, v52, v63
	v_max_u32_e32 v63, v49, v50
	v_min_u32_e32 v49, v49, v50
	v_max_u32_e32 v50, v72, v41
	v_min_u32_e32 v41, v72, v41
	v_max_u32_e32 v72, v45, v37
	v_min_u32_e32 v37, v45, v37
	v_max_u32_e32 v45, v42, v43
	v_min_u32_e32 v42, v42, v43
	v_max_u32_e32 v43, v48, v60
	v_min_u32_e32 v48, v48, v60
	v_max_u32_e32 v60, v54, v53
	v_min_u32_e32 v53, v54, v53
	v_max_u32_e32 v54, v55, v74
	v_min_u32_e32 v55, v55, v74
	v_max_u32_e32 v74, v51, v40
; DI void merge_top16(unsigned (&A)[16], const unsigned (&B)[16]) {
; #pragma unroll
;     for (int i = 0; i < 16; ++i) A[i] = max(A[i], B[15 - i]);
; #pragma unroll
;     for (int n = 0; n < 32; ++n) cex(A[BMERGE16[n][0]], A[BMERGE16[n][1]]);
; }
; DI void peer_topk_phase(const bf16_t* __restrict__ qpk, const bf16_t* __restrict__ subk, int* __restrict__ eidx, float* __restrict__ gout) {
;     ...
; #pragma unroll
;         for (int n = 0; n < 63; ++n) { cex(c1[SORT16[n][0]], c1[SORT16[n][1]]); cex(c2[SORT16[n][0]], c2[SORT16[n][1]]); }
;         merge_top16(c0, c1); merge_top16(c2, c3); merge_top16(c0, c2);
	v_min_u32_e32 v40, v51, v40
	v_max_u32_e32 v51, v54, v48
	v_min_u32_e32 v48, v54, v48
	v_max_u32_e32 v54, v74, v53
	v_min_u32_e32 v53, v74, v53
	v_max_u32_e32 v74, v62, v73
	v_min_u32_e32 v62, v62, v73
	v_max_u32_e32 v73, v59, v38
	v_min_u32_e32 v38, v59, v38
	v_max_u32_e32 v59, v2, v34
	v_min_u32_e32 v2, v2, v34
	v_max_u32_e32 v34, v44, v36
	v_min_u32_e32 v36, v44, v36
	v_max_u32_e32 v44, v59, v62
	v_min_u32_e32 v59, v59, v62
	v_max_u32_e32 v62, v34, v38
	v_min_u32_e32 v34, v34, v38
	v_max_u32_e32 v38, v74, v51
	v_min_u32_e32 v51, v74, v51
	v_max_u32_e32 v74, v73, v54
	v_min_u32_e32 v54, v73, v54
	v_max_u32_e32 v73, v44, v48
	v_min_u32_e32 v44, v44, v48
	v_max_u32_e32 v48, v62, v53
	v_min_u32_e32 v53, v62, v53
	v_max_u32_e32 v62, v59, v55
	v_min_u32_e32 v55, v59, v55
	v_max_u32_e32 v59, v34, v40
	v_min_u32_e32 v34, v34, v40
	v_and_or_b32 v32, v32, s21, 15
	v_min_u32_e32 v40, v43, v57
	v_max_u32_e32 v90, v60, v56
	v_min_u32_e32 v56, v60, v56
	v_min_u32_e32 v60, v38, v47
	v_max_u32_e32 v91, v74, v52
	v_min_u32_e32 v52, v74, v52
	v_min_u32_e32 v74, v51, v63
	v_max_u32_e32 v92, v54, v50
	v_min_u32_e32 v50, v54, v50
	v_min_u32_e32 v54, v73, v49
	v_max_u32_e32 v93, v48, v41
	v_min_u32_e32 v41, v48, v41
	v_min_u32_e32 v48, v44, v72
	v_max_u32_e32 v94, v53, v45
	v_min_u32_e32 v45, v53, v45
	v_min_u32_e32 v53, v62, v37
	v_max_u32_e32 v95, v59, v42
	v_min_u32_e32 v42, v59, v42
	v_min_u32_e32 v59, v55, v39
	v_max_u32_e32 v96, v34, v35
	v_min_u32_e32 v34, v34, v35
	v_max_u32_e32 v0, v0, v2
	v_max_u32_e32 v2, v58, v59
	v_max3_u32 v31, v31, v55, v39
	v_max_u32_e32 v30, v30, v53
	v_max3_u32 v18, v18, v62, v37
	v_max_u32_e32 v19, v19, v48
	v_max3_u32 v29, v29, v44, v72
	v_max_u32_e32 v20, v20, v54
	v_max3_u32 v21, v21, v73, v49
	v_max_u32_e32 v22, v22, v74
	v_max3_u32 v23, v23, v51, v63
	v_max_u32_e32 v24, v24, v60
	v_max3_u32 v25, v25, v38, v47
	v_max_u32_e32 v26, v26, v40
	v_max3_u32 v27, v27, v43, v57
	v_max3_u32 v28, v28, v46, v61
	v_max_u32_e32 v32, v34, v32
	v_max_u32_e32 v33, v36, v33
	v_max_u32_e32 v35, v0, v21
	v_min_u32_e32 v0, v0, v21
	v_max_u32_e32 v21, v2, v22
	v_min_u32_e32 v2, v2, v22
	v_max_u32_e32 v22, v31, v23
	v_min_u32_e32 v23, v31, v23
	v_max_u32_e32 v31, v30, v24
	v_min_u32_e32 v24, v30, v24
	v_max_u32_e32 v30, v18, v25
	v_min_u32_e32 v18, v18, v25
	v_max_u32_e32 v25, v19, v26
	v_min_u32_e32 v19, v19, v26
	v_max_u32_e32 v26, v29, v27
	v_min_u32_e32 v27, v29, v27
	v_max_u32_e32 v29, v20, v28
	v_min_u32_e32 v20, v20, v28
	v_max_u32_e32 v34, v75, v41
	v_min_u32_e32 v36, v75, v41
	v_max_u32_e32 v41, v90, v94
	v_min_u32_e32 v47, v90, v94
	v_max_u32_e32 v48, v56, v45
	v_min_u32_e32 v45, v56, v45
	v_max_u32_e32 v49, v91, v95
	v_min_u32_e32 v51, v91, v95
	v_max_u32_e32 v53, v52, v42
	v_min_u32_e32 v42, v52, v42
	v_max_u32_e32 v52, v92, v96
	v_min_u32_e32 v54, v92, v96
	v_max_u32_e32 v55, v50, v32
	v_min_u32_e32 v32, v50, v32
	v_max_u32_e32 v50, v93, v33
	v_min_u32_e32 v33, v93, v33
	v_max_u32_e32 v28, v35, v30
	v_min_u32_e32 v30, v35, v30
	v_max_u32_e32 v35, v21, v25
	v_min_u32_e32 v21, v21, v25
	v_max_u32_e32 v25, v22, v26
	v_min_u32_e32 v22, v22, v26
	v_max_u32_e32 v26, v31, v29
	v_min_u32_e32 v29, v31, v29
	v_max_u32_e32 v31, v0, v18
	v_min_u32_e32 v0, v0, v18
	v_max_u32_e32 v18, v2, v19
	v_min_u32_e32 v2, v2, v19
	v_max_u32_e32 v19, v23, v27
	v_min_u32_e32 v23, v23, v27
	v_max_u32_e32 v27, v24, v20
	v_min_u32_e32 v20, v24, v20
	v_max_u32_e32 v56, v34, v53
	v_min_u32_e32 v34, v34, v53
	v_max_u32_e32 v53, v41, v52
	v_min_u32_e32 v41, v41, v52
	v_max_u32_e32 v52, v48, v55
	v_min_u32_e32 v48, v48, v55
	v_max_u32_e32 v55, v49, v50
	v_min_u32_e32 v49, v49, v50
	v_max_u32_e32 v50, v36, v42
	v_min_u32_e32 v36, v36, v42
	v_max_u32_e32 v42, v47, v54
	v_min_u32_e32 v47, v47, v54
	v_max_u32_e32 v54, v45, v32
	v_min_u32_e32 v32, v45, v32
	v_max_u32_e32 v45, v51, v33
	v_min_u32_e32 v33, v51, v33
	v_max_u32_e32 v24, v28, v25
	v_min_u32_e32 v25, v28, v25
	v_max_u32_e32 v28, v35, v26
	v_min_u32_e32 v26, v35, v26
	v_max_u32_e32 v35, v30, v22
	v_min_u32_e32 v22, v30, v22
	v_max_u32_e32 v30, v21, v29
	v_min_u32_e32 v21, v21, v29
	v_max_u32_e32 v29, v31, v19
	v_min_u32_e32 v19, v31, v19
	v_max_u32_e32 v31, v18, v27
	v_min_u32_e32 v18, v18, v27
	v_max_u32_e32 v27, v0, v23
	v_min_u32_e32 v0, v0, v23
	v_max_u32_e32 v23, v2, v20
	v_min_u32_e32 v2, v2, v20
	v_max_u32_e32 v51, v56, v52
	v_min_u32_e32 v52, v56, v52
	v_max_u32_e32 v56, v53, v55
	v_min_u32_e32 v53, v53, v55
	v_max_u32_e32 v55, v34, v48
	v_min_u32_e32 v34, v34, v48
	v_max_u32_e32 v48, v41, v49
	v_min_u32_e32 v41, v41, v49
	v_max_u32_e32 v49, v50, v54
	v_min_u32_e32 v50, v50, v54
	v_max_u32_e32 v54, v42, v45
	v_min_u32_e32 v42, v42, v45
	v_max_u32_e32 v45, v36, v32
	v_min_u32_e32 v32, v36, v32
	v_max_u32_e32 v36, v47, v33
	v_min_u32_e32 v33, v47, v33
	v_min_u32_e32 v20, v24, v28
	v_min_u32_e32 v37, v25, v26
	v_min_u32_e32 v38, v35, v30
	v_min_u32_e32 v39, v22, v21
	v_min_u32_e32 v40, v29, v31
	v_min_u32_e32 v43, v19, v18
	v_min_u32_e32 v44, v27, v23
	v_min_u32_e32 v46, v0, v2
	v_min_u32_e32 v47, v51, v56
	v_min_u32_e32 v57, v52, v53
	v_min_u32_e32 v58, v55, v48
	v_min_u32_e32 v59, v34, v41
	v_min_u32_e32 v60, v49, v54
	v_min_u32_e32 v61, v50, v42
	v_min_u32_e32 v62, v45, v36
	v_min_u32_e32 v63, v32, v33
	v_max3_u32 v24, v24, v28, v63
	v_max3_u32 v20, v20, v32, v33
	v_max3_u32 v25, v25, v26, v62
	v_max3_u32 v26, v37, v45, v36
	v_max3_u32 v28, v35, v30, v61
	v_max3_u32 v30, v38, v50, v42
	v_max3_u32 v21, v22, v21, v60
	v_max3_u32 v22, v39, v49, v54
	v_max3_u32 v29, v29, v31, v59
	v_max3_u32 v31, v40, v34, v41
	v_max3_u32 v18, v19, v18, v58
	v_max3_u32 v19, v43, v55, v48
	v_max3_u32 v23, v27, v23, v57
; DI float ord2f(unsigned o) { const unsigned u = (o & 0x80000000u) ? (o & 0x7fffffffu) : ~o; return __uint_as_float(u); }
; DI void peer_topk_phase(const bf16_t* __restrict__ qpk, const bf16_t* __restrict__ subk, int* __restrict__ eidx, float* __restrict__ gout) {
;     ...
;         merge_top16(c0, c1); merge_top16(c2, c3); merge_top16(c0, c2);
;         float sv[16]; int se[16];
; #pragma unroll
;         for (int rd = 0; rd < 16; ++rd) {
;             const unsigned m = c0[rd];
;             const int asel = 15 - (int)((m >> 4) & 15u), bsel = 15 - (int)(m & 15u);
;             unsigned ka = top[0][0], kb = top[1][0];
; #pragma unroll
;             for (int i = 1; i < 16; ++i) { ka = (asel == i) ? top[0][i] : ka; kb = (bsel == i) ? top[1][i] : kb; }
;             sv[rd] = ord2f(ka & ~127u) + ord2f(kb & ~127u);
;             se[rd] = (127 - (int)(ka & 127u)) * 128 + (127 - (int)(kb & 127u));
;         }
	v_max3_u32 v27, v44, v52, v53
	v_max3_u32 v0, v0, v2, v47
	v_max3_u32 v2, v46, v51, v56
	v_max_u32_e32 v32, v24, v29
	v_min_u32_e32 v24, v24, v29
	v_max_u32_e32 v29, v20, v31
	v_min_u32_e32 v20, v20, v31
	v_max_u32_e32 v31, v25, v18
	v_min_u32_e32 v18, v25, v18
	v_max_u32_e32 v25, v26, v19
	v_min_u32_e32 v19, v26, v19
	v_max_u32_e32 v26, v28, v23
	v_min_u32_e32 v23, v28, v23
	v_max_u32_e32 v28, v30, v27
	v_min_u32_e32 v27, v30, v27
	v_max_u32_e32 v30, v21, v0
	v_min_u32_e32 v0, v21, v0
	v_max_u32_e32 v21, v22, v2
	v_min_u32_e32 v2, v22, v2
	v_max_u32_e32 v22, v32, v26
	v_min_u32_e32 v26, v32, v26
	v_max_u32_e32 v32, v29, v28
	v_min_u32_e32 v28, v29, v28
	v_max_u32_e32 v29, v31, v30
	v_min_u32_e32 v30, v31, v30
	v_max_u32_e32 v31, v25, v21
	v_min_u32_e32 v21, v25, v21
	v_max_u32_e32 v25, v24, v23
	v_min_u32_e32 v23, v24, v23
	v_max_u32_e32 v24, v20, v27
	v_min_u32_e32 v20, v20, v27
	v_max_u32_e32 v27, v18, v0
	v_min_u32_e32 v0, v18, v0
	v_max_u32_e32 v18, v19, v2
	v_min_u32_e32 v2, v19, v2
	v_max_u32_e32 v19, v22, v29
	v_min_u32_e32 v22, v22, v29
	v_max_u32_e32 v29, v32, v31
	v_min_u32_e32 v31, v32, v31
	v_max_u32_e32 v32, v26, v30
	v_min_u32_e32 v26, v26, v30
	v_max_u32_e32 v30, v28, v21
	v_min_u32_e32 v21, v28, v21
	v_max_u32_e32 v28, v25, v27
	v_min_u32_e32 v25, v25, v27
	v_max_u32_e32 v27, v24, v18
	v_min_u32_e32 v18, v24, v18
	v_max_u32_e32 v24, v23, v0
	v_min_u32_e32 v23, v23, v0
	v_max_u32_e32 v33, v20, v2
	v_min_u32_e32 v2, v20, v2
	v_max_u32_e32 v0, v19, v29
	v_min_u32_e32 v19, v19, v29
	v_max_u32_e32 v20, v22, v31
	v_min_u32_e32 v22, v22, v31
	v_max_u32_e32 v29, v32, v30
	v_min_u32_e32 v31, v32, v30
	v_max_u32_e32 v35, v28, v27
	v_min_u32_e32 v37, v28, v27
	v_max_u32_e32 v30, v23, v2
	v_min_u32_e32 v27, v23, v2
	v_max_u32_e32 v40, v25, v18
	v_min_u32_e32 v39, v25, v18
	v_max_u32_e32 v32, v26, v21
	v_min_u32_e32 v34, v26, v21
	v_max_u32_e32 v36, v24, v33
	v_min_u32_e32 v33, v24, v33
	v_lshrrev_b32_e32 v46, 6, v174
	v_lshlrev_b32_e32 v46, 13, v46
	v_lshl_or_b32 v46, v172, 2, v46
	v_mov_b32_e32 v47, 0xf00
	ds_write_b32 v46, v64
	ds_write_b32 v46, v65 offset:256
	ds_write_b32 v46, v66 offset:512
	ds_write_b32 v46, v67 offset:768
	ds_write_b32 v46, v68 offset:1024
	ds_write_b32 v46, v69 offset:1280
	ds_write_b32 v46, v70 offset:1536
	ds_write_b32 v46, v71 offset:1792
	s_waitcnt lgkmcnt(7)
	ds_write_b32 v46, v76 offset:2048
	ds_write_b32 v46, v77 offset:2304
	ds_write_b32 v46, v78 offset:2560
	ds_write_b32 v46, v79 offset:2816
	ds_write_b32 v46, v85 offset:3072
	ds_write_b32 v46, v89 offset:3328
	ds_write_b32 v46, v88 offset:3584
	ds_write_b32 v46, v80 offset:3840
	s_waitcnt lgkmcnt(7)
	ds_write_b32 v46, v1 offset:4096
	ds_write_b32 v46, v3 offset:4352
	ds_write_b32 v46, v4 offset:4608
	ds_write_b32 v46, v5 offset:4864
	ds_write_b32 v46, v6 offset:5120
	ds_write_b32 v46, v7 offset:5376
	ds_write_b32 v46, v8 offset:5632
	ds_write_b32 v46, v9 offset:5888
	s_waitcnt lgkmcnt(7)
	ds_write_b32 v46, v10 offset:6144
	ds_write_b32 v46, v11 offset:6400
	ds_write_b32 v46, v12 offset:6656
	ds_write_b32 v46, v13 offset:6912
	ds_write_b32 v46, v14 offset:7168
	ds_write_b32 v46, v16 offset:7424
	ds_write_b32 v46, v17 offset:7680
	ds_write_b32 v46, v15 offset:7936
	s_waitcnt lgkmcnt(0)
	v_lshlrev_b32_e32 v18, 4, v19
	v_and_or_b32 v18, v18, v47, v46
	ds_read_b32 v18, v18
	v_lshlrev_b32_e32 v2, 8, v19
	v_and_or_b32 v2, v2, v47, v46
	ds_read_b32 v2, v2 offset:4096
	v_lshlrev_b32_e32 v19, 8, v20
	v_and_or_b32 v19, v19, v47, v46
	ds_read_b32 v19, v19 offset:4096
	v_lshlrev_b32_e32 v20, 4, v20
	v_and_or_b32 v20, v20, v47, v46
	ds_read_b32 v20, v20
	v_lshlrev_b32_e32 v21, 8, v22
	v_and_or_b32 v21, v21, v47, v46
	ds_read_b32 v21, v21 offset:4096
	v_lshlrev_b32_e32 v22, 4, v22
	v_and_or_b32 v22, v22, v47, v46
	ds_read_b32 v22, v22
	v_lshlrev_b32_e32 v24, 4, v29
	v_and_or_b32 v24, v24, v47, v46
	ds_read_b32 v24, v24
	v_lshlrev_b32_e32 v23, 8, v29
	v_and_or_b32 v23, v23, v47, v46
	ds_read_b32 v23, v23 offset:4096
	s_waitcnt lgkmcnt(7)
	v_lshlrev_b32_e32 v26, 4, v31
	v_and_or_b32 v26, v26, v47, v46
	ds_read_b32 v26, v26
	v_lshlrev_b32_e32 v25, 8, v31
	v_and_or_b32 v25, v25, v47, v46
	ds_read_b32 v25, v25 offset:4096
	v_lshlrev_b32_e32 v29, 4, v32
	v_and_or_b32 v29, v29, v47, v46
	ds_read_b32 v29, v29
	v_lshlrev_b32_e32 v28, 8, v32
	v_and_or_b32 v28, v28, v47, v46
	ds_read_b32 v28, v28 offset:4096
	v_lshlrev_b32_e32 v32, 4, v34
	v_and_or_b32 v32, v32, v47, v46
	ds_read_b32 v32, v32
	v_lshlrev_b32_e32 v31, 8, v34
	v_and_or_b32 v31, v31, v47, v46
	ds_read_b32 v31, v31 offset:4096
	v_lshlrev_b32_e32 v34, 8, v35
	v_and_or_b32 v34, v34, v47, v46
	ds_read_b32 v34, v34 offset:4096
	v_lshlrev_b32_e32 v35, 4, v35
	v_and_or_b32 v35, v35, v47, v46
	ds_read_b32 v35, v35
	s_waitcnt lgkmcnt(7)
	v_lshlrev_b32_e32 v38, 4, v37
	v_and_or_b32 v38, v38, v47, v46
	ds_read_b32 v38, v38
	v_lshlrev_b32_e32 v37, 8, v37
	v_and_or_b32 v37, v37, v47, v46
	ds_read_b32 v37, v37 offset:4096
	v_lshlrev_b32_e32 v41, 4, v40
	v_and_or_b32 v41, v41, v47, v46
	ds_read_b32 v41, v41
	v_lshlrev_b32_e32 v40, 8, v40
	v_and_or_b32 v40, v40, v47, v46
	ds_read_b32 v40, v40 offset:4096
	v_lshlrev_b32_e32 v42, 4, v39
	v_and_or_b32 v42, v42, v47, v46
	ds_read_b32 v42, v42
	v_lshlrev_b32_e32 v39, 8, v39
	v_and_or_b32 v39, v39, v47, v46
	ds_read_b32 v39, v39 offset:4096
	v_lshlrev_b32_e32 v43, 4, v36
	v_and_or_b32 v43, v43, v47, v46
	ds_read_b32 v43, v43
	v_lshlrev_b32_e32 v36, 8, v36
	v_and_or_b32 v36, v36, v47, v46
	ds_read_b32 v36, v36 offset:4096
	s_waitcnt lgkmcnt(7)
	v_lshlrev_b32_e32 v44, 4, v33
	v_and_or_b32 v44, v44, v47, v46
	ds_read_b32 v44, v44
	v_lshlrev_b32_e32 v33, 8, v33
	v_and_or_b32 v33, v33, v47, v46
	ds_read_b32 v33, v33 offset:4096
	v_lshlrev_b32_e32 v45, 4, v30
	v_and_or_b32 v45, v45, v47, v46
	ds_read_b32 v45, v45
	v_lshlrev_b32_e32 v30, 8, v30
	v_and_or_b32 v30, v30, v47, v46
	ds_read_b32 v30, v30 offset:4096
	v_lshlrev_b32_e32 v6, 4, v0
	v_and_or_b32 v6, v6, v47, v46
	ds_read_b32 v6, v6
	v_lshlrev_b32_e32 v5, 8, v0
	v_and_or_b32 v5, v5, v47, v46
	ds_read_b32 v5, v5 offset:4096
	v_lshlrev_b32_e32 v4, 4, v27
	v_and_or_b32 v4, v4, v47, v46
	ds_read_b32 v4, v4
	v_lshlrev_b32_e32 v3, 8, v27
	v_and_or_b32 v3, v3, v47, v46
	ds_read_b32 v3, v3 offset:4096
	s_waitcnt lgkmcnt(0)
	v_lshlrev_b64 v[0:1], 7, v[86:87]
	v_lshl_or_b32 v0, v179, 4, v0
	s_and_saveexec_b64 s[8:9], s[6:7]
	s_xor_b64 s[8:9], exec, s[8:9]
	s_cbranch_execz .LBB0_1166
; DI float ord2f(unsigned o) { const unsigned u = (o & 0x80000000u) ? (o & 0x7fffffffu) : ~o; return __uint_as_float(u); }
; DI void peer_topk_phase(const bf16_t* __restrict__ qpk, const bf16_t* __restrict__ subk, int* __restrict__ eidx, float* __restrict__ gout) {
;     ...
;         for (int rd = 0; rd < 16; ++rd) {
;             const unsigned m = c0[rd];
;             const int asel = 15 - (int)((m >> 4) & 15u), bsel = 15 - (int)(m & 15u);
;             unsigned ka = top[0][0], kb = top[1][0];
; #pragma unroll
;             for (int i = 1; i < 16; ++i) { ka = (asel == i) ? top[0][i] : ka; kb = (bsel == i) ? top[1][i] : kb; }
;             sv[rd] = ord2f(ka & ~127u) + ord2f(kb & ~127u);
;             se[rd] = (127 - (int)(ka & 127u)) * 128 + (127 - (int)(kb & 127u));
;         }
	v_and_b32_e32 v7, 0x7fffff80, v45
	v_bitop3_b32 v8, v45, s11, v45 bitop3:0xcf
	v_cmp_gt_i32_e32 vcc, 0, v45
	v_bitop3_b32 v9, v30, s11, v30 bitop3:0xcf
	s_nop 0
	v_cndmask_b32_e32 v7, v8, v7, vcc
	v_and_b32_e32 v8, 0x7fffff80, v30
	v_cmp_gt_i32_e32 vcc, 0, v30
	s_nop 1
	v_cndmask_b32_e32 v8, v9, v8, vcc
	v_add_f32_e32 v27, v8, v7
	v_and_b32_e32 v7, 0x7fffff80, v44
	v_bitop3_b32 v8, v44, s11, v44 bitop3:0xcf
	v_cmp_gt_i32_e32 vcc, 0, v44
	v_bitop3_b32 v9, v33, s11, v33 bitop3:0xcf
	s_nop 0
	v_cndmask_b32_e32 v7, v8, v7, vcc
	v_and_b32_e32 v8, 0x7fffff80, v33
	v_cmp_gt_i32_e32 vcc, 0, v33
	s_nop 1
	v_cndmask_b32_e32 v8, v9, v8, vcc
	v_add_f32_e32 v17, v8, v7
	v_and_b32_e32 v7, 0x7fffff80, v43
	v_bitop3_b32 v8, v43, s11, v43 bitop3:0xcf
	v_cmp_gt_i32_e32 vcc, 0, v43
	v_bitop3_b32 v9, v36, s11, v36 bitop3:0xcf
	s_nop 0
	v_cndmask_b32_e32 v7, v8, v7, vcc
	v_and_b32_e32 v8, 0x7fffff80, v36
	v_cmp_gt_i32_e32 vcc, 0, v36
	s_nop 1
	v_cndmask_b32_e32 v8, v9, v8, vcc
	v_add_f32_e32 v16, v8, v7
	v_and_b32_e32 v7, 0x7fffff80, v42
	v_bitop3_b32 v8, v42, s11, v42 bitop3:0xcf
	v_cmp_gt_i32_e32 vcc, 0, v42
	v_bitop3_b32 v9, v39, s11, v39 bitop3:0xcf
	s_nop 0
	v_cndmask_b32_e32 v7, v8, v7, vcc
	v_and_b32_e32 v8, 0x7fffff80, v39
	v_cmp_gt_i32_e32 vcc, 0, v39
	s_nop 1
	v_cndmask_b32_e32 v8, v9, v8, vcc
	v_add_f32_e32 v15, v8, v7
	v_and_b32_e32 v7, 0x7fffff80, v41
	v_bitop3_b32 v8, v41, s11, v41 bitop3:0xcf
	v_cmp_gt_i32_e32 vcc, 0, v41
	v_bitop3_b32 v9, v40, s11, v40 bitop3:0xcf
	s_nop 0
	v_cndmask_b32_e32 v7, v8, v7, vcc
	v_and_b32_e32 v8, 0x7fffff80, v40
	v_cmp_gt_i32_e32 vcc, 0, v40
	s_nop 1
	v_cndmask_b32_e32 v8, v9, v8, vcc
	v_add_f32_e32 v14, v8, v7
	v_and_b32_e32 v7, 0x7fffff80, v38
	v_bitop3_b32 v8, v38, s11, v38 bitop3:0xcf
	v_cmp_gt_i32_e32 vcc, 0, v38
	v_bitop3_b32 v9, v37, s11, v37 bitop3:0xcf
	s_nop 0
	v_cndmask_b32_e32 v7, v8, v7, vcc
	v_and_b32_e32 v8, 0x7fffff80, v37
	v_cmp_gt_i32_e32 vcc, 0, v37
	s_nop 1
	v_cndmask_b32_e32 v8, v9, v8, vcc
	v_add_f32_e32 v13, v8, v7
	v_and_b32_e32 v7, 0x7fffff80, v35
	v_bitop3_b32 v8, v35, s11, v35 bitop3:0xcf
	v_cmp_gt_i32_e32 vcc, 0, v35
	v_bitop3_b32 v9, v34, s11, v34 bitop3:0xcf
	s_nop 0
	v_cndmask_b32_e32 v7, v8, v7, vcc
	v_and_b32_e32 v8, 0x7fffff80, v34
	v_cmp_gt_i32_e32 vcc, 0, v34
	s_nop 1
	v_cndmask_b32_e32 v8, v9, v8, vcc
	v_add_f32_e32 v12, v8, v7
	v_and_b32_e32 v7, 0x7fffff80, v32
	v_bitop3_b32 v8, v32, s11, v32 bitop3:0xcf
	v_cmp_gt_i32_e32 vcc, 0, v32
	v_bitop3_b32 v9, v31, s11, v31 bitop3:0xcf
	s_nop 0
	v_cndmask_b32_e32 v7, v8, v7, vcc
	v_and_b32_e32 v8, 0x7fffff80, v31
	v_cmp_gt_i32_e32 vcc, 0, v31
	s_nop 1
	v_cndmask_b32_e32 v8, v9, v8, vcc
	v_add_f32_e32 v11, v8, v7
	v_and_b32_e32 v7, 0x7fffff80, v29
	v_bitop3_b32 v8, v29, s11, v29 bitop3:0xcf
	v_cmp_gt_i32_e32 vcc, 0, v29
	v_bitop3_b32 v9, v28, s11, v28 bitop3:0xcf
	s_nop 0
	v_cndmask_b32_e32 v7, v8, v7, vcc
	v_and_b32_e32 v8, 0x7fffff80, v28
	v_cmp_gt_i32_e32 vcc, 0, v28
	s_nop 1
	v_cndmask_b32_e32 v8, v9, v8, vcc
	v_add_f32_e32 v10, v8, v7
	v_and_b32_e32 v7, 0x7fffff80, v26
	v_bitop3_b32 v8, v26, s11, v26 bitop3:0xcf
	v_cmp_gt_i32_e32 vcc, 0, v26
	v_bitop3_b32 v9, v25, s11, v25 bitop3:0xcf
	v_and_b32_e32 v26, 0xffffff80, v3
	v_cndmask_b32_e32 v7, v8, v7, vcc
	v_and_b32_e32 v8, 0x7fffff80, v25
	v_cmp_gt_i32_e32 vcc, 0, v25
	v_and_b32_e32 v25, 0xffffff80, v5
	s_nop 0
	v_cndmask_b32_e32 v8, v9, v8, vcc
	v_add_f32_e32 v9, v8, v7
	v_and_b32_e32 v7, 0x7fffff80, v24
	v_bitop3_b32 v8, v24, s11, v24 bitop3:0xcf
	v_cmp_gt_i32_e32 vcc, 0, v24
	v_bitop3_b32 v24, v23, s11, v23 bitop3:0xcf
	s_nop 0
	v_cndmask_b32_e32 v7, v8, v7, vcc
	v_and_b32_e32 v8, 0x7fffff80, v23
	v_cmp_gt_i32_e32 vcc, 0, v23
	v_bitop3_b32 v23, v22, s11, v22 bitop3:0xcf
	s_nop 0
	v_cndmask_b32_e32 v8, v24, v8, vcc
	v_add_f32_e32 v8, v8, v7
	v_and_b32_e32 v7, 0x7fffff80, v22
	v_cmp_gt_i32_e32 vcc, 0, v22
	v_and_b32_e32 v22, 0x7fffff80, v21
	v_and_b32_e32 v24, 0x7fffff80, v3
	v_cndmask_b32_e32 v7, v23, v7, vcc
	v_bitop3_b32 v23, v21, s11, v21 bitop3:0xcf
	v_cmp_gt_i32_e32 vcc, 0, v21
	s_nop 1
	v_cndmask_b32_e32 v21, v23, v22, vcc
	v_add_f32_e32 v21, v21, v7
	v_and_b32_e32 v7, 0x7fffff80, v20
	v_bitop3_b32 v22, v20, s11, v20 bitop3:0xcf
; DI void peer_topk_phase(const bf16_t* __restrict__ qpk, const bf16_t* __restrict__ subk, int* __restrict__ eidx, float* __restrict__ gout) {
;     ...
;         float den = 0.f;
;         const float mx0 = sv[0];
; #pragma unroll
;         for (int i = 0; i < 16; ++i) { sv[i] = __expf(sv[i] - mx0); den += sv[i]; }
;         const float inv = 1.0f / den;
;         const size_t ob = (size_t)(t0 + r) * 128 + hh * 16;
;         if (h == 0) {
; #pragma unroll
;             for (int i = 0; i < 4; ++i) { int4 v = make_int4(se[4 * i], se[4 * i + 1], se[4 * i + 2], se[4 * i + 3]); *(int4*)(eidx + ob + 4 * i) = v; }
;         } else {
; #pragma unroll
;             for (int i = 0; i < 4; ++i) { f32x4 v = {sv[4 * i] * inv, sv[4 * i + 1] * inv, sv[4 * i + 2] * inv, sv[4 * i + 3] * inv}; *(f32x4*)(gout + ob + 4 * i) = v; }
;         }
	v_cmp_gt_i32_e32 vcc, 0, v20
	v_and_b32_e32 v20, 0x7fffff80, v19
	v_and_b32_e32 v23, 0x7fffff80, v5
	v_cndmask_b32_e32 v7, v22, v7, vcc
	v_bitop3_b32 v22, v19, s11, v19 bitop3:0xcf
	v_cmp_gt_i32_e32 vcc, 0, v19
	s_nop 1
	v_cndmask_b32_e32 v19, v22, v20, vcc
	v_add_f32_e32 v19, v19, v7
	v_and_b32_e32 v7, 0x7fffff80, v18
	v_bitop3_b32 v20, v18, s11, v18 bitop3:0xcf
	v_cmp_gt_i32_e32 vcc, 0, v18
	v_and_b32_e32 v18, 0x7fffff80, v2
	v_and_b32_e32 v22, 0xffffff80, v4
	v_cndmask_b32_e32 v7, v20, v7, vcc
	v_bitop3_b32 v20, v2, s11, v2 bitop3:0xcf
	v_cmp_gt_i32_e32 vcc, 0, v2
	v_xor_b32_e32 v22, -1, v22
	s_nop 0
	v_cndmask_b32_e32 v2, v20, v18, vcc
	v_add_f32_e32 v18, v2, v7
	v_and_b32_e32 v7, 0xffffff80, v6
	v_and_b32_e32 v2, 0x7fffff80, v6
	v_xor_b32_e32 v7, -1, v7
	v_cmp_gt_i32_e32 vcc, 0, v6
	v_and_b32_e32 v20, 0x7fffff80, v4
	s_nop 0
	v_cndmask_b32_e32 v7, v7, v2, vcc
	v_cmp_gt_i32_e32 vcc, 0, v4
	v_xor_b32_e32 v2, -1, v25
	v_xor_b32_e32 v4, -1, v26
	v_cndmask_b32_e32 v6, v22, v20, vcc
	v_cmp_gt_i32_e32 vcc, 0, v5
	s_nop 1
	v_cndmask_b32_e32 v5, v2, v23, vcc
	v_cmp_gt_i32_e32 vcc, 0, v3
	s_nop 1
	v_cndmask_b32_e32 v4, v4, v24, vcc
	v_pk_add_f32 v[2:3], v[4:5], v[6:7]
	s_nop 0
	v_sub_f32_e32 v4, v3, v3
	v_mul_f32_e32 v4, 0x3fb8aa3b, v4
	v_sub_f32_e32 v5, v18, v3
	v_exp_f32_e32 v4, v4
	v_mul_f32_e32 v5, 0x3fb8aa3b, v5
	v_sub_f32_e32 v6, v19, v3
	v_exp_f32_e32 v5, v5
	v_mul_f32_e32 v6, 0x3fb8aa3b, v6
	v_sub_f32_e32 v7, v21, v3
	v_exp_f32_e32 v6, v6
	v_mul_f32_e32 v7, 0x3fb8aa3b, v7
	v_sub_f32_e32 v8, v8, v3
	v_exp_f32_e32 v7, v7
	v_mul_f32_e32 v8, 0x3fb8aa3b, v8
	v_sub_f32_e32 v9, v9, v3
	v_add_f32_e32 v18, 0, v4
	v_exp_f32_e32 v8, v8
	v_mul_f32_e32 v9, 0x3fb8aa3b, v9
	v_sub_f32_e32 v10, v10, v3
	v_add_f32_e32 v18, v5, v18
	v_exp_f32_e32 v9, v9
	v_mul_f32_e32 v10, 0x3fb8aa3b, v10
	v_sub_f32_e32 v11, v11, v3
	v_add_f32_e32 v18, v6, v18
	v_exp_f32_e32 v10, v10
	v_mul_f32_e32 v11, 0x3fb8aa3b, v11
	v_sub_f32_e32 v12, v12, v3
	v_add_f32_e32 v18, v7, v18
	v_exp_f32_e32 v11, v11
	v_mul_f32_e32 v12, 0x3fb8aa3b, v12
	v_sub_f32_e32 v13, v13, v3
	v_add_f32_e32 v18, v8, v18
	v_exp_f32_e32 v12, v12
	v_mul_f32_e32 v13, 0x3fb8aa3b, v13
	v_sub_f32_e32 v14, v14, v3
	v_add_f32_e32 v18, v9, v18
	v_exp_f32_e32 v13, v13
	v_mul_f32_e32 v14, 0x3fb8aa3b, v14
	v_sub_f32_e32 v15, v15, v3
	v_add_f32_e32 v18, v10, v18
	v_exp_f32_e32 v14, v14
	v_mul_f32_e32 v15, 0x3fb8aa3b, v15
	v_add_f32_e32 v18, v11, v18
	v_exp_f32_e32 v15, v15
	v_add_f32_e32 v18, v12, v18
	v_add_f32_e32 v18, v13, v18
	v_sub_f32_e32 v16, v16, v3
	v_add_f32_e32 v18, v14, v18
	v_mul_f32_e32 v16, 0x3fb8aa3b, v16
	v_sub_f32_e32 v17, v17, v3
	v_add_f32_e32 v20, v15, v18
	v_exp_f32_e32 v16, v16
	v_mul_f32_e32 v17, 0x3fb8aa3b, v17
	v_sub_f32_e32 v18, v27, v3
	v_exp_f32_e32 v17, v17
	v_mul_f32_e32 v18, 0x3fb8aa3b, v18
	v_sub_f32_e32 v2, v2, v3
	v_exp_f32_e32 v18, v18
	v_mul_f32_e32 v2, 0x3fb8aa3b, v2
	v_exp_f32_e32 v19, v2
	v_add_f32_e32 v2, v16, v20
	v_add_f32_e32 v2, v17, v2
	v_add_f32_e32 v2, v18, v2
	v_add_f32_e32 v2, v19, v2
	v_div_scale_f32 v3, s[24:25], v2, v2, 1.0
	v_rcp_f32_e32 v20, v3
	v_readlane_b32 s24, v253, 18
	v_readlane_b32 s25, v253, 19
	v_fma_f32 v21, -v3, v20, 1.0
	v_fmac_f32_e32 v20, v21, v20
	v_div_scale_f32 v21, vcc, 1.0, v2, 1.0
	v_mul_f32_e32 v22, v21, v20
	v_fma_f32 v23, -v3, v22, v21
	v_fmac_f32_e32 v22, v23, v20
	v_fma_f32 v3, -v3, v22, v21
	v_div_fmas_f32 v3, v3, v20, v22
	v_div_fixup_f32 v20, v3, v2, 1.0
	v_lshl_add_u64 v[22:23], v[0:1], 2, s[24:25]
	v_pk_mul_f32 v[2:3], v[6:7], v[20:21] op_sel_hi:[1,0]
	v_pk_mul_f32 v[0:1], v[4:5], v[20:21] op_sel_hi:[1,0]
	global_store_dwordx4 v[22:23], v[0:3], off
	s_nop 1
	v_pk_mul_f32 v[2:3], v[10:11], v[20:21] op_sel_hi:[1,0]
	v_pk_mul_f32 v[0:1], v[8:9], v[20:21] op_sel_hi:[1,0]
	global_store_dwordx4 v[22:23], v[0:3], off offset:16
	s_nop 1
	v_pk_mul_f32 v[2:3], v[14:15], v[20:21] op_sel_hi:[1,0]
	v_pk_mul_f32 v[0:1], v[12:13], v[20:21] op_sel_hi:[1,0]
	global_store_dwordx4 v[22:23], v[0:3], off offset:32
	s_nop 1
	v_pk_mul_f32 v[2:3], v[18:19], v[20:21] op_sel_hi:[1,0]
	v_pk_mul_f32 v[0:1], v[16:17], v[20:21] op_sel_hi:[1,0]
	global_store_dwordx4 v[22:23], v[0:3], off offset:48

; #define U_ISSUE(SEG, E0, E1) { _Pragma("unroll") for (int b = 0; b < 16; ++b) { const int e = __shfl((b < 8) ? (E0) : (E1), (b & 7) * 8 + grp); SEG[b] = *(const u32x4*)(ub + (size_t)e * DM); } }
; DI void peer_u_phase(const bf16_t* __restrict__ x1, const int* __restrict__ eidx, const unsigned char* __restrict__ U8, float* __restrict__ ph) {
;     ...
;     for (int j_ = sm.j0; j_ < 8 * REP_PU; j_ += sm.jstep) {
;         const int j = j_ & 7;
;         const unsigned char* ub = U8 + 128 * j + 16 * l8;
;         const bf16_t* xb_ = x1 + 128 * j + 16 * l8;
;         float* pj = ph + (size_t)j * T_TOK * 128;
;         const int step = sm.nslot;
;         int t = sm.wslot;
;         if (t >= T_TOK) continue;
;         u32x4 sa[16], sb[16];
;         int e0n = 0, e1n = 0;
;         u32x4 xa, xb, xan, xbn;
;     ...
;         {
;             const int e0 = eidx[(size_t)t * 128 + lane], e1 = eidx[(size_t)t * 128 + 64 + lane];
;             xa = *(const u32x4*)(xb_ + (size_t)t * DM); xb = *(const u32x4*)(xb_ + (size_t)t * DM + 8);
;             U_ISSUE(sa, e0, e1)
;             if (t + step < T_TOK) { e0n = eidx[(size_t)(t + step) * 128 + lane]; e1n = eidx[(size_t)(t + step) * 128 + 64 + lane]; }
;         }
;         for (; t < T_TOK; t += 2 * step) {
;             int e0nn = 0, e1nn = 0;
;             const bool n1 = t + step < T_TOK, n2 = t + 2 * step < T_TOK, n3 = t + 3 * step < T_TOK;
;             if (n1) { U_ISSUE(sb, e0n, e1n) xan = *(const u32x4*)(xb_ + (size_t)(t + step) * DM); xbn = *(const u32x4*)(xb_ + (size_t)(t + step) * DM + 8); }
.LBB0_1223:
	s_and_saveexec_b64 s[18:19], vcc
	s_cbranch_execz .LBB0_1222
	global_load_dword v79, v[156:157], off
	global_load_dword v81, v[156:157], off offset:256
	s_lshl_b32 s2, s24, 7
	v_lshl_add_u64 v[166:167], v[152:153], 0, s[2:3]
	v_and_b32_e32 v252, 7, v172
	v_lshlrev_b32_e32 v252, 4, v252
	v_readfirstlane_b32 s98, v166
	v_readfirstlane_b32 s99, v167
	s_lshl_b32 s2, s24, 8
	v_lshl_add_u64 v[168:169], v[154:155], 0, s[2:3]
	v_lshl_add_u64 v[76:77], v[168:169], 0, v[158:159]
	global_load_dwordx4 v[72:75], v[76:77], off
	v_mov_b32_e32 v200, 0
	v_mov_b32_e32 v199, 0
	s_waitcnt vmcnt(2)
	ds_bpermute_b32 v78, v149, v79
	ds_bpermute_b32 v80, v151, v79
	ds_bpermute_b32 v82, v187, v79
	ds_bpermute_b32 v84, v188, v79
	ds_bpermute_b32 v86, v189, v79
	ds_bpermute_b32 v88, v190, v79
	ds_bpermute_b32 v90, v191, v79
	ds_bpermute_b32 v92, v198, v79
	s_waitcnt vmcnt(1)
	ds_bpermute_b32 v94, v149, v81
	ds_bpermute_b32 v96, v151, v81
	ds_bpermute_b32 v98, v187, v81
	ds_bpermute_b32 v100, v188, v81
	ds_bpermute_b32 v102, v189, v81
	ds_bpermute_b32 v104, v190, v81
	ds_bpermute_b32 v106, v191, v81
	ds_bpermute_b32 v108, v198, v81
	s_waitcnt lgkmcnt(0)
	v_lshl_add_u32 v78, v78, 10, v252
	v_lshl_add_u32 v80, v80, 10, v252
	v_lshl_add_u32 v82, v82, 10, v252
	v_lshl_add_u32 v84, v84, 10, v252
	v_lshl_add_u32 v86, v86, 10, v252
	v_lshl_add_u32 v88, v88, 10, v252
	v_lshl_add_u32 v90, v90, 10, v252
	v_lshl_add_u32 v92, v92, 10, v252
	v_lshl_add_u32 v94, v94, 10, v252
	v_lshl_add_u32 v96, v96, 10, v252
	v_lshl_add_u32 v98, v98, 10, v252
	v_lshl_add_u32 v100, v100, 10, v252
	v_lshl_add_u32 v102, v102, 10, v252
	v_lshl_add_u32 v104, v104, 10, v252
	v_lshl_add_u32 v106, v106, 10, v252
	v_lshl_add_u32 v108, v108, 10, v252
	v_mov_b32_e32 v110, v82
	v_mov_b32_e32 v112, v84
	v_mov_b32_e32 v114, v86
	v_mov_b32_e32 v116, v88
	v_mov_b32_e32 v118, v90
	v_mov_b32_e32 v120, v92
	v_mov_b32_e32 v122, v94
	v_mov_b32_e32 v124, v96
	v_mov_b32_e32 v126, v98
	v_mov_b32_e32 v128, v100
	v_mov_b32_e32 v130, v102
	v_mov_b32_e32 v132, v104
	v_mov_b32_e32 v134, v106
	v_mov_b32_e32 v136, v108
	global_load_dwordx4 v[140:143], v[76:77], off offset:16
	s_nop 0
	global_load_dwordx4 v[76:79], v78, s[98:99]
	s_nop 0
	global_load_dwordx4 v[80:83], v80, s[98:99]
	s_nop 0
	global_load_dwordx4 v[84:87], v110, s[98:99]
	global_load_dwordx4 v[88:91], v112, s[98:99]
	global_load_dwordx4 v[92:95], v114, s[98:99]
	global_load_dwordx4 v[96:99], v116, s[98:99]
	global_load_dwordx4 v[100:103], v118, s[98:99]
	global_load_dwordx4 v[104:107], v120, s[98:99]
	global_load_dwordx4 v[108:111], v122, s[98:99]
	s_nop 0
	global_load_dwordx4 v[112:115], v124, s[98:99]
	global_load_dwordx4 v[116:119], v126, s[98:99]
	global_load_dwordx4 v[120:123], v128, s[98:99]
	s_nop 0
	global_load_dwordx4 v[124:127], v130, s[98:99]
	s_nop 0
	global_load_dwordx4 v[128:131], v132, s[98:99]
	s_nop 0
	global_load_dwordx4 v[132:135], v134, s[98:99]
	s_nop 0
	global_load_dwordx4 v[136:139], v136, s[98:99]
	s_and_saveexec_b64 s[0:1], s[6:7]
	s_cbranch_execz .LBB0_1226
	global_load_dword v199, v[160:161], off
	global_load_dword v200, v[160:161], off offset:256

; #define U_ISSUE(SEG, E0, E1) { _Pragma("unroll") for (int b = 0; b < 16; ++b) { const int e = __shfl((b < 8) ? (E0) : (E1), (b & 7) * 8 + grp); SEG[b] = *(const u32x4*)(ub + (size_t)e * DM); } }
; DI void peer_u_phase(const bf16_t* __restrict__ x1, const int* __restrict__ eidx, const unsigned char* __restrict__ U8, float* __restrict__ ph) {
;     ...
;         for (; t < T_TOK; t += 2 * step) {
;             int e0nn = 0, e1nn = 0;
;             const bool n1 = t + step < T_TOK, n2 = t + 2 * step < T_TOK, n3 = t + 3 * step < T_TOK;
;             if (n1) { U_ISSUE(sb, e0n, e1n) xan = *(const u32x4*)(xb_ + (size_t)(t + step) * DM); xbn = *(const u32x4*)(xb_ + (size_t)(t + step) * DM + 8); }
;             if (n2) { e0nn = eidx[(size_t)(t + 2 * step) * 128 + lane]; e1nn = eidx[(size_t)(t + 2 * step) * 128 + 64 + lane]; }
.LBB0_1229:
	v_add_u32_e32 v180, s54, v182
	v_cmp_gt_i32_e64 s[14:15], s22, v180
	v_ashrrev_i32_e32 v181, 31, v180
	s_and_saveexec_b64 s[0:1], s[14:15]
	s_cbranch_execz .LBB0_1231
	s_waitcnt vmcnt(1)
	ds_bpermute_b32 v0, v149, v199
	ds_bpermute_b32 v2, v151, v199
	ds_bpermute_b32 v8, v187, v199
	ds_bpermute_b32 v10, v188, v199
	ds_bpermute_b32 v16, v189, v199
	ds_bpermute_b32 v18, v190, v199
	ds_bpermute_b32 v24, v191, v199
	ds_bpermute_b32 v26, v198, v199
	s_waitcnt vmcnt(0)
	ds_bpermute_b32 v32, v149, v200
	ds_bpermute_b32 v34, v151, v200
	ds_bpermute_b32 v40, v187, v200
	ds_bpermute_b32 v42, v188, v200
	ds_bpermute_b32 v48, v189, v200
	ds_bpermute_b32 v50, v190, v200
	ds_bpermute_b32 v56, v191, v200
	ds_bpermute_b32 v58, v198, v200
	s_waitcnt lgkmcnt(0)
	v_lshl_add_u32 v0, v0, 10, v252
	v_lshl_add_u32 v2, v2, 10, v252
	v_lshl_add_u32 v8, v8, 10, v252
	v_lshl_add_u32 v10, v10, 10, v252
	v_lshl_add_u32 v16, v16, 10, v252
	v_lshl_add_u32 v18, v18, 10, v252
	v_lshl_add_u32 v24, v24, 10, v252
	v_lshl_add_u32 v26, v26, 10, v252
	v_lshl_add_u32 v32, v32, 10, v252
	v_lshl_add_u32 v34, v34, 10, v252
	v_lshl_add_u32 v40, v40, 10, v252
	v_lshl_add_u32 v42, v42, 10, v252
	v_lshl_add_u32 v48, v48, 10, v252
	v_lshl_add_u32 v50, v50, 10, v252
	v_lshl_add_u32 v56, v56, 10, v252
	v_lshl_add_u32 v58, v58, 10, v252
	v_lshlrev_b64 v[64:65], 11, v[180:181]
	v_lshl_add_u64 v[64:65], v[168:169], 0, v[64:65]
	global_load_dwordx4 v[4:7], v0, s[98:99]
	s_nop 0
	global_load_dwordx4 v[0:3], v2, s[98:99]
	s_nop 0
	global_load_dwordx4 v[12:15], v8, s[98:99]
	s_nop 0
	global_load_dwordx4 v[8:11], v10, s[98:99]
	s_nop 0
	global_load_dwordx4 v[20:23], v16, s[98:99]
	s_nop 0
	global_load_dwordx4 v[16:19], v18, s[98:99]
	s_nop 0
	global_load_dwordx4 v[28:31], v24, s[98:99]
	s_nop 0
	global_load_dwordx4 v[24:27], v26, s[98:99]
	s_nop 0
	global_load_dwordx4 v[36:39], v32, s[98:99]
	s_nop 0
	global_load_dwordx4 v[32:35], v34, s[98:99]
	s_nop 0
	global_load_dwordx4 v[44:47], v40, s[98:99]
	s_nop 0
	global_load_dwordx4 v[40:43], v42, s[98:99]
	s_nop 0
	global_load_dwordx4 v[52:55], v48, s[98:99]
	s_nop 0
	global_load_dwordx4 v[48:51], v50, s[98:99]
	s_nop 0
	global_load_dwordx4 v[60:63], v56, s[98:99]
	s_nop 0
	global_load_dwordx4 v[56:59], v58, s[98:99]
	s_nop 0
	global_load_dwordx4 v[68:71], v[64:65], off offset:16
	s_nop 0
	global_load_dwordx4 v[64:67], v[64:65], off

; DI float dot_fp8_row(u32x4 u, u32x4 xa, u32x4 xb) {
;     unsigned a[8];
; #pragma unroll
;     for (int j = 0; j < 4; ++j) {
;         a[2 * j] = __builtin_bit_cast(unsigned, __builtin_amdgcn_cvt_scalef32_pk_bf16_fp8(u[j], 1.0f, false));
;         a[2 * j + 1] = __builtin_bit_cast(unsigned, __builtin_amdgcn_cvt_scalef32_pk_bf16_fp8(u[j], 1.0f, true));
;     }
;     return dot16(a, xa, xb);
; }
.LBB0_1233:
	s_or_b64 exec, exec, s[0:1]
	s_setprio 1
	s_waitcnt vmcnt(15)
	v_cvt_scalef32_pk_bf16_fp8 v203, v77, 1.0
	v_cvt_scalef32_pk_bf16_fp8 v183, v76, 1.0
	v_cvt_scalef32_pk_bf16_fp8 v202, v76, 1.0 op_sel:[1,0,0]
	v_cvt_scalef32_pk_bf16_fp8 v204, v77, 1.0 op_sel:[1,0,0]
	v_cvt_scalef32_pk_bf16_fp8 v205, v78, 1.0
	v_cvt_scalef32_pk_bf16_fp8 v206, v78, 1.0 op_sel:[1,0,0]
	v_cvt_scalef32_pk_bf16_fp8 v207, v79, 1.0
	v_cvt_scalef32_pk_bf16_fp8 v208, v79, 1.0 op_sel:[1,0,0]
	v_dot2_f32_bf16 v209, v183, v72, 0
	v_dot2_f32_bf16 v209, v202, v73, v209
	v_dot2_f32_bf16 v209, v203, v74, v209
	v_dot2_f32_bf16 v209, v204, v75, v209
	v_dot2_f32_bf16 v209, v205, v140, v209
	v_dot2_f32_bf16 v209, v206, v141, v209
	v_dot2_f32_bf16 v209, v207, v142, v209
	v_dot2_f32_bf16 v209, v208, v143, v209
	s_nop 2
	s_waitcnt vmcnt(14)
	v_cvt_scalef32_pk_bf16_fp8 v203, v81, 1.0
	v_cvt_scalef32_pk_bf16_fp8 v183, v80, 1.0
	v_cvt_scalef32_pk_bf16_fp8 v202, v80, 1.0 op_sel:[1,0,0]
	v_cvt_scalef32_pk_bf16_fp8 v204, v81, 1.0 op_sel:[1,0,0]
	v_cvt_scalef32_pk_bf16_fp8 v205, v82, 1.0
	v_cvt_scalef32_pk_bf16_fp8 v206, v82, 1.0 op_sel:[1,0,0]
	v_cvt_scalef32_pk_bf16_fp8 v207, v83, 1.0
	v_cvt_scalef32_pk_bf16_fp8 v208, v83, 1.0 op_sel:[1,0,0]
	v_dot2_f32_bf16 v210, v183, v72, 0
	v_dot2_f32_bf16 v210, v202, v73, v210
	v_dot2_f32_bf16 v210, v203, v74, v210
	v_dot2_f32_bf16 v210, v204, v75, v210
	v_dot2_f32_bf16 v210, v205, v140, v210
	v_dot2_f32_bf16 v210, v206, v141, v210
	v_dot2_f32_bf16 v210, v207, v142, v210
	v_dot2_f32_bf16 v210, v208, v143, v210
	s_nop 2
	s_waitcnt vmcnt(13)
	v_cvt_scalef32_pk_bf16_fp8 v203, v85, 1.0
	v_cvt_scalef32_pk_bf16_fp8 v183, v84, 1.0
	v_cvt_scalef32_pk_bf16_fp8 v202, v84, 1.0 op_sel:[1,0,0]
	v_cvt_scalef32_pk_bf16_fp8 v204, v85, 1.0 op_sel:[1,0,0]
	v_cvt_scalef32_pk_bf16_fp8 v205, v86, 1.0
	v_cvt_scalef32_pk_bf16_fp8 v206, v86, 1.0 op_sel:[1,0,0]
	v_cvt_scalef32_pk_bf16_fp8 v207, v87, 1.0
	v_cvt_scalef32_pk_bf16_fp8 v208, v87, 1.0 op_sel:[1,0,0]
	v_dot2_f32_bf16 v211, v183, v72, 0
	v_dot2_f32_bf16 v211, v202, v73, v211
	v_dot2_f32_bf16 v211, v203, v74, v211
	v_dot2_f32_bf16 v211, v204, v75, v211
	v_dot2_f32_bf16 v211, v205, v140, v211
	v_dot2_f32_bf16 v211, v206, v141, v211
	v_dot2_f32_bf16 v211, v207, v142, v211
	v_dot2_f32_bf16 v211, v208, v143, v211
	s_nop 2
	s_waitcnt vmcnt(12)
	v_cvt_scalef32_pk_bf16_fp8 v203, v89, 1.0
	v_cvt_scalef32_pk_bf16_fp8 v183, v88, 1.0
	v_cvt_scalef32_pk_bf16_fp8 v202, v88, 1.0 op_sel:[1,0,0]
	v_cvt_scalef32_pk_bf16_fp8 v204, v89, 1.0 op_sel:[1,0,0]
	v_cvt_scalef32_pk_bf16_fp8 v205, v90, 1.0
	v_cvt_scalef32_pk_bf16_fp8 v206, v90, 1.0 op_sel:[1,0,0]
	v_cvt_scalef32_pk_bf16_fp8 v207, v91, 1.0
	v_cvt_scalef32_pk_bf16_fp8 v208, v91, 1.0 op_sel:[1,0,0]
	v_dot2_f32_bf16 v212, v183, v72, 0
	v_dot2_f32_bf16 v212, v202, v73, v212
	v_dot2_f32_bf16 v212, v203, v74, v212
	v_dot2_f32_bf16 v212, v204, v75, v212
	v_dot2_f32_bf16 v212, v205, v140, v212
	v_dot2_f32_bf16 v212, v206, v141, v212
	v_dot2_f32_bf16 v212, v207, v142, v212
	v_dot2_f32_bf16 v212, v208, v143, v212
	s_nop 2
	s_waitcnt vmcnt(11)
	v_cvt_scalef32_pk_bf16_fp8 v203, v93, 1.0
	v_cvt_scalef32_pk_bf16_fp8 v183, v92, 1.0
	v_cvt_scalef32_pk_bf16_fp8 v202, v92, 1.0 op_sel:[1,0,0]
	v_cvt_scalef32_pk_bf16_fp8 v204, v93, 1.0 op_sel:[1,0,0]
	v_cvt_scalef32_pk_bf16_fp8 v205, v94, 1.0
	v_cvt_scalef32_pk_bf16_fp8 v206, v94, 1.0 op_sel:[1,0,0]
	v_cvt_scalef32_pk_bf16_fp8 v207, v95, 1.0
	v_cvt_scalef32_pk_bf16_fp8 v208, v95, 1.0 op_sel:[1,0,0]
	v_dot2_f32_bf16 v213, v183, v72, 0
	v_dot2_f32_bf16 v213, v202, v73, v213
	v_dot2_f32_bf16 v213, v203, v74, v213
	v_dot2_f32_bf16 v213, v204, v75, v213
	v_dot2_f32_bf16 v213, v205, v140, v213
	v_dot2_f32_bf16 v213, v206, v141, v213
	v_dot2_f32_bf16 v213, v207, v142, v213
	v_dot2_f32_bf16 v213, v208, v143, v213
	s_nop 2
	s_waitcnt vmcnt(10)
	v_cvt_scalef32_pk_bf16_fp8 v203, v97, 1.0
	v_cvt_scalef32_pk_bf16_fp8 v183, v96, 1.0
	v_cvt_scalef32_pk_bf16_fp8 v202, v96, 1.0 op_sel:[1,0,0]
	v_cvt_scalef32_pk_bf16_fp8 v204, v97, 1.0 op_sel:[1,0,0]
	v_cvt_scalef32_pk_bf16_fp8 v205, v98, 1.0
	v_cvt_scalef32_pk_bf16_fp8 v206, v98, 1.0 op_sel:[1,0,0]
	v_cvt_scalef32_pk_bf16_fp8 v207, v99, 1.0
	v_cvt_scalef32_pk_bf16_fp8 v208, v99, 1.0 op_sel:[1,0,0]
	v_dot2_f32_bf16 v214, v183, v72, 0
	v_dot2_f32_bf16 v214, v202, v73, v214
	v_dot2_f32_bf16 v214, v203, v74, v214
	v_dot2_f32_bf16 v214, v204, v75, v214
	v_dot2_f32_bf16 v214, v205, v140, v214
	v_dot2_f32_bf16 v214, v206, v141, v214
	v_dot2_f32_bf16 v214, v207, v142, v214
	v_dot2_f32_bf16 v214, v208, v143, v214
	s_nop 2
	s_waitcnt vmcnt(9)
	v_cvt_scalef32_pk_bf16_fp8 v203, v101, 1.0
	v_cvt_scalef32_pk_bf16_fp8 v183, v100, 1.0
	v_cvt_scalef32_pk_bf16_fp8 v202, v100, 1.0 op_sel:[1,0,0]
	v_cvt_scalef32_pk_bf16_fp8 v204, v101, 1.0 op_sel:[1,0,0]
	v_cvt_scalef32_pk_bf16_fp8 v205, v102, 1.0
	v_cvt_scalef32_pk_bf16_fp8 v206, v102, 1.0 op_sel:[1,0,0]
	v_cvt_scalef32_pk_bf16_fp8 v207, v103, 1.0
	v_cvt_scalef32_pk_bf16_fp8 v208, v103, 1.0 op_sel:[1,0,0]
	v_dot2_f32_bf16 v215, v183, v72, 0
	v_dot2_f32_bf16 v215, v202, v73, v215
	v_dot2_f32_bf16 v215, v203, v74, v215
	v_dot2_f32_bf16 v215, v204, v75, v215
	v_dot2_f32_bf16 v215, v205, v140, v215
	v_dot2_f32_bf16 v215, v206, v141, v215
	v_dot2_f32_bf16 v215, v207, v142, v215
	v_dot2_f32_bf16 v215, v208, v143, v215
	s_nop 2
	s_waitcnt vmcnt(8)
; DI float dot16(const unsigned (&a)[8], u32x4 b0, u32x4 b1) {
;     float acc;
;     asm volatile("v_dot2_f32_bf16 %0, %1, %9, 0\n\tv_dot2_f32_bf16 %0, %2, %10, %0\n\tv_dot2_f32_bf16 %0, %3, %11, %0\n\tv_dot2_f32_bf16 %0, %4, %12, %0\n\t"
;                  "v_dot2_f32_bf16 %0, %5, %13, %0\n\tv_dot2_f32_bf16 %0, %6, %14, %0\n\tv_dot2_f32_bf16 %0, %7, %15, %0\n\tv_dot2_f32_bf16 %0, %8, %16, %0\n\ts_nop 2"
;                  : "=&v"(acc)
;                  : "v"(a[0]), "v"(a[1]), "v"(a[2]), "v"(a[3]), "v"(a[4]), "v"(a[5]), "v"(a[6]), "v"(a[7]),
;                    "v"(b0.x), "v"(b0.y), "v"(b0.z), "v"(b0.w), "v"(b1.x), "v"(b1.y), "v"(b1.z), "v"(b1.w));
;     return acc;
; }
; DI float dot_fp8_row(u32x4 u, u32x4 xa, u32x4 xb) {
;     unsigned a[8];
; #pragma unroll
;     for (int j = 0; j < 4; ++j) {
;         a[2 * j] = __builtin_bit_cast(unsigned, __builtin_amdgcn_cvt_scalef32_pk_bf16_fp8(u[j], 1.0f, false));
;         a[2 * j + 1] = __builtin_bit_cast(unsigned, __builtin_amdgcn_cvt_scalef32_pk_bf16_fp8(u[j], 1.0f, true));
;     }
;     return dot16(a, xa, xb);
; }
	v_cvt_scalef32_pk_bf16_fp8 v203, v105, 1.0
	v_cvt_scalef32_pk_bf16_fp8 v183, v104, 1.0
	v_cvt_scalef32_pk_bf16_fp8 v202, v104, 1.0 op_sel:[1,0,0]
	v_cvt_scalef32_pk_bf16_fp8 v204, v105, 1.0 op_sel:[1,0,0]
	v_cvt_scalef32_pk_bf16_fp8 v205, v106, 1.0
	v_cvt_scalef32_pk_bf16_fp8 v206, v106, 1.0 op_sel:[1,0,0]
	v_cvt_scalef32_pk_bf16_fp8 v208, v107, 1.0
	v_cvt_scalef32_pk_bf16_fp8 v216, v107, 1.0 op_sel:[1,0,0]
	v_dot2_f32_bf16 v217, v183, v72, 0
	v_dot2_f32_bf16 v217, v202, v73, v217
	v_dot2_f32_bf16 v217, v203, v74, v217
	v_dot2_f32_bf16 v217, v204, v75, v217
	v_dot2_f32_bf16 v217, v205, v140, v217
	v_dot2_f32_bf16 v217, v206, v141, v217
	v_dot2_f32_bf16 v217, v208, v142, v217
	v_dot2_f32_bf16 v217, v216, v143, v217
	s_nop 2
	v_cndmask_b32_e64 v203, v210, v214, s[8:9]
	ds_bpermute_b32 v203, v193, v203
	v_cndmask_b32_e64 v204, v211, v215, s[8:9]
	ds_bpermute_b32 v204, v193, v204
	v_cndmask_b32_e64 v205, v212, v217, s[8:9]
	v_cndmask_b32_e64 v207, v209, v213, s[8:9]
	ds_bpermute_b32 v205, v193, v205
	ds_bpermute_b32 v207, v193, v207
	v_cndmask_b32_e64 v202, v214, v210, s[8:9]
	s_waitcnt lgkmcnt(3)
	v_add_f32_e32 v202, v202, v203
	v_cndmask_b32_e64 v203, v215, v211, s[8:9]
	s_waitcnt lgkmcnt(2)
	v_add_f32_e32 v203, v203, v204
	v_cndmask_b32_e64 v204, v217, v212, s[8:9]
	v_cndmask_b32_e64 v183, v213, v209, s[8:9]
	s_waitcnt lgkmcnt(1)
	v_add_f32_e32 v204, v204, v205
	s_waitcnt lgkmcnt(0)
	v_add_f32_e32 v183, v183, v207
	v_cndmask_b32_e64 v206, v202, v204, s[10:11]
	v_cndmask_b32_e64 v205, v183, v203, s[10:11]
	ds_bpermute_b32 v206, v194, v206
	ds_bpermute_b32 v205, v194, v205
	v_cndmask_b32_e64 v202, v204, v202, s[10:11]
	v_cndmask_b32_e64 v183, v203, v183, s[10:11]
	s_waitcnt vmcnt(7)
	v_cvt_scalef32_pk_bf16_fp8 v204, v108, 1.0
	s_waitcnt lgkmcnt(1)
	v_add_f32_e32 v202, v202, v206
	v_cvt_scalef32_pk_bf16_fp8 v206, v109, 1.0
	s_waitcnt lgkmcnt(0)
	v_add_f32_e32 v183, v183, v205
	v_cvt_scalef32_pk_bf16_fp8 v205, v108, 1.0 op_sel:[1,0,0]
	v_cvt_scalef32_pk_bf16_fp8 v207, v109, 1.0 op_sel:[1,0,0]
	v_cvt_scalef32_pk_bf16_fp8 v208, v110, 1.0
	v_cvt_scalef32_pk_bf16_fp8 v209, v110, 1.0 op_sel:[1,0,0]
	v_cvt_scalef32_pk_bf16_fp8 v210, v111, 1.0
	v_cvt_scalef32_pk_bf16_fp8 v211, v111, 1.0 op_sel:[1,0,0]
	v_dot2_f32_bf16 v212, v204, v72, 0
	v_dot2_f32_bf16 v212, v205, v73, v212
	v_dot2_f32_bf16 v212, v206, v74, v212
	v_dot2_f32_bf16 v212, v207, v75, v212
	v_dot2_f32_bf16 v212, v208, v140, v212
	v_dot2_f32_bf16 v212, v209, v141, v212
	v_dot2_f32_bf16 v212, v210, v142, v212
	v_dot2_f32_bf16 v212, v211, v143, v212
	s_nop 2
	s_waitcnt vmcnt(6)
	v_cvt_scalef32_pk_bf16_fp8 v206, v113, 1.0
	v_cvt_scalef32_pk_bf16_fp8 v204, v112, 1.0
	v_cvt_scalef32_pk_bf16_fp8 v205, v112, 1.0 op_sel:[1,0,0]
	v_cvt_scalef32_pk_bf16_fp8 v207, v113, 1.0 op_sel:[1,0,0]
	v_cvt_scalef32_pk_bf16_fp8 v208, v114, 1.0
	v_cvt_scalef32_pk_bf16_fp8 v209, v114, 1.0 op_sel:[1,0,0]
	v_cvt_scalef32_pk_bf16_fp8 v210, v115, 1.0
	v_cvt_scalef32_pk_bf16_fp8 v211, v115, 1.0 op_sel:[1,0,0]
	v_dot2_f32_bf16 v213, v204, v72, 0
	v_dot2_f32_bf16 v213, v205, v73, v213
	v_dot2_f32_bf16 v213, v206, v74, v213
	v_dot2_f32_bf16 v213, v207, v75, v213
	v_dot2_f32_bf16 v213, v208, v140, v213
	v_dot2_f32_bf16 v213, v209, v141, v213
	v_dot2_f32_bf16 v213, v210, v142, v213
	v_dot2_f32_bf16 v213, v211, v143, v213
	s_nop 2
	s_waitcnt vmcnt(5)
	v_cvt_scalef32_pk_bf16_fp8 v206, v117, 1.0
	v_cvt_scalef32_pk_bf16_fp8 v204, v116, 1.0
	v_cvt_scalef32_pk_bf16_fp8 v205, v116, 1.0 op_sel:[1,0,0]
	v_cvt_scalef32_pk_bf16_fp8 v207, v117, 1.0 op_sel:[1,0,0]
	v_cvt_scalef32_pk_bf16_fp8 v208, v118, 1.0
	v_cvt_scalef32_pk_bf16_fp8 v209, v118, 1.0 op_sel:[1,0,0]
	v_cvt_scalef32_pk_bf16_fp8 v210, v119, 1.0
	v_cvt_scalef32_pk_bf16_fp8 v211, v119, 1.0 op_sel:[1,0,0]
	v_dot2_f32_bf16 v214, v204, v72, 0
	v_dot2_f32_bf16 v214, v205, v73, v214
	v_dot2_f32_bf16 v214, v206, v74, v214
	v_dot2_f32_bf16 v214, v207, v75, v214
	v_dot2_f32_bf16 v214, v208, v140, v214
	v_dot2_f32_bf16 v214, v209, v141, v214
	v_dot2_f32_bf16 v214, v210, v142, v214
	v_dot2_f32_bf16 v214, v211, v143, v214
	s_nop 2
	s_waitcnt vmcnt(4)
	v_cvt_scalef32_pk_bf16_fp8 v206, v121, 1.0
	v_cvt_scalef32_pk_bf16_fp8 v204, v120, 1.0
	v_cvt_scalef32_pk_bf16_fp8 v205, v120, 1.0 op_sel:[1,0,0]
	v_cvt_scalef32_pk_bf16_fp8 v207, v121, 1.0 op_sel:[1,0,0]
	v_cvt_scalef32_pk_bf16_fp8 v208, v122, 1.0
	v_cvt_scalef32_pk_bf16_fp8 v209, v122, 1.0 op_sel:[1,0,0]
	v_cvt_scalef32_pk_bf16_fp8 v210, v123, 1.0
	v_cvt_scalef32_pk_bf16_fp8 v211, v123, 1.0 op_sel:[1,0,0]
	v_dot2_f32_bf16 v215, v204, v72, 0
	v_dot2_f32_bf16 v215, v205, v73, v215
	v_dot2_f32_bf16 v215, v206, v74, v215
	v_dot2_f32_bf16 v215, v207, v75, v215
	v_dot2_f32_bf16 v215, v208, v140, v215
	v_dot2_f32_bf16 v215, v209, v141, v215
	v_dot2_f32_bf16 v215, v210, v142, v215
	v_dot2_f32_bf16 v215, v211, v143, v215
	s_nop 2
	s_waitcnt vmcnt(3)
	v_cvt_scalef32_pk_bf16_fp8 v206, v125, 1.0
	v_cvt_scalef32_pk_bf16_fp8 v204, v124, 1.0
	v_cvt_scalef32_pk_bf16_fp8 v205, v124, 1.0 op_sel:[1,0,0]
	v_cvt_scalef32_pk_bf16_fp8 v207, v125, 1.0 op_sel:[1,0,0]
	v_cvt_scalef32_pk_bf16_fp8 v208, v126, 1.0
	v_cvt_scalef32_pk_bf16_fp8 v209, v126, 1.0 op_sel:[1,0,0]
	v_cvt_scalef32_pk_bf16_fp8 v210, v127, 1.0
	v_cvt_scalef32_pk_bf16_fp8 v211, v127, 1.0 op_sel:[1,0,0]
	v_dot2_f32_bf16 v216, v204, v72, 0
	v_dot2_f32_bf16 v216, v205, v73, v216
	v_dot2_f32_bf16 v216, v206, v74, v216
	v_dot2_f32_bf16 v216, v207, v75, v216
	v_dot2_f32_bf16 v216, v208, v140, v216
	v_dot2_f32_bf16 v216, v209, v141, v216
	v_dot2_f32_bf16 v216, v210, v142, v216
	v_dot2_f32_bf16 v216, v211, v143, v216
	s_nop 2
	s_waitcnt vmcnt(2)
; #define U_ISSUE(SEG, E0, E1) { _Pragma("unroll") for (int b = 0; b < 16; ++b) { const int e = __shfl((b < 8) ? (E0) : (E1), (b & 7) * 8 + grp); SEG[b] = *(const u32x4*)(ub + (size_t)e * DM); } }
; DI float dot_fp8_row(u32x4 u, u32x4 xa, u32x4 xb) {
;     unsigned a[8];
; #pragma unroll
;     for (int j = 0; j < 4; ++j) {
;         a[2 * j] = __builtin_bit_cast(unsigned, __builtin_amdgcn_cvt_scalef32_pk_bf16_fp8(u[j], 1.0f, false));
;         a[2 * j + 1] = __builtin_bit_cast(unsigned, __builtin_amdgcn_cvt_scalef32_pk_bf16_fp8(u[j], 1.0f, true));
;     }
;     return dot16(a, xa, xb);
; }
; DI void peer_u_phase(const bf16_t* __restrict__ x1, const int* __restrict__ eidx, const unsigned char* __restrict__ U8, float* __restrict__ ph) {
;     ...
;         {
;             const int e0 = eidx[(size_t)t * 128 + lane], e1 = eidx[(size_t)t * 128 + 64 + lane];
;             xa = *(const u32x4*)(xb_ + (size_t)t * DM); xb = *(const u32x4*)(xb_ + (size_t)t * DM + 8);
;             U_ISSUE(sa, e0, e1)
;             if (t + step < T_TOK) { e0n = eidx[(size_t)(t + step) * 128 + lane]; e1n = eidx[(size_t)(t + step) * 128 + 64 + lane]; }
;         }
;         for (; t < T_TOK; t += 2 * step) {
;             int e0nn = 0, e1nn = 0;
;             const bool n1 = t + step < T_TOK, n2 = t + 2 * step < T_TOK, n3 = t + 3 * step < T_TOK;
;             if (n1) { U_ISSUE(sb, e0n, e1n) xan = *(const u32x4*)(xb_ + (size_t)(t + step) * DM); xbn = *(const u32x4*)(xb_ + (size_t)(t + step) * DM + 8); }
;             if (n2) { e0nn = eidx[(size_t)(t + 2 * step) * 128 + lane]; e1nn = eidx[(size_t)(t + 2 * step) * 128 + 64 + lane]; }
;             U_COMPUTE(sa, t)
;             if (n1) {
;                 xa = xan; xb = xbn;
;                 if (n2) { U_ISSUE(sa, e0nn, e1nn) xan = *(const u32x4*)(xb_ + (size_t)(t + 2 * step) * DM); xbn = *(const u32x4*)(xb_ + (size_t)(t + 2 * step) * DM + 8); }
	v_cvt_scalef32_pk_bf16_fp8 v206, v129, 1.0
	v_cvt_scalef32_pk_bf16_fp8 v204, v128, 1.0
	v_cvt_scalef32_pk_bf16_fp8 v205, v128, 1.0 op_sel:[1,0,0]
	v_cvt_scalef32_pk_bf16_fp8 v207, v129, 1.0 op_sel:[1,0,0]
	v_cvt_scalef32_pk_bf16_fp8 v208, v130, 1.0
	v_cvt_scalef32_pk_bf16_fp8 v209, v130, 1.0 op_sel:[1,0,0]
	v_cvt_scalef32_pk_bf16_fp8 v210, v131, 1.0
	v_cvt_scalef32_pk_bf16_fp8 v211, v131, 1.0 op_sel:[1,0,0]
	v_dot2_f32_bf16 v217, v204, v72, 0
	v_dot2_f32_bf16 v217, v205, v73, v217
	v_dot2_f32_bf16 v217, v206, v74, v217
	v_dot2_f32_bf16 v217, v207, v75, v217
	v_dot2_f32_bf16 v217, v208, v140, v217
	v_dot2_f32_bf16 v217, v209, v141, v217
	v_dot2_f32_bf16 v217, v210, v142, v217
	v_dot2_f32_bf16 v217, v211, v143, v217
	s_nop 2
	s_waitcnt vmcnt(1)
	v_cvt_scalef32_pk_bf16_fp8 v206, v133, 1.0
	v_cvt_scalef32_pk_bf16_fp8 v204, v132, 1.0
	v_cvt_scalef32_pk_bf16_fp8 v205, v132, 1.0 op_sel:[1,0,0]
	v_cvt_scalef32_pk_bf16_fp8 v207, v133, 1.0 op_sel:[1,0,0]
	v_cvt_scalef32_pk_bf16_fp8 v208, v134, 1.0
	v_cvt_scalef32_pk_bf16_fp8 v209, v134, 1.0 op_sel:[1,0,0]
	v_cvt_scalef32_pk_bf16_fp8 v210, v135, 1.0
	v_cvt_scalef32_pk_bf16_fp8 v211, v135, 1.0 op_sel:[1,0,0]
	v_dot2_f32_bf16 v218, v204, v72, 0
	v_dot2_f32_bf16 v218, v205, v73, v218
	v_dot2_f32_bf16 v218, v206, v74, v218
	v_dot2_f32_bf16 v218, v207, v75, v218
	v_dot2_f32_bf16 v218, v208, v140, v218
	v_dot2_f32_bf16 v218, v209, v141, v218
	v_dot2_f32_bf16 v218, v210, v142, v218
	v_dot2_f32_bf16 v218, v211, v143, v218
	s_nop 2
	s_waitcnt vmcnt(0)
	v_cvt_scalef32_pk_bf16_fp8 v206, v137, 1.0
	v_cvt_scalef32_pk_bf16_fp8 v204, v136, 1.0
	v_cvt_scalef32_pk_bf16_fp8 v205, v136, 1.0 op_sel:[1,0,0]
	v_cvt_scalef32_pk_bf16_fp8 v207, v137, 1.0 op_sel:[1,0,0]
	v_cvt_scalef32_pk_bf16_fp8 v208, v138, 1.0
	v_cvt_scalef32_pk_bf16_fp8 v209, v138, 1.0 op_sel:[1,0,0]
	v_cvt_scalef32_pk_bf16_fp8 v211, v139, 1.0
	v_cvt_scalef32_pk_bf16_fp8 v219, v139, 1.0 op_sel:[1,0,0]
	v_dot2_f32_bf16 v220, v204, v72, 0
	v_dot2_f32_bf16 v220, v205, v73, v220
	v_dot2_f32_bf16 v220, v206, v74, v220
	v_dot2_f32_bf16 v220, v207, v75, v220
	v_dot2_f32_bf16 v220, v208, v140, v220
	v_dot2_f32_bf16 v220, v209, v141, v220
	v_dot2_f32_bf16 v220, v211, v142, v220
	v_dot2_f32_bf16 v220, v219, v143, v220
	s_nop 2
	v_cndmask_b32_e64 v206, v213, v217, s[8:9]
	ds_bpermute_b32 v206, v193, v206
	v_cndmask_b32_e64 v207, v214, v218, s[8:9]
	v_cndmask_b32_e64 v210, v212, v216, s[8:9]
	ds_bpermute_b32 v207, v193, v207
	v_cndmask_b32_e64 v208, v215, v220, s[8:9]
	ds_bpermute_b32 v210, v193, v210
	ds_bpermute_b32 v208, v193, v208
	v_cndmask_b32_e64 v205, v217, v213, s[8:9]
	s_waitcnt lgkmcnt(3)
	v_add_f32_e32 v205, v205, v206
	v_cndmask_b32_e64 v206, v218, v214, s[8:9]
	v_cndmask_b32_e64 v204, v216, v212, s[8:9]
	s_waitcnt lgkmcnt(2)
	v_add_f32_e32 v206, v206, v207
	v_cndmask_b32_e64 v207, v220, v215, s[8:9]
	s_waitcnt lgkmcnt(1)
	v_add_f32_e32 v204, v204, v210
	s_waitcnt lgkmcnt(0)
	v_add_f32_e32 v207, v207, v208
	v_cndmask_b32_e64 v208, v204, v206, s[10:11]
	v_cndmask_b32_e64 v209, v205, v207, s[10:11]
	ds_bpermute_b32 v208, v194, v208
	ds_bpermute_b32 v209, v194, v209
	v_cndmask_b32_e64 v204, v206, v204, s[10:11]
	v_cndmask_b32_e64 v205, v207, v205, s[10:11]
	v_cndmask_b32_e64 v203, v183, v202, s[12:13]
	s_waitcnt lgkmcnt(1)
	v_add_f32_e32 v204, v204, v208
	s_waitcnt lgkmcnt(0)
	v_add_f32_e32 v205, v205, v209
	ds_bpermute_b32 v203, v195, v203
	v_cndmask_b32_e64 v206, v204, v205, s[12:13]
	ds_bpermute_b32 v206, v195, v206
	v_cndmask_b32_e64 v183, v202, v183, s[12:13]
	s_waitcnt lgkmcnt(1)
	v_add_f32_e32 v207, v183, v203
	v_cndmask_b32_e64 v183, v205, v204, s[12:13]
	s_waitcnt lgkmcnt(0)
	v_add_f32_e32 v204, v183, v206
	s_setprio 0
	v_ashrrev_i32_e32 v183, 31, v182
	v_lshlrev_b64 v[202:203], 9, v[182:183]
	v_lshl_add_u64 v[202:203], v[178:179], 0, v[202:203]
	global_store_dword v[202:203], v207, off
	global_store_dword v[202:203], v204, off offset:256
	s_and_saveexec_b64 s[36:37], s[14:15]
	s_cbranch_execz .LBB0_1228
	v_mov_b64_e32 v[142:143], v[70:71]
	v_mov_b64_e32 v[74:75], v[66:67]
	v_mov_b64_e32 v[140:141], v[68:69]
	v_mov_b64_e32 v[72:73], v[64:65]
	s_and_saveexec_b64 s[0:1], s[16:17]
	s_cbranch_execz .LBB0_1236
	ds_bpermute_b32 v72, v149, v201
	ds_bpermute_b32 v74, v151, v201
	ds_bpermute_b32 v84, v187, v201
	ds_bpermute_b32 v86, v188, v201
	ds_bpermute_b32 v92, v189, v201
	s_waitcnt lgkmcnt(4)
	ds_bpermute_b32 v94, v190, v201
	s_waitcnt lgkmcnt(4)
	v_lshl_add_u32 v72, v72, 10, v252
	ds_bpermute_b32 v100, v191, v201
	v_lshl_add_u32 v74, v74, 10, v252
	s_waitcnt lgkmcnt(4)
	ds_bpermute_b32 v102, v198, v201
	global_load_dwordx4 v[76:79], v72, s[98:99]
	global_load_dwordx4 v[80:83], v74, s[98:99]
	v_lshl_add_u32 v72, v84, 10, v252
	s_waitcnt lgkmcnt(4)
	ds_bpermute_b32 v108, v149, v185
	v_lshl_add_u32 v74, v86, 10, v252
	s_waitcnt lgkmcnt(4)
	ds_bpermute_b32 v110, v151, v185
	global_load_dwordx4 v[84:87], v72, s[98:99]
	global_load_dwordx4 v[88:91], v74, s[98:99]
	v_lshl_add_u32 v72, v92, 10, v252
	s_waitcnt lgkmcnt(4)
	ds_bpermute_b32 v116, v187, v185
	v_lshl_add_u32 v74, v94, 10, v252
	s_waitcnt lgkmcnt(4)
	ds_bpermute_b32 v118, v188, v185
	global_load_dwordx4 v[92:95], v72, s[98:99]
	global_load_dwordx4 v[96:99], v74, s[98:99]
	v_lshl_add_u32 v72, v100, 10, v252
	s_waitcnt lgkmcnt(4)
	ds_bpermute_b32 v124, v189, v185
	v_lshl_add_u32 v74, v102, 10, v252
	s_waitcnt lgkmcnt(4)
	ds_bpermute_b32 v126, v190, v185
	global_load_dwordx4 v[100:103], v72, s[98:99]
	global_load_dwordx4 v[104:107], v74, s[98:99]
	v_lshl_add_u32 v72, v108, 10, v252
	s_waitcnt lgkmcnt(4)
	ds_bpermute_b32 v132, v191, v185
	v_lshl_add_u32 v74, v110, 10, v252
	s_waitcnt lgkmcnt(4)
	ds_bpermute_b32 v134, v198, v185
	global_load_dwordx4 v[108:111], v72, s[98:99]
	global_load_dwordx4 v[112:115], v74, s[98:99]
	v_lshl_add_u32 v72, v116, 10, v252
	s_waitcnt lgkmcnt(4)
	v_lshl_add_u32 v74, v118, 10, v252
	s_waitcnt lgkmcnt(3)
	global_load_dwordx4 v[116:119], v72, s[98:99]
	global_load_dwordx4 v[120:123], v74, s[98:99]
	v_lshl_add_u32 v72, v124, 10, v252
	s_waitcnt lgkmcnt(2)
	v_lshl_add_u32 v74, v126, 10, v252
	s_waitcnt lgkmcnt(1)
	global_load_dwordx4 v[124:127], v72, s[98:99]
	global_load_dwordx4 v[128:131], v74, s[98:99]
	v_lshl_add_u32 v72, v132, 10, v252
	s_waitcnt lgkmcnt(0)
	v_lshl_add_u32 v74, v134, 10, v252
	v_ashrrev_i32_e32 v185, 31, v184
	global_load_dwordx4 v[132:135], v72, s[98:99]
	global_load_dwordx4 v[136:139], v74, s[98:99]
	v_lshlrev_b64 v[72:73], 11, v[184:185]
	v_lshl_add_u64 v[72:73], v[168:169], 0, v[72:73]
	global_load_dwordx4 v[140:143], v[72:73], off offset:16
	s_nop 0
	global_load_dwordx4 v[72:75], v[72:73], off

; #define V_ISSUE(SEG, E0, E1) { _Pragma("unroll") for (int b = 0; b < 16; ++b) { const int e = __shfl((b < 8) ? (E0) : (E1), (b & 7) * 8 + grp); SEG[b] = *(const u32x4*)(vb + (size_t)e * DM); } }
; DI void peer_v_phase(const bf16_t* __restrict__ x1, const int* __restrict__ eidx, const float* __restrict__ wgt, const unsigned char* __restrict__ V8, bf16_t* __restrict__ y) {
;     ...
;         const unsigned char* vb = V8 + 128 * j + 16 * l8;
;         const int col = 128 * j + 16 * l8 + 2 * grp;
;         const int step = sm.nslot;
;         int t = sm.wslot;
;         if (t >= T_TOK) continue;
;         u32x4 sa[16], sb[16];
;         int e0n = 0, e1n = 0;
;         float w0, w1, w0n = 0.f, w1n = 0.f;
;     ...
;         {
;             const int e0 = eidx[(size_t)t * 128 + lane], e1 = eidx[(size_t)t * 128 + 64 + lane];
;             w0 = wgt[(size_t)t * 128 + lane]; w1 = wgt[(size_t)t * 128 + 64 + lane];
;             V_ISSUE(sa, e0, e1)
;             if (t + step < T_TOK) { e0n = eidx[(size_t)(t + step) * 128 + lane]; e1n = eidx[(size_t)(t + step) * 128 + 64 + lane]; }
;         }
.LBB0_1352:
	s_and_saveexec_b64 s[20:21], vcc
	s_cbranch_execz .LBB0_1351
	global_load_dword v65, v[134:135], off
	global_load_dword v67, v[136:137], off
	s_lshl_b32 s16, s5, 7
	v_lshl_add_u64 v[152:153], v[132:133], 0, s[16:17]
	v_and_b32_e32 v252, 7, v172
	v_lshlrev_b32_e32 v252, 4, v252
	v_readfirstlane_b32 s98, v152
	v_readfirstlane_b32 s99, v153
	global_load_dword v177, v[138:139], off
	global_load_dword v179, v[140:141], off
	v_mov_b32_e32 v180, 0
	v_mov_b32_e32 v178, 0
	v_mov_b32_e32 v176, 0
	s_waitcnt vmcnt(3)
	ds_bpermute_b32 v64, v129, v65
	ds_bpermute_b32 v66, v164, v65
	ds_bpermute_b32 v68, v165, v65
	ds_bpermute_b32 v70, v166, v65
	ds_bpermute_b32 v72, v167, v65
	ds_bpermute_b32 v74, v168, v65
	ds_bpermute_b32 v76, v169, v65
	ds_bpermute_b32 v78, v174, v65
	s_waitcnt vmcnt(2)
	ds_bpermute_b32 v80, v129, v67
	ds_bpermute_b32 v82, v164, v67
	ds_bpermute_b32 v84, v165, v67
	ds_bpermute_b32 v86, v166, v67
	ds_bpermute_b32 v88, v167, v67
	ds_bpermute_b32 v90, v168, v67
	ds_bpermute_b32 v92, v169, v67
	ds_bpermute_b32 v94, v174, v67
	s_waitcnt lgkmcnt(0)
	v_lshl_add_u32 v64, v64, 10, v252
	v_lshl_add_u32 v66, v66, 10, v252
	v_lshl_add_u32 v68, v68, 10, v252
	v_lshl_add_u32 v70, v70, 10, v252
	v_lshl_add_u32 v72, v72, 10, v252
	v_lshl_add_u32 v74, v74, 10, v252
	v_lshl_add_u32 v76, v76, 10, v252
	v_lshl_add_u32 v78, v78, 10, v252
	v_lshl_add_u32 v80, v80, 10, v252
	v_lshl_add_u32 v82, v82, 10, v252
	v_lshl_add_u32 v84, v84, 10, v252
	v_lshl_add_u32 v86, v86, 10, v252
	v_lshl_add_u32 v88, v88, 10, v252
	v_lshl_add_u32 v90, v90, 10, v252
	v_lshl_add_u32 v92, v92, 10, v252
	v_lshl_add_u32 v94, v94, 10, v252
	v_mov_b32_e32 v96, v66
	v_mov_b32_e32 v98, v68
	v_mov_b32_e32 v100, v70
	v_mov_b32_e32 v102, v72
	v_mov_b32_e32 v104, v74
	v_mov_b32_e32 v106, v76
	v_mov_b32_e32 v108, v78
	v_mov_b32_e32 v110, v80
	v_mov_b32_e32 v112, v82
	v_mov_b32_e32 v114, v84
	v_mov_b32_e32 v116, v86
	v_mov_b32_e32 v118, v88
	v_mov_b32_e32 v120, v90
	v_mov_b32_e32 v122, v92
	v_mov_b32_e32 v124, v94
	global_load_dwordx4 v[64:67], v64, s[98:99]
	s_nop 0
	global_load_dwordx4 v[68:71], v96, s[98:99]
	global_load_dwordx4 v[72:75], v98, s[98:99]
	global_load_dwordx4 v[76:79], v100, s[98:99]
	global_load_dwordx4 v[80:83], v102, s[98:99]
	global_load_dwordx4 v[84:87], v104, s[98:99]
	global_load_dwordx4 v[88:91], v106, s[98:99]
	global_load_dwordx4 v[92:95], v108, s[98:99]
	global_load_dwordx4 v[96:99], v110, s[98:99]
	s_nop 0
	global_load_dwordx4 v[100:103], v112, s[98:99]
	global_load_dwordx4 v[104:107], v114, s[98:99]
	global_load_dwordx4 v[108:111], v116, s[98:99]
	s_nop 0
	global_load_dwordx4 v[112:115], v118, s[98:99]
	s_nop 0
	global_load_dwordx4 v[116:119], v120, s[98:99]
	s_nop 0
	global_load_dwordx4 v[120:123], v122, s[98:99]
	s_nop 0
	global_load_dwordx4 v[124:127], v124, s[98:99]
	s_and_saveexec_b64 s[0:1], s[2:3]
	s_cbranch_execz .LBB0_1355
	global_load_dword v176, v[142:143], off
	global_load_dword v178, v[142:143], off offset:256

; #define V_ISSUE(SEG, E0, E1) { _Pragma("unroll") for (int b = 0; b < 16; ++b) { const int e = __shfl((b < 8) ? (E0) : (E1), (b & 7) * 8 + grp); SEG[b] = *(const u32x4*)(vb + (size_t)e * DM); } }
; DI void peer_v_phase(const bf16_t* __restrict__ x1, const int* __restrict__ eidx, const float* __restrict__ wgt, const unsigned char* __restrict__ V8, bf16_t* __restrict__ y) {
;     ...
;         {
;             const int e0 = eidx[(size_t)t * 128 + lane], e1 = eidx[(size_t)t * 128 + 64 + lane];
;             w0 = wgt[(size_t)t * 128 + lane]; w1 = wgt[(size_t)t * 128 + 64 + lane];
;             V_ISSUE(sa, e0, e1)
;             if (t + step < T_TOK) { e0n = eidx[(size_t)(t + step) * 128 + lane]; e1n = eidx[(size_t)(t + step) * 128 + 64 + lane]; }
;         }
;         for (; t < T_TOK; t += 2 * step) {
;             int e0nn = 0, e1nn = 0;
;             const bool n1 = t + step < T_TOK, n2 = t + 2 * step < T_TOK, n3 = t + 3 * step < T_TOK;
;             if (n1) { V_ISSUE(sb, e0n, e1n) w0n = wgt[(size_t)(t + step) * 128 + lane]; w1n = wgt[(size_t)(t + step) * 128 + 64 + lane]; }
;             if (n2) { e0nn = eidx[(size_t)(t + 2 * step) * 128 + lane]; e1nn = eidx[(size_t)(t + 2 * step) * 128 + 64 + lane]; }
.LBB0_1358:
	v_add_u32_e32 v158, s54, v160
	v_cmp_gt_i32_e64 s[12:13], s19, v158
	v_ashrrev_i32_e32 v159, 31, v158
	s_and_saveexec_b64 s[0:1], s[12:13]
	s_cbranch_execz .LBB0_1360
	s_waitcnt vmcnt(1)
	ds_bpermute_b32 v0, v129, v176
	ds_bpermute_b32 v2, v164, v176
	ds_bpermute_b32 v8, v165, v176
	ds_bpermute_b32 v10, v166, v176
	ds_bpermute_b32 v16, v167, v176
	ds_bpermute_b32 v18, v168, v176
	ds_bpermute_b32 v24, v169, v176
	ds_bpermute_b32 v26, v174, v176
	s_waitcnt vmcnt(0)
	ds_bpermute_b32 v32, v129, v178
	ds_bpermute_b32 v34, v164, v178
	ds_bpermute_b32 v40, v165, v178
	ds_bpermute_b32 v42, v166, v178
	ds_bpermute_b32 v48, v167, v178
	ds_bpermute_b32 v50, v168, v178
	ds_bpermute_b32 v56, v169, v178
	ds_bpermute_b32 v58, v174, v178
	s_waitcnt lgkmcnt(0)
	v_lshl_add_u32 v0, v0, 10, v252
	v_lshl_add_u32 v2, v2, 10, v252
	v_lshl_add_u32 v8, v8, 10, v252
	v_lshl_add_u32 v10, v10, 10, v252
	v_lshl_add_u32 v16, v16, 10, v252
	v_lshl_add_u32 v18, v18, 10, v252
	v_lshl_add_u32 v24, v24, 10, v252
	v_lshl_add_u32 v26, v26, 10, v252
	v_lshl_add_u32 v32, v32, 10, v252
	v_lshl_add_u32 v34, v34, 10, v252
	v_lshl_add_u32 v40, v40, 10, v252
	v_lshl_add_u32 v42, v42, 10, v252
	v_lshl_add_u32 v48, v48, 10, v252
	v_lshl_add_u32 v50, v50, 10, v252
	v_lshl_add_u32 v56, v56, 10, v252
	v_lshl_add_u32 v58, v58, 10, v252
	v_lshlrev_b64 v[162:163], 9, v[158:159]
	v_mov_b32_e32 v20, v18
	v_mov_b32_e32 v28, v26
	v_mov_b32_e32 v36, v34
	v_mov_b32_e32 v44, v42
	v_mov_b32_e32 v52, v50
	v_mov_b32_e32 v60, v58
	v_lshl_add_u64 v[162:163], v[144:145], 0, v[162:163]
	global_load_dwordx4 v[4:7], v0, s[98:99]
	s_nop 0
	global_load_dwordx4 v[0:3], v2, s[98:99]
	s_nop 0
	global_load_dwordx4 v[12:15], v8, s[98:99]
	s_nop 0
	global_load_dwordx4 v[8:11], v10, s[98:99]
	s_nop 0
	global_load_dwordx4 v[16:19], v16, s[98:99]
	s_nop 0
	global_load_dwordx4 v[20:23], v20, s[98:99]
	s_nop 0
	global_load_dwordx4 v[24:27], v24, s[98:99]
	s_nop 0
	global_load_dwordx4 v[28:31], v28, s[98:99]
	s_nop 0
	global_load_dwordx4 v[32:35], v32, s[98:99]
	s_nop 0
	global_load_dwordx4 v[36:39], v36, s[98:99]
	s_nop 0
	global_load_dwordx4 v[40:43], v40, s[98:99]
	s_nop 0
	global_load_dwordx4 v[44:47], v44, s[98:99]
	s_nop 0
	global_load_dwordx4 v[48:51], v48, s[98:99]
	s_nop 0
	global_load_dwordx4 v[52:55], v52, s[98:99]
	s_nop 0
	global_load_dwordx4 v[56:59], v56, s[98:99]
	s_nop 0
	global_load_dwordx4 v[60:63], v60, s[98:99]
	s_nop 0
	global_load_dword v180, v[162:163], off
	global_load_dword v130, v[162:163], off offset:256

; DI void axpy_fp8_row(f32x2 (&o)[8], float wgt, u32x4 v) {
;     const f32x2 w2 = {wgt, wgt};
; #pragma unroll
;     for (int j = 0; j < 4; ++j) {
;         const f32x2 lo = __builtin_amdgcn_cvt_pk_f32_fp8(v[j], false), hi = __builtin_amdgcn_cvt_pk_f32_fp8(v[j], true);
;         o[2 * j] = __builtin_elementwise_fma(w2, lo, o[2 * j]);
;         o[2 * j + 1] = __builtin_elementwise_fma(w2, hi, o[2 * j + 1]);
;     }
; }
.LBB0_1362:
	s_or_b64 exec, exec, s[0:1]
	s_setprio 1
	s_waitcnt vmcnt(17)
	ds_bpermute_b32 v182, v129, v177
	s_waitcnt vmcnt(15)
	v_cvt_pk_f32_fp8_e32 v[184:185], v64
	v_cvt_pk_f32_fp8_sdwa v[188:189], v64 src0_sel:WORD_1
	v_cvt_pk_f32_fp8_e32 v[190:191], v65
	v_cvt_pk_f32_fp8_sdwa v[198:199], v65 src0_sel:WORD_1
	v_cvt_pk_f32_fp8_e32 v[200:201], v66
	v_cvt_pk_f32_fp8_sdwa v[202:203], v66 src0_sel:WORD_1
	v_cvt_pk_f32_fp8_e32 v[204:205], v67
	v_cvt_pk_f32_fp8_sdwa v[206:207], v67 src0_sel:WORD_1
	ds_bpermute_b32 v196, v164, v177
	s_waitcnt lgkmcnt(1)
	v_pk_fma_f32 v[184:185], v[182:183], v[184:185], 0 op_sel_hi:[0,1,0]
	v_pk_fma_f32 v[188:189], v[182:183], v[188:189], 0 op_sel_hi:[0,1,0]
	v_pk_fma_f32 v[190:191], v[182:183], v[190:191], 0 op_sel_hi:[0,1,0]
	v_pk_fma_f32 v[198:199], v[182:183], v[198:199], 0 op_sel_hi:[0,1,0]
	v_pk_fma_f32 v[200:201], v[182:183], v[200:201], 0 op_sel_hi:[0,1,0]
	v_pk_fma_f32 v[202:203], v[182:183], v[202:203], 0 op_sel_hi:[0,1,0]
	v_pk_fma_f32 v[204:205], v[182:183], v[204:205], 0 op_sel_hi:[0,1,0]
	v_pk_fma_f32 v[182:183], v[182:183], v[206:207], 0 op_sel_hi:[0,1,0]
	s_waitcnt vmcnt(14)
	v_cvt_pk_f32_fp8_e32 v[206:207], v68
	v_cvt_pk_f32_fp8_sdwa v[208:209], v68 src0_sel:WORD_1
	v_cvt_pk_f32_fp8_e32 v[210:211], v69
	v_cvt_pk_f32_fp8_sdwa v[212:213], v69 src0_sel:WORD_1
	s_waitcnt lgkmcnt(0)
	v_pk_fma_f32 v[184:185], v[196:197], v[206:207], v[184:185] op_sel_hi:[0,1,1]
	v_pk_fma_f32 v[188:189], v[196:197], v[208:209], v[188:189] op_sel_hi:[0,1,1]
	v_pk_fma_f32 v[190:191], v[196:197], v[210:211], v[190:191] op_sel_hi:[0,1,1]
	v_pk_fma_f32 v[198:199], v[196:197], v[212:213], v[198:199] op_sel_hi:[0,1,1]
	v_cvt_pk_f32_fp8_e32 v[206:207], v70
	v_cvt_pk_f32_fp8_sdwa v[208:209], v70 src0_sel:WORD_1
	v_cvt_pk_f32_fp8_e32 v[210:211], v71
	v_cvt_pk_f32_fp8_sdwa v[212:213], v71 src0_sel:WORD_1
	v_pk_fma_f32 v[200:201], v[196:197], v[206:207], v[200:201] op_sel_hi:[0,1,1]
	v_pk_fma_f32 v[202:203], v[196:197], v[208:209], v[202:203] op_sel_hi:[0,1,1]
	v_pk_fma_f32 v[204:205], v[196:197], v[210:211], v[204:205] op_sel_hi:[0,1,1]
	v_pk_fma_f32 v[182:183], v[196:197], v[212:213], v[182:183] op_sel_hi:[0,1,1]
	ds_bpermute_b32 v196, v165, v177
	s_waitcnt vmcnt(13)
	v_cvt_pk_f32_fp8_e32 v[206:207], v72
	v_cvt_pk_f32_fp8_sdwa v[208:209], v72 src0_sel:WORD_1
	v_cvt_pk_f32_fp8_e32 v[210:211], v73
	v_cvt_pk_f32_fp8_sdwa v[212:213], v73 src0_sel:WORD_1
	s_waitcnt lgkmcnt(0)
	v_pk_fma_f32 v[184:185], v[196:197], v[206:207], v[184:185] op_sel_hi:[0,1,1]
	v_pk_fma_f32 v[188:189], v[196:197], v[208:209], v[188:189] op_sel_hi:[0,1,1]
	v_pk_fma_f32 v[190:191], v[196:197], v[210:211], v[190:191] op_sel_hi:[0,1,1]
	v_pk_fma_f32 v[198:199], v[196:197], v[212:213], v[198:199] op_sel_hi:[0,1,1]
	v_cvt_pk_f32_fp8_e32 v[206:207], v74
	v_cvt_pk_f32_fp8_sdwa v[208:209], v74 src0_sel:WORD_1
	v_cvt_pk_f32_fp8_e32 v[210:211], v75
	v_cvt_pk_f32_fp8_sdwa v[212:213], v75 src0_sel:WORD_1
	v_pk_fma_f32 v[200:201], v[196:197], v[206:207], v[200:201] op_sel_hi:[0,1,1]
	v_pk_fma_f32 v[202:203], v[196:197], v[208:209], v[202:203] op_sel_hi:[0,1,1]
	v_pk_fma_f32 v[204:205], v[196:197], v[210:211], v[204:205] op_sel_hi:[0,1,1]
	v_pk_fma_f32 v[182:183], v[196:197], v[212:213], v[182:183] op_sel_hi:[0,1,1]
	ds_bpermute_b32 v196, v166, v177
	s_waitcnt vmcnt(12)
	v_cvt_pk_f32_fp8_e32 v[206:207], v76
	v_cvt_pk_f32_fp8_sdwa v[208:209], v76 src0_sel:WORD_1
	v_cvt_pk_f32_fp8_e32 v[210:211], v77
	v_cvt_pk_f32_fp8_sdwa v[212:213], v77 src0_sel:WORD_1
	s_waitcnt lgkmcnt(0)
	v_pk_fma_f32 v[184:185], v[196:197], v[206:207], v[184:185] op_sel_hi:[0,1,1]
	v_pk_fma_f32 v[188:189], v[196:197], v[208:209], v[188:189] op_sel_hi:[0,1,1]
	v_pk_fma_f32 v[190:191], v[196:197], v[210:211], v[190:191] op_sel_hi:[0,1,1]
	v_pk_fma_f32 v[198:199], v[196:197], v[212:213], v[198:199] op_sel_hi:[0,1,1]
	v_cvt_pk_f32_fp8_e32 v[206:207], v78
	v_cvt_pk_f32_fp8_sdwa v[208:209], v78 src0_sel:WORD_1
	v_cvt_pk_f32_fp8_e32 v[210:211], v79
	v_cvt_pk_f32_fp8_sdwa v[212:213], v79 src0_sel:WORD_1
	v_pk_fma_f32 v[200:201], v[196:197], v[206:207], v[200:201] op_sel_hi:[0,1,1]
	v_pk_fma_f32 v[202:203], v[196:197], v[208:209], v[202:203] op_sel_hi:[0,1,1]
	v_pk_fma_f32 v[204:205], v[196:197], v[210:211], v[204:205] op_sel_hi:[0,1,1]
	v_pk_fma_f32 v[182:183], v[196:197], v[212:213], v[182:183] op_sel_hi:[0,1,1]
	ds_bpermute_b32 v196, v167, v177
	s_waitcnt vmcnt(11)
	v_cvt_pk_f32_fp8_e32 v[206:207], v80
	v_cvt_pk_f32_fp8_sdwa v[208:209], v80 src0_sel:WORD_1
	v_cvt_pk_f32_fp8_e32 v[210:211], v81
	v_cvt_pk_f32_fp8_sdwa v[212:213], v81 src0_sel:WORD_1
	s_waitcnt lgkmcnt(0)
	v_pk_fma_f32 v[184:185], v[196:197], v[206:207], v[184:185] op_sel_hi:[0,1,1]
	v_pk_fma_f32 v[188:189], v[196:197], v[208:209], v[188:189] op_sel_hi:[0,1,1]
	v_pk_fma_f32 v[190:191], v[196:197], v[210:211], v[190:191] op_sel_hi:[0,1,1]
	v_pk_fma_f32 v[198:199], v[196:197], v[212:213], v[198:199] op_sel_hi:[0,1,1]
	v_cvt_pk_f32_fp8_e32 v[206:207], v82
	v_cvt_pk_f32_fp8_sdwa v[208:209], v82 src0_sel:WORD_1
	v_cvt_pk_f32_fp8_e32 v[210:211], v83
	v_cvt_pk_f32_fp8_sdwa v[212:213], v83 src0_sel:WORD_1
	v_pk_fma_f32 v[200:201], v[196:197], v[206:207], v[200:201] op_sel_hi:[0,1,1]
	v_pk_fma_f32 v[202:203], v[196:197], v[208:209], v[202:203] op_sel_hi:[0,1,1]
	v_pk_fma_f32 v[204:205], v[196:197], v[210:211], v[204:205] op_sel_hi:[0,1,1]
	v_pk_fma_f32 v[182:183], v[196:197], v[212:213], v[182:183] op_sel_hi:[0,1,1]
	ds_bpermute_b32 v196, v168, v177
	s_waitcnt vmcnt(10)
	v_cvt_pk_f32_fp8_e32 v[206:207], v84
	v_cvt_pk_f32_fp8_sdwa v[208:209], v84 src0_sel:WORD_1
	v_cvt_pk_f32_fp8_e32 v[210:211], v85
	v_cvt_pk_f32_fp8_sdwa v[212:213], v85 src0_sel:WORD_1
	s_waitcnt lgkmcnt(0)
; DI void axpy_fp8_row(f32x2 (&o)[8], float wgt, u32x4 v) {
;     const f32x2 w2 = {wgt, wgt};
; #pragma unroll
;     for (int j = 0; j < 4; ++j) {
;         const f32x2 lo = __builtin_amdgcn_cvt_pk_f32_fp8(v[j], false), hi = __builtin_amdgcn_cvt_pk_f32_fp8(v[j], true);
;         o[2 * j] = __builtin_elementwise_fma(w2, lo, o[2 * j]);
;         o[2 * j + 1] = __builtin_elementwise_fma(w2, hi, o[2 * j + 1]);
;     }
; }
	v_pk_fma_f32 v[184:185], v[196:197], v[206:207], v[184:185] op_sel_hi:[0,1,1]
	v_pk_fma_f32 v[188:189], v[196:197], v[208:209], v[188:189] op_sel_hi:[0,1,1]
	v_pk_fma_f32 v[190:191], v[196:197], v[210:211], v[190:191] op_sel_hi:[0,1,1]
	v_pk_fma_f32 v[198:199], v[196:197], v[212:213], v[198:199] op_sel_hi:[0,1,1]
	v_cvt_pk_f32_fp8_e32 v[206:207], v86
	v_cvt_pk_f32_fp8_sdwa v[208:209], v86 src0_sel:WORD_1
	v_cvt_pk_f32_fp8_e32 v[210:211], v87
	v_cvt_pk_f32_fp8_sdwa v[212:213], v87 src0_sel:WORD_1
	v_pk_fma_f32 v[200:201], v[196:197], v[206:207], v[200:201] op_sel_hi:[0,1,1]
	v_pk_fma_f32 v[202:203], v[196:197], v[208:209], v[202:203] op_sel_hi:[0,1,1]
	v_pk_fma_f32 v[204:205], v[196:197], v[210:211], v[204:205] op_sel_hi:[0,1,1]
	v_pk_fma_f32 v[182:183], v[196:197], v[212:213], v[182:183] op_sel_hi:[0,1,1]
	ds_bpermute_b32 v196, v169, v177
	s_waitcnt vmcnt(9)
	v_cvt_pk_f32_fp8_e32 v[206:207], v88
	v_cvt_pk_f32_fp8_sdwa v[208:209], v88 src0_sel:WORD_1
	v_cvt_pk_f32_fp8_e32 v[210:211], v89
	v_cvt_pk_f32_fp8_sdwa v[212:213], v89 src0_sel:WORD_1
	s_waitcnt lgkmcnt(0)
	v_pk_fma_f32 v[184:185], v[196:197], v[206:207], v[184:185] op_sel_hi:[0,1,1]
	v_pk_fma_f32 v[188:189], v[196:197], v[208:209], v[188:189] op_sel_hi:[0,1,1]
	v_pk_fma_f32 v[190:191], v[196:197], v[210:211], v[190:191] op_sel_hi:[0,1,1]
	v_pk_fma_f32 v[198:199], v[196:197], v[212:213], v[198:199] op_sel_hi:[0,1,1]
	v_cvt_pk_f32_fp8_e32 v[206:207], v90
	v_cvt_pk_f32_fp8_sdwa v[208:209], v90 src0_sel:WORD_1
	v_cvt_pk_f32_fp8_e32 v[210:211], v91
	v_cvt_pk_f32_fp8_sdwa v[212:213], v91 src0_sel:WORD_1
	v_pk_fma_f32 v[200:201], v[196:197], v[206:207], v[200:201] op_sel_hi:[0,1,1]
	v_pk_fma_f32 v[202:203], v[196:197], v[208:209], v[202:203] op_sel_hi:[0,1,1]
	v_pk_fma_f32 v[204:205], v[196:197], v[210:211], v[204:205] op_sel_hi:[0,1,1]
	v_pk_fma_f32 v[182:183], v[196:197], v[212:213], v[182:183] op_sel_hi:[0,1,1]
	ds_bpermute_b32 v196, v174, v177
	s_waitcnt vmcnt(8)
	v_cvt_pk_f32_fp8_e32 v[206:207], v92
	v_cvt_pk_f32_fp8_sdwa v[208:209], v92 src0_sel:WORD_1
	v_cvt_pk_f32_fp8_e32 v[210:211], v93
	v_cvt_pk_f32_fp8_sdwa v[212:213], v93 src0_sel:WORD_1
	s_waitcnt lgkmcnt(0)
	v_pk_fma_f32 v[184:185], v[196:197], v[206:207], v[184:185] op_sel_hi:[0,1,1]
	v_pk_fma_f32 v[188:189], v[196:197], v[208:209], v[188:189] op_sel_hi:[0,1,1]
	v_pk_fma_f32 v[190:191], v[196:197], v[210:211], v[190:191] op_sel_hi:[0,1,1]
	v_pk_fma_f32 v[198:199], v[196:197], v[212:213], v[198:199] op_sel_hi:[0,1,1]
	v_cvt_pk_f32_fp8_e32 v[206:207], v94
	v_cvt_pk_f32_fp8_sdwa v[208:209], v94 src0_sel:WORD_1
	v_cvt_pk_f32_fp8_e32 v[210:211], v95
	v_cvt_pk_f32_fp8_sdwa v[212:213], v95 src0_sel:WORD_1
	v_pk_fma_f32 v[200:201], v[196:197], v[206:207], v[200:201] op_sel_hi:[0,1,1]
	v_pk_fma_f32 v[202:203], v[196:197], v[208:209], v[202:203] op_sel_hi:[0,1,1]
	v_pk_fma_f32 v[204:205], v[196:197], v[210:211], v[204:205] op_sel_hi:[0,1,1]
	v_pk_fma_f32 v[182:183], v[196:197], v[212:213], v[182:183] op_sel_hi:[0,1,1]
	ds_bpermute_b32 v196, v129, v179
	s_waitcnt vmcnt(7)
	v_cvt_pk_f32_fp8_e32 v[206:207], v96
	v_cvt_pk_f32_fp8_sdwa v[208:209], v96 src0_sel:WORD_1
	v_cvt_pk_f32_fp8_e32 v[210:211], v97
	v_cvt_pk_f32_fp8_sdwa v[212:213], v97 src0_sel:WORD_1
	s_waitcnt lgkmcnt(0)
	v_pk_fma_f32 v[184:185], v[196:197], v[206:207], v[184:185] op_sel_hi:[0,1,1]
	v_pk_fma_f32 v[188:189], v[196:197], v[208:209], v[188:189] op_sel_hi:[0,1,1]
	v_pk_fma_f32 v[190:191], v[196:197], v[210:211], v[190:191] op_sel_hi:[0,1,1]
	v_pk_fma_f32 v[198:199], v[196:197], v[212:213], v[198:199] op_sel_hi:[0,1,1]
	v_cvt_pk_f32_fp8_e32 v[206:207], v98
	v_cvt_pk_f32_fp8_sdwa v[208:209], v98 src0_sel:WORD_1
	v_cvt_pk_f32_fp8_e32 v[210:211], v99
	v_cvt_pk_f32_fp8_sdwa v[212:213], v99 src0_sel:WORD_1
	v_pk_fma_f32 v[200:201], v[196:197], v[206:207], v[200:201] op_sel_hi:[0,1,1]
	v_pk_fma_f32 v[202:203], v[196:197], v[208:209], v[202:203] op_sel_hi:[0,1,1]
	v_pk_fma_f32 v[204:205], v[196:197], v[210:211], v[204:205] op_sel_hi:[0,1,1]
	v_pk_fma_f32 v[182:183], v[196:197], v[212:213], v[182:183] op_sel_hi:[0,1,1]
	ds_bpermute_b32 v196, v164, v179
	s_waitcnt vmcnt(6)
	v_cvt_pk_f32_fp8_e32 v[206:207], v100
	v_cvt_pk_f32_fp8_sdwa v[208:209], v100 src0_sel:WORD_1
	v_cvt_pk_f32_fp8_e32 v[210:211], v101
	v_cvt_pk_f32_fp8_sdwa v[212:213], v101 src0_sel:WORD_1
	s_waitcnt lgkmcnt(0)
	v_pk_fma_f32 v[184:185], v[196:197], v[206:207], v[184:185] op_sel_hi:[0,1,1]
	v_pk_fma_f32 v[188:189], v[196:197], v[208:209], v[188:189] op_sel_hi:[0,1,1]
	v_pk_fma_f32 v[190:191], v[196:197], v[210:211], v[190:191] op_sel_hi:[0,1,1]
	v_pk_fma_f32 v[198:199], v[196:197], v[212:213], v[198:199] op_sel_hi:[0,1,1]
	v_cvt_pk_f32_fp8_e32 v[206:207], v102
	v_cvt_pk_f32_fp8_sdwa v[208:209], v102 src0_sel:WORD_1
	v_cvt_pk_f32_fp8_e32 v[210:211], v103
	v_cvt_pk_f32_fp8_sdwa v[212:213], v103 src0_sel:WORD_1
	v_pk_fma_f32 v[200:201], v[196:197], v[206:207], v[200:201] op_sel_hi:[0,1,1]
	v_pk_fma_f32 v[202:203], v[196:197], v[208:209], v[202:203] op_sel_hi:[0,1,1]
	v_pk_fma_f32 v[204:205], v[196:197], v[210:211], v[204:205] op_sel_hi:[0,1,1]
	v_pk_fma_f32 v[182:183], v[196:197], v[212:213], v[182:183] op_sel_hi:[0,1,1]
	ds_bpermute_b32 v196, v165, v179
	s_waitcnt vmcnt(5)
	v_cvt_pk_f32_fp8_e32 v[206:207], v104
	v_cvt_pk_f32_fp8_sdwa v[208:209], v104 src0_sel:WORD_1
	v_cvt_pk_f32_fp8_e32 v[210:211], v105
	v_cvt_pk_f32_fp8_sdwa v[212:213], v105 src0_sel:WORD_1
	s_waitcnt lgkmcnt(0)
; DI void axpy_fp8_row(f32x2 (&o)[8], float wgt, u32x4 v) {
;     const f32x2 w2 = {wgt, wgt};
; #pragma unroll
;     for (int j = 0; j < 4; ++j) {
;         const f32x2 lo = __builtin_amdgcn_cvt_pk_f32_fp8(v[j], false), hi = __builtin_amdgcn_cvt_pk_f32_fp8(v[j], true);
;         o[2 * j] = __builtin_elementwise_fma(w2, lo, o[2 * j]);
;         o[2 * j + 1] = __builtin_elementwise_fma(w2, hi, o[2 * j + 1]);
;     }
; }
	v_pk_fma_f32 v[184:185], v[196:197], v[206:207], v[184:185] op_sel_hi:[0,1,1]
	v_pk_fma_f32 v[188:189], v[196:197], v[208:209], v[188:189] op_sel_hi:[0,1,1]
	v_pk_fma_f32 v[190:191], v[196:197], v[210:211], v[190:191] op_sel_hi:[0,1,1]
	v_pk_fma_f32 v[198:199], v[196:197], v[212:213], v[198:199] op_sel_hi:[0,1,1]
	v_cvt_pk_f32_fp8_e32 v[206:207], v106
	v_cvt_pk_f32_fp8_sdwa v[208:209], v106 src0_sel:WORD_1
	v_cvt_pk_f32_fp8_e32 v[210:211], v107
	v_cvt_pk_f32_fp8_sdwa v[212:213], v107 src0_sel:WORD_1
	v_pk_fma_f32 v[200:201], v[196:197], v[206:207], v[200:201] op_sel_hi:[0,1,1]
	v_pk_fma_f32 v[202:203], v[196:197], v[208:209], v[202:203] op_sel_hi:[0,1,1]
	v_pk_fma_f32 v[204:205], v[196:197], v[210:211], v[204:205] op_sel_hi:[0,1,1]
	v_pk_fma_f32 v[182:183], v[196:197], v[212:213], v[182:183] op_sel_hi:[0,1,1]
	ds_bpermute_b32 v196, v166, v179
	s_waitcnt vmcnt(4)
	v_cvt_pk_f32_fp8_e32 v[206:207], v108
	v_cvt_pk_f32_fp8_sdwa v[208:209], v108 src0_sel:WORD_1
	v_cvt_pk_f32_fp8_e32 v[210:211], v109
	v_cvt_pk_f32_fp8_sdwa v[212:213], v109 src0_sel:WORD_1
	s_waitcnt lgkmcnt(0)
	v_pk_fma_f32 v[184:185], v[196:197], v[206:207], v[184:185] op_sel_hi:[0,1,1]
	v_pk_fma_f32 v[188:189], v[196:197], v[208:209], v[188:189] op_sel_hi:[0,1,1]
	v_pk_fma_f32 v[190:191], v[196:197], v[210:211], v[190:191] op_sel_hi:[0,1,1]
	v_pk_fma_f32 v[198:199], v[196:197], v[212:213], v[198:199] op_sel_hi:[0,1,1]
	v_cvt_pk_f32_fp8_e32 v[206:207], v110
	v_cvt_pk_f32_fp8_sdwa v[208:209], v110 src0_sel:WORD_1
	v_cvt_pk_f32_fp8_e32 v[210:211], v111
	v_cvt_pk_f32_fp8_sdwa v[212:213], v111 src0_sel:WORD_1
	v_pk_fma_f32 v[200:201], v[196:197], v[206:207], v[200:201] op_sel_hi:[0,1,1]
	v_pk_fma_f32 v[202:203], v[196:197], v[208:209], v[202:203] op_sel_hi:[0,1,1]
	v_pk_fma_f32 v[204:205], v[196:197], v[210:211], v[204:205] op_sel_hi:[0,1,1]
	v_pk_fma_f32 v[182:183], v[196:197], v[212:213], v[182:183] op_sel_hi:[0,1,1]
	ds_bpermute_b32 v196, v167, v179
	s_waitcnt vmcnt(3)
	v_cvt_pk_f32_fp8_e32 v[206:207], v112
	v_cvt_pk_f32_fp8_sdwa v[208:209], v112 src0_sel:WORD_1
	v_cvt_pk_f32_fp8_e32 v[210:211], v113
	v_cvt_pk_f32_fp8_sdwa v[212:213], v113 src0_sel:WORD_1
	s_waitcnt lgkmcnt(0)
	v_pk_fma_f32 v[184:185], v[196:197], v[206:207], v[184:185] op_sel_hi:[0,1,1]
	v_pk_fma_f32 v[188:189], v[196:197], v[208:209], v[188:189] op_sel_hi:[0,1,1]
	v_pk_fma_f32 v[190:191], v[196:197], v[210:211], v[190:191] op_sel_hi:[0,1,1]
	v_pk_fma_f32 v[198:199], v[196:197], v[212:213], v[198:199] op_sel_hi:[0,1,1]
	v_cvt_pk_f32_fp8_e32 v[206:207], v114
	v_cvt_pk_f32_fp8_sdwa v[208:209], v114 src0_sel:WORD_1
	v_cvt_pk_f32_fp8_e32 v[210:211], v115
	v_cvt_pk_f32_fp8_sdwa v[212:213], v115 src0_sel:WORD_1
	v_pk_fma_f32 v[200:201], v[196:197], v[206:207], v[200:201] op_sel_hi:[0,1,1]
	v_pk_fma_f32 v[202:203], v[196:197], v[208:209], v[202:203] op_sel_hi:[0,1,1]
	v_pk_fma_f32 v[204:205], v[196:197], v[210:211], v[204:205] op_sel_hi:[0,1,1]
	v_pk_fma_f32 v[182:183], v[196:197], v[212:213], v[182:183] op_sel_hi:[0,1,1]
	ds_bpermute_b32 v196, v168, v179
	s_waitcnt vmcnt(2)
	v_cvt_pk_f32_fp8_e32 v[206:207], v116
	v_cvt_pk_f32_fp8_sdwa v[208:209], v116 src0_sel:WORD_1
	v_cvt_pk_f32_fp8_e32 v[210:211], v117
	v_cvt_pk_f32_fp8_sdwa v[212:213], v117 src0_sel:WORD_1
	s_waitcnt lgkmcnt(0)
	v_pk_fma_f32 v[184:185], v[196:197], v[206:207], v[184:185] op_sel_hi:[0,1,1]
	v_pk_fma_f32 v[188:189], v[196:197], v[208:209], v[188:189] op_sel_hi:[0,1,1]
	v_pk_fma_f32 v[190:191], v[196:197], v[210:211], v[190:191] op_sel_hi:[0,1,1]
	v_pk_fma_f32 v[198:199], v[196:197], v[212:213], v[198:199] op_sel_hi:[0,1,1]
	v_cvt_pk_f32_fp8_e32 v[206:207], v118
	v_cvt_pk_f32_fp8_sdwa v[208:209], v118 src0_sel:WORD_1
	v_cvt_pk_f32_fp8_e32 v[210:211], v119
	v_cvt_pk_f32_fp8_sdwa v[212:213], v119 src0_sel:WORD_1
	v_pk_fma_f32 v[200:201], v[196:197], v[206:207], v[200:201] op_sel_hi:[0,1,1]
	v_pk_fma_f32 v[202:203], v[196:197], v[208:209], v[202:203] op_sel_hi:[0,1,1]
	v_pk_fma_f32 v[204:205], v[196:197], v[210:211], v[204:205] op_sel_hi:[0,1,1]
	v_pk_fma_f32 v[182:183], v[196:197], v[212:213], v[182:183] op_sel_hi:[0,1,1]
	ds_bpermute_b32 v196, v169, v179
	s_waitcnt vmcnt(1)
	v_cvt_pk_f32_fp8_e32 v[206:207], v120
	v_cvt_pk_f32_fp8_sdwa v[208:209], v120 src0_sel:WORD_1
	v_cvt_pk_f32_fp8_e32 v[210:211], v121
	v_cvt_pk_f32_fp8_sdwa v[212:213], v121 src0_sel:WORD_1
	s_waitcnt lgkmcnt(0)
	v_pk_fma_f32 v[184:185], v[196:197], v[206:207], v[184:185] op_sel_hi:[0,1,1]
	v_pk_fma_f32 v[188:189], v[196:197], v[208:209], v[188:189] op_sel_hi:[0,1,1]
	v_pk_fma_f32 v[190:191], v[196:197], v[210:211], v[190:191] op_sel_hi:[0,1,1]
	v_pk_fma_f32 v[198:199], v[196:197], v[212:213], v[198:199] op_sel_hi:[0,1,1]
	v_cvt_pk_f32_fp8_e32 v[206:207], v122
	v_cvt_pk_f32_fp8_sdwa v[208:209], v122 src0_sel:WORD_1
	v_cvt_pk_f32_fp8_e32 v[210:211], v123
	v_cvt_pk_f32_fp8_sdwa v[212:213], v123 src0_sel:WORD_1
	v_pk_fma_f32 v[200:201], v[196:197], v[206:207], v[200:201] op_sel_hi:[0,1,1]
	v_pk_fma_f32 v[202:203], v[196:197], v[208:209], v[202:203] op_sel_hi:[0,1,1]
	v_pk_fma_f32 v[204:205], v[196:197], v[210:211], v[204:205] op_sel_hi:[0,1,1]
	v_pk_fma_f32 v[182:183], v[196:197], v[212:213], v[182:183] op_sel_hi:[0,1,1]
	ds_bpermute_b32 v196, v174, v179
	s_waitcnt vmcnt(0)
	v_cvt_pk_f32_fp8_e32 v[206:207], v124
	v_cvt_pk_f32_fp8_sdwa v[208:209], v124 src0_sel:WORD_1
	v_cvt_pk_f32_fp8_e32 v[210:211], v125
	v_cvt_pk_f32_fp8_sdwa v[212:213], v125 src0_sel:WORD_1
	s_waitcnt lgkmcnt(0)
; #define V_ISSUE(SEG, E0, E1) { _Pragma("unroll") for (int b = 0; b < 16; ++b) { const int e = __shfl((b < 8) ? (E0) : (E1), (b & 7) * 8 + grp); SEG[b] = *(const u32x4*)(vb + (size_t)e * DM); } }
; DI void peer_v_phase(const bf16_t* __restrict__ x1, const int* __restrict__ eidx, const float* __restrict__ wgt, const unsigned char* __restrict__ V8, bf16_t* __restrict__ y) {
;     ...
;         {
;             const int e0 = eidx[(size_t)t * 128 + lane], e1 = eidx[(size_t)t * 128 + 64 + lane];
;             w0 = wgt[(size_t)t * 128 + lane]; w1 = wgt[(size_t)t * 128 + 64 + lane];
;             V_ISSUE(sa, e0, e1)
;             if (t + step < T_TOK) { e0n = eidx[(size_t)(t + step) * 128 + lane]; e1n = eidx[(size_t)(t + step) * 128 + 64 + lane]; }
;         }
;         for (; t < T_TOK; t += 2 * step) {
;             int e0nn = 0, e1nn = 0;
;             const bool n1 = t + step < T_TOK, n2 = t + 2 * step < T_TOK, n3 = t + 3 * step < T_TOK;
;             if (n1) { V_ISSUE(sb, e0n, e1n) w0n = wgt[(size_t)(t + step) * 128 + lane]; w1n = wgt[(size_t)(t + step) * 128 + 64 + lane]; }
;             if (n2) { e0nn = eidx[(size_t)(t + 2 * step) * 128 + lane]; e1nn = eidx[(size_t)(t + 2 * step) * 128 + 64 + lane]; }
;             V_COMPUTE(sa, t)
;             if (n1) {
;                 w0 = w0n; w1 = w1n;
;                 if (n2) { V_ISSUE(sa, e0nn, e1nn) w0n = wgt[(size_t)(t + 2 * step) * 128 + lane]; w1n = wgt[(size_t)(t + 2 * step) * 128 + 64 + lane]; }
	v_pk_fma_f32 v[184:185], v[196:197], v[206:207], v[184:185] op_sel_hi:[0,1,1]
	v_cvt_pk_f32_fp8_e32 v[206:207], v126
	v_pk_fma_f32 v[188:189], v[196:197], v[208:209], v[188:189] op_sel_hi:[0,1,1]
	v_cvt_pk_f32_fp8_sdwa v[208:209], v126 src0_sel:WORD_1
	v_pk_fma_f32 v[190:191], v[196:197], v[210:211], v[190:191] op_sel_hi:[0,1,1]
	v_cvt_pk_f32_fp8_e32 v[210:211], v127
	v_pk_fma_f32 v[200:201], v[196:197], v[206:207], v[200:201] op_sel_hi:[0,1,1]
	v_cndmask_b32_e64 v161, v184, v200, s[6:7]
	v_pk_fma_f32 v[198:199], v[196:197], v[212:213], v[198:199] op_sel_hi:[0,1,1]
	v_cvt_pk_f32_fp8_sdwa v[212:213], v127 src0_sel:WORD_1
	v_pk_fma_f32 v[202:203], v[196:197], v[208:209], v[202:203] op_sel_hi:[0,1,1]
	ds_bpermute_b32 v206, v173, v161
	v_cndmask_b32_e64 v161, v185, v201, s[6:7]
	ds_bpermute_b32 v207, v173, v161
	v_cndmask_b32_e64 v161, v188, v202, s[6:7]
	v_pk_fma_f32 v[204:205], v[196:197], v[210:211], v[204:205] op_sel_hi:[0,1,1]
	ds_bpermute_b32 v208, v173, v161
	v_cndmask_b32_e64 v161, v189, v203, s[6:7]
	ds_bpermute_b32 v209, v173, v161
	v_cndmask_b32_e64 v161, v190, v204, s[6:7]
	v_pk_fma_f32 v[182:183], v[196:197], v[212:213], v[182:183] op_sel_hi:[0,1,1]
	ds_bpermute_b32 v210, v173, v161
	v_cndmask_b32_e64 v161, v191, v205, s[6:7]
	ds_bpermute_b32 v211, v173, v161
	v_cndmask_b32_e64 v161, v198, v182, s[6:7]
	ds_bpermute_b32 v212, v173, v161
	v_cndmask_b32_e64 v161, v199, v183, s[6:7]
	ds_bpermute_b32 v213, v173, v161
	s_setprio 0
	v_ashrrev_i32_e32 v161, 31, v160
	v_lshlrev_b64 v[214:215], 11, v[160:161]
	v_lshl_add_u64 v[216:217], v[154:155], 0, v[214:215]
	global_load_dword v161, v[216:217], off
	v_cndmask_b32_e64 v185, v201, v185, s[6:7]
	v_cndmask_b32_e64 v184, v200, v184, s[6:7]
	v_cndmask_b32_e64 v189, v203, v189, s[6:7]
	v_cndmask_b32_e64 v188, v202, v188, s[6:7]
	v_cndmask_b32_e64 v191, v205, v191, s[6:7]
	v_cndmask_b32_e64 v190, v204, v190, s[6:7]
	v_cndmask_b32_e64 v183, v183, v199, s[6:7]
	v_cndmask_b32_e64 v182, v182, v198, s[6:7]
	s_waitcnt lgkmcnt(6)
	v_pk_add_f32 v[184:185], v[184:185], v[206:207]
	s_waitcnt lgkmcnt(4)
	v_pk_add_f32 v[188:189], v[188:189], v[208:209]
	s_waitcnt lgkmcnt(2)
	v_pk_add_f32 v[190:191], v[190:191], v[210:211]
	s_waitcnt lgkmcnt(0)
	v_pk_add_f32 v[182:183], v[182:183], v[212:213]
	v_cndmask_b32_e64 v187, v184, v190, s[8:9]
	v_cndmask_b32_e64 v199, v191, v185, s[8:9]
	v_cndmask_b32_e64 v185, v185, v191, s[8:9]
	v_cndmask_b32_e64 v191, v188, v182, s[8:9]
	v_cndmask_b32_e64 v196, v189, v183, s[8:9]
	ds_bpermute_b32 v200, v175, v187
	ds_bpermute_b32 v201, v175, v185
	ds_bpermute_b32 v202, v175, v191
	ds_bpermute_b32 v203, v175, v196
	v_cndmask_b32_e64 v198, v190, v184, s[8:9]
	v_cndmask_b32_e64 v183, v183, v189, s[8:9]
	v_cndmask_b32_e64 v182, v182, v188, s[8:9]
	s_waitcnt lgkmcnt(2)
	v_pk_add_f32 v[184:185], v[198:199], v[200:201]
	s_waitcnt lgkmcnt(0)
	v_pk_add_f32 v[182:183], v[182:183], v[202:203]
	s_nop 0
	v_cndmask_b32_e64 v187, v184, v182, s[10:11]
	v_cndmask_b32_e64 v189, v185, v183, s[10:11]
	ds_bpermute_b32 v188, v192, v187
	ds_bpermute_b32 v189, v192, v189
	v_cndmask_b32_e64 v183, v183, v185, s[10:11]
	v_cndmask_b32_e64 v182, v182, v184, s[10:11]
	s_waitcnt lgkmcnt(0)
	v_pk_add_f32 v[182:183], v[182:183], v[188:189]
	s_waitcnt vmcnt(0)
	v_lshlrev_b32_e32 v184, 16, v161
	v_and_b32_e32 v185, 0xffff0000, v161
	v_pk_fma_f32 v[182:183], v[184:185], s[18:19], v[182:183] op_sel_hi:[1,0,1]
	s_nop 0
	v_cvt_pk_bf16_f32 v161, v182, v183
	v_lshl_add_u64 v[182:183], v[156:157], 0, v[214:215]
	global_store_dword v[182:183], v161, off
	s_and_saveexec_b64 s[34:35], s[12:13]
	s_cbranch_execz .LBB0_1357
	v_mov_b32_e32 v179, v130
	v_mov_b32_e32 v177, v180
	s_and_saveexec_b64 s[0:1], s[14:15]
	s_cbranch_execz .LBB0_1365
	ds_bpermute_b32 v64, v129, v181
	ds_bpermute_b32 v66, v164, v181
	ds_bpermute_b32 v72, v165, v181
	ds_bpermute_b32 v74, v166, v181
	ds_bpermute_b32 v80, v167, v181
	ds_bpermute_b32 v82, v168, v181
	ds_bpermute_b32 v88, v169, v181
	ds_bpermute_b32 v90, v174, v181
	ds_bpermute_b32 v96, v129, v163
	ds_bpermute_b32 v98, v164, v163
	ds_bpermute_b32 v104, v165, v163
	ds_bpermute_b32 v106, v166, v163
	ds_bpermute_b32 v112, v167, v163
	ds_bpermute_b32 v114, v168, v163
	ds_bpermute_b32 v120, v169, v163
	ds_bpermute_b32 v122, v174, v163
	s_waitcnt lgkmcnt(0)
	v_ashrrev_i32_e32 v163, 31, v162
	v_lshl_add_u32 v64, v64, 10, v252
	v_lshl_add_u32 v66, v66, 10, v252
	v_lshl_add_u32 v72, v72, 10, v252
	v_lshl_add_u32 v74, v74, 10, v252
	v_lshl_add_u32 v80, v80, 10, v252
	v_lshl_add_u32 v82, v82, 10, v252
	v_lshl_add_u32 v88, v88, 10, v252
	v_lshl_add_u32 v90, v90, 10, v252
	v_lshl_add_u32 v96, v96, 10, v252
	v_lshl_add_u32 v98, v98, 10, v252
	v_lshl_add_u32 v104, v104, 10, v252
	v_lshl_add_u32 v106, v106, 10, v252
	v_lshl_add_u32 v112, v112, 10, v252
	v_lshl_add_u32 v114, v114, 10, v252
	v_lshl_add_u32 v120, v120, 10, v252
	v_lshl_add_u32 v122, v122, 10, v252
	v_lshlrev_b64 v[162:163], 9, v[162:163]
	v_mov_b32_e32 v68, v66
	v_mov_b32_e32 v76, v74
	v_mov_b32_e32 v84, v82
	v_mov_b32_e32 v92, v90
	v_mov_b32_e32 v100, v98
	v_mov_b32_e32 v108, v106
	v_mov_b32_e32 v116, v114
	v_mov_b32_e32 v124, v122
	v_lshl_add_u64 v[162:163], v[144:145], 0, v[162:163]
	global_load_dwordx4 v[64:67], v64, s[98:99]
	s_nop 0
	global_load_dwordx4 v[68:71], v68, s[98:99]
	s_nop 0
	global_load_dwordx4 v[72:75], v72, s[98:99]
	s_nop 0
	global_load_dwordx4 v[76:79], v76, s[98:99]
	s_nop 0
	global_load_dwordx4 v[80:83], v80, s[98:99]
	s_nop 0
	global_load_dwordx4 v[84:87], v84, s[98:99]
	s_nop 0
	global_load_dwordx4 v[88:91], v88, s[98:99]
	s_nop 0
	global_load_dwordx4 v[92:95], v92, s[98:99]
	s_nop 0
	global_load_dwordx4 v[96:99], v96, s[98:99]
	s_nop 0
	global_load_dwordx4 v[100:103], v100, s[98:99]
	s_nop 0
	global_load_dwordx4 v[104:107], v104, s[98:99]
	s_nop 0
	global_load_dwordx4 v[108:111], v108, s[98:99]
	s_nop 0
	global_load_dwordx4 v[112:115], v112, s[98:99]
	s_nop 0
	global_load_dwordx4 v[116:119], v116, s[98:99]
	s_nop 0
	global_load_dwordx4 v[120:123], v120, s[98:99]
	s_nop 0
	global_load_dwordx4 v[124:127], v124, s[98:99]
	s_nop 0
	global_load_dword v177, v[162:163], off
	global_load_dword v179, v[162:163], off offset:256

; __global__ void __launch_bounds__(256, 2) mega_fwd(Params P) {
;     extern __shared__ __attribute__((aligned(16))) unsigned char lds[];
	.amdhsa_kernel _Z8mega_fwd6Params
		.amdhsa_group_segment_fixed_size 0
		.amdhsa_private_segment_fixed_size 0
		.amdhsa_kernarg_size 416
		.amdhsa_user_sgpr_count 2
		.amdhsa_user_sgpr_dispatch_ptr 0
		.amdhsa_user_sgpr_queue_ptr 0
		.amdhsa_user_sgpr_kernarg_segment_ptr 1
		.amdhsa_user_sgpr_dispatch_id 0
		.amdhsa_user_sgpr_kernarg_preload_length 0
		.amdhsa_user_sgpr_kernarg_preload_offset 0
		.amdhsa_user_sgpr_private_segment_size 0
		.amdhsa_uses_dynamic_stack 0
		.amdhsa_enable_private_segment 0
		.amdhsa_system_sgpr_workgroup_id_x 1
		.amdhsa_system_sgpr_workgroup_id_y 0
		.amdhsa_system_sgpr_workgroup_id_z 0
		.amdhsa_system_sgpr_workgroup_info 0
		.amdhsa_system_vgpr_workitem_id 2
		.amdhsa_next_free_vgpr 254
		.amdhsa_next_free_sgpr 102
		.amdhsa_accum_offset 256
		.amdhsa_reserve_vcc 1
		.amdhsa_float_round_mode_32 0
		.amdhsa_float_round_mode_16_64 0
		.amdhsa_float_denorm_mode_32 3
		.amdhsa_float_denorm_mode_16_64 3
		.amdhsa_dx10_clamp 1
		.amdhsa_ieee_mode 1
		.amdhsa_fp16_overflow 0
		.amdhsa_tg_split 0
		.amdhsa_exception_fp_ieee_invalid_op 0
		.amdhsa_exception_fp_denorm_src 0
		.amdhsa_exception_fp_ieee_div_zero 0
		.amdhsa_exception_fp_ieee_overflow 0
		.amdhsa_exception_fp_ieee_underflow 0
		.amdhsa_exception_fp_ieee_inexact 0
		.amdhsa_exception_int_div_zero 0
	.end_amdhsa_kernel

; __global__ void __launch_bounds__(256, 2) mega_fwd(Params P) {
;     extern __shared__ __attribute__((aligned(16))) unsigned char lds[];
amdhsa.kernels:
  - .agpr_count:     0
    .args:
      - .offset:         0
        .size:           160
        .value_kind:     by_value
      - .offset:         160
        .size:           4
        .value_kind:     hidden_block_count_x
      - .offset:         164
        .size:           4
        .value_kind:     hidden_block_count_y
      - .offset:         168
        .size:           4
        .value_kind:     hidden_block_count_z
      - .offset:         172
        .size:           2
        .value_kind:     hidden_group_size_x
      - .offset:         174
        .size:           2
        .value_kind:     hidden_group_size_y
      - .offset:         176
        .size:           2
        .value_kind:     hidden_group_size_z
      - .offset:         178
        .size:           2
        .value_kind:     hidden_remainder_x
      - .offset:         180
        .size:           2
        .value_kind:     hidden_remainder_y
      - .offset:         182
        .size:           2
        .value_kind:     hidden_remainder_z
      - .offset:         200
        .size:           8
        .value_kind:     hidden_global_offset_x
      - .offset:         208
        .size:           8
        .value_kind:     hidden_global_offset_y
      - .offset:         216
        .size:           8
        .value_kind:     hidden_global_offset_z
      - .offset:         224
        .size:           2
        .value_kind:     hidden_grid_dims
      - .offset:         248
        .size:           8
        .value_kind:     hidden_multigrid_sync_arg
      - .offset:         280
        .size:           4
        .value_kind:     hidden_dynamic_lds_size
    .group_segment_fixed_size: 0
    .kernarg_segment_align: 8
    .kernarg_segment_size: 416
    .language:       OpenCL C
    .language_version:
      - 2
      - 0
    .max_flat_workgroup_size: 256
    .name:           _Z8mega_fwd6Params
    .private_segment_fixed_size: 0
    .sgpr_count:     108
    .sgpr_spill_count: 20
    .symbol:         _Z8mega_fwd6Params.kd
    .uniform_work_group_size: 1
    .uses_dynamic_stack: false
    .vgpr_count:     254
    .vgpr_spill_count: 0
    .wavefront_size: 64
